# x3 + xgen + B-read base folded into offsets (no VALU in load segments) + merged waits and dropped redundant lgkmcnt waits/nops in the K-loops
# speedup vs baseline: 1.0154x; 1.0154x over previous
; #define PG8_STAGE(bufoff, gbase, voff) do { _Pragma("unroll") for (int _i = 0; _i < 2; ++_i) \
;         __builtin_amdgcn_global_load_lds((const unsigned*)((const char*)(gbase) + (voff)[_i]), (LAS unsigned*)(lds + (bufoff) + ldsw + _i * 8192), 16, 0, 0); } while (0)
; #define PG8_LDA(dst, b, h) do { _Pragma("unroll") for (int m = 0; m < 4; ++m) _Pragma("unroll") for (int k = 0; k < 2; ++k) dst[m][k] = *(const LAS bf16x8*)(lds + PG8_SA(b, h) + aoff + m * 2048 + k * 1024); } while (0)
; #define PG8_LDB(dst, b, h) do { _Pragma("unroll") for (int n = 0; n < 2; ++n) _Pragma("unroll") for (int k = 0; k < 2; ++k) dst[n][k] = *(const LAS bf16x8*)(lds + PG8_SB(b, h) + boff + n * 2048 + k * 1024); } while (0)
; #define PG8_MMA(ai, bj, At, Bt) do { __builtin_amdgcn_s_setprio(1); _Pragma("unroll") for (int m = 0; m < 4; ++m) _Pragma("unroll") for (int n = 0; n < 2; ++n) _Pragma("unroll") for (int k = 0; k < 2; ++k) \
;         acc[ai][bj][m][n] = __builtin_amdgcn_mfma_f32_16x16x32_bf16(Bt[n][k], At[m][k], acc[ai][bj][m][n], 0, 0, 0); __builtin_amdgcn_s_setprio(0); } while (0)
; template <class Epi, bool ALIGN_EPI = true>
; __device__ __forceinline__ void gemm_phase(LAS unsigned char* lds, const Gemm g, const Sched& S, const Epi& E) {
;     ...
;         for (int t = t_lo; t < t_hi; t += 2) {
;             const bool last = (t == nt - 2);
;             const char* a1 = cA + (size_t)(t + 1) * kstep;
;             const char* a2 = last ? nA : cA + (size_t)(t + 2) * kstep; const char* b2 = last ? nB : cB + (size_t)(t + 2) * kstep;
;             const char* a3 = a2 + kstep; const char* b3 = b2 + kstep;
;             const int rflag = __builtin_amdgcn_readfirstlane(t | (int)(ui == 0));
;             PG8_LDB(B0, 0, 0); PG8_LDB(B1, 0, 1); PG8_SCHED; PG8_LDA(At, 0, 0); PG8_STAGE(PG8_SA(1, 1), a1 + hstepA, voffA);
;             if constexpr (Epi::NSTORES > 0) PG8_WAIT_RELAX(rflag, 8 + Epi::NSTORES); else PG8_WAIT_V(8);
;             PG8_WAIT_L(0); PG8_BAR; PG8_MMA(0, 0, At, B0); PG8_MMA(0, 1, At, B1); PG8_BAR; PG8_SCHED;
;             PG8_LDA(At, 0, 1); PG8_STAGE(PG8_SB(0, 0), b2, voffB); PG8_STAGE(PG8_SB(0, 1), b2 + hstepB, voffB); PG8_STAGE(PG8_SA(0, 0), a2, voffA);
;             if constexpr (Epi::NSTORES > 0) PG8_WAIT_RELAX(rflag, 8 + Epi::NSTORES); else PG8_WAIT_V(8);
;             PG8_WAIT_L(0); PG8_BAR; PG8_MMA(1, 0, At, B0); PG8_MMA(1, 1, At, B1); PG8_BAR; PG8_SCHED;
.LBB0_314:
	ds_read_b128 v[154:157], v149
	ds_read_b128 v[158:161], v149 offset:1024
	ds_read_b128 v[162:165], v149 offset:2048
	ds_read_b128 v[166:169], v149 offset:3072
	ds_read_b128 v[170:173], v151
	ds_read_b128 v[174:177], v151 offset:1024
	ds_read_b128 v[178:181], v151 offset:2048
	ds_read_b128 v[182:185], v151 offset:3072
	s_add_i32 s49, s44, 2
	s_add_u32 s42, s40, 0xfff80080
	s_addc_u32 s43, s41, -1
	s_cmp_eq_u32 s70, s44
	v_add_u32_e32 v146, s44, v138
	s_cselect_b32 s44, s23, s42
	s_cselect_b32 s45, s21, s43
	s_cselect_b32 s43, s37, s48
	s_cselect_b32 s42, s46, s47
	ds_read_b128 v[186:189], v153
	ds_read_b128 v[190:193], v153 offset:1024
	ds_read_b128 v[194:197], v153 offset:2048
	ds_read_b128 v[198:201], v153 offset:3072
	ds_read_b128 v[202:205], v153 offset:4096
	ds_read_b128 v[206:209], v153 offset:5120
	ds_read_b128 v[210:213], v153 offset:6144
	ds_read_b128 v[214:217], v153 offset:7168
	s_mov_b32 m0, s68
	s_add_u32 s100, s40, 0xfff80000
	s_addc_u32 s101, s41, -1
	global_load_lds_dwordx4 v140, s[100:101]
	s_mov_b32 m0, s69
	s_nop 0
	global_load_lds_dwordx4 v142, s[100:101]
	s_add_i32 m0, s59, 0xc000
	s_nop 0
	global_load_lds_dwordx4 v140, s[40:41]
	s_add_i32 m0, s59, 0xe000
	v_readfirstlane_b32 s52, v146
	global_load_lds_dwordx4 v142, s[40:41]
	s_cmp_eq_u32 s52, 0
	s_cbranch_scc1 .Lrw0
	s_waitcnt vmcnt(8)
.Lrw0:
	s_waitcnt vmcnt(24) lgkmcnt(0)
	s_barrier
	s_setprio 1
	v_mfma_f32_16x16x32_bf16 v[122:125], v[154:157], v[186:189], v[122:125]
	v_mfma_f32_16x16x32_bf16 v[126:129], v[162:165], v[186:189], v[126:129]
	v_mfma_f32_16x16x32_bf16 v[110:113], v[154:157], v[194:197], v[110:113]
	v_mfma_f32_16x16x32_bf16 v[106:109], v[162:165], v[194:197], v[106:109]
	v_mfma_f32_16x16x32_bf16 v[94:97], v[154:157], v[202:205], v[94:97]
	v_mfma_f32_16x16x32_bf16 v[90:93], v[162:165], v[202:205], v[90:93]
	v_mfma_f32_16x16x32_bf16 v[78:81], v[154:157], v[210:213], v[78:81]
	v_mfma_f32_16x16x32_bf16 v[74:77], v[162:165], v[210:213], v[74:77]
	v_mfma_f32_16x16x32_bf16 v[122:125], v[158:161], v[190:193], v[122:125]
	v_mfma_f32_16x16x32_bf16 v[126:129], v[166:169], v[190:193], v[126:129]
	v_mfma_f32_16x16x32_bf16 v[110:113], v[158:161], v[198:201], v[110:113]
	v_mfma_f32_16x16x32_bf16 v[106:109], v[166:169], v[198:201], v[106:109]
	v_mfma_f32_16x16x32_bf16 v[94:97], v[158:161], v[206:209], v[94:97]
	v_mfma_f32_16x16x32_bf16 v[90:93], v[166:169], v[206:209], v[90:93]
	v_mfma_f32_16x16x32_bf16 v[78:81], v[158:161], v[214:217], v[78:81]
	v_mfma_f32_16x16x32_bf16 v[74:77], v[166:169], v[214:217], v[74:77]
	s_setprio 0
	s_setprio 1
	v_mfma_f32_16x16x32_bf16 v[118:121], v[170:173], v[186:189], v[118:121]
	v_mfma_f32_16x16x32_bf16 v[114:117], v[178:181], v[186:189], v[114:117]
	v_mfma_f32_16x16x32_bf16 v[102:105], v[170:173], v[194:197], v[102:105]
	v_mfma_f32_16x16x32_bf16 v[98:101], v[178:181], v[194:197], v[98:101]
	v_mfma_f32_16x16x32_bf16 v[86:89], v[170:173], v[202:205], v[86:89]
	v_mfma_f32_16x16x32_bf16 v[82:85], v[178:181], v[202:205], v[82:85]
	v_mfma_f32_16x16x32_bf16 v[70:73], v[170:173], v[210:213], v[70:73]
	v_mfma_f32_16x16x32_bf16 v[66:69], v[178:181], v[210:213], v[66:69]
	v_mfma_f32_16x16x32_bf16 v[118:121], v[174:177], v[190:193], v[118:121]
	v_mfma_f32_16x16x32_bf16 v[114:117], v[182:185], v[190:193], v[114:117]
	v_mfma_f32_16x16x32_bf16 v[102:105], v[174:177], v[198:201], v[102:105]
	v_mfma_f32_16x16x32_bf16 v[98:101], v[182:185], v[198:201], v[98:101]
	v_mfma_f32_16x16x32_bf16 v[86:89], v[174:177], v[206:209], v[86:89]
	v_mfma_f32_16x16x32_bf16 v[82:85], v[182:185], v[206:209], v[82:85]
	v_mfma_f32_16x16x32_bf16 v[70:73], v[174:177], v[214:217], v[70:73]
	v_mfma_f32_16x16x32_bf16 v[66:69], v[182:185], v[214:217], v[66:69]
	s_setprio 0
	s_barrier
	s_add_i32 s50, s72, s58
	s_mov_b32 m0, s50
	ds_read_b128 v[186:189], v153 offset:16384
	ds_read_b128 v[190:193], v153 offset:17408
	ds_read_b128 v[194:197], v153 offset:18432
	ds_read_b128 v[198:201], v153 offset:19456
	ds_read_b128 v[202:205], v153 offset:20480
	ds_read_b128 v[206:209], v153 offset:21504
	ds_read_b128 v[210:213], v153 offset:22528
	ds_read_b128 v[214:217], v153 offset:23552
	global_load_lds_dwordx4 v132, s[42:43]
	s_add_i32 m0, s50, 0x2000
	s_add_u32 s50, s42, 0x80000
	s_addc_u32 s51, s43, 0
	s_add_i32 s53, s73, s58
	global_load_lds_dwordx4 v136, s[42:43]
	s_mov_b32 m0, s53
	s_nop 0
	global_load_lds_dwordx4 v132, s[50:51]
	s_add_i32 m0, s53, 0x2000
	s_nop 0
	global_load_lds_dwordx4 v136, s[50:51]
; #define PG8_STAGE(bufoff, gbase, voff) do { _Pragma("unroll") for (int _i = 0; _i < 2; ++_i) \
;         __builtin_amdgcn_global_load_lds((const unsigned*)((const char*)(gbase) + (voff)[_i]), (LAS unsigned*)(lds + (bufoff) + ldsw + _i * 8192), 16, 0, 0); } while (0)
; #define PG8_LDA(dst, b, h) do { _Pragma("unroll") for (int m = 0; m < 4; ++m) _Pragma("unroll") for (int k = 0; k < 2; ++k) dst[m][k] = *(const LAS bf16x8*)(lds + PG8_SA(b, h) + aoff + m * 2048 + k * 1024); } while (0)
; #define PG8_LDB(dst, b, h) do { _Pragma("unroll") for (int n = 0; n < 2; ++n) _Pragma("unroll") for (int k = 0; k < 2; ++k) dst[n][k] = *(const LAS bf16x8*)(lds + PG8_SB(b, h) + boff + n * 2048 + k * 1024); } while (0)
; #define PG8_MMA(ai, bj, At, Bt) do { __builtin_amdgcn_s_setprio(1); _Pragma("unroll") for (int m = 0; m < 4; ++m) _Pragma("unroll") for (int n = 0; n < 2; ++n) _Pragma("unroll") for (int k = 0; k < 2; ++k) \
;         acc[ai][bj][m][n] = __builtin_amdgcn_mfma_f32_16x16x32_bf16(Bt[n][k], At[m][k], acc[ai][bj][m][n], 0, 0, 0); __builtin_amdgcn_s_setprio(0); } while (0)
; #define PG8_WAIT_V(n) asm volatile("s_waitcnt vmcnt(" #n ")" ::: "memory")
; #define PG8_WAIT_L(n) asm volatile("s_waitcnt lgkmcnt(" #n ")" ::: "memory")
; #define PG8_BAR __builtin_amdgcn_s_barrier()
; #define PG8_WAIT_RELAX(flag, n) asm volatile("s_cmp_eq_u32 %0, 0\n\ts_cbranch_scc1 .Lrw%=\n\ts_waitcnt vmcnt(8)\n.Lrw%=:\n\ts_waitcnt vmcnt(%1)" :: "s"(flag), "n"(n) : "scc", "memory")
; #define PG8_SCHED __builtin_amdgcn_sched_barrier(0)
; template <class Epi, bool ALIGN_EPI = true>
; __device__ __forceinline__ void gemm_phase(LAS unsigned char* lds, const Gemm g, const Sched& S, const Epi& E) {
;     ...
;             if constexpr (Epi::NSTORES > 0) PG8_WAIT_RELAX(rflag, 8 + Epi::NSTORES); else PG8_WAIT_V(8);
;             PG8_WAIT_L(0); PG8_BAR; PG8_MMA(1, 0, At, B0); PG8_MMA(1, 1, At, B1); PG8_BAR; PG8_SCHED;
;             PG8_LDB(B0, 1, 0); PG8_LDB(B1, 1, 1); PG8_SCHED; PG8_LDA(At, 1, 0); PG8_STAGE(PG8_SA(0, 1), a2 + hstepA, voffA);
;             PG8_WAIT_V(8); PG8_WAIT_L(0); PG8_BAR; PG8_MMA(0, 0, At, B0); PG8_MMA(0, 1, At, B1); PG8_BAR; PG8_SCHED;
.Lrw1:
	s_waitcnt vmcnt(6) lgkmcnt(0)
	s_barrier
	s_setprio 1
	v_mfma_f32_16x16x32_bf16 v[62:65], v[154:157], v[186:189], v[62:65]
	v_mfma_f32_16x16x32_bf16 v[58:61], v[162:165], v[186:189], v[58:61]
	v_mfma_f32_16x16x32_bf16 v[46:49], v[154:157], v[194:197], v[46:49]
	v_mfma_f32_16x16x32_bf16 v[42:45], v[162:165], v[194:197], v[42:45]
	v_mfma_f32_16x16x32_bf16 v[30:33], v[154:157], v[202:205], v[30:33]
	v_mfma_f32_16x16x32_bf16 v[26:29], v[162:165], v[202:205], v[26:29]
	v_mfma_f32_16x16x32_bf16 v[14:17], v[154:157], v[210:213], v[14:17]
	v_mfma_f32_16x16x32_bf16 v[10:13], v[162:165], v[210:213], v[10:13]
	v_mfma_f32_16x16x32_bf16 v[62:65], v[158:161], v[190:193], v[62:65]
	v_mfma_f32_16x16x32_bf16 v[58:61], v[166:169], v[190:193], v[58:61]
	v_mfma_f32_16x16x32_bf16 v[46:49], v[158:161], v[198:201], v[46:49]
	v_mfma_f32_16x16x32_bf16 v[42:45], v[166:169], v[198:201], v[42:45]
	v_mfma_f32_16x16x32_bf16 v[30:33], v[158:161], v[206:209], v[30:33]
	v_mfma_f32_16x16x32_bf16 v[26:29], v[166:169], v[206:209], v[26:29]
	v_mfma_f32_16x16x32_bf16 v[14:17], v[158:161], v[214:217], v[14:17]
	v_mfma_f32_16x16x32_bf16 v[10:13], v[166:169], v[214:217], v[10:13]
	s_setprio 0
	s_setprio 1
	v_mfma_f32_16x16x32_bf16 v[54:57], v[170:173], v[186:189], v[54:57]
	v_mfma_f32_16x16x32_bf16 v[50:53], v[178:181], v[186:189], v[50:53]
	v_mfma_f32_16x16x32_bf16 v[38:41], v[170:173], v[194:197], v[38:41]
	v_mfma_f32_16x16x32_bf16 v[34:37], v[178:181], v[194:197], v[34:37]
	v_mfma_f32_16x16x32_bf16 v[22:25], v[170:173], v[202:205], v[22:25]
	v_mfma_f32_16x16x32_bf16 v[18:21], v[178:181], v[202:205], v[18:21]
	v_mfma_f32_16x16x32_bf16 v[6:9], v[170:173], v[210:213], v[6:9]
	v_mfma_f32_16x16x32_bf16 v[2:5], v[178:181], v[210:213], v[2:5]
	v_mfma_f32_16x16x32_bf16 v[54:57], v[174:177], v[190:193], v[54:57]
	v_mfma_f32_16x16x32_bf16 v[50:53], v[182:185], v[190:193], v[50:53]
	v_mfma_f32_16x16x32_bf16 v[38:41], v[174:177], v[198:201], v[38:41]
	v_mfma_f32_16x16x32_bf16 v[34:37], v[182:185], v[198:201], v[34:37]
	v_mfma_f32_16x16x32_bf16 v[22:25], v[174:177], v[206:209], v[22:25]
	v_mfma_f32_16x16x32_bf16 v[18:21], v[182:185], v[206:209], v[18:21]
	v_mfma_f32_16x16x32_bf16 v[6:9], v[174:177], v[214:217], v[6:9]
	v_mfma_f32_16x16x32_bf16 v[2:5], v[182:185], v[214:217], v[2:5]
	s_setprio 0
	s_barrier
	s_add_i32 s50, 0, 0x18000
	v_add_u32_e32 v146, s50, v147
	s_add_i32 s51, 0, 0x1c000
	ds_read_b128 v[154:157], v146
	ds_read_b128 v[158:161], v146 offset:1024
	ds_read_b128 v[162:165], v146 offset:2048
	ds_read_b128 v[166:169], v146 offset:3072
	v_add_u32_e32 v146, s51, v147
	ds_read_b128 v[170:173], v146
	ds_read_b128 v[174:177], v146 offset:1024
	ds_read_b128 v[178:181], v146 offset:2048
	ds_read_b128 v[182:185], v146 offset:3072
	s_add_u32 s44, s44, 0x80000
	s_addc_u32 s45, s45, 0
	ds_read_b128 v[186:189], v153 offset:32768
	ds_read_b128 v[190:193], v153 offset:33792
	ds_read_b128 v[194:197], v153 offset:34816
	ds_read_b128 v[198:201], v153 offset:35840
	ds_read_b128 v[202:205], v153 offset:36864
	ds_read_b128 v[206:209], v153 offset:37888
	ds_read_b128 v[210:213], v153 offset:38912
	ds_read_b128 v[214:217], v153 offset:39936
	s_mov_b32 m0, s59
	s_add_u32 s100, s44, 0xfff80000
	s_addc_u32 s101, s45, -1
	global_load_lds_dwordx4 v130, s[100:101]
	s_mov_b32 m0, s60
	s_nop 0
	global_load_lds_dwordx4 v134, s[100:101]
	s_mov_b32 m0, s61
	s_nop 0
	global_load_lds_dwordx4 v130, s[44:45]
	s_mov_b32 m0, s62
	s_nop 0
	global_load_lds_dwordx4 v134, s[44:45]
	s_waitcnt vmcnt(8) lgkmcnt(0)
	s_barrier
; #define PG8_STAGE(bufoff, gbase, voff) do { _Pragma("unroll") for (int _i = 0; _i < 2; ++_i) \
;         __builtin_amdgcn_global_load_lds((const unsigned*)((const char*)(gbase) + (voff)[_i]), (LAS unsigned*)(lds + (bufoff) + ldsw + _i * 8192), 16, 0, 0); } while (0)
; #define PG8_LDA(dst, b, h) do { _Pragma("unroll") for (int m = 0; m < 4; ++m) _Pragma("unroll") for (int k = 0; k < 2; ++k) dst[m][k] = *(const LAS bf16x8*)(lds + PG8_SA(b, h) + aoff + m * 2048 + k * 1024); } while (0)
; #define PG8_MMA(ai, bj, At, Bt) do { __builtin_amdgcn_s_setprio(1); _Pragma("unroll") for (int m = 0; m < 4; ++m) _Pragma("unroll") for (int n = 0; n < 2; ++n) _Pragma("unroll") for (int k = 0; k < 2; ++k) \
;         acc[ai][bj][m][n] = __builtin_amdgcn_mfma_f32_16x16x32_bf16(Bt[n][k], At[m][k], acc[ai][bj][m][n], 0, 0, 0); __builtin_amdgcn_s_setprio(0); } while (0)
; #define PG8_WAIT_V(n) asm volatile("s_waitcnt vmcnt(" #n ")" ::: "memory")
; #define PG8_WAIT_L(n) asm volatile("s_waitcnt lgkmcnt(" #n ")" ::: "memory")
; #define PG8_BAR __builtin_amdgcn_s_barrier()
; #define PG8_SCHED __builtin_amdgcn_sched_barrier(0)
; template <class Epi, bool ALIGN_EPI = true>
; __device__ __forceinline__ void gemm_phase(LAS unsigned char* lds, const Gemm g, const Sched& S, const Epi& E) {
;     ...
;             PG8_WAIT_V(8); PG8_WAIT_L(0); PG8_BAR; PG8_MMA(0, 0, At, B0); PG8_MMA(0, 1, At, B1); PG8_BAR; PG8_SCHED;
;             PG8_LDA(At, 1, 1); PG8_STAGE(PG8_SB(1, 0), b3, voffB); PG8_STAGE(PG8_SB(1, 1), b3 + hstepB, voffB); PG8_STAGE(PG8_SA(1, 0), a3, voffA);
;             PG8_WAIT_V(8); PG8_WAIT_L(0); PG8_BAR; PG8_MMA(1, 0, At, B0); PG8_MMA(1, 1, At, B1); PG8_BAR; PG8_SCHED;
;         }
	s_setprio 1
	v_mfma_f32_16x16x32_bf16 v[122:125], v[154:157], v[186:189], v[122:125]
	v_mfma_f32_16x16x32_bf16 v[126:129], v[162:165], v[186:189], v[126:129]
	v_mfma_f32_16x16x32_bf16 v[110:113], v[154:157], v[194:197], v[110:113]
	v_mfma_f32_16x16x32_bf16 v[106:109], v[162:165], v[194:197], v[106:109]
	v_mfma_f32_16x16x32_bf16 v[94:97], v[154:157], v[202:205], v[94:97]
	v_mfma_f32_16x16x32_bf16 v[90:93], v[162:165], v[202:205], v[90:93]
	v_mfma_f32_16x16x32_bf16 v[78:81], v[154:157], v[210:213], v[78:81]
	v_mfma_f32_16x16x32_bf16 v[74:77], v[162:165], v[210:213], v[74:77]
	v_mfma_f32_16x16x32_bf16 v[122:125], v[158:161], v[190:193], v[122:125]
	v_mfma_f32_16x16x32_bf16 v[126:129], v[166:169], v[190:193], v[126:129]
	v_mfma_f32_16x16x32_bf16 v[110:113], v[158:161], v[198:201], v[110:113]
	v_mfma_f32_16x16x32_bf16 v[106:109], v[166:169], v[198:201], v[106:109]
	v_mfma_f32_16x16x32_bf16 v[94:97], v[158:161], v[206:209], v[94:97]
	v_mfma_f32_16x16x32_bf16 v[90:93], v[166:169], v[206:209], v[90:93]
	v_mfma_f32_16x16x32_bf16 v[78:81], v[158:161], v[214:217], v[78:81]
	v_mfma_f32_16x16x32_bf16 v[74:77], v[166:169], v[214:217], v[74:77]
	s_setprio 0
	s_setprio 1
	v_mfma_f32_16x16x32_bf16 v[118:121], v[170:173], v[186:189], v[118:121]
	v_mfma_f32_16x16x32_bf16 v[114:117], v[178:181], v[186:189], v[114:117]
	v_mfma_f32_16x16x32_bf16 v[102:105], v[170:173], v[194:197], v[102:105]
	v_mfma_f32_16x16x32_bf16 v[98:101], v[178:181], v[194:197], v[98:101]
	v_mfma_f32_16x16x32_bf16 v[86:89], v[170:173], v[202:205], v[86:89]
	v_mfma_f32_16x16x32_bf16 v[82:85], v[178:181], v[202:205], v[82:85]
	v_mfma_f32_16x16x32_bf16 v[70:73], v[170:173], v[210:213], v[70:73]
	v_mfma_f32_16x16x32_bf16 v[66:69], v[178:181], v[210:213], v[66:69]
	v_mfma_f32_16x16x32_bf16 v[118:121], v[174:177], v[190:193], v[118:121]
	v_mfma_f32_16x16x32_bf16 v[114:117], v[182:185], v[190:193], v[114:117]
	v_mfma_f32_16x16x32_bf16 v[102:105], v[174:177], v[198:201], v[102:105]
	v_mfma_f32_16x16x32_bf16 v[98:101], v[182:185], v[198:201], v[98:101]
	v_mfma_f32_16x16x32_bf16 v[86:89], v[174:177], v[206:209], v[86:89]
	v_mfma_f32_16x16x32_bf16 v[82:85], v[182:185], v[206:209], v[82:85]
	v_mfma_f32_16x16x32_bf16 v[70:73], v[174:177], v[214:217], v[70:73]
	v_mfma_f32_16x16x32_bf16 v[66:69], v[182:185], v[214:217], v[66:69]
	s_setprio 0
	s_barrier
	s_add_u32 s100, s42, 0x80
	s_addc_u32 s101, s43, 0
	s_add_i32 s44, s50, s58
	s_mov_b32 m0, s44
	ds_read_b128 v[186:189], v153 offset:49152
	ds_read_b128 v[190:193], v153 offset:50176
	ds_read_b128 v[194:197], v153 offset:51200
	ds_read_b128 v[198:201], v153 offset:52224
	ds_read_b128 v[202:205], v153 offset:53248
	ds_read_b128 v[206:209], v153 offset:54272
	ds_read_b128 v[210:213], v153 offset:55296
	ds_read_b128 v[214:217], v153 offset:56320
	global_load_lds_dwordx4 v132, s[100:101]
	s_add_i32 m0, s44, 0x2000
	s_add_u32 s42, s42, 0x80080
	s_addc_u32 s43, s43, 0
	s_add_i32 s44, s51, s58
	global_load_lds_dwordx4 v136, s[100:101]
	s_mov_b32 m0, s44
	s_nop 0
	global_load_lds_dwordx4 v132, s[42:43]
	s_add_i32 m0, s44, 0x2000
	s_nop 0
	global_load_lds_dwordx4 v136, s[42:43]
	s_waitcnt vmcnt(6) lgkmcnt(0)
	s_barrier
	s_setprio 1
	v_mfma_f32_16x16x32_bf16 v[62:65], v[154:157], v[186:189], v[62:65]
	v_mfma_f32_16x16x32_bf16 v[58:61], v[162:165], v[186:189], v[58:61]
	v_mfma_f32_16x16x32_bf16 v[46:49], v[154:157], v[194:197], v[46:49]
	v_mfma_f32_16x16x32_bf16 v[42:45], v[162:165], v[194:197], v[42:45]
	v_mfma_f32_16x16x32_bf16 v[30:33], v[154:157], v[202:205], v[30:33]
	v_mfma_f32_16x16x32_bf16 v[26:29], v[162:165], v[202:205], v[26:29]
	v_mfma_f32_16x16x32_bf16 v[14:17], v[154:157], v[210:213], v[14:17]
	v_mfma_f32_16x16x32_bf16 v[10:13], v[162:165], v[210:213], v[10:13]
	v_mfma_f32_16x16x32_bf16 v[62:65], v[158:161], v[190:193], v[62:65]
	v_mfma_f32_16x16x32_bf16 v[58:61], v[166:169], v[190:193], v[58:61]
	v_mfma_f32_16x16x32_bf16 v[46:49], v[158:161], v[198:201], v[46:49]
	v_mfma_f32_16x16x32_bf16 v[42:45], v[166:169], v[198:201], v[42:45]
	v_mfma_f32_16x16x32_bf16 v[30:33], v[158:161], v[206:209], v[30:33]
	v_mfma_f32_16x16x32_bf16 v[26:29], v[166:169], v[206:209], v[26:29]
	v_mfma_f32_16x16x32_bf16 v[14:17], v[158:161], v[214:217], v[14:17]
	v_mfma_f32_16x16x32_bf16 v[10:13], v[166:169], v[214:217], v[10:13]
	s_setprio 0
	s_setprio 1
	v_mfma_f32_16x16x32_bf16 v[54:57], v[170:173], v[186:189], v[54:57]
	v_mfma_f32_16x16x32_bf16 v[50:53], v[178:181], v[186:189], v[50:53]
	v_mfma_f32_16x16x32_bf16 v[38:41], v[170:173], v[194:197], v[38:41]
	v_mfma_f32_16x16x32_bf16 v[34:37], v[178:181], v[194:197], v[34:37]
	v_mfma_f32_16x16x32_bf16 v[22:25], v[170:173], v[202:205], v[22:25]
	v_mfma_f32_16x16x32_bf16 v[18:21], v[178:181], v[202:205], v[18:21]
	v_mfma_f32_16x16x32_bf16 v[6:9], v[170:173], v[210:213], v[6:9]
	v_mfma_f32_16x16x32_bf16 v[2:5], v[178:181], v[210:213], v[2:5]
	v_mfma_f32_16x16x32_bf16 v[54:57], v[174:177], v[190:193], v[54:57]
	v_mfma_f32_16x16x32_bf16 v[50:53], v[182:185], v[190:193], v[50:53]
	v_mfma_f32_16x16x32_bf16 v[38:41], v[174:177], v[198:201], v[38:41]
	v_mfma_f32_16x16x32_bf16 v[34:37], v[182:185], v[198:201], v[34:37]
	v_mfma_f32_16x16x32_bf16 v[22:25], v[174:177], v[206:209], v[22:25]
	v_mfma_f32_16x16x32_bf16 v[18:21], v[182:185], v[206:209], v[18:21]
	v_mfma_f32_16x16x32_bf16 v[6:9], v[174:177], v[214:217], v[6:9]
	v_mfma_f32_16x16x32_bf16 v[2:5], v[182:185], v[214:217], v[2:5]
	s_setprio 0
	s_barrier
	s_add_u32 s40, s40, 0x100
	s_addc_u32 s41, s41, 0
	s_add_u32 s47, s47, 0x100
	s_addc_u32 s48, s48, 0
	s_cmp_ge_i32 s49, s65
	s_mov_b32 s44, s49
	s_cbranch_scc0 .LBB0_314

; #define PG8_STAGE(bufoff, gbase, voff) do { _Pragma("unroll") for (int _i = 0; _i < 2; ++_i) \
;         __builtin_amdgcn_global_load_lds((const unsigned*)((const char*)(gbase) + (voff)[_i]), (LAS unsigned*)(lds + (bufoff) + ldsw + _i * 8192), 16, 0, 0); } while (0)
; #define PG8_LDA(dst, b, h) do { _Pragma("unroll") for (int m = 0; m < 4; ++m) _Pragma("unroll") for (int k = 0; k < 2; ++k) dst[m][k] = *(const LAS bf16x8*)(lds + PG8_SA(b, h) + aoff + m * 2048 + k * 1024); } while (0)
; #define PG8_LDB(dst, b, h) do { _Pragma("unroll") for (int n = 0; n < 2; ++n) _Pragma("unroll") for (int k = 0; k < 2; ++k) dst[n][k] = *(const LAS bf16x8*)(lds + PG8_SB(b, h) + boff + n * 2048 + k * 1024); } while (0)
; #define PG8_MMA(ai, bj, At, Bt) do { __builtin_amdgcn_s_setprio(1); _Pragma("unroll") for (int m = 0; m < 4; ++m) _Pragma("unroll") for (int n = 0; n < 2; ++n) _Pragma("unroll") for (int k = 0; k < 2; ++k) \
;         acc[ai][bj][m][n] = __builtin_amdgcn_mfma_f32_16x16x32_bf16(Bt[n][k], At[m][k], acc[ai][bj][m][n], 0, 0, 0); __builtin_amdgcn_s_setprio(0); } while (0)
; template <class Epi, bool ALIGN_EPI = true>
; __device__ __forceinline__ void gemm_phase(LAS unsigned char* lds, const Gemm g, const Sched& S, const Epi& E) {
;     ...
;         for (int t = t_lo; t < t_hi; t += 2) {
;             const bool last = (t == nt - 2);
;             const char* a1 = cA + (size_t)(t + 1) * kstep;
;             const char* a2 = last ? nA : cA + (size_t)(t + 2) * kstep; const char* b2 = last ? nB : cB + (size_t)(t + 2) * kstep;
;             const char* a3 = a2 + kstep; const char* b3 = b2 + kstep;
;             const int rflag = __builtin_amdgcn_readfirstlane(t | (int)(ui == 0));
;             PG8_LDB(B0, 0, 0); PG8_LDB(B1, 0, 1); PG8_SCHED; PG8_LDA(At, 0, 0); PG8_STAGE(PG8_SA(1, 1), a1 + hstepA, voffA);
;             if constexpr (Epi::NSTORES > 0) PG8_WAIT_RELAX(rflag, 8 + Epi::NSTORES); else PG8_WAIT_V(8);
;             PG8_WAIT_L(0); PG8_BAR; PG8_MMA(0, 0, At, B0); PG8_MMA(0, 1, At, B1); PG8_BAR; PG8_SCHED;
;             PG8_LDA(At, 0, 1); PG8_STAGE(PG8_SB(0, 0), b2, voffB); PG8_STAGE(PG8_SB(0, 1), b2 + hstepB, voffB); PG8_STAGE(PG8_SA(0, 0), a2, voffA);
;             if constexpr (Epi::NSTORES > 0) PG8_WAIT_RELAX(rflag, 8 + Epi::NSTORES); else PG8_WAIT_V(8);
;             PG8_WAIT_L(0); PG8_BAR; PG8_MMA(1, 0, At, B0); PG8_MMA(1, 1, At, B1); PG8_BAR; PG8_SCHED;
.LBB0_388:
	ds_read_b128 v[150:153], v145
	ds_read_b128 v[154:157], v145 offset:1024
	ds_read_b128 v[158:161], v145 offset:2048
	ds_read_b128 v[162:165], v145 offset:3072
	ds_read_b128 v[166:169], v146
	ds_read_b128 v[170:173], v146 offset:1024
	ds_read_b128 v[174:177], v146 offset:2048
	ds_read_b128 v[178:181], v146 offset:3072
	s_add_i32 s72, s40, 2
	s_add_u32 s36, s34, 0xfff80080
	s_addc_u32 s37, s35, -1
	s_cmp_eq_u32 s59, s40
	v_add_u32_e32 v149, s40, v148
	s_cselect_b32 s40, s67, s36
	s_cselect_b32 s41, s21, s37
	s_cselect_b32 s37, s68, s71
	s_cselect_b32 s36, s69, s70
	ds_read_b128 v[182:185], v147
	ds_read_b128 v[186:189], v147 offset:1024
	ds_read_b128 v[190:193], v147 offset:2048
	ds_read_b128 v[194:197], v147 offset:3072
	ds_read_b128 v[198:201], v147 offset:4096
	ds_read_b128 v[202:205], v147 offset:5120
	ds_read_b128 v[206:209], v147 offset:6144
	ds_read_b128 v[210:213], v147 offset:7168
	s_mov_b32 m0, s57
	s_add_u32 s100, s34, 0xfff80000
	s_addc_u32 s101, s35, -1
	global_load_lds_dwordx4 v138, s[100:101]
	s_mov_b32 m0, s58
	s_nop 0
	global_load_lds_dwordx4 v140, s[100:101]
	s_add_i32 m0, s47, 0xc000
	s_nop 0
	global_load_lds_dwordx4 v138, s[34:35]
	s_add_i32 m0, s47, 0xe000
	v_readfirstlane_b32 s73, v149
	global_load_lds_dwordx4 v140, s[34:35]
	s_cmp_eq_u32 s73, 0
	s_cbranch_scc1 .Lrw2
	s_waitcnt vmcnt(8)
.Lrw2:
	s_waitcnt vmcnt(24) lgkmcnt(0)
	s_barrier
	s_setprio 1
	v_mfma_f32_16x16x32_bf16 v[122:125], v[150:153], v[182:185], v[122:125]
	v_mfma_f32_16x16x32_bf16 v[126:129], v[158:161], v[182:185], v[126:129]
	v_mfma_f32_16x16x32_bf16 v[110:113], v[150:153], v[190:193], v[110:113]
	v_mfma_f32_16x16x32_bf16 v[106:109], v[158:161], v[190:193], v[106:109]
	v_mfma_f32_16x16x32_bf16 v[94:97], v[150:153], v[198:201], v[94:97]
	v_mfma_f32_16x16x32_bf16 v[90:93], v[158:161], v[198:201], v[90:93]
	v_mfma_f32_16x16x32_bf16 v[78:81], v[150:153], v[206:209], v[78:81]
	v_mfma_f32_16x16x32_bf16 v[74:77], v[158:161], v[206:209], v[74:77]
	v_mfma_f32_16x16x32_bf16 v[122:125], v[154:157], v[186:189], v[122:125]
	v_mfma_f32_16x16x32_bf16 v[126:129], v[162:165], v[186:189], v[126:129]
	v_mfma_f32_16x16x32_bf16 v[110:113], v[154:157], v[194:197], v[110:113]
	v_mfma_f32_16x16x32_bf16 v[106:109], v[162:165], v[194:197], v[106:109]
	v_mfma_f32_16x16x32_bf16 v[94:97], v[154:157], v[202:205], v[94:97]
	v_mfma_f32_16x16x32_bf16 v[90:93], v[162:165], v[202:205], v[90:93]
	v_mfma_f32_16x16x32_bf16 v[78:81], v[154:157], v[210:213], v[78:81]
	v_mfma_f32_16x16x32_bf16 v[74:77], v[162:165], v[210:213], v[74:77]
	s_setprio 0
	s_setprio 1
	v_mfma_f32_16x16x32_bf16 v[118:121], v[166:169], v[182:185], v[118:121]
	v_mfma_f32_16x16x32_bf16 v[114:117], v[174:177], v[182:185], v[114:117]
	v_mfma_f32_16x16x32_bf16 v[102:105], v[166:169], v[190:193], v[102:105]
	v_mfma_f32_16x16x32_bf16 v[98:101], v[174:177], v[190:193], v[98:101]
	v_mfma_f32_16x16x32_bf16 v[86:89], v[166:169], v[198:201], v[86:89]
	v_mfma_f32_16x16x32_bf16 v[82:85], v[174:177], v[198:201], v[82:85]
	v_mfma_f32_16x16x32_bf16 v[70:73], v[166:169], v[206:209], v[70:73]
	v_mfma_f32_16x16x32_bf16 v[66:69], v[174:177], v[206:209], v[66:69]
	v_mfma_f32_16x16x32_bf16 v[118:121], v[170:173], v[186:189], v[118:121]
	v_mfma_f32_16x16x32_bf16 v[114:117], v[178:181], v[186:189], v[114:117]
	v_mfma_f32_16x16x32_bf16 v[102:105], v[170:173], v[194:197], v[102:105]
	v_mfma_f32_16x16x32_bf16 v[98:101], v[178:181], v[194:197], v[98:101]
	v_mfma_f32_16x16x32_bf16 v[86:89], v[170:173], v[202:205], v[86:89]
	v_mfma_f32_16x16x32_bf16 v[82:85], v[178:181], v[202:205], v[82:85]
	v_mfma_f32_16x16x32_bf16 v[70:73], v[170:173], v[210:213], v[70:73]
	v_mfma_f32_16x16x32_bf16 v[66:69], v[178:181], v[210:213], v[66:69]
	s_setprio 0
	s_barrier
	s_add_i32 s74, s61, s46
	s_mov_b32 m0, s74
	ds_read_b128 v[182:185], v147 offset:16384
	ds_read_b128 v[186:189], v147 offset:17408
	ds_read_b128 v[190:193], v147 offset:18432
	ds_read_b128 v[194:197], v147 offset:19456
	ds_read_b128 v[198:201], v147 offset:20480
	ds_read_b128 v[202:205], v147 offset:21504
	ds_read_b128 v[206:209], v147 offset:22528
	ds_read_b128 v[210:213], v147 offset:23552
	global_load_lds_dwordx4 v134, s[36:37]
	s_add_i32 m0, s74, 0x2000
	s_add_u32 s74, s36, 0x400000
	s_addc_u32 s75, s37, 0
	s_add_i32 s76, s62, s46
	global_load_lds_dwordx4 v130, s[36:37]
	s_mov_b32 m0, s76
	s_nop 0
	global_load_lds_dwordx4 v134, s[74:75]
	s_add_i32 m0, s76, 0x2000
	s_nop 0
	global_load_lds_dwordx4 v130, s[74:75]
; #define PG8_STAGE(bufoff, gbase, voff) do { _Pragma("unroll") for (int _i = 0; _i < 2; ++_i) \
;         __builtin_amdgcn_global_load_lds((const unsigned*)((const char*)(gbase) + (voff)[_i]), (LAS unsigned*)(lds + (bufoff) + ldsw + _i * 8192), 16, 0, 0); } while (0)
; #define PG8_LDA(dst, b, h) do { _Pragma("unroll") for (int m = 0; m < 4; ++m) _Pragma("unroll") for (int k = 0; k < 2; ++k) dst[m][k] = *(const LAS bf16x8*)(lds + PG8_SA(b, h) + aoff + m * 2048 + k * 1024); } while (0)
; #define PG8_LDB(dst, b, h) do { _Pragma("unroll") for (int n = 0; n < 2; ++n) _Pragma("unroll") for (int k = 0; k < 2; ++k) dst[n][k] = *(const LAS bf16x8*)(lds + PG8_SB(b, h) + boff + n * 2048 + k * 1024); } while (0)
; #define PG8_MMA(ai, bj, At, Bt) do { __builtin_amdgcn_s_setprio(1); _Pragma("unroll") for (int m = 0; m < 4; ++m) _Pragma("unroll") for (int n = 0; n < 2; ++n) _Pragma("unroll") for (int k = 0; k < 2; ++k) \
;         acc[ai][bj][m][n] = __builtin_amdgcn_mfma_f32_16x16x32_bf16(Bt[n][k], At[m][k], acc[ai][bj][m][n], 0, 0, 0); __builtin_amdgcn_s_setprio(0); } while (0)
; #define PG8_WAIT_V(n) asm volatile("s_waitcnt vmcnt(" #n ")" ::: "memory")
; #define PG8_WAIT_L(n) asm volatile("s_waitcnt lgkmcnt(" #n ")" ::: "memory")
; #define PG8_BAR __builtin_amdgcn_s_barrier()
; #define PG8_WAIT_RELAX(flag, n) asm volatile("s_cmp_eq_u32 %0, 0\n\ts_cbranch_scc1 .Lrw%=\n\ts_waitcnt vmcnt(8)\n.Lrw%=:\n\ts_waitcnt vmcnt(%1)" :: "s"(flag), "n"(n) : "scc", "memory")
; #define PG8_SCHED __builtin_amdgcn_sched_barrier(0)
; template <class Epi, bool ALIGN_EPI = true>
; __device__ __forceinline__ void gemm_phase(LAS unsigned char* lds, const Gemm g, const Sched& S, const Epi& E) {
;     ...
;             if constexpr (Epi::NSTORES > 0) PG8_WAIT_RELAX(rflag, 8 + Epi::NSTORES); else PG8_WAIT_V(8);
;             PG8_WAIT_L(0); PG8_BAR; PG8_MMA(1, 0, At, B0); PG8_MMA(1, 1, At, B1); PG8_BAR; PG8_SCHED;
;             PG8_LDB(B0, 1, 0); PG8_LDB(B1, 1, 1); PG8_SCHED; PG8_LDA(At, 1, 0); PG8_STAGE(PG8_SA(0, 1), a2 + hstepA, voffA);
;             PG8_WAIT_V(8); PG8_WAIT_L(0); PG8_BAR; PG8_MMA(0, 0, At, B0); PG8_MMA(0, 1, At, B1); PG8_BAR; PG8_SCHED;
.Lrw3:
	s_waitcnt vmcnt(6) lgkmcnt(0)
	s_barrier
	s_setprio 1
	v_mfma_f32_16x16x32_bf16 v[62:65], v[150:153], v[182:185], v[62:65]
	v_mfma_f32_16x16x32_bf16 v[58:61], v[158:161], v[182:185], v[58:61]
	v_mfma_f32_16x16x32_bf16 v[46:49], v[150:153], v[190:193], v[46:49]
	v_mfma_f32_16x16x32_bf16 v[42:45], v[158:161], v[190:193], v[42:45]
	v_mfma_f32_16x16x32_bf16 v[30:33], v[150:153], v[198:201], v[30:33]
	v_mfma_f32_16x16x32_bf16 v[26:29], v[158:161], v[198:201], v[26:29]
	v_mfma_f32_16x16x32_bf16 v[14:17], v[150:153], v[206:209], v[14:17]
	v_mfma_f32_16x16x32_bf16 v[10:13], v[158:161], v[206:209], v[10:13]
	v_mfma_f32_16x16x32_bf16 v[62:65], v[154:157], v[186:189], v[62:65]
	v_mfma_f32_16x16x32_bf16 v[58:61], v[162:165], v[186:189], v[58:61]
	v_mfma_f32_16x16x32_bf16 v[46:49], v[154:157], v[194:197], v[46:49]
	v_mfma_f32_16x16x32_bf16 v[42:45], v[162:165], v[194:197], v[42:45]
	v_mfma_f32_16x16x32_bf16 v[30:33], v[154:157], v[202:205], v[30:33]
	v_mfma_f32_16x16x32_bf16 v[26:29], v[162:165], v[202:205], v[26:29]
	v_mfma_f32_16x16x32_bf16 v[14:17], v[154:157], v[210:213], v[14:17]
	v_mfma_f32_16x16x32_bf16 v[10:13], v[162:165], v[210:213], v[10:13]
	s_setprio 0
	s_setprio 1
	v_mfma_f32_16x16x32_bf16 v[54:57], v[166:169], v[182:185], v[54:57]
	v_mfma_f32_16x16x32_bf16 v[50:53], v[174:177], v[182:185], v[50:53]
	v_mfma_f32_16x16x32_bf16 v[38:41], v[166:169], v[190:193], v[38:41]
	v_mfma_f32_16x16x32_bf16 v[34:37], v[174:177], v[190:193], v[34:37]
	v_mfma_f32_16x16x32_bf16 v[22:25], v[166:169], v[198:201], v[22:25]
	v_mfma_f32_16x16x32_bf16 v[18:21], v[174:177], v[198:201], v[18:21]
	v_mfma_f32_16x16x32_bf16 v[6:9], v[166:169], v[206:209], v[6:9]
	v_mfma_f32_16x16x32_bf16 v[2:5], v[174:177], v[206:209], v[2:5]
	v_mfma_f32_16x16x32_bf16 v[54:57], v[170:173], v[186:189], v[54:57]
	v_mfma_f32_16x16x32_bf16 v[50:53], v[178:181], v[186:189], v[50:53]
	v_mfma_f32_16x16x32_bf16 v[38:41], v[170:173], v[194:197], v[38:41]
	v_mfma_f32_16x16x32_bf16 v[34:37], v[178:181], v[194:197], v[34:37]
	v_mfma_f32_16x16x32_bf16 v[22:25], v[170:173], v[202:205], v[22:25]
	v_mfma_f32_16x16x32_bf16 v[18:21], v[178:181], v[202:205], v[18:21]
	v_mfma_f32_16x16x32_bf16 v[6:9], v[170:173], v[210:213], v[6:9]
	v_mfma_f32_16x16x32_bf16 v[2:5], v[178:181], v[210:213], v[2:5]
	s_setprio 0
	s_barrier
	s_add_i32 s73, 0, 0x18000
	v_add_u32_e32 v149, s73, v144
	s_add_i32 s74, 0, 0x1c000
	ds_read_b128 v[150:153], v149
	ds_read_b128 v[154:157], v149 offset:1024
	ds_read_b128 v[158:161], v149 offset:2048
	ds_read_b128 v[162:165], v149 offset:3072
	v_add_u32_e32 v149, s74, v144
	ds_read_b128 v[166:169], v149
	ds_read_b128 v[170:173], v149 offset:1024
	ds_read_b128 v[174:177], v149 offset:2048
	ds_read_b128 v[178:181], v149 offset:3072
	s_add_u32 s40, s40, 0x80000
	s_addc_u32 s41, s41, 0
	ds_read_b128 v[182:185], v147 offset:32768
	ds_read_b128 v[186:189], v147 offset:33792
	ds_read_b128 v[190:193], v147 offset:34816
	ds_read_b128 v[194:197], v147 offset:35840
	ds_read_b128 v[198:201], v147 offset:36864
	ds_read_b128 v[202:205], v147 offset:37888
	ds_read_b128 v[206:209], v147 offset:38912
	ds_read_b128 v[210:213], v147 offset:39936
	s_mov_b32 m0, s47
	s_add_u32 s100, s40, 0xfff80000
	s_addc_u32 s101, s41, -1
	global_load_lds_dwordx4 v136, s[100:101]
	s_mov_b32 m0, s48
	s_nop 0
	global_load_lds_dwordx4 v132, s[100:101]
	s_mov_b32 m0, s49
	s_nop 0
	global_load_lds_dwordx4 v136, s[40:41]
	s_mov_b32 m0, s50
	s_nop 0
	global_load_lds_dwordx4 v132, s[40:41]
	s_waitcnt vmcnt(8) lgkmcnt(0)
	s_barrier
; #define PG8_STAGE(bufoff, gbase, voff) do { _Pragma("unroll") for (int _i = 0; _i < 2; ++_i) \
;         __builtin_amdgcn_global_load_lds((const unsigned*)((const char*)(gbase) + (voff)[_i]), (LAS unsigned*)(lds + (bufoff) + ldsw + _i * 8192), 16, 0, 0); } while (0)
; #define PG8_LDA(dst, b, h) do { _Pragma("unroll") for (int m = 0; m < 4; ++m) _Pragma("unroll") for (int k = 0; k < 2; ++k) dst[m][k] = *(const LAS bf16x8*)(lds + PG8_SA(b, h) + aoff + m * 2048 + k * 1024); } while (0)
; #define PG8_MMA(ai, bj, At, Bt) do { __builtin_amdgcn_s_setprio(1); _Pragma("unroll") for (int m = 0; m < 4; ++m) _Pragma("unroll") for (int n = 0; n < 2; ++n) _Pragma("unroll") for (int k = 0; k < 2; ++k) \
;         acc[ai][bj][m][n] = __builtin_amdgcn_mfma_f32_16x16x32_bf16(Bt[n][k], At[m][k], acc[ai][bj][m][n], 0, 0, 0); __builtin_amdgcn_s_setprio(0); } while (0)
; #define PG8_WAIT_V(n) asm volatile("s_waitcnt vmcnt(" #n ")" ::: "memory")
; #define PG8_WAIT_L(n) asm volatile("s_waitcnt lgkmcnt(" #n ")" ::: "memory")
; #define PG8_BAR __builtin_amdgcn_s_barrier()
; #define PG8_SCHED __builtin_amdgcn_sched_barrier(0)
; template <class Epi, bool ALIGN_EPI = true>
; __device__ __forceinline__ void gemm_phase(LAS unsigned char* lds, const Gemm g, const Sched& S, const Epi& E) {
;     ...
;             PG8_WAIT_V(8); PG8_WAIT_L(0); PG8_BAR; PG8_MMA(0, 0, At, B0); PG8_MMA(0, 1, At, B1); PG8_BAR; PG8_SCHED;
;             PG8_LDA(At, 1, 1); PG8_STAGE(PG8_SB(1, 0), b3, voffB); PG8_STAGE(PG8_SB(1, 1), b3 + hstepB, voffB); PG8_STAGE(PG8_SA(1, 0), a3, voffA);
;             PG8_WAIT_V(8); PG8_WAIT_L(0); PG8_BAR; PG8_MMA(1, 0, At, B0); PG8_MMA(1, 1, At, B1); PG8_BAR; PG8_SCHED;
;         }
	s_setprio 1
	v_mfma_f32_16x16x32_bf16 v[122:125], v[150:153], v[182:185], v[122:125]
	v_mfma_f32_16x16x32_bf16 v[126:129], v[158:161], v[182:185], v[126:129]
	v_mfma_f32_16x16x32_bf16 v[110:113], v[150:153], v[190:193], v[110:113]
	v_mfma_f32_16x16x32_bf16 v[106:109], v[158:161], v[190:193], v[106:109]
	v_mfma_f32_16x16x32_bf16 v[94:97], v[150:153], v[198:201], v[94:97]
	v_mfma_f32_16x16x32_bf16 v[90:93], v[158:161], v[198:201], v[90:93]
	v_mfma_f32_16x16x32_bf16 v[78:81], v[150:153], v[206:209], v[78:81]
	v_mfma_f32_16x16x32_bf16 v[74:77], v[158:161], v[206:209], v[74:77]
	v_mfma_f32_16x16x32_bf16 v[122:125], v[154:157], v[186:189], v[122:125]
	v_mfma_f32_16x16x32_bf16 v[126:129], v[162:165], v[186:189], v[126:129]
	v_mfma_f32_16x16x32_bf16 v[110:113], v[154:157], v[194:197], v[110:113]
	v_mfma_f32_16x16x32_bf16 v[106:109], v[162:165], v[194:197], v[106:109]
	v_mfma_f32_16x16x32_bf16 v[94:97], v[154:157], v[202:205], v[94:97]
	v_mfma_f32_16x16x32_bf16 v[90:93], v[162:165], v[202:205], v[90:93]
	v_mfma_f32_16x16x32_bf16 v[78:81], v[154:157], v[210:213], v[78:81]
	v_mfma_f32_16x16x32_bf16 v[74:77], v[162:165], v[210:213], v[74:77]
	s_setprio 0
	s_setprio 1
	v_mfma_f32_16x16x32_bf16 v[118:121], v[166:169], v[182:185], v[118:121]
	v_mfma_f32_16x16x32_bf16 v[114:117], v[174:177], v[182:185], v[114:117]
	v_mfma_f32_16x16x32_bf16 v[102:105], v[166:169], v[190:193], v[102:105]
	v_mfma_f32_16x16x32_bf16 v[98:101], v[174:177], v[190:193], v[98:101]
	v_mfma_f32_16x16x32_bf16 v[86:89], v[166:169], v[198:201], v[86:89]
	v_mfma_f32_16x16x32_bf16 v[82:85], v[174:177], v[198:201], v[82:85]
	v_mfma_f32_16x16x32_bf16 v[70:73], v[166:169], v[206:209], v[70:73]
	v_mfma_f32_16x16x32_bf16 v[66:69], v[174:177], v[206:209], v[66:69]
	v_mfma_f32_16x16x32_bf16 v[118:121], v[170:173], v[186:189], v[118:121]
	v_mfma_f32_16x16x32_bf16 v[114:117], v[178:181], v[186:189], v[114:117]
	v_mfma_f32_16x16x32_bf16 v[102:105], v[170:173], v[194:197], v[102:105]
	v_mfma_f32_16x16x32_bf16 v[98:101], v[178:181], v[194:197], v[98:101]
	v_mfma_f32_16x16x32_bf16 v[86:89], v[170:173], v[202:205], v[86:89]
	v_mfma_f32_16x16x32_bf16 v[82:85], v[178:181], v[202:205], v[82:85]
	v_mfma_f32_16x16x32_bf16 v[70:73], v[170:173], v[210:213], v[70:73]
	v_mfma_f32_16x16x32_bf16 v[66:69], v[178:181], v[210:213], v[66:69]
	s_setprio 0
	s_barrier
	s_add_u32 s100, s36, 0x80
	s_addc_u32 s101, s37, 0
	s_add_i32 s40, s73, s46
	s_mov_b32 m0, s40
	ds_read_b128 v[182:185], v147 offset:49152
	ds_read_b128 v[186:189], v147 offset:50176
	ds_read_b128 v[190:193], v147 offset:51200
	ds_read_b128 v[194:197], v147 offset:52224
	ds_read_b128 v[198:201], v147 offset:53248
	ds_read_b128 v[202:205], v147 offset:54272
	ds_read_b128 v[206:209], v147 offset:55296
	ds_read_b128 v[210:213], v147 offset:56320
	global_load_lds_dwordx4 v134, s[100:101]
	s_add_i32 m0, s40, 0x2000
	s_add_u32 s36, s36, 0x400080
	s_addc_u32 s37, s37, 0
	s_add_i32 s40, s74, s46
	global_load_lds_dwordx4 v130, s[100:101]
	s_mov_b32 m0, s40
	s_nop 0
	global_load_lds_dwordx4 v134, s[36:37]
	s_add_i32 m0, s40, 0x2000
	s_nop 0
	global_load_lds_dwordx4 v130, s[36:37]
	s_waitcnt vmcnt(6) lgkmcnt(0)
	s_barrier
	s_setprio 1
	v_mfma_f32_16x16x32_bf16 v[62:65], v[150:153], v[182:185], v[62:65]
	v_mfma_f32_16x16x32_bf16 v[58:61], v[158:161], v[182:185], v[58:61]
	v_mfma_f32_16x16x32_bf16 v[46:49], v[150:153], v[190:193], v[46:49]
	v_mfma_f32_16x16x32_bf16 v[42:45], v[158:161], v[190:193], v[42:45]
	v_mfma_f32_16x16x32_bf16 v[30:33], v[150:153], v[198:201], v[30:33]
	v_mfma_f32_16x16x32_bf16 v[26:29], v[158:161], v[198:201], v[26:29]
	v_mfma_f32_16x16x32_bf16 v[14:17], v[150:153], v[206:209], v[14:17]
	v_mfma_f32_16x16x32_bf16 v[10:13], v[158:161], v[206:209], v[10:13]
	v_mfma_f32_16x16x32_bf16 v[62:65], v[154:157], v[186:189], v[62:65]
	v_mfma_f32_16x16x32_bf16 v[58:61], v[162:165], v[186:189], v[58:61]
	v_mfma_f32_16x16x32_bf16 v[46:49], v[154:157], v[194:197], v[46:49]
	v_mfma_f32_16x16x32_bf16 v[42:45], v[162:165], v[194:197], v[42:45]
	v_mfma_f32_16x16x32_bf16 v[30:33], v[154:157], v[202:205], v[30:33]
	v_mfma_f32_16x16x32_bf16 v[26:29], v[162:165], v[202:205], v[26:29]
	v_mfma_f32_16x16x32_bf16 v[14:17], v[154:157], v[210:213], v[14:17]
	v_mfma_f32_16x16x32_bf16 v[10:13], v[162:165], v[210:213], v[10:13]
	s_setprio 0
	s_setprio 1
	v_mfma_f32_16x16x32_bf16 v[54:57], v[166:169], v[182:185], v[54:57]
	v_mfma_f32_16x16x32_bf16 v[50:53], v[174:177], v[182:185], v[50:53]
	v_mfma_f32_16x16x32_bf16 v[38:41], v[166:169], v[190:193], v[38:41]
	v_mfma_f32_16x16x32_bf16 v[34:37], v[174:177], v[190:193], v[34:37]
	v_mfma_f32_16x16x32_bf16 v[22:25], v[166:169], v[198:201], v[22:25]
	v_mfma_f32_16x16x32_bf16 v[18:21], v[174:177], v[198:201], v[18:21]
	v_mfma_f32_16x16x32_bf16 v[6:9], v[166:169], v[206:209], v[6:9]
	v_mfma_f32_16x16x32_bf16 v[2:5], v[174:177], v[206:209], v[2:5]
	v_mfma_f32_16x16x32_bf16 v[54:57], v[170:173], v[186:189], v[54:57]
	v_mfma_f32_16x16x32_bf16 v[50:53], v[178:181], v[186:189], v[50:53]
	v_mfma_f32_16x16x32_bf16 v[38:41], v[170:173], v[194:197], v[38:41]
	v_mfma_f32_16x16x32_bf16 v[34:37], v[178:181], v[194:197], v[34:37]
	v_mfma_f32_16x16x32_bf16 v[22:25], v[170:173], v[202:205], v[22:25]
	v_mfma_f32_16x16x32_bf16 v[18:21], v[178:181], v[202:205], v[18:21]
	v_mfma_f32_16x16x32_bf16 v[6:9], v[170:173], v[210:213], v[6:9]
	v_mfma_f32_16x16x32_bf16 v[2:5], v[178:181], v[210:213], v[2:5]
	s_setprio 0
	s_barrier
	s_add_u32 s34, s34, 0x100
	s_addc_u32 s35, s35, 0
	s_add_u32 s70, s70, 0x100
	s_addc_u32 s71, s71, 0
	s_cmp_ge_i32 s72, s54
	s_mov_b32 s40, s72
	s_cbranch_scc0 .LBB0_388

; #define PG8_STAGE(bufoff, gbase, voff) do { _Pragma("unroll") for (int _i = 0; _i < 2; ++_i) \
;         __builtin_amdgcn_global_load_lds((const unsigned*)((const char*)(gbase) + (voff)[_i]), (LAS unsigned*)(lds + (bufoff) + ldsw + _i * 8192), 16, 0, 0); } while (0)
; #define PG8_LDA(dst, b, h) do { _Pragma("unroll") for (int m = 0; m < 4; ++m) _Pragma("unroll") for (int k = 0; k < 2; ++k) dst[m][k] = *(const LAS bf16x8*)(lds + PG8_SA(b, h) + aoff + m * 2048 + k * 1024); } while (0)
; #define PG8_LDB(dst, b, h) do { _Pragma("unroll") for (int n = 0; n < 2; ++n) _Pragma("unroll") for (int k = 0; k < 2; ++k) dst[n][k] = *(const LAS bf16x8*)(lds + PG8_SB(b, h) + boff + n * 2048 + k * 1024); } while (0)
; #define PG8_MMA(ai, bj, At, Bt) do { __builtin_amdgcn_s_setprio(1); _Pragma("unroll") for (int m = 0; m < 4; ++m) _Pragma("unroll") for (int n = 0; n < 2; ++n) _Pragma("unroll") for (int k = 0; k < 2; ++k) \
;         acc[ai][bj][m][n] = __builtin_amdgcn_mfma_f32_16x16x32_bf16(Bt[n][k], At[m][k], acc[ai][bj][m][n], 0, 0, 0); __builtin_amdgcn_s_setprio(0); } while (0)
; template <class Epi, bool ALIGN_EPI = true>
; __device__ __forceinline__ void gemm_phase(LAS unsigned char* lds, const Gemm g, const Sched& S, const Epi& E) {
;     ...
;         for (int t = t_lo; t < t_hi; t += 2) {
;             const bool last = (t == nt - 2);
;             const char* a1 = cA + (size_t)(t + 1) * kstep;
;             const char* a2 = last ? nA : cA + (size_t)(t + 2) * kstep; const char* b2 = last ? nB : cB + (size_t)(t + 2) * kstep;
;             const char* a3 = a2 + kstep; const char* b3 = b2 + kstep;
;             const int rflag = __builtin_amdgcn_readfirstlane(t | (int)(ui == 0));
;             PG8_LDB(B0, 0, 0); PG8_LDB(B1, 0, 1); PG8_SCHED; PG8_LDA(At, 0, 0); PG8_STAGE(PG8_SA(1, 1), a1 + hstepA, voffA);
;             if constexpr (Epi::NSTORES > 0) PG8_WAIT_RELAX(rflag, 8 + Epi::NSTORES); else PG8_WAIT_V(8);
;             PG8_WAIT_L(0); PG8_BAR; PG8_MMA(0, 0, At, B0); PG8_MMA(0, 1, At, B1); PG8_BAR; PG8_SCHED;
;             PG8_LDA(At, 0, 1); PG8_STAGE(PG8_SB(0, 0), b2, voffB); PG8_STAGE(PG8_SB(0, 1), b2 + hstepB, voffB); PG8_STAGE(PG8_SA(0, 0), a2, voffA);
;             if constexpr (Epi::NSTORES > 0) PG8_WAIT_RELAX(rflag, 8 + Epi::NSTORES); else PG8_WAIT_V(8);
;             PG8_WAIT_L(0); PG8_BAR; PG8_MMA(1, 0, At, B0); PG8_MMA(1, 1, At, B1); PG8_BAR; PG8_SCHED;
.LBB0_415:
	ds_read_b128 v[150:153], v145
	ds_read_b128 v[154:157], v145 offset:1024
	ds_read_b128 v[158:161], v145 offset:2048
	ds_read_b128 v[162:165], v145 offset:3072
	ds_read_b128 v[166:169], v146
	ds_read_b128 v[170:173], v146 offset:1024
	ds_read_b128 v[174:177], v146 offset:2048
	ds_read_b128 v[178:181], v146 offset:3072
	s_add_i32 s69, s36, 2
	s_add_u32 s34, s30, 0xffc00080
	s_addc_u32 s35, s31, -1
	s_cmp_eq_u32 s56, s36
	v_add_u32_e32 v149, s36, v148
	s_cselect_b32 s36, s64, s34
	s_cselect_b32 s37, s19, s35
	s_cselect_b32 s35, s65, s68
	s_cselect_b32 s34, s66, s67
	ds_read_b128 v[182:185], v147
	ds_read_b128 v[186:189], v147 offset:1024
	ds_read_b128 v[190:193], v147 offset:2048
	ds_read_b128 v[194:197], v147 offset:3072
	ds_read_b128 v[198:201], v147 offset:4096
	ds_read_b128 v[202:205], v147 offset:5120
	ds_read_b128 v[206:209], v147 offset:6144
	ds_read_b128 v[210:213], v147 offset:7168
	s_mov_b32 m0, s54
	s_add_u32 s100, s30, 0xffc00000
	s_addc_u32 s101, s31, -1
	global_load_lds_dwordx4 v138, s[100:101]
	s_mov_b32 m0, s55
	s_nop 0
	global_load_lds_dwordx4 v140, s[100:101]
	s_add_i32 m0, s45, 0xc000
	s_nop 0
	global_load_lds_dwordx4 v138, s[30:31]
	s_add_i32 m0, s45, 0xe000
	v_readfirstlane_b32 s72, v149
	global_load_lds_dwordx4 v140, s[30:31]
	s_cmp_eq_u32 s72, 0
	s_cbranch_scc1 .Lrw4
	s_waitcnt vmcnt(8)
.Lrw4:
	s_waitcnt vmcnt(24) lgkmcnt(0)
	s_barrier
	s_setprio 1
	v_mfma_f32_16x16x32_bf16 v[122:125], v[150:153], v[182:185], v[122:125]
	v_mfma_f32_16x16x32_bf16 v[126:129], v[158:161], v[182:185], v[126:129]
	v_mfma_f32_16x16x32_bf16 v[110:113], v[150:153], v[190:193], v[110:113]
	v_mfma_f32_16x16x32_bf16 v[106:109], v[158:161], v[190:193], v[106:109]
	v_mfma_f32_16x16x32_bf16 v[94:97], v[150:153], v[198:201], v[94:97]
	v_mfma_f32_16x16x32_bf16 v[90:93], v[158:161], v[198:201], v[90:93]
	v_mfma_f32_16x16x32_bf16 v[78:81], v[150:153], v[206:209], v[78:81]
	v_mfma_f32_16x16x32_bf16 v[74:77], v[158:161], v[206:209], v[74:77]
	v_mfma_f32_16x16x32_bf16 v[122:125], v[154:157], v[186:189], v[122:125]
	v_mfma_f32_16x16x32_bf16 v[126:129], v[162:165], v[186:189], v[126:129]
	v_mfma_f32_16x16x32_bf16 v[110:113], v[154:157], v[194:197], v[110:113]
	v_mfma_f32_16x16x32_bf16 v[106:109], v[162:165], v[194:197], v[106:109]
	v_mfma_f32_16x16x32_bf16 v[94:97], v[154:157], v[202:205], v[94:97]
	v_mfma_f32_16x16x32_bf16 v[90:93], v[162:165], v[202:205], v[90:93]
	v_mfma_f32_16x16x32_bf16 v[78:81], v[154:157], v[210:213], v[78:81]
	v_mfma_f32_16x16x32_bf16 v[74:77], v[162:165], v[210:213], v[74:77]
	s_setprio 0
	s_setprio 1
	v_mfma_f32_16x16x32_bf16 v[118:121], v[166:169], v[182:185], v[118:121]
	v_mfma_f32_16x16x32_bf16 v[114:117], v[174:177], v[182:185], v[114:117]
	v_mfma_f32_16x16x32_bf16 v[102:105], v[166:169], v[190:193], v[102:105]
	v_mfma_f32_16x16x32_bf16 v[98:101], v[174:177], v[190:193], v[98:101]
	v_mfma_f32_16x16x32_bf16 v[86:89], v[166:169], v[198:201], v[86:89]
	v_mfma_f32_16x16x32_bf16 v[82:85], v[174:177], v[198:201], v[82:85]
	v_mfma_f32_16x16x32_bf16 v[70:73], v[166:169], v[206:209], v[70:73]
	v_mfma_f32_16x16x32_bf16 v[66:69], v[174:177], v[206:209], v[66:69]
	v_mfma_f32_16x16x32_bf16 v[118:121], v[170:173], v[186:189], v[118:121]
	v_mfma_f32_16x16x32_bf16 v[114:117], v[178:181], v[186:189], v[114:117]
	v_mfma_f32_16x16x32_bf16 v[102:105], v[170:173], v[194:197], v[102:105]
	v_mfma_f32_16x16x32_bf16 v[98:101], v[178:181], v[194:197], v[98:101]
	v_mfma_f32_16x16x32_bf16 v[86:89], v[170:173], v[202:205], v[86:89]
	v_mfma_f32_16x16x32_bf16 v[82:85], v[178:181], v[202:205], v[82:85]
	v_mfma_f32_16x16x32_bf16 v[70:73], v[170:173], v[210:213], v[70:73]
	v_mfma_f32_16x16x32_bf16 v[66:69], v[178:181], v[210:213], v[66:69]
	s_setprio 0
	s_barrier
	s_add_i32 s70, s58, s44
	s_mov_b32 m0, s70
	ds_read_b128 v[182:185], v147 offset:16384
	ds_read_b128 v[186:189], v147 offset:17408
	ds_read_b128 v[190:193], v147 offset:18432
	ds_read_b128 v[194:197], v147 offset:19456
	ds_read_b128 v[198:201], v147 offset:20480
	ds_read_b128 v[202:205], v147 offset:21504
	ds_read_b128 v[206:209], v147 offset:22528
	ds_read_b128 v[210:213], v147 offset:23552
	global_load_lds_dwordx4 v132, s[34:35]
	s_add_i32 m0, s70, 0x2000
	s_add_u32 s70, s34, 0x80000
	s_addc_u32 s71, s35, 0
	s_add_i32 s73, s59, s44
	global_load_lds_dwordx4 v136, s[34:35]
	s_mov_b32 m0, s73
	s_nop 0
	global_load_lds_dwordx4 v132, s[70:71]
	s_add_i32 m0, s73, 0x2000
	s_nop 0
	global_load_lds_dwordx4 v136, s[70:71]
; #define PG8_STAGE(bufoff, gbase, voff) do { _Pragma("unroll") for (int _i = 0; _i < 2; ++_i) \
;         __builtin_amdgcn_global_load_lds((const unsigned*)((const char*)(gbase) + (voff)[_i]), (LAS unsigned*)(lds + (bufoff) + ldsw + _i * 8192), 16, 0, 0); } while (0)
; #define PG8_LDA(dst, b, h) do { _Pragma("unroll") for (int m = 0; m < 4; ++m) _Pragma("unroll") for (int k = 0; k < 2; ++k) dst[m][k] = *(const LAS bf16x8*)(lds + PG8_SA(b, h) + aoff + m * 2048 + k * 1024); } while (0)
; #define PG8_LDB(dst, b, h) do { _Pragma("unroll") for (int n = 0; n < 2; ++n) _Pragma("unroll") for (int k = 0; k < 2; ++k) dst[n][k] = *(const LAS bf16x8*)(lds + PG8_SB(b, h) + boff + n * 2048 + k * 1024); } while (0)
; #define PG8_MMA(ai, bj, At, Bt) do { __builtin_amdgcn_s_setprio(1); _Pragma("unroll") for (int m = 0; m < 4; ++m) _Pragma("unroll") for (int n = 0; n < 2; ++n) _Pragma("unroll") for (int k = 0; k < 2; ++k) \
;         acc[ai][bj][m][n] = __builtin_amdgcn_mfma_f32_16x16x32_bf16(Bt[n][k], At[m][k], acc[ai][bj][m][n], 0, 0, 0); __builtin_amdgcn_s_setprio(0); } while (0)
; #define PG8_WAIT_V(n) asm volatile("s_waitcnt vmcnt(" #n ")" ::: "memory")
; #define PG8_WAIT_L(n) asm volatile("s_waitcnt lgkmcnt(" #n ")" ::: "memory")
; #define PG8_BAR __builtin_amdgcn_s_barrier()
; #define PG8_WAIT_RELAX(flag, n) asm volatile("s_cmp_eq_u32 %0, 0\n\ts_cbranch_scc1 .Lrw%=\n\ts_waitcnt vmcnt(8)\n.Lrw%=:\n\ts_waitcnt vmcnt(%1)" :: "s"(flag), "n"(n) : "scc", "memory")
; #define PG8_SCHED __builtin_amdgcn_sched_barrier(0)
; template <class Epi, bool ALIGN_EPI = true>
; __device__ __forceinline__ void gemm_phase(LAS unsigned char* lds, const Gemm g, const Sched& S, const Epi& E) {
;     ...
;             if constexpr (Epi::NSTORES > 0) PG8_WAIT_RELAX(rflag, 8 + Epi::NSTORES); else PG8_WAIT_V(8);
;             PG8_WAIT_L(0); PG8_BAR; PG8_MMA(1, 0, At, B0); PG8_MMA(1, 1, At, B1); PG8_BAR; PG8_SCHED;
;             PG8_LDB(B0, 1, 0); PG8_LDB(B1, 1, 1); PG8_SCHED; PG8_LDA(At, 1, 0); PG8_STAGE(PG8_SA(0, 1), a2 + hstepA, voffA);
;             PG8_WAIT_V(8); PG8_WAIT_L(0); PG8_BAR; PG8_MMA(0, 0, At, B0); PG8_MMA(0, 1, At, B1); PG8_BAR; PG8_SCHED;
.Lrw5:
	s_waitcnt vmcnt(6) lgkmcnt(0)
	s_barrier
	s_setprio 1
	v_mfma_f32_16x16x32_bf16 v[62:65], v[150:153], v[182:185], v[62:65]
	v_mfma_f32_16x16x32_bf16 v[58:61], v[158:161], v[182:185], v[58:61]
	v_mfma_f32_16x16x32_bf16 v[46:49], v[150:153], v[190:193], v[46:49]
	v_mfma_f32_16x16x32_bf16 v[42:45], v[158:161], v[190:193], v[42:45]
	v_mfma_f32_16x16x32_bf16 v[30:33], v[150:153], v[198:201], v[30:33]
	v_mfma_f32_16x16x32_bf16 v[26:29], v[158:161], v[198:201], v[26:29]
	v_mfma_f32_16x16x32_bf16 v[14:17], v[150:153], v[206:209], v[14:17]
	v_mfma_f32_16x16x32_bf16 v[10:13], v[158:161], v[206:209], v[10:13]
	v_mfma_f32_16x16x32_bf16 v[62:65], v[154:157], v[186:189], v[62:65]
	v_mfma_f32_16x16x32_bf16 v[58:61], v[162:165], v[186:189], v[58:61]
	v_mfma_f32_16x16x32_bf16 v[46:49], v[154:157], v[194:197], v[46:49]
	v_mfma_f32_16x16x32_bf16 v[42:45], v[162:165], v[194:197], v[42:45]
	v_mfma_f32_16x16x32_bf16 v[30:33], v[154:157], v[202:205], v[30:33]
	v_mfma_f32_16x16x32_bf16 v[26:29], v[162:165], v[202:205], v[26:29]
	v_mfma_f32_16x16x32_bf16 v[14:17], v[154:157], v[210:213], v[14:17]
	v_mfma_f32_16x16x32_bf16 v[10:13], v[162:165], v[210:213], v[10:13]
	s_setprio 0
	s_setprio 1
	v_mfma_f32_16x16x32_bf16 v[54:57], v[166:169], v[182:185], v[54:57]
	v_mfma_f32_16x16x32_bf16 v[50:53], v[174:177], v[182:185], v[50:53]
	v_mfma_f32_16x16x32_bf16 v[38:41], v[166:169], v[190:193], v[38:41]
	v_mfma_f32_16x16x32_bf16 v[34:37], v[174:177], v[190:193], v[34:37]
	v_mfma_f32_16x16x32_bf16 v[22:25], v[166:169], v[198:201], v[22:25]
	v_mfma_f32_16x16x32_bf16 v[18:21], v[174:177], v[198:201], v[18:21]
	v_mfma_f32_16x16x32_bf16 v[6:9], v[166:169], v[206:209], v[6:9]
	v_mfma_f32_16x16x32_bf16 v[2:5], v[174:177], v[206:209], v[2:5]
	v_mfma_f32_16x16x32_bf16 v[54:57], v[170:173], v[186:189], v[54:57]
	v_mfma_f32_16x16x32_bf16 v[50:53], v[178:181], v[186:189], v[50:53]
	v_mfma_f32_16x16x32_bf16 v[38:41], v[170:173], v[194:197], v[38:41]
	v_mfma_f32_16x16x32_bf16 v[34:37], v[178:181], v[194:197], v[34:37]
	v_mfma_f32_16x16x32_bf16 v[22:25], v[170:173], v[202:205], v[22:25]
	v_mfma_f32_16x16x32_bf16 v[18:21], v[178:181], v[202:205], v[18:21]
	v_mfma_f32_16x16x32_bf16 v[6:9], v[170:173], v[210:213], v[6:9]
	v_mfma_f32_16x16x32_bf16 v[2:5], v[178:181], v[210:213], v[2:5]
	s_setprio 0
	s_barrier
	s_add_i32 s70, 0, 0x18000
	v_add_u32_e32 v149, s70, v144
	s_add_i32 s71, 0, 0x1c000
	ds_read_b128 v[150:153], v149
	ds_read_b128 v[154:157], v149 offset:1024
	ds_read_b128 v[158:161], v149 offset:2048
	ds_read_b128 v[162:165], v149 offset:3072
	v_add_u32_e32 v149, s71, v144
	ds_read_b128 v[166:169], v149
	ds_read_b128 v[170:173], v149 offset:1024
	ds_read_b128 v[174:177], v149 offset:2048
	ds_read_b128 v[178:181], v149 offset:3072
	s_add_u32 s36, s36, 0x400000
	s_addc_u32 s37, s37, 0
	ds_read_b128 v[182:185], v147 offset:32768
	ds_read_b128 v[186:189], v147 offset:33792
	ds_read_b128 v[190:193], v147 offset:34816
	ds_read_b128 v[194:197], v147 offset:35840
	ds_read_b128 v[198:201], v147 offset:36864
	ds_read_b128 v[202:205], v147 offset:37888
	ds_read_b128 v[206:209], v147 offset:38912
	ds_read_b128 v[210:213], v147 offset:39936
	s_mov_b32 m0, s45
	s_add_u32 s100, s36, 0xffc00000
	s_addc_u32 s101, s37, -1
	global_load_lds_dwordx4 v130, s[100:101]
	s_mov_b32 m0, s46
	s_nop 0
	global_load_lds_dwordx4 v134, s[100:101]
	s_mov_b32 m0, s47
	s_nop 0
	global_load_lds_dwordx4 v130, s[36:37]
	s_mov_b32 m0, s48
	s_nop 0
	global_load_lds_dwordx4 v134, s[36:37]
	s_waitcnt vmcnt(8) lgkmcnt(0)
	s_barrier
; #define PG8_STAGE(bufoff, gbase, voff) do { _Pragma("unroll") for (int _i = 0; _i < 2; ++_i) \
;         __builtin_amdgcn_global_load_lds((const unsigned*)((const char*)(gbase) + (voff)[_i]), (LAS unsigned*)(lds + (bufoff) + ldsw + _i * 8192), 16, 0, 0); } while (0)
; #define PG8_LDA(dst, b, h) do { _Pragma("unroll") for (int m = 0; m < 4; ++m) _Pragma("unroll") for (int k = 0; k < 2; ++k) dst[m][k] = *(const LAS bf16x8*)(lds + PG8_SA(b, h) + aoff + m * 2048 + k * 1024); } while (0)
; #define PG8_MMA(ai, bj, At, Bt) do { __builtin_amdgcn_s_setprio(1); _Pragma("unroll") for (int m = 0; m < 4; ++m) _Pragma("unroll") for (int n = 0; n < 2; ++n) _Pragma("unroll") for (int k = 0; k < 2; ++k) \
;         acc[ai][bj][m][n] = __builtin_amdgcn_mfma_f32_16x16x32_bf16(Bt[n][k], At[m][k], acc[ai][bj][m][n], 0, 0, 0); __builtin_amdgcn_s_setprio(0); } while (0)
; #define PG8_WAIT_V(n) asm volatile("s_waitcnt vmcnt(" #n ")" ::: "memory")
; #define PG8_WAIT_L(n) asm volatile("s_waitcnt lgkmcnt(" #n ")" ::: "memory")
; #define PG8_BAR __builtin_amdgcn_s_barrier()
; #define PG8_SCHED __builtin_amdgcn_sched_barrier(0)
; template <class Epi, bool ALIGN_EPI = true>
; __device__ __forceinline__ void gemm_phase(LAS unsigned char* lds, const Gemm g, const Sched& S, const Epi& E) {
;     ...
;             PG8_WAIT_V(8); PG8_WAIT_L(0); PG8_BAR; PG8_MMA(0, 0, At, B0); PG8_MMA(0, 1, At, B1); PG8_BAR; PG8_SCHED;
;             PG8_LDA(At, 1, 1); PG8_STAGE(PG8_SB(1, 0), b3, voffB); PG8_STAGE(PG8_SB(1, 1), b3 + hstepB, voffB); PG8_STAGE(PG8_SA(1, 0), a3, voffA);
;             PG8_WAIT_V(8); PG8_WAIT_L(0); PG8_BAR; PG8_MMA(1, 0, At, B0); PG8_MMA(1, 1, At, B1); PG8_BAR; PG8_SCHED;
;         }
	s_setprio 1
	v_mfma_f32_16x16x32_bf16 v[122:125], v[150:153], v[182:185], v[122:125]
	v_mfma_f32_16x16x32_bf16 v[126:129], v[158:161], v[182:185], v[126:129]
	v_mfma_f32_16x16x32_bf16 v[110:113], v[150:153], v[190:193], v[110:113]
	v_mfma_f32_16x16x32_bf16 v[106:109], v[158:161], v[190:193], v[106:109]
	v_mfma_f32_16x16x32_bf16 v[94:97], v[150:153], v[198:201], v[94:97]
	v_mfma_f32_16x16x32_bf16 v[90:93], v[158:161], v[198:201], v[90:93]
	v_mfma_f32_16x16x32_bf16 v[78:81], v[150:153], v[206:209], v[78:81]
	v_mfma_f32_16x16x32_bf16 v[74:77], v[158:161], v[206:209], v[74:77]
	v_mfma_f32_16x16x32_bf16 v[122:125], v[154:157], v[186:189], v[122:125]
	v_mfma_f32_16x16x32_bf16 v[126:129], v[162:165], v[186:189], v[126:129]
	v_mfma_f32_16x16x32_bf16 v[110:113], v[154:157], v[194:197], v[110:113]
	v_mfma_f32_16x16x32_bf16 v[106:109], v[162:165], v[194:197], v[106:109]
	v_mfma_f32_16x16x32_bf16 v[94:97], v[154:157], v[202:205], v[94:97]
	v_mfma_f32_16x16x32_bf16 v[90:93], v[162:165], v[202:205], v[90:93]
	v_mfma_f32_16x16x32_bf16 v[78:81], v[154:157], v[210:213], v[78:81]
	v_mfma_f32_16x16x32_bf16 v[74:77], v[162:165], v[210:213], v[74:77]
	s_setprio 0
	s_setprio 1
	v_mfma_f32_16x16x32_bf16 v[118:121], v[166:169], v[182:185], v[118:121]
	v_mfma_f32_16x16x32_bf16 v[114:117], v[174:177], v[182:185], v[114:117]
	v_mfma_f32_16x16x32_bf16 v[102:105], v[166:169], v[190:193], v[102:105]
	v_mfma_f32_16x16x32_bf16 v[98:101], v[174:177], v[190:193], v[98:101]
	v_mfma_f32_16x16x32_bf16 v[86:89], v[166:169], v[198:201], v[86:89]
	v_mfma_f32_16x16x32_bf16 v[82:85], v[174:177], v[198:201], v[82:85]
	v_mfma_f32_16x16x32_bf16 v[70:73], v[166:169], v[206:209], v[70:73]
	v_mfma_f32_16x16x32_bf16 v[66:69], v[174:177], v[206:209], v[66:69]
	v_mfma_f32_16x16x32_bf16 v[118:121], v[170:173], v[186:189], v[118:121]
	v_mfma_f32_16x16x32_bf16 v[114:117], v[178:181], v[186:189], v[114:117]
	v_mfma_f32_16x16x32_bf16 v[102:105], v[170:173], v[194:197], v[102:105]
	v_mfma_f32_16x16x32_bf16 v[98:101], v[178:181], v[194:197], v[98:101]
	v_mfma_f32_16x16x32_bf16 v[86:89], v[170:173], v[202:205], v[86:89]
	v_mfma_f32_16x16x32_bf16 v[82:85], v[178:181], v[202:205], v[82:85]
	v_mfma_f32_16x16x32_bf16 v[70:73], v[170:173], v[210:213], v[70:73]
	v_mfma_f32_16x16x32_bf16 v[66:69], v[178:181], v[210:213], v[66:69]
	s_setprio 0
	s_barrier
	s_add_u32 s100, s34, 0x80
	s_addc_u32 s101, s35, 0
	s_add_i32 s36, s70, s44
	s_mov_b32 m0, s36
	ds_read_b128 v[182:185], v147 offset:49152
	ds_read_b128 v[186:189], v147 offset:50176
	ds_read_b128 v[190:193], v147 offset:51200
	ds_read_b128 v[194:197], v147 offset:52224
	ds_read_b128 v[198:201], v147 offset:53248
	ds_read_b128 v[202:205], v147 offset:54272
	ds_read_b128 v[206:209], v147 offset:55296
	ds_read_b128 v[210:213], v147 offset:56320
	global_load_lds_dwordx4 v132, s[100:101]
	s_add_i32 m0, s36, 0x2000
	s_add_u32 s34, s34, 0x80080
	s_addc_u32 s35, s35, 0
	s_add_i32 s36, s71, s44
	global_load_lds_dwordx4 v136, s[100:101]
	s_mov_b32 m0, s36
	s_nop 0
	global_load_lds_dwordx4 v132, s[34:35]
	s_add_i32 m0, s36, 0x2000
	s_nop 0
	global_load_lds_dwordx4 v136, s[34:35]
	s_waitcnt vmcnt(6) lgkmcnt(0)
	s_barrier
	s_setprio 1
	v_mfma_f32_16x16x32_bf16 v[62:65], v[150:153], v[182:185], v[62:65]
	v_mfma_f32_16x16x32_bf16 v[58:61], v[158:161], v[182:185], v[58:61]
	v_mfma_f32_16x16x32_bf16 v[46:49], v[150:153], v[190:193], v[46:49]
	v_mfma_f32_16x16x32_bf16 v[42:45], v[158:161], v[190:193], v[42:45]
	v_mfma_f32_16x16x32_bf16 v[30:33], v[150:153], v[198:201], v[30:33]
	v_mfma_f32_16x16x32_bf16 v[26:29], v[158:161], v[198:201], v[26:29]
	v_mfma_f32_16x16x32_bf16 v[14:17], v[150:153], v[206:209], v[14:17]
	v_mfma_f32_16x16x32_bf16 v[10:13], v[158:161], v[206:209], v[10:13]
	v_mfma_f32_16x16x32_bf16 v[62:65], v[154:157], v[186:189], v[62:65]
	v_mfma_f32_16x16x32_bf16 v[58:61], v[162:165], v[186:189], v[58:61]
	v_mfma_f32_16x16x32_bf16 v[46:49], v[154:157], v[194:197], v[46:49]
	v_mfma_f32_16x16x32_bf16 v[42:45], v[162:165], v[194:197], v[42:45]
	v_mfma_f32_16x16x32_bf16 v[30:33], v[154:157], v[202:205], v[30:33]
	v_mfma_f32_16x16x32_bf16 v[26:29], v[162:165], v[202:205], v[26:29]
	v_mfma_f32_16x16x32_bf16 v[14:17], v[154:157], v[210:213], v[14:17]
	v_mfma_f32_16x16x32_bf16 v[10:13], v[162:165], v[210:213], v[10:13]
	s_setprio 0
	s_setprio 1
	v_mfma_f32_16x16x32_bf16 v[54:57], v[166:169], v[182:185], v[54:57]
	v_mfma_f32_16x16x32_bf16 v[50:53], v[174:177], v[182:185], v[50:53]
	v_mfma_f32_16x16x32_bf16 v[38:41], v[166:169], v[190:193], v[38:41]
	v_mfma_f32_16x16x32_bf16 v[34:37], v[174:177], v[190:193], v[34:37]
	v_mfma_f32_16x16x32_bf16 v[22:25], v[166:169], v[198:201], v[22:25]
	v_mfma_f32_16x16x32_bf16 v[18:21], v[174:177], v[198:201], v[18:21]
	v_mfma_f32_16x16x32_bf16 v[6:9], v[166:169], v[206:209], v[6:9]
	v_mfma_f32_16x16x32_bf16 v[2:5], v[174:177], v[206:209], v[2:5]
	v_mfma_f32_16x16x32_bf16 v[54:57], v[170:173], v[186:189], v[54:57]
	v_mfma_f32_16x16x32_bf16 v[50:53], v[178:181], v[186:189], v[50:53]
	v_mfma_f32_16x16x32_bf16 v[38:41], v[170:173], v[194:197], v[38:41]
	v_mfma_f32_16x16x32_bf16 v[34:37], v[178:181], v[194:197], v[34:37]
	v_mfma_f32_16x16x32_bf16 v[22:25], v[170:173], v[202:205], v[22:25]
	v_mfma_f32_16x16x32_bf16 v[18:21], v[178:181], v[202:205], v[18:21]
	v_mfma_f32_16x16x32_bf16 v[6:9], v[170:173], v[210:213], v[6:9]
	v_mfma_f32_16x16x32_bf16 v[2:5], v[178:181], v[210:213], v[2:5]
	s_setprio 0
	s_barrier
	s_add_u32 s30, s30, 0x100
	s_addc_u32 s31, s31, 0
	s_add_u32 s67, s67, 0x100
	s_addc_u32 s68, s68, 0
	s_cmp_ge_i32 s69, s51
	s_mov_b32 s36, s69
	s_cbranch_scc0 .LBB0_415

;     __device__ __forceinline__ void init_plain(int nM_, int nN_, int G_, int c_, int lda, int ldb) { init(nM_, nN_, G_, c_, (long)BM * lda * 2, 0, 0, 0, 0, (long)BM * ldb * 2); }
; #define PG8_STAGE(bufoff, gbase, voff) do { _Pragma("unroll") for (int _i = 0; _i < 2; ++_i) \
;         __builtin_amdgcn_global_load_lds((const unsigned*)((const char*)(gbase) + (voff)[_i]), (LAS unsigned*)(lds + (bufoff) + ldsw + _i * 8192), 16, 0, 0); } while (0)
; #define PG8_WAIT_V(n) asm volatile("s_waitcnt vmcnt(" #n ")" ::: "memory")
; #define PG8_BAR __builtin_amdgcn_s_barrier()
; __device__ __forceinline__ size_t oq(size_t c) { asm volatile("" : "+s"(c)); return c; }
; template <class Epi, bool ALIGN_EPI = true>
; __device__ __forceinline__ void gemm_phase(LAS unsigned char* lds, const Gemm g, const Sched& S, const Epi& E) {
;     ...
;     f32x4 acc[2][2][4][2];
; #pragma unroll
;     for (int a = 0; a < 2; ++a)
; #pragma unroll
;         for (int b = 0; b < 2; ++b)
; #pragma unroll
;             for (int m = 0; m < 4; ++m)
; #pragma unroll
;                 for (int n = 0; n < 2; ++n) acc[a][b][m][n] = (f32x4){0.f, 0.f, 0.f, 0.f};
;     bf16x8 At[4][2], B0[2][2], B1[2][2];
;     const char* cA = (const char*)g.A + cur.aoff; const char* cB = (const char*)g.Bt + cur.boff;
;     PG8_STAGE(PG8_SB(0, 0), cB, voffB); PG8_STAGE(PG8_SB(0, 1), cB + hstepB, voffB); PG8_STAGE(PG8_SA(0, 0), cA, voffA); PG8_STAGE(PG8_SA(0, 1), cA + hstepA, voffA);
;     if (wr == 1) PG8_BAR;
;     PG8_WAIT_V(2); PG8_BAR;
;     PG8_STAGE(PG8_SB(1, 0), cB + kstep, voffB); PG8_STAGE(PG8_SA(1, 0), cA + kstep, voffA); PG8_STAGE(PG8_SB(1, 1), cB + hstepB + kstep, voffB);
;     PG8_WAIT_V(6); PG8_BAR;
; __global__ void __launch_bounds__(NWAVES * 64, 2) mk_fwd(Args args) {
;     ...
;             pg8::Gemm g{(const bf16_t*)(ws + oq(WS_HB)), (const bf16_t*)(wl + WL_WIN), DM, DM, DM}; pg8::Sched S; S.init_plain(MROWS / 256, INC / 256, G, c0, DM, DM);
;             pg8::EpiZ E{(bf16_t*)(ws + oq(WS_ZP)), (bf16_t*)(ws + oq(WS_Q)), (bf16_t*)(ws + oq(WS_KK)), (bf16_t*)(ws + oq(WS_V)), (bf16_t*)(ws + oq(WS_OG)), (bf16_t*)(ws + oq(WS_GA)), (bf16_t*)(ws + oq(WS_GB)),
;                         (float*)(ws + oq(WS_G)), (const float*)(ws + oq(WS_SS)), (const float*)(ws + oq(WS_LB)) + l * HDIM};
;             S.i1 = 4;
;             pg8::gemm_phase<pg8::EpiZ>(ring, g, S, E);
.LBB0_492:
	v_readlane_b32 s60, v246, 42
	v_readlane_b32 s62, v246, 44
	v_readlane_b32 s63, v246, 45
	s_add_u32 s44, s62, s44
	s_addc_u32 s45, s63, s45
	s_add_u32 s24, s62, s24
	s_addc_u32 s25, s63, s25
	s_add_u32 s31, s62, s20
	s_addc_u32 s34, s63, s21
	s_add_u32 s20, s62, s22
	s_addc_u32 s21, s63, s23
	s_add_u32 s18, s62, s18
	v_writelane_b32 v242, s20, 29
	s_addc_u32 s19, s63, s19
	s_add_u32 s16, s62, s16
	v_writelane_b32 v242, s21, 30
	v_writelane_b32 v242, s18, 31
	s_addc_u32 s17, s63, s17
	s_add_u32 s6, s62, s6
	v_writelane_b32 v242, s19, 32
	v_writelane_b32 v242, s16, 33
	s_addc_u32 s7, s63, s7
	s_add_u32 s33, s62, s4
	v_writelane_b32 v242, s17, 34
	v_writelane_b32 v242, s6, 35
	s_addc_u32 s30, s63, s5
	v_lshl_add_u64 v[10:11], v[10:11], 0, s[8:9]
	v_writelane_b32 v242, s7, 36
	s_add_u32 s6, s62, s14
	s_addc_u32 s7, s63, s15
	s_lshl_b32 s94, s38, 10
	s_lshl_b64 s[4:5], s[94:95], 2
	s_add_u32 s84, s6, s4
	s_addc_u32 s85, s7, s5
	s_ashr_i32 s4, s48, 31
	s_lshr_b32 s4, s4, 26
	s_add_i32 s4, s48, s4
	s_ashr_i32 s46, s4, 6
	s_lshl_b32 s4, s40, 5
	s_and_b32 s89, s4, 0x60
	s_add_i32 m0, s50, 0x18000
	s_lshl_b32 s88, s41, 6
	s_lshl_b32 s6, s41, 13
	s_lshl_b32 s7, s89, 7
	s_waitcnt vmcnt(2)
	s_barrier
	global_load_lds_dwordx4 v[10:11], off
	v_lshl_add_u64 v[8:9], v[8:9], 0, s[8:9]
	s_add_i32 m0, s50, 0x1a000
	s_add_i32 s92, s50, 0x8000
	s_add_i32 s93, s50, 0xa000
	global_load_lds_dwordx4 v[8:9], off
	v_lshl_add_u64 v[4:5], v[4:5], 0, s[8:9]
	s_mov_b32 m0, s92
	s_add_u32 s4, s54, 0x80080
	global_load_lds_dwordx4 v[4:5], off
	v_lshl_add_u64 v[4:5], v[6:7], 0, s[8:9]
	s_mov_b32 m0, s93
	s_addc_u32 s5, s55, 0
	global_load_lds_dwordx4 v[4:5], off
	s_add_i32 m0, s50, 0x1c000
	v_lshl_add_u64 v[4:5], s[4:5], 0, v[152:153]
	global_load_lds_dwordx4 v[4:5], off
	v_lshl_add_u64 v[4:5], s[4:5], 0, v[156:157]
	s_add_i32 m0, s50, 0x1e000
	s_movk_i32 s4, 0x3c0
	global_load_lds_dwordx4 v[4:5], off
	v_and_b32_e32 v4, 48, v12
	v_lshlrev_b32_e32 v5, 6, v12
	v_and_or_b32 v4, v5, s4, v4
	v_lshlrev_b32_e32 v5, 2, v12
	v_and_b32_e32 v5, 32, v5
	v_bitop3_b32 v6, v4, s6, v5 bitop3:0xde
	v_bitop3_b32 v185, s7, v4, v5 bitop3:0xf6
	v_add_u32_e32 v185, 0x10000, v185
	v_lshlrev_b32_e32 v4, 15, v2
	v_and_b32_e32 v4, 0xffff0000, v4
	v_lshl_add_u32 v4, v13, 12, v4
	v_and_b32_e32 v2, 1, v2
	v_lshl_or_b32 v2, v2, 6, v4
	v_readlane_b32 s61, v246, 43
	s_cmp_gt_i32 s48, 63
	v_lshl_add_u32 v158, v14, 1, v2
	v_lshlrev_b32_e32 v2, 15, v15
	s_cselect_b64 s[60:61], -1, 0
	s_add_i32 s94, s46, -2
	v_and_b32_e32 v2, 0xffff0000, v2
	s_cmpk_lt_u32 s47, 0x100
	v_lshl_add_u32 v2, v16, 12, v2
	v_and_b32_e32 v4, 1, v15
	s_waitcnt vmcnt(6)
	s_cselect_b64 s[62:63], -1, 0
	s_and_b32 s4, s47, 0xffffff00
	v_lshl_or_b32 v2, v4, 6, v2
	v_mov_b32_e32 v4, v3
	v_mov_b32_e32 v5, v3
	v_and_b32_e32 v184, 63, v12
	s_add_i32 s47, s4, 0
	v_lshl_add_u32 v160, v17, 1, v2
	v_mov_b32_e32 v2, v3
	v_add_u32_e32 v186, 0, v6
	v_mov_b64_e32 v[8:9], v[4:5]
	v_mov_b64_e32 v[12:13], v[4:5]
	v_mov_b64_e32 v[16:17], v[4:5]
	v_mov_b64_e32 v[20:21], v[4:5]
	v_mov_b64_e32 v[24:25], v[4:5]
	v_mov_b64_e32 v[28:29], v[4:5]
	v_mov_b64_e32 v[32:33], v[4:5]
	v_mov_b64_e32 v[36:37], v[4:5]
	v_mov_b64_e32 v[40:41], v[4:5]
	v_mov_b64_e32 v[44:45], v[4:5]
	v_mov_b64_e32 v[48:49], v[4:5]
	v_mov_b64_e32 v[52:53], v[4:5]
	v_mov_b64_e32 v[56:57], v[4:5]
	v_mov_b64_e32 v[60:61], v[4:5]
	v_mov_b64_e32 v[64:65], v[4:5]
	v_mov_b64_e32 v[68:69], v[4:5]
	v_mov_b64_e32 v[72:73], v[4:5]
	v_mov_b64_e32 v[76:77], v[4:5]
	v_mov_b64_e32 v[80:81], v[4:5]
	v_mov_b64_e32 v[84:85], v[4:5]
	v_mov_b64_e32 v[88:89], v[4:5]
	v_mov_b64_e32 v[92:93], v[4:5]
	v_mov_b64_e32 v[96:97], v[4:5]
	v_mov_b64_e32 v[100:101], v[4:5]
	v_mov_b64_e32 v[104:105], v[4:5]
	v_mov_b64_e32 v[108:109], v[4:5]
	v_mov_b64_e32 v[112:113], v[4:5]
	v_mov_b64_e32 v[116:117], v[4:5]
	v_mov_b64_e32 v[120:121], v[4:5]
	v_mov_b64_e32 v[124:125], v[4:5]
	v_mov_b64_e32 v[128:129], v[4:5]
	v_mov_b64_e32 v[132:133], v[4:5]
	s_mov_b64 s[38:39], s[24:25]
	s_add_i32 s47, s47, 0x20000
	v_mov_b32_e32 v159, v3
	v_mov_b32_e32 v161, v3
	s_mov_b32 s96, 0
	v_mov_b64_e32 v[6:7], v[2:3]
	v_mov_b64_e32 v[10:11], v[2:3]
	v_mov_b64_e32 v[14:15], v[2:3]
	v_mov_b64_e32 v[18:19], v[2:3]
	v_mov_b64_e32 v[22:23], v[2:3]
	v_mov_b64_e32 v[26:27], v[2:3]
	v_mov_b64_e32 v[30:31], v[2:3]
	v_mov_b64_e32 v[34:35], v[2:3]
	v_mov_b64_e32 v[38:39], v[2:3]
	v_mov_b64_e32 v[42:43], v[2:3]
	v_mov_b64_e32 v[46:47], v[2:3]
	v_mov_b64_e32 v[50:51], v[2:3]
	v_mov_b64_e32 v[54:55], v[2:3]
	v_mov_b64_e32 v[58:59], v[2:3]
	v_mov_b64_e32 v[62:63], v[2:3]
	v_mov_b64_e32 v[66:67], v[2:3]
	v_mov_b64_e32 v[70:71], v[2:3]
	v_mov_b64_e32 v[74:75], v[2:3]
	v_mov_b64_e32 v[78:79], v[2:3]
	v_mov_b64_e32 v[82:83], v[2:3]
	v_mov_b64_e32 v[86:87], v[2:3]
	v_mov_b64_e32 v[90:91], v[2:3]
	v_mov_b64_e32 v[94:95], v[2:3]
	v_mov_b64_e32 v[98:99], v[2:3]
	v_mov_b64_e32 v[102:103], v[2:3]
	v_mov_b64_e32 v[106:107], v[2:3]
	v_mov_b64_e32 v[110:111], v[2:3]
	v_mov_b64_e32 v[114:115], v[2:3]
	v_mov_b64_e32 v[118:119], v[2:3]
	v_mov_b64_e32 v[122:123], v[2:3]
	v_mov_b64_e32 v[126:127], v[2:3]
	v_mov_b64_e32 v[130:131], v[2:3]
	s_barrier
	s_branch .LBB0_495

; #define PG8_STAGE(bufoff, gbase, voff) do { _Pragma("unroll") for (int _i = 0; _i < 2; ++_i) \
;         __builtin_amdgcn_global_load_lds((const unsigned*)((const char*)(gbase) + (voff)[_i]), (LAS unsigned*)(lds + (bufoff) + ldsw + _i * 8192), 16, 0, 0); } while (0)
; #define PG8_LDA(dst, b, h) do { _Pragma("unroll") for (int m = 0; m < 4; ++m) _Pragma("unroll") for (int k = 0; k < 2; ++k) dst[m][k] = *(const LAS bf16x8*)(lds + PG8_SA(b, h) + aoff + m * 2048 + k * 1024); } while (0)
; #define PG8_LDB(dst, b, h) do { _Pragma("unroll") for (int n = 0; n < 2; ++n) _Pragma("unroll") for (int k = 0; k < 2; ++k) dst[n][k] = *(const LAS bf16x8*)(lds + PG8_SB(b, h) + boff + n * 2048 + k * 1024); } while (0)
; #define PG8_MMA(ai, bj, At, Bt) do { __builtin_amdgcn_s_setprio(1); _Pragma("unroll") for (int m = 0; m < 4; ++m) _Pragma("unroll") for (int n = 0; n < 2; ++n) _Pragma("unroll") for (int k = 0; k < 2; ++k) \
;         acc[ai][bj][m][n] = __builtin_amdgcn_mfma_f32_16x16x32_bf16(Bt[n][k], At[m][k], acc[ai][bj][m][n], 0, 0, 0); __builtin_amdgcn_s_setprio(0); } while (0)
; template <class Epi, bool ALIGN_EPI = true>
; __device__ __forceinline__ void gemm_phase(LAS unsigned char* lds, const Gemm g, const Sched& S, const Epi& E) {
;     ...
;         for (int t = t_lo; t < t_hi; t += 2) {
;             const bool last = (t == nt - 2);
;             const char* a1 = cA + (size_t)(t + 1) * kstep;
;             const char* a2 = last ? nA : cA + (size_t)(t + 2) * kstep; const char* b2 = last ? nB : cB + (size_t)(t + 2) * kstep;
;             const char* a3 = a2 + kstep; const char* b3 = b2 + kstep;
;             const int rflag = __builtin_amdgcn_readfirstlane(t | (int)(ui == 0));
;             PG8_LDB(B0, 0, 0); PG8_LDB(B1, 0, 1); PG8_SCHED; PG8_LDA(At, 0, 0); PG8_STAGE(PG8_SA(1, 1), a1 + hstepA, voffA);
;             if constexpr (Epi::NSTORES > 0) PG8_WAIT_RELAX(rflag, 8 + Epi::NSTORES); else PG8_WAIT_V(8);
;             PG8_WAIT_L(0); PG8_BAR; PG8_MMA(0, 0, At, B0); PG8_MMA(0, 1, At, B1); PG8_BAR; PG8_SCHED;
;             PG8_LDA(At, 0, 1); PG8_STAGE(PG8_SB(0, 0), b2, voffB); PG8_STAGE(PG8_SB(0, 1), b2 + hstepB, voffB); PG8_STAGE(PG8_SA(0, 0), a2, voffA);
;             if constexpr (Epi::NSTORES > 0) PG8_WAIT_RELAX(rflag, 8 + Epi::NSTORES); else PG8_WAIT_V(8);
;             PG8_WAIT_L(0); PG8_BAR; PG8_MMA(1, 0, At, B0); PG8_MMA(1, 1, At, B1); PG8_BAR; PG8_SCHED;
.LBB0_500:
	s_add_i32 s22, s6, 2
	s_add_u32 s7, s4, 0xfff80080
	s_addc_u32 s14, s5, -1
	s_add_i32 s23, 0, 0x10000
	s_cmp_eq_u32 s94, s6
	v_add_u32_e32 v182, s6, v2
	s_cselect_b32 s15, s16, s14
	s_cselect_b32 s14, s17, s7
	s_waitcnt lgkmcnt(0)
	s_cselect_b32 s7, s18, s21
	s_cselect_b32 s6, s19, s20
	s_add_i32 s52, 0, 0x14000
	ds_read_b128 v[134:137], v185
	ds_read_b128 v[138:141], v185 offset:1024
	ds_read_b128 v[142:145], v185 offset:2048
	ds_read_b128 v[146:149], v185 offset:3072
	ds_read_b128 v[162:165], v185 offset:16384
	ds_read_b128 v[166:169], v185 offset:17408
	ds_read_b128 v[170:173], v185 offset:18432
	ds_read_b128 v[174:177], v185 offset:19456
	ds_read_b128 v[178:181], v186
	ds_read_b128 v[188:191], v186 offset:1024
	ds_read_b128 v[192:195], v186 offset:2048
	ds_read_b128 v[206:209], v186 offset:3072
	ds_read_b128 v[224:227], v186 offset:4096
	ds_read_b128 v[228:231], v186 offset:5120
	ds_read_b128 v[232:235], v186 offset:6144
	ds_read_b128 v[236:239], v186 offset:7168
	s_mov_b32 m0, s92
	s_add_u32 s100, s4, 0xfff80000
	s_addc_u32 s101, s5, -1
	global_load_lds_dwordx4 v158, s[100:101]
	s_mov_b32 m0, s93
	s_nop 0
	global_load_lds_dwordx4 v160, s[100:101]
	s_add_i32 m0, s50, 0xc000
	s_nop 0
	global_load_lds_dwordx4 v158, s[4:5]
	s_add_i32 m0, s50, 0xe000
	v_readfirstlane_b32 s53, v182
	global_load_lds_dwordx4 v160, s[4:5]
	s_cmp_eq_u32 s53, 0
	s_cbranch_scc1 .Lrw6
	s_waitcnt vmcnt(8)
.Lrw6:
	s_waitcnt vmcnt(24) lgkmcnt(0)
	s_barrier
	s_setprio 1
	v_mfma_f32_16x16x32_bf16 v[130:133], v[134:137], v[178:181], v[130:133]
	v_mfma_f32_16x16x32_bf16 v[126:129], v[142:145], v[178:181], v[126:129]
	v_mfma_f32_16x16x32_bf16 v[122:125], v[134:137], v[192:195], v[122:125]
	v_mfma_f32_16x16x32_bf16 v[118:121], v[142:145], v[192:195], v[118:121]
	v_mfma_f32_16x16x32_bf16 v[114:117], v[134:137], v[224:227], v[114:117]
	v_mfma_f32_16x16x32_bf16 v[110:113], v[142:145], v[224:227], v[110:113]
	v_mfma_f32_16x16x32_bf16 v[106:109], v[134:137], v[232:235], v[106:109]
	v_mfma_f32_16x16x32_bf16 v[102:105], v[142:145], v[232:235], v[102:105]
	v_mfma_f32_16x16x32_bf16 v[130:133], v[138:141], v[188:191], v[130:133]
	v_mfma_f32_16x16x32_bf16 v[126:129], v[146:149], v[188:191], v[126:129]
	v_mfma_f32_16x16x32_bf16 v[122:125], v[138:141], v[206:209], v[122:125]
	v_mfma_f32_16x16x32_bf16 v[118:121], v[146:149], v[206:209], v[118:121]
	v_mfma_f32_16x16x32_bf16 v[114:117], v[138:141], v[228:231], v[114:117]
	v_mfma_f32_16x16x32_bf16 v[110:113], v[146:149], v[228:231], v[110:113]
	v_mfma_f32_16x16x32_bf16 v[106:109], v[138:141], v[236:239], v[106:109]
	v_mfma_f32_16x16x32_bf16 v[102:105], v[146:149], v[236:239], v[102:105]
	s_setprio 0
	s_setprio 1
	v_mfma_f32_16x16x32_bf16 v[98:101], v[162:165], v[178:181], v[98:101]
	v_mfma_f32_16x16x32_bf16 v[94:97], v[170:173], v[178:181], v[94:97]
	v_mfma_f32_16x16x32_bf16 v[90:93], v[162:165], v[192:195], v[90:93]
	v_mfma_f32_16x16x32_bf16 v[86:89], v[170:173], v[192:195], v[86:89]
	v_mfma_f32_16x16x32_bf16 v[82:85], v[162:165], v[224:227], v[82:85]
	v_mfma_f32_16x16x32_bf16 v[78:81], v[170:173], v[224:227], v[78:81]
	v_mfma_f32_16x16x32_bf16 v[74:77], v[162:165], v[232:235], v[74:77]
	v_mfma_f32_16x16x32_bf16 v[70:73], v[170:173], v[232:235], v[70:73]
	v_mfma_f32_16x16x32_bf16 v[98:101], v[166:169], v[188:191], v[98:101]
	v_mfma_f32_16x16x32_bf16 v[94:97], v[174:177], v[188:191], v[94:97]
	v_mfma_f32_16x16x32_bf16 v[90:93], v[166:169], v[206:209], v[90:93]
	v_mfma_f32_16x16x32_bf16 v[86:89], v[174:177], v[206:209], v[86:89]
	v_mfma_f32_16x16x32_bf16 v[82:85], v[166:169], v[228:231], v[82:85]
	v_mfma_f32_16x16x32_bf16 v[78:81], v[174:177], v[228:231], v[78:81]
	v_mfma_f32_16x16x32_bf16 v[74:77], v[166:169], v[236:239], v[74:77]
	v_mfma_f32_16x16x32_bf16 v[70:73], v[174:177], v[236:239], v[70:73]
	s_setprio 0
	s_barrier
	s_add_i32 s23, s23, s27
	s_mov_b32 m0, s23
	ds_read_b128 v[178:181], v186 offset:16384
	ds_read_b128 v[188:191], v186 offset:17408
	ds_read_b128 v[192:195], v186 offset:18432
	ds_read_b128 v[206:209], v186 offset:19456
	ds_read_b128 v[224:227], v186 offset:20480
	ds_read_b128 v[228:231], v186 offset:21504
	ds_read_b128 v[232:235], v186 offset:22528
	ds_read_b128 v[236:239], v186 offset:23552
	global_load_lds_dwordx4 v152, s[6:7]
	s_add_i32 m0, s23, 0x2000
	s_add_u32 s24, s6, 0x80000
	s_addc_u32 s25, s7, 0
	s_add_i32 s23, s52, s27
	global_load_lds_dwordx4 v156, s[6:7]
	s_mov_b32 m0, s23
	s_nop 0
	global_load_lds_dwordx4 v152, s[24:25]
	s_add_i32 m0, s23, 0x2000
	s_nop 0
	global_load_lds_dwordx4 v156, s[24:25]
; #define PG8_STAGE(bufoff, gbase, voff) do { _Pragma("unroll") for (int _i = 0; _i < 2; ++_i) \
;         __builtin_amdgcn_global_load_lds((const unsigned*)((const char*)(gbase) + (voff)[_i]), (LAS unsigned*)(lds + (bufoff) + ldsw + _i * 8192), 16, 0, 0); } while (0)
; #define PG8_LDA(dst, b, h) do { _Pragma("unroll") for (int m = 0; m < 4; ++m) _Pragma("unroll") for (int k = 0; k < 2; ++k) dst[m][k] = *(const LAS bf16x8*)(lds + PG8_SA(b, h) + aoff + m * 2048 + k * 1024); } while (0)
; #define PG8_LDB(dst, b, h) do { _Pragma("unroll") for (int n = 0; n < 2; ++n) _Pragma("unroll") for (int k = 0; k < 2; ++k) dst[n][k] = *(const LAS bf16x8*)(lds + PG8_SB(b, h) + boff + n * 2048 + k * 1024); } while (0)
; #define PG8_MMA(ai, bj, At, Bt) do { __builtin_amdgcn_s_setprio(1); _Pragma("unroll") for (int m = 0; m < 4; ++m) _Pragma("unroll") for (int n = 0; n < 2; ++n) _Pragma("unroll") for (int k = 0; k < 2; ++k) \
;         acc[ai][bj][m][n] = __builtin_amdgcn_mfma_f32_16x16x32_bf16(Bt[n][k], At[m][k], acc[ai][bj][m][n], 0, 0, 0); __builtin_amdgcn_s_setprio(0); } while (0)
; #define PG8_WAIT_V(n) asm volatile("s_waitcnt vmcnt(" #n ")" ::: "memory")
; #define PG8_WAIT_L(n) asm volatile("s_waitcnt lgkmcnt(" #n ")" ::: "memory")
; #define PG8_BAR __builtin_amdgcn_s_barrier()
; #define PG8_SCHED __builtin_amdgcn_sched_barrier(0)
; template <class Epi, bool ALIGN_EPI = true>
; __device__ __forceinline__ void gemm_phase(LAS unsigned char* lds, const Gemm g, const Sched& S, const Epi& E) {
;     ...
;             PG8_WAIT_L(0); PG8_BAR; PG8_MMA(1, 0, At, B0); PG8_MMA(1, 1, At, B1); PG8_BAR; PG8_SCHED;
;             PG8_LDB(B0, 1, 0); PG8_LDB(B1, 1, 1); PG8_SCHED; PG8_LDA(At, 1, 0); PG8_STAGE(PG8_SA(0, 1), a2 + hstepA, voffA);
;             PG8_WAIT_V(8); PG8_WAIT_L(0); PG8_BAR; PG8_MMA(0, 0, At, B0); PG8_MMA(0, 1, At, B1); PG8_BAR; PG8_SCHED;
.Lrw7:
	s_waitcnt vmcnt(6) lgkmcnt(0)
	s_barrier
	s_setprio 1
	v_mfma_f32_16x16x32_bf16 v[66:69], v[134:137], v[178:181], v[66:69]
	v_mfma_f32_16x16x32_bf16 v[62:65], v[142:145], v[178:181], v[62:65]
	v_mfma_f32_16x16x32_bf16 v[58:61], v[134:137], v[192:195], v[58:61]
	v_mfma_f32_16x16x32_bf16 v[54:57], v[142:145], v[192:195], v[54:57]
	v_mfma_f32_16x16x32_bf16 v[50:53], v[134:137], v[224:227], v[50:53]
	v_mfma_f32_16x16x32_bf16 v[46:49], v[142:145], v[224:227], v[46:49]
	v_mfma_f32_16x16x32_bf16 v[42:45], v[134:137], v[232:235], v[42:45]
	v_mfma_f32_16x16x32_bf16 v[38:41], v[142:145], v[232:235], v[38:41]
	v_mfma_f32_16x16x32_bf16 v[66:69], v[138:141], v[188:191], v[66:69]
	v_mfma_f32_16x16x32_bf16 v[62:65], v[146:149], v[188:191], v[62:65]
	v_mfma_f32_16x16x32_bf16 v[58:61], v[138:141], v[206:209], v[58:61]
	v_mfma_f32_16x16x32_bf16 v[54:57], v[146:149], v[206:209], v[54:57]
	v_mfma_f32_16x16x32_bf16 v[50:53], v[138:141], v[228:231], v[50:53]
	v_mfma_f32_16x16x32_bf16 v[46:49], v[146:149], v[228:231], v[46:49]
	v_mfma_f32_16x16x32_bf16 v[42:45], v[138:141], v[236:239], v[42:45]
	v_mfma_f32_16x16x32_bf16 v[38:41], v[146:149], v[236:239], v[38:41]
	s_setprio 0
	s_setprio 1
	v_mfma_f32_16x16x32_bf16 v[34:37], v[162:165], v[178:181], v[34:37]
	v_mfma_f32_16x16x32_bf16 v[30:33], v[170:173], v[178:181], v[30:33]
	v_mfma_f32_16x16x32_bf16 v[26:29], v[162:165], v[192:195], v[26:29]
	v_mfma_f32_16x16x32_bf16 v[22:25], v[170:173], v[192:195], v[22:25]
	v_mfma_f32_16x16x32_bf16 v[18:21], v[162:165], v[224:227], v[18:21]
	v_mfma_f32_16x16x32_bf16 v[14:17], v[170:173], v[224:227], v[14:17]
	v_mfma_f32_16x16x32_bf16 v[10:13], v[162:165], v[232:235], v[10:13]
	v_mfma_f32_16x16x32_bf16 v[4:7], v[170:173], v[232:235], v[6:9]
	v_mfma_f32_16x16x32_bf16 v[34:37], v[166:169], v[188:191], v[34:37]
	v_mfma_f32_16x16x32_bf16 v[30:33], v[174:177], v[188:191], v[30:33]
	v_mfma_f32_16x16x32_bf16 v[26:29], v[166:169], v[206:209], v[26:29]
	v_mfma_f32_16x16x32_bf16 v[22:25], v[174:177], v[206:209], v[22:25]
	v_mfma_f32_16x16x32_bf16 v[18:21], v[166:169], v[228:231], v[18:21]
	v_mfma_f32_16x16x32_bf16 v[14:17], v[174:177], v[228:231], v[14:17]
	v_mfma_f32_16x16x32_bf16 v[10:13], v[166:169], v[236:239], v[10:13]
	v_mfma_f32_16x16x32_bf16 v[4:7], v[174:177], v[236:239], v[4:7]
	s_setprio 0
	s_barrier
	s_add_i32 s23, 0, 0x18000
	s_add_i32 s24, 0, 0x1c000
	ds_read_b128 v[134:137], v185 offset:32768
	ds_read_b128 v[138:141], v185 offset:33792
	ds_read_b128 v[142:145], v185 offset:34816
	ds_read_b128 v[146:149], v185 offset:35840
	ds_read_b128 v[162:165], v185 offset:49152
	ds_read_b128 v[166:169], v185 offset:50176
	ds_read_b128 v[170:173], v185 offset:51200
	ds_read_b128 v[174:177], v185 offset:52224
	s_add_u32 s14, s14, 0x80000
	s_addc_u32 s15, s15, 0
	ds_read_b128 v[178:181], v186 offset:32768
	ds_read_b128 v[188:191], v186 offset:33792
	ds_read_b128 v[192:195], v186 offset:34816
	ds_read_b128 v[206:209], v186 offset:35840
	ds_read_b128 v[224:227], v186 offset:36864
	ds_read_b128 v[228:231], v186 offset:37888
	ds_read_b128 v[232:235], v186 offset:38912
	ds_read_b128 v[236:239], v186 offset:39936
	s_mov_b32 m0, s50
	s_add_u32 s100, s14, 0xfff80000
	s_addc_u32 s101, s15, -1
	global_load_lds_dwordx4 v150, s[100:101]
	s_mov_b32 m0, s51
	s_nop 0
	global_load_lds_dwordx4 v154, s[100:101]
	s_mov_b32 m0, s36
	s_nop 0
	global_load_lds_dwordx4 v150, s[14:15]
	s_mov_b32 m0, s37
	s_nop 0
	global_load_lds_dwordx4 v154, s[14:15]
	s_waitcnt vmcnt(8) lgkmcnt(0)
	s_barrier
; #define PG8_STAGE(bufoff, gbase, voff) do { _Pragma("unroll") for (int _i = 0; _i < 2; ++_i) \
;         __builtin_amdgcn_global_load_lds((const unsigned*)((const char*)(gbase) + (voff)[_i]), (LAS unsigned*)(lds + (bufoff) + ldsw + _i * 8192), 16, 0, 0); } while (0)
; #define PG8_LDA(dst, b, h) do { _Pragma("unroll") for (int m = 0; m < 4; ++m) _Pragma("unroll") for (int k = 0; k < 2; ++k) dst[m][k] = *(const LAS bf16x8*)(lds + PG8_SA(b, h) + aoff + m * 2048 + k * 1024); } while (0)
; #define PG8_MMA(ai, bj, At, Bt) do { __builtin_amdgcn_s_setprio(1); _Pragma("unroll") for (int m = 0; m < 4; ++m) _Pragma("unroll") for (int n = 0; n < 2; ++n) _Pragma("unroll") for (int k = 0; k < 2; ++k) \
;         acc[ai][bj][m][n] = __builtin_amdgcn_mfma_f32_16x16x32_bf16(Bt[n][k], At[m][k], acc[ai][bj][m][n], 0, 0, 0); __builtin_amdgcn_s_setprio(0); } while (0)
; #define PG8_WAIT_V(n) asm volatile("s_waitcnt vmcnt(" #n ")" ::: "memory")
; #define PG8_WAIT_L(n) asm volatile("s_waitcnt lgkmcnt(" #n ")" ::: "memory")
; #define PG8_BAR __builtin_amdgcn_s_barrier()
; #define PG8_SCHED __builtin_amdgcn_sched_barrier(0)
; template <class Epi, bool ALIGN_EPI = true>
; __device__ __forceinline__ void gemm_phase(LAS unsigned char* lds, const Gemm g, const Sched& S, const Epi& E) {
;     ...
;             PG8_WAIT_V(8); PG8_WAIT_L(0); PG8_BAR; PG8_MMA(0, 0, At, B0); PG8_MMA(0, 1, At, B1); PG8_BAR; PG8_SCHED;
;             PG8_LDA(At, 1, 1); PG8_STAGE(PG8_SB(1, 0), b3, voffB); PG8_STAGE(PG8_SB(1, 1), b3 + hstepB, voffB); PG8_STAGE(PG8_SA(1, 0), a3, voffA);
;             PG8_WAIT_V(8); PG8_WAIT_L(0); PG8_BAR; PG8_MMA(1, 0, At, B0); PG8_MMA(1, 1, At, B1); PG8_BAR; PG8_SCHED;
;         }
	s_setprio 1
	v_mfma_f32_16x16x32_bf16 v[130:133], v[134:137], v[178:181], v[130:133]
	v_mfma_f32_16x16x32_bf16 v[126:129], v[142:145], v[178:181], v[126:129]
	v_mfma_f32_16x16x32_bf16 v[122:125], v[134:137], v[192:195], v[122:125]
	v_mfma_f32_16x16x32_bf16 v[118:121], v[142:145], v[192:195], v[118:121]
	v_mfma_f32_16x16x32_bf16 v[114:117], v[134:137], v[224:227], v[114:117]
	v_mfma_f32_16x16x32_bf16 v[110:113], v[142:145], v[224:227], v[110:113]
	v_mfma_f32_16x16x32_bf16 v[106:109], v[134:137], v[232:235], v[106:109]
	v_mfma_f32_16x16x32_bf16 v[102:105], v[142:145], v[232:235], v[102:105]
	v_mfma_f32_16x16x32_bf16 v[130:133], v[138:141], v[188:191], v[130:133]
	v_mfma_f32_16x16x32_bf16 v[126:129], v[146:149], v[188:191], v[126:129]
	v_mfma_f32_16x16x32_bf16 v[122:125], v[138:141], v[206:209], v[122:125]
	v_mfma_f32_16x16x32_bf16 v[118:121], v[146:149], v[206:209], v[118:121]
	v_mfma_f32_16x16x32_bf16 v[114:117], v[138:141], v[228:231], v[114:117]
	v_mfma_f32_16x16x32_bf16 v[110:113], v[146:149], v[228:231], v[110:113]
	v_mfma_f32_16x16x32_bf16 v[106:109], v[138:141], v[236:239], v[106:109]
	v_mfma_f32_16x16x32_bf16 v[102:105], v[146:149], v[236:239], v[102:105]
	s_setprio 0
	s_setprio 1
	v_mfma_f32_16x16x32_bf16 v[98:101], v[162:165], v[178:181], v[98:101]
	v_mfma_f32_16x16x32_bf16 v[94:97], v[170:173], v[178:181], v[94:97]
	v_mfma_f32_16x16x32_bf16 v[90:93], v[162:165], v[192:195], v[90:93]
	v_mfma_f32_16x16x32_bf16 v[86:89], v[170:173], v[192:195], v[86:89]
	v_mfma_f32_16x16x32_bf16 v[82:85], v[162:165], v[224:227], v[82:85]
	v_mfma_f32_16x16x32_bf16 v[78:81], v[170:173], v[224:227], v[78:81]
	v_mfma_f32_16x16x32_bf16 v[74:77], v[162:165], v[232:235], v[74:77]
	v_mfma_f32_16x16x32_bf16 v[70:73], v[170:173], v[232:235], v[70:73]
	v_mfma_f32_16x16x32_bf16 v[98:101], v[166:169], v[188:191], v[98:101]
	v_mfma_f32_16x16x32_bf16 v[94:97], v[174:177], v[188:191], v[94:97]
	v_mfma_f32_16x16x32_bf16 v[90:93], v[166:169], v[206:209], v[90:93]
	v_mfma_f32_16x16x32_bf16 v[86:89], v[174:177], v[206:209], v[86:89]
	v_mfma_f32_16x16x32_bf16 v[82:85], v[166:169], v[228:231], v[82:85]
	v_mfma_f32_16x16x32_bf16 v[78:81], v[174:177], v[228:231], v[78:81]
	v_mfma_f32_16x16x32_bf16 v[74:77], v[166:169], v[236:239], v[74:77]
	v_mfma_f32_16x16x32_bf16 v[70:73], v[174:177], v[236:239], v[70:73]
	s_setprio 0
	s_barrier
	s_add_u32 s100, s6, 0x80
	s_addc_u32 s101, s7, 0
	s_add_i32 s14, s23, s27
	s_mov_b32 m0, s14
	ds_read_b128 v[178:181], v186 offset:49152
	ds_read_b128 v[188:191], v186 offset:50176
	ds_read_b128 v[192:195], v186 offset:51200
	ds_read_b128 v[206:209], v186 offset:52224
	ds_read_b128 v[224:227], v186 offset:53248
	ds_read_b128 v[228:231], v186 offset:54272
	ds_read_b128 v[232:235], v186 offset:55296
	ds_read_b128 v[236:239], v186 offset:56320
	global_load_lds_dwordx4 v152, s[100:101]
	s_add_i32 m0, s14, 0x2000
	s_add_u32 s6, s6, 0x80080
	s_addc_u32 s7, s7, 0
	s_add_i32 s14, s24, s27
	global_load_lds_dwordx4 v156, s[100:101]
	s_mov_b32 m0, s14
	s_nop 0
	global_load_lds_dwordx4 v152, s[6:7]
	s_add_i32 m0, s14, 0x2000
	s_nop 0
	global_load_lds_dwordx4 v156, s[6:7]
	s_waitcnt vmcnt(6) lgkmcnt(0)
	s_barrier
	s_setprio 1
	v_mfma_f32_16x16x32_bf16 v[66:69], v[134:137], v[178:181], v[66:69]
	v_mfma_f32_16x16x32_bf16 v[62:65], v[142:145], v[178:181], v[62:65]
	v_mfma_f32_16x16x32_bf16 v[58:61], v[134:137], v[192:195], v[58:61]
	v_mfma_f32_16x16x32_bf16 v[54:57], v[142:145], v[192:195], v[54:57]
	v_mfma_f32_16x16x32_bf16 v[50:53], v[134:137], v[224:227], v[50:53]
	v_mfma_f32_16x16x32_bf16 v[46:49], v[142:145], v[224:227], v[46:49]
	v_mfma_f32_16x16x32_bf16 v[42:45], v[134:137], v[232:235], v[42:45]
	v_mfma_f32_16x16x32_bf16 v[38:41], v[142:145], v[232:235], v[38:41]
	v_mfma_f32_16x16x32_bf16 v[66:69], v[138:141], v[188:191], v[66:69]
	v_mfma_f32_16x16x32_bf16 v[62:65], v[146:149], v[188:191], v[62:65]
	v_mfma_f32_16x16x32_bf16 v[58:61], v[138:141], v[206:209], v[58:61]
	v_mfma_f32_16x16x32_bf16 v[54:57], v[146:149], v[206:209], v[54:57]
	v_mfma_f32_16x16x32_bf16 v[50:53], v[138:141], v[228:231], v[50:53]
	v_mfma_f32_16x16x32_bf16 v[46:49], v[146:149], v[228:231], v[46:49]
	v_mfma_f32_16x16x32_bf16 v[42:45], v[138:141], v[236:239], v[42:45]
	v_mfma_f32_16x16x32_bf16 v[38:41], v[146:149], v[236:239], v[38:41]
	s_setprio 0
	s_setprio 1
	v_mfma_f32_16x16x32_bf16 v[34:37], v[162:165], v[178:181], v[34:37]
	v_mfma_f32_16x16x32_bf16 v[30:33], v[170:173], v[178:181], v[30:33]
	v_mfma_f32_16x16x32_bf16 v[26:29], v[162:165], v[192:195], v[26:29]
	v_mfma_f32_16x16x32_bf16 v[22:25], v[170:173], v[192:195], v[22:25]
	v_mfma_f32_16x16x32_bf16 v[18:21], v[162:165], v[224:227], v[18:21]
	v_mfma_f32_16x16x32_bf16 v[14:17], v[170:173], v[224:227], v[14:17]
	v_mfma_f32_16x16x32_bf16 v[8:11], v[162:165], v[232:235], v[10:13]
	v_mfma_f32_16x16x32_bf16 v[4:7], v[170:173], v[232:235], v[4:7]
	v_mfma_f32_16x16x32_bf16 v[34:37], v[166:169], v[188:191], v[34:37]
	v_mfma_f32_16x16x32_bf16 v[30:33], v[174:177], v[188:191], v[30:33]
	v_mfma_f32_16x16x32_bf16 v[26:29], v[166:169], v[206:209], v[26:29]
	v_mfma_f32_16x16x32_bf16 v[22:25], v[174:177], v[206:209], v[22:25]
	v_mfma_f32_16x16x32_bf16 v[18:21], v[166:169], v[228:231], v[18:21]
	v_mfma_f32_16x16x32_bf16 v[14:17], v[174:177], v[228:231], v[14:17]
	v_mfma_f32_16x16x32_bf16 v[10:13], v[166:169], v[236:239], v[8:11]
	v_mfma_f32_16x16x32_bf16 v[6:9], v[174:177], v[236:239], v[4:7]
	s_setprio 0
	s_barrier
	s_add_u32 s4, s4, 0x100
	s_addc_u32 s5, s5, 0
	s_add_u32 s20, s20, 0x100
	s_addc_u32 s21, s21, 0
	s_cmp_ge_i32 s22, s46
	s_mov_b32 s6, s22
	s_cbranch_scc0 .LBB0_500

; #define PG8_STAGE(bufoff, gbase, voff) do { _Pragma("unroll") for (int _i = 0; _i < 2; ++_i) \
;         __builtin_amdgcn_global_load_lds((const unsigned*)((const char*)(gbase) + (voff)[_i]), (LAS unsigned*)(lds + (bufoff) + ldsw + _i * 8192), 16, 0, 0); } while (0)
; #define PG8_WAIT_V(n) asm volatile("s_waitcnt vmcnt(" #n ")" ::: "memory")
; #define PG8_BAR __builtin_amdgcn_s_barrier()
; template <class Epi, bool ALIGN_EPI = true>
; __device__ __forceinline__ void gemm_phase(LAS unsigned char* lds, const Gemm g, const Sched& S, const Epi& E) {
;     ...
;     f32x4 acc[2][2][4][2];
; #pragma unroll
;     for (int a = 0; a < 2; ++a)
; #pragma unroll
;         for (int b = 0; b < 2; ++b)
; #pragma unroll
;             for (int m = 0; m < 4; ++m)
; #pragma unroll
;                 for (int n = 0; n < 2; ++n) acc[a][b][m][n] = (f32x4){0.f, 0.f, 0.f, 0.f};
;     bf16x8 At[4][2], B0[2][2], B1[2][2];
;     const char* cA = (const char*)g.A + cur.aoff; const char* cB = (const char*)g.Bt + cur.boff;
;     PG8_STAGE(PG8_SB(0, 0), cB, voffB); PG8_STAGE(PG8_SB(0, 1), cB + hstepB, voffB); PG8_STAGE(PG8_SA(0, 0), cA, voffA); PG8_STAGE(PG8_SA(0, 1), cA + hstepA, voffA);
;     if (wr == 1) PG8_BAR;
;     PG8_WAIT_V(2); PG8_BAR;
;     PG8_STAGE(PG8_SB(1, 0), cB + kstep, voffB); PG8_STAGE(PG8_SA(1, 0), cA + kstep, voffA); PG8_STAGE(PG8_SB(1, 1), cB + hstepB + kstep, voffB);
;     PG8_WAIT_V(6); PG8_BAR;
.LBB0_740:
	v_readlane_b32 s60, v246, 10
	s_add_u32 s52, s54, s6
	v_readlane_b32 s0, v242, 25
	v_readlane_b32 s61, v246, 11
	v_readlane_b32 s62, v246, 12
	v_readlane_b32 s63, v246, 13
	v_readlane_b32 s64, v246, 14
	v_readlane_b32 s65, v246, 15
	s_addc_u32 s53, s55, s7
	s_lshl_b32 s94, s0, 10
	v_readlane_b32 s66, v246, 16
	v_readlane_b32 s67, v246, 17
	v_readlane_b32 s68, v246, 18
	v_readlane_b32 s69, v246, 19
	s_mov_b64 s[60:61], s[64:65]
	s_lshl_b64 s[6:7], s[94:95], 2
	s_mov_b64 s[62:63], s[66:67]
	s_mov_b64 s[64:65], s[68:69]
	s_add_u32 s6, s64, s6
	s_addc_u32 s7, s65, s7
	s_ashr_i32 s18, s14, 31
	s_lshr_b32 s18, s18, 26
	s_lshl_b32 s15, s15, 5
	s_add_i32 s18, s14, s18
	s_and_b32 s58, s15, 0x60
	s_add_i32 m0, s36, 0x18000
	v_lshl_add_u64 v[10:11], v[10:11], 0, s[8:9]
	s_ashr_i32 s54, s18, 6
	s_lshl_b32 s55, s17, 6
	s_lshl_b32 s17, s17, 13
	s_lshl_b32 s15, s58, 7
	s_waitcnt vmcnt(2)
	s_barrier
	global_load_lds_dwordx4 v[10:11], off
	v_lshl_add_u64 v[8:9], v[8:9], 0, s[8:9]
	s_add_i32 m0, s36, 0x1a000
	s_add_i32 s59, s36, 0x8000
	s_add_i32 s60, s36, 0xa000
	global_load_lds_dwordx4 v[8:9], off
	v_lshl_add_u64 v[4:5], v[4:5], 0, s[8:9]
	s_mov_b32 m0, s59
	s_add_u32 s18, s26, 0x10080
	global_load_lds_dwordx4 v[4:5], off
	v_lshl_add_u64 v[4:5], v[6:7], 0, s[8:9]
	s_mov_b32 m0, s60
	s_addc_u32 s19, s27, 0
	global_load_lds_dwordx4 v[4:5], off
	s_add_i32 m0, s36, 0x1c000
	v_lshl_add_u64 v[4:5], s[18:19], 0, v[2:3]
	global_load_lds_dwordx4 v[4:5], off
	v_lshl_add_u64 v[4:5], s[18:19], 0, v[148:149]
	s_add_i32 m0, s36, 0x1e000
	v_and_b32_e32 v162, 63, v18
	global_load_lds_dwordx4 v[4:5], off
	v_lshlrev_b32_e32 v4, 14, v16
	v_and_b32_e32 v4, 0xffff8000, v4
	v_lshl_add_u32 v4, v15, 11, v4
	v_and_b32_e32 v5, 1, v16
	v_lshl_or_b32 v4, v5, 6, v4
	v_and_b32_e32 v19, 48, v18
	v_lshlrev_b32_e32 v20, 6, v18
	s_movk_i32 s10, 0x3c0
	v_lshlrev_b32_e32 v18, 2, v18
	v_lshl_add_u32 v154, v17, 1, v4
	v_lshlrev_b32_e32 v4, 14, v12
	v_and_or_b32 v19, v20, s10, v19
	v_and_b32_e32 v18, 32, v18
	s_cmp_gt_i32 s14, 63
	v_and_b32_e32 v4, 0xffff8000, v4
	v_readlane_b32 s18, v243, 35
	v_bitop3_b32 v163, s15, v19, v18 bitop3:0xf6
	v_add_u32_e32 v163, 0x10000, v163
	s_waitcnt vmcnt(6)
	s_cselect_b64 s[14:15], -1, 0
	s_add_i32 s61, s54, -2
	v_lshl_add_u32 v4, v13, 11, v4
	v_and_b32_e32 v5, 1, v12
	v_readlane_b32 s19, v243, 36
	v_readlane_b32 s1, v242, 26
	v_bitop3_b32 v20, v19, s17, v18 bitop3:0xde
	s_cmpk_lt_u32 s16, 0x100
	v_lshl_or_b32 v4, v5, 6, v4
	s_mov_b32 s64, s18
	v_readlane_b32 s18, v243, 23
	s_mov_b64 s[0:1], s[94:95]
	s_cselect_b64 s[16:17], -1, 0
	v_mov_b32_e32 v155, v3
	v_lshl_add_u32 v156, v14, 1, v4
	v_mov_b32_e32 v157, v3
	s_mov_b32 s49, 0
	v_add_u32_e32 v164, 0, v20
	s_mov_b32 s63, s18
	v_readlane_b32 s70, v246, 20
	v_readlane_b32 s71, v246, 21
	v_readlane_b32 s72, v246, 22
	v_readlane_b32 s73, v246, 23
	v_readlane_b32 s74, v246, 24
	v_readlane_b32 s75, v246, 25
	s_barrier
	v_readlane_b32 s19, v243, 24
	s_branch .LBB0_743

; #define PG8_STAGE(bufoff, gbase, voff) do { _Pragma("unroll") for (int _i = 0; _i < 2; ++_i) \
;         __builtin_amdgcn_global_load_lds((const unsigned*)((const char*)(gbase) + (voff)[_i]), (LAS unsigned*)(lds + (bufoff) + ldsw + _i * 8192), 16, 0, 0); } while (0)
; #define PG8_LDA(dst, b, h) do { _Pragma("unroll") for (int m = 0; m < 4; ++m) _Pragma("unroll") for (int k = 0; k < 2; ++k) dst[m][k] = *(const LAS bf16x8*)(lds + PG8_SA(b, h) + aoff + m * 2048 + k * 1024); } while (0)
; #define PG8_LDB(dst, b, h) do { _Pragma("unroll") for (int n = 0; n < 2; ++n) _Pragma("unroll") for (int k = 0; k < 2; ++k) dst[n][k] = *(const LAS bf16x8*)(lds + PG8_SB(b, h) + boff + n * 2048 + k * 1024); } while (0)
; #define PG8_MMA(ai, bj, At, Bt) do { __builtin_amdgcn_s_setprio(1); _Pragma("unroll") for (int m = 0; m < 4; ++m) _Pragma("unroll") for (int n = 0; n < 2; ++n) _Pragma("unroll") for (int k = 0; k < 2; ++k) \
;         acc[ai][bj][m][n] = __builtin_amdgcn_mfma_f32_16x16x32_bf16(Bt[n][k], At[m][k], acc[ai][bj][m][n], 0, 0, 0); __builtin_amdgcn_s_setprio(0); } while (0)
; #define PG8_WAIT_V(n) asm volatile("s_waitcnt vmcnt(" #n ")" ::: "memory")
; #define PG8_WAIT_L(n) asm volatile("s_waitcnt lgkmcnt(" #n ")" ::: "memory")
; #define PG8_BAR __builtin_amdgcn_s_barrier()
; template <class Epi, bool ALIGN_EPI = true>
; __device__ __forceinline__ void gemm_phase(LAS unsigned char* lds, const Gemm g, const Sched& S, const Epi& E) {
;     ...
;         for (int t = t_lo; t < t_hi; t += 2) {
;             const bool last = (t == nt - 2);
;             const char* a1 = cA + (size_t)(t + 1) * kstep;
;             const char* a2 = last ? nA : cA + (size_t)(t + 2) * kstep; const char* b2 = last ? nB : cB + (size_t)(t + 2) * kstep;
;             const char* a3 = a2 + kstep; const char* b3 = b2 + kstep;
;             const int rflag = __builtin_amdgcn_readfirstlane(t | (int)(ui == 0));
;             PG8_LDB(B0, 0, 0); PG8_LDB(B1, 0, 1); PG8_SCHED; PG8_LDA(At, 0, 0); PG8_STAGE(PG8_SA(1, 1), a1 + hstepA, voffA);
;             if constexpr (Epi::NSTORES > 0) PG8_WAIT_RELAX(rflag, 8 + Epi::NSTORES); else PG8_WAIT_V(8);
;             PG8_WAIT_L(0); PG8_BAR; PG8_MMA(0, 0, At, B0); PG8_MMA(0, 1, At, B1); PG8_BAR; PG8_SCHED;
;             PG8_LDA(At, 0, 1); PG8_STAGE(PG8_SB(0, 0), b2, voffB); PG8_STAGE(PG8_SB(0, 1), b2 + hstepB, voffB); PG8_STAGE(PG8_SA(0, 0), a2, voffA);
.LBB0_752:
	s_add_i32 s69, s48, 2
	s_add_u32 s26, s40, 0xfffc0080
	s_addc_u32 s27, s41, -1
	s_add_i32 s70, 0, 0x10000
	s_cmp_eq_u32 s61, s48
	v_add_u32_e32 v133, s48, v132
	s_cselect_b32 s49, s19, s27
	s_cselect_b32 s48, s21, s26
	s_cselect_b32 s27, s65, s68
	s_cselect_b32 s26, s66, s67
	s_add_i32 s72, 0, 0x14000
	ds_read_b128 v[134:137], v163
	ds_read_b128 v[138:141], v163 offset:1024
	ds_read_b128 v[142:145], v163 offset:2048
	ds_read_b128 v[158:161], v163 offset:3072
	ds_read_b128 v[166:169], v163 offset:16384
	ds_read_b128 v[170:173], v163 offset:17408
	ds_read_b128 v[174:177], v163 offset:18432
	ds_read_b128 v[178:181], v163 offset:19456
	ds_read_b128 v[182:185], v164
	ds_read_b128 v[186:189], v164 offset:1024
	ds_read_b128 v[190:193], v164 offset:2048
	ds_read_b128 v[194:197], v164 offset:3072
	ds_read_b128 v[206:209], v164 offset:4096
	ds_read_b128 v[224:227], v164 offset:5120
	ds_read_b128 v[228:231], v164 offset:6144
	ds_read_b128 v[232:235], v164 offset:7168
	s_mov_b32 m0, s59
	s_add_u32 s100, s40, 0xfffc0000
	s_addc_u32 s101, s41, -1
	global_load_lds_dwordx4 v154, s[100:101]
	s_mov_b32 m0, s60
	s_nop 0
	global_load_lds_dwordx4 v156, s[100:101]
	s_add_i32 m0, s36, 0xc000
	s_nop 0
	global_load_lds_dwordx4 v154, s[40:41]
	s_add_i32 m0, s36, 0xe000
	v_readfirstlane_b32 s73, v133
	global_load_lds_dwordx4 v156, s[40:41]
	s_cmp_eq_u32 s73, 0
	s_cbranch_scc1 .Lrw8
	s_waitcnt vmcnt(8)
.Lrw8:
	s_waitcnt vmcnt(24) lgkmcnt(0)
	s_barrier
	s_setprio 1
	v_mfma_f32_16x16x32_bf16 v[128:131], v[134:137], v[182:185], v[128:131]
	v_mfma_f32_16x16x32_bf16 v[124:127], v[142:145], v[182:185], v[124:127]
	v_mfma_f32_16x16x32_bf16 v[112:115], v[134:137], v[190:193], v[112:115]
	v_mfma_f32_16x16x32_bf16 v[108:111], v[142:145], v[190:193], v[108:111]
	v_mfma_f32_16x16x32_bf16 v[96:99], v[134:137], v[206:209], v[96:99]
	v_mfma_f32_16x16x32_bf16 v[92:95], v[142:145], v[206:209], v[92:95]
	v_mfma_f32_16x16x32_bf16 v[80:83], v[134:137], v[228:231], v[80:83]
	v_mfma_f32_16x16x32_bf16 v[76:79], v[142:145], v[228:231], v[76:79]
	v_mfma_f32_16x16x32_bf16 v[128:131], v[138:141], v[186:189], v[128:131]
	v_mfma_f32_16x16x32_bf16 v[124:127], v[158:161], v[186:189], v[124:127]
	v_mfma_f32_16x16x32_bf16 v[112:115], v[138:141], v[194:197], v[112:115]
	v_mfma_f32_16x16x32_bf16 v[108:111], v[158:161], v[194:197], v[108:111]
	v_mfma_f32_16x16x32_bf16 v[96:99], v[138:141], v[224:227], v[96:99]
	v_mfma_f32_16x16x32_bf16 v[92:95], v[158:161], v[224:227], v[92:95]
	v_mfma_f32_16x16x32_bf16 v[80:83], v[138:141], v[232:235], v[80:83]
	v_mfma_f32_16x16x32_bf16 v[76:79], v[158:161], v[232:235], v[76:79]
	s_setprio 0
	s_setprio 1
	v_mfma_f32_16x16x32_bf16 v[120:123], v[166:169], v[182:185], v[120:123]
	v_mfma_f32_16x16x32_bf16 v[116:119], v[174:177], v[182:185], v[116:119]
	v_mfma_f32_16x16x32_bf16 v[104:107], v[166:169], v[190:193], v[104:107]
	v_mfma_f32_16x16x32_bf16 v[100:103], v[174:177], v[190:193], v[100:103]
	v_mfma_f32_16x16x32_bf16 v[88:91], v[166:169], v[206:209], v[88:91]
	v_mfma_f32_16x16x32_bf16 v[84:87], v[174:177], v[206:209], v[84:87]
	v_mfma_f32_16x16x32_bf16 v[72:75], v[166:169], v[228:231], v[72:75]
	v_mfma_f32_16x16x32_bf16 v[68:71], v[174:177], v[228:231], v[68:71]
	v_mfma_f32_16x16x32_bf16 v[120:123], v[170:173], v[186:189], v[120:123]
	v_mfma_f32_16x16x32_bf16 v[116:119], v[178:181], v[186:189], v[116:119]
	v_mfma_f32_16x16x32_bf16 v[104:107], v[170:173], v[194:197], v[104:107]
	v_mfma_f32_16x16x32_bf16 v[100:103], v[178:181], v[194:197], v[100:103]
	v_mfma_f32_16x16x32_bf16 v[88:91], v[170:173], v[224:227], v[88:91]
	v_mfma_f32_16x16x32_bf16 v[84:87], v[178:181], v[224:227], v[84:87]
	v_mfma_f32_16x16x32_bf16 v[72:75], v[170:173], v[232:235], v[72:75]
	v_mfma_f32_16x16x32_bf16 v[68:71], v[178:181], v[232:235], v[68:71]
	s_setprio 0
	s_barrier
	s_add_i32 s70, s70, s35
	s_mov_b32 m0, s70
	ds_read_b128 v[182:185], v164 offset:16384
	ds_read_b128 v[186:189], v164 offset:17408
	ds_read_b128 v[190:193], v164 offset:18432
	ds_read_b128 v[194:197], v164 offset:19456
	ds_read_b128 v[206:209], v164 offset:20480
	ds_read_b128 v[224:227], v164 offset:21504
	ds_read_b128 v[228:231], v164 offset:22528
	ds_read_b128 v[232:235], v164 offset:23552
	global_load_lds_dwordx4 v2, s[26:27]
	s_add_i32 m0, s70, 0x2000
	s_add_u32 s70, s26, 0x10000
	s_addc_u32 s71, s27, 0
	s_add_i32 s72, s72, s35
	global_load_lds_dwordx4 v148, s[26:27]
	s_mov_b32 m0, s72
	s_nop 0
	global_load_lds_dwordx4 v2, s[70:71]
	s_add_i32 m0, s72, 0x2000
	s_nop 0
	global_load_lds_dwordx4 v148, s[70:71]
; #define PG8_STAGE(bufoff, gbase, voff) do { _Pragma("unroll") for (int _i = 0; _i < 2; ++_i) \
;         __builtin_amdgcn_global_load_lds((const unsigned*)((const char*)(gbase) + (voff)[_i]), (LAS unsigned*)(lds + (bufoff) + ldsw + _i * 8192), 16, 0, 0); } while (0)
; #define PG8_LDA(dst, b, h) do { _Pragma("unroll") for (int m = 0; m < 4; ++m) _Pragma("unroll") for (int k = 0; k < 2; ++k) dst[m][k] = *(const LAS bf16x8*)(lds + PG8_SA(b, h) + aoff + m * 2048 + k * 1024); } while (0)
; #define PG8_LDB(dst, b, h) do { _Pragma("unroll") for (int n = 0; n < 2; ++n) _Pragma("unroll") for (int k = 0; k < 2; ++k) dst[n][k] = *(const LAS bf16x8*)(lds + PG8_SB(b, h) + boff + n * 2048 + k * 1024); } while (0)
; #define PG8_MMA(ai, bj, At, Bt) do { __builtin_amdgcn_s_setprio(1); _Pragma("unroll") for (int m = 0; m < 4; ++m) _Pragma("unroll") for (int n = 0; n < 2; ++n) _Pragma("unroll") for (int k = 0; k < 2; ++k) \
;         acc[ai][bj][m][n] = __builtin_amdgcn_mfma_f32_16x16x32_bf16(Bt[n][k], At[m][k], acc[ai][bj][m][n], 0, 0, 0); __builtin_amdgcn_s_setprio(0); } while (0)
; #define PG8_WAIT_V(n) asm volatile("s_waitcnt vmcnt(" #n ")" ::: "memory")
; #define PG8_WAIT_L(n) asm volatile("s_waitcnt lgkmcnt(" #n ")" ::: "memory")
; #define PG8_BAR __builtin_amdgcn_s_barrier()
; #define PG8_WAIT_RELAX(flag, n) asm volatile("s_cmp_eq_u32 %0, 0\n\ts_cbranch_scc1 .Lrw%=\n\ts_waitcnt vmcnt(8)\n.Lrw%=:\n\ts_waitcnt vmcnt(%1)" :: "s"(flag), "n"(n) : "scc", "memory")
; #define PG8_SCHED __builtin_amdgcn_sched_barrier(0)
; template <class Epi, bool ALIGN_EPI = true>
; __device__ __forceinline__ void gemm_phase(LAS unsigned char* lds, const Gemm g, const Sched& S, const Epi& E) {
;     ...
;             if constexpr (Epi::NSTORES > 0) PG8_WAIT_RELAX(rflag, 8 + Epi::NSTORES); else PG8_WAIT_V(8);
;             PG8_WAIT_L(0); PG8_BAR; PG8_MMA(1, 0, At, B0); PG8_MMA(1, 1, At, B1); PG8_BAR; PG8_SCHED;
;             PG8_LDB(B0, 1, 0); PG8_LDB(B1, 1, 1); PG8_SCHED; PG8_LDA(At, 1, 0); PG8_STAGE(PG8_SA(0, 1), a2 + hstepA, voffA);
;             PG8_WAIT_V(8); PG8_WAIT_L(0); PG8_BAR; PG8_MMA(0, 0, At, B0); PG8_MMA(0, 1, At, B1); PG8_BAR; PG8_SCHED;
.Lrw9:
	s_waitcnt vmcnt(6) lgkmcnt(0)
	s_barrier
	s_setprio 1
	v_mfma_f32_16x16x32_bf16 v[64:67], v[134:137], v[182:185], v[64:67]
	v_mfma_f32_16x16x32_bf16 v[60:63], v[142:145], v[182:185], v[60:63]
	v_mfma_f32_16x16x32_bf16 v[48:51], v[134:137], v[190:193], v[48:51]
	v_mfma_f32_16x16x32_bf16 v[44:47], v[142:145], v[190:193], v[44:47]
	v_mfma_f32_16x16x32_bf16 v[32:35], v[134:137], v[206:209], v[32:35]
	v_mfma_f32_16x16x32_bf16 v[28:31], v[142:145], v[206:209], v[28:31]
	v_mfma_f32_16x16x32_bf16 v[16:19], v[134:137], v[228:231], v[16:19]
	v_mfma_f32_16x16x32_bf16 v[12:15], v[142:145], v[228:231], v[12:15]
	v_mfma_f32_16x16x32_bf16 v[64:67], v[138:141], v[186:189], v[64:67]
	v_mfma_f32_16x16x32_bf16 v[60:63], v[158:161], v[186:189], v[60:63]
	v_mfma_f32_16x16x32_bf16 v[48:51], v[138:141], v[194:197], v[48:51]
	v_mfma_f32_16x16x32_bf16 v[44:47], v[158:161], v[194:197], v[44:47]
	v_mfma_f32_16x16x32_bf16 v[32:35], v[138:141], v[224:227], v[32:35]
	v_mfma_f32_16x16x32_bf16 v[28:31], v[158:161], v[224:227], v[28:31]
	v_mfma_f32_16x16x32_bf16 v[16:19], v[138:141], v[232:235], v[16:19]
	v_mfma_f32_16x16x32_bf16 v[12:15], v[158:161], v[232:235], v[12:15]
	s_setprio 0
	s_setprio 1
	v_mfma_f32_16x16x32_bf16 v[56:59], v[166:169], v[182:185], v[56:59]
	v_mfma_f32_16x16x32_bf16 v[52:55], v[174:177], v[182:185], v[52:55]
	v_mfma_f32_16x16x32_bf16 v[40:43], v[166:169], v[190:193], v[40:43]
	v_mfma_f32_16x16x32_bf16 v[36:39], v[174:177], v[190:193], v[36:39]
	v_mfma_f32_16x16x32_bf16 v[24:27], v[166:169], v[206:209], v[24:27]
	v_mfma_f32_16x16x32_bf16 v[20:23], v[174:177], v[206:209], v[20:23]
	v_mfma_f32_16x16x32_bf16 v[8:11], v[166:169], v[228:231], v[8:11]
	v_mfma_f32_16x16x32_bf16 v[4:7], v[174:177], v[228:231], v[4:7]
	v_mfma_f32_16x16x32_bf16 v[56:59], v[170:173], v[186:189], v[56:59]
	v_mfma_f32_16x16x32_bf16 v[52:55], v[178:181], v[186:189], v[52:55]
	v_mfma_f32_16x16x32_bf16 v[40:43], v[170:173], v[194:197], v[40:43]
	v_mfma_f32_16x16x32_bf16 v[36:39], v[178:181], v[194:197], v[36:39]
	v_mfma_f32_16x16x32_bf16 v[24:27], v[170:173], v[224:227], v[24:27]
	v_mfma_f32_16x16x32_bf16 v[20:23], v[178:181], v[224:227], v[20:23]
	v_mfma_f32_16x16x32_bf16 v[8:11], v[170:173], v[232:235], v[8:11]
	v_mfma_f32_16x16x32_bf16 v[4:7], v[178:181], v[232:235], v[4:7]
	s_setprio 0
	s_barrier
	s_add_i32 s70, 0, 0x18000
	s_add_i32 s71, 0, 0x1c000
	ds_read_b128 v[134:137], v163 offset:32768
	ds_read_b128 v[138:141], v163 offset:33792
	ds_read_b128 v[142:145], v163 offset:34816
	ds_read_b128 v[158:161], v163 offset:35840
	ds_read_b128 v[166:169], v163 offset:49152
	ds_read_b128 v[170:173], v163 offset:50176
	ds_read_b128 v[174:177], v163 offset:51200
	ds_read_b128 v[178:181], v163 offset:52224
	s_add_u32 s48, s48, 0x40000
	s_addc_u32 s49, s49, 0
	ds_read_b128 v[182:185], v164 offset:32768
	ds_read_b128 v[186:189], v164 offset:33792
	ds_read_b128 v[190:193], v164 offset:34816
	ds_read_b128 v[194:197], v164 offset:35840
	ds_read_b128 v[206:209], v164 offset:36864
	ds_read_b128 v[224:227], v164 offset:37888
	ds_read_b128 v[228:231], v164 offset:38912
	ds_read_b128 v[232:235], v164 offset:39936
	s_mov_b32 m0, s36
	s_add_u32 s100, s48, 0xfffc0000
	s_addc_u32 s101, s49, -1
	global_load_lds_dwordx4 v152, s[100:101]
	s_mov_b32 m0, s37
	s_nop 0
	global_load_lds_dwordx4 v150, s[100:101]
	s_mov_b32 m0, s50
	s_nop 0
	global_load_lds_dwordx4 v152, s[48:49]
	s_mov_b32 m0, s51
	s_nop 0
	global_load_lds_dwordx4 v150, s[48:49]
	s_waitcnt vmcnt(8) lgkmcnt(0)
	s_barrier
; #define PG8_STAGE(bufoff, gbase, voff) do { _Pragma("unroll") for (int _i = 0; _i < 2; ++_i) \
;         __builtin_amdgcn_global_load_lds((const unsigned*)((const char*)(gbase) + (voff)[_i]), (LAS unsigned*)(lds + (bufoff) + ldsw + _i * 8192), 16, 0, 0); } while (0)
; #define PG8_LDA(dst, b, h) do { _Pragma("unroll") for (int m = 0; m < 4; ++m) _Pragma("unroll") for (int k = 0; k < 2; ++k) dst[m][k] = *(const LAS bf16x8*)(lds + PG8_SA(b, h) + aoff + m * 2048 + k * 1024); } while (0)
; #define PG8_MMA(ai, bj, At, Bt) do { __builtin_amdgcn_s_setprio(1); _Pragma("unroll") for (int m = 0; m < 4; ++m) _Pragma("unroll") for (int n = 0; n < 2; ++n) _Pragma("unroll") for (int k = 0; k < 2; ++k) \
;         acc[ai][bj][m][n] = __builtin_amdgcn_mfma_f32_16x16x32_bf16(Bt[n][k], At[m][k], acc[ai][bj][m][n], 0, 0, 0); __builtin_amdgcn_s_setprio(0); } while (0)
; #define PG8_WAIT_V(n) asm volatile("s_waitcnt vmcnt(" #n ")" ::: "memory")
; #define PG8_WAIT_L(n) asm volatile("s_waitcnt lgkmcnt(" #n ")" ::: "memory")
; #define PG8_BAR __builtin_amdgcn_s_barrier()
; #define PG8_SCHED __builtin_amdgcn_sched_barrier(0)
; template <class Epi, bool ALIGN_EPI = true>
; __device__ __forceinline__ void gemm_phase(LAS unsigned char* lds, const Gemm g, const Sched& S, const Epi& E) {
;     ...
;             PG8_WAIT_V(8); PG8_WAIT_L(0); PG8_BAR; PG8_MMA(0, 0, At, B0); PG8_MMA(0, 1, At, B1); PG8_BAR; PG8_SCHED;
;             PG8_LDA(At, 1, 1); PG8_STAGE(PG8_SB(1, 0), b3, voffB); PG8_STAGE(PG8_SB(1, 1), b3 + hstepB, voffB); PG8_STAGE(PG8_SA(1, 0), a3, voffA);
;             PG8_WAIT_V(8); PG8_WAIT_L(0); PG8_BAR; PG8_MMA(1, 0, At, B0); PG8_MMA(1, 1, At, B1); PG8_BAR; PG8_SCHED;
;         }
	s_setprio 1
	v_mfma_f32_16x16x32_bf16 v[128:131], v[134:137], v[182:185], v[128:131]
	v_mfma_f32_16x16x32_bf16 v[124:127], v[142:145], v[182:185], v[124:127]
	v_mfma_f32_16x16x32_bf16 v[112:115], v[134:137], v[190:193], v[112:115]
	v_mfma_f32_16x16x32_bf16 v[108:111], v[142:145], v[190:193], v[108:111]
	v_mfma_f32_16x16x32_bf16 v[96:99], v[134:137], v[206:209], v[96:99]
	v_mfma_f32_16x16x32_bf16 v[92:95], v[142:145], v[206:209], v[92:95]
	v_mfma_f32_16x16x32_bf16 v[80:83], v[134:137], v[228:231], v[80:83]
	v_mfma_f32_16x16x32_bf16 v[76:79], v[142:145], v[228:231], v[76:79]
	v_mfma_f32_16x16x32_bf16 v[128:131], v[138:141], v[186:189], v[128:131]
	v_mfma_f32_16x16x32_bf16 v[124:127], v[158:161], v[186:189], v[124:127]
	v_mfma_f32_16x16x32_bf16 v[112:115], v[138:141], v[194:197], v[112:115]
	v_mfma_f32_16x16x32_bf16 v[108:111], v[158:161], v[194:197], v[108:111]
	v_mfma_f32_16x16x32_bf16 v[96:99], v[138:141], v[224:227], v[96:99]
	v_mfma_f32_16x16x32_bf16 v[92:95], v[158:161], v[224:227], v[92:95]
	v_mfma_f32_16x16x32_bf16 v[80:83], v[138:141], v[232:235], v[80:83]
	v_mfma_f32_16x16x32_bf16 v[76:79], v[158:161], v[232:235], v[76:79]
	s_setprio 0
	s_setprio 1
	v_mfma_f32_16x16x32_bf16 v[120:123], v[166:169], v[182:185], v[120:123]
	v_mfma_f32_16x16x32_bf16 v[116:119], v[174:177], v[182:185], v[116:119]
	v_mfma_f32_16x16x32_bf16 v[104:107], v[166:169], v[190:193], v[104:107]
	v_mfma_f32_16x16x32_bf16 v[100:103], v[174:177], v[190:193], v[100:103]
	v_mfma_f32_16x16x32_bf16 v[88:91], v[166:169], v[206:209], v[88:91]
	v_mfma_f32_16x16x32_bf16 v[84:87], v[174:177], v[206:209], v[84:87]
	v_mfma_f32_16x16x32_bf16 v[72:75], v[166:169], v[228:231], v[72:75]
	v_mfma_f32_16x16x32_bf16 v[68:71], v[174:177], v[228:231], v[68:71]
	v_mfma_f32_16x16x32_bf16 v[120:123], v[170:173], v[186:189], v[120:123]
	v_mfma_f32_16x16x32_bf16 v[116:119], v[178:181], v[186:189], v[116:119]
	v_mfma_f32_16x16x32_bf16 v[104:107], v[170:173], v[194:197], v[104:107]
	v_mfma_f32_16x16x32_bf16 v[100:103], v[178:181], v[194:197], v[100:103]
	v_mfma_f32_16x16x32_bf16 v[88:91], v[170:173], v[224:227], v[88:91]
	v_mfma_f32_16x16x32_bf16 v[84:87], v[178:181], v[224:227], v[84:87]
	v_mfma_f32_16x16x32_bf16 v[72:75], v[170:173], v[232:235], v[72:75]
	v_mfma_f32_16x16x32_bf16 v[68:71], v[178:181], v[232:235], v[68:71]
	s_setprio 0
	s_barrier
	s_add_u32 s100, s26, 0x80
	s_addc_u32 s101, s27, 0
	s_add_i32 s48, s70, s35
	s_mov_b32 m0, s48
	ds_read_b128 v[182:185], v164 offset:49152
	ds_read_b128 v[186:189], v164 offset:50176
	ds_read_b128 v[190:193], v164 offset:51200
	ds_read_b128 v[194:197], v164 offset:52224
	ds_read_b128 v[206:209], v164 offset:53248
	ds_read_b128 v[224:227], v164 offset:54272
	ds_read_b128 v[228:231], v164 offset:55296
	ds_read_b128 v[232:235], v164 offset:56320
	global_load_lds_dwordx4 v2, s[100:101]
	s_add_i32 m0, s48, 0x2000
	s_add_u32 s26, s26, 0x10080
	s_addc_u32 s27, s27, 0
	s_add_i32 s48, s71, s35
	global_load_lds_dwordx4 v148, s[100:101]
	s_mov_b32 m0, s48
	s_nop 0
	global_load_lds_dwordx4 v2, s[26:27]
	s_add_i32 m0, s48, 0x2000
	s_nop 0
	global_load_lds_dwordx4 v148, s[26:27]
	s_waitcnt vmcnt(6) lgkmcnt(0)
	s_barrier
	s_setprio 1
	v_mfma_f32_16x16x32_bf16 v[64:67], v[134:137], v[182:185], v[64:67]
	v_mfma_f32_16x16x32_bf16 v[60:63], v[142:145], v[182:185], v[60:63]
	v_mfma_f32_16x16x32_bf16 v[48:51], v[134:137], v[190:193], v[48:51]
	v_mfma_f32_16x16x32_bf16 v[44:47], v[142:145], v[190:193], v[44:47]
	v_mfma_f32_16x16x32_bf16 v[32:35], v[134:137], v[206:209], v[32:35]
	v_mfma_f32_16x16x32_bf16 v[28:31], v[142:145], v[206:209], v[28:31]
	v_mfma_f32_16x16x32_bf16 v[16:19], v[134:137], v[228:231], v[16:19]
	v_mfma_f32_16x16x32_bf16 v[12:15], v[142:145], v[228:231], v[12:15]
	v_mfma_f32_16x16x32_bf16 v[64:67], v[138:141], v[186:189], v[64:67]
	v_mfma_f32_16x16x32_bf16 v[60:63], v[158:161], v[186:189], v[60:63]
	v_mfma_f32_16x16x32_bf16 v[48:51], v[138:141], v[194:197], v[48:51]
	v_mfma_f32_16x16x32_bf16 v[44:47], v[158:161], v[194:197], v[44:47]
	v_mfma_f32_16x16x32_bf16 v[32:35], v[138:141], v[224:227], v[32:35]
	v_mfma_f32_16x16x32_bf16 v[28:31], v[158:161], v[224:227], v[28:31]
	v_mfma_f32_16x16x32_bf16 v[16:19], v[138:141], v[232:235], v[16:19]
	v_mfma_f32_16x16x32_bf16 v[12:15], v[158:161], v[232:235], v[12:15]
	s_setprio 0
	s_setprio 1
	v_mfma_f32_16x16x32_bf16 v[56:59], v[166:169], v[182:185], v[56:59]
	v_mfma_f32_16x16x32_bf16 v[52:55], v[174:177], v[182:185], v[52:55]
	v_mfma_f32_16x16x32_bf16 v[40:43], v[166:169], v[190:193], v[40:43]
	v_mfma_f32_16x16x32_bf16 v[36:39], v[174:177], v[190:193], v[36:39]
	v_mfma_f32_16x16x32_bf16 v[24:27], v[166:169], v[206:209], v[24:27]
	v_mfma_f32_16x16x32_bf16 v[20:23], v[174:177], v[206:209], v[20:23]
	v_mfma_f32_16x16x32_bf16 v[8:11], v[166:169], v[228:231], v[8:11]
	v_mfma_f32_16x16x32_bf16 v[4:7], v[174:177], v[228:231], v[4:7]
	v_mfma_f32_16x16x32_bf16 v[56:59], v[170:173], v[186:189], v[56:59]
	v_mfma_f32_16x16x32_bf16 v[52:55], v[178:181], v[186:189], v[52:55]
	v_mfma_f32_16x16x32_bf16 v[40:43], v[170:173], v[194:197], v[40:43]
	v_mfma_f32_16x16x32_bf16 v[36:39], v[178:181], v[194:197], v[36:39]
	v_mfma_f32_16x16x32_bf16 v[24:27], v[170:173], v[224:227], v[24:27]
	v_mfma_f32_16x16x32_bf16 v[20:23], v[178:181], v[224:227], v[20:23]
	v_mfma_f32_16x16x32_bf16 v[8:11], v[170:173], v[232:235], v[8:11]
	v_mfma_f32_16x16x32_bf16 v[4:7], v[178:181], v[232:235], v[4:7]
	s_setprio 0
	s_barrier
	s_add_u32 s40, s40, 0x100
	s_addc_u32 s41, s41, 0
	s_add_u32 s67, s67, 0x100
	s_addc_u32 s68, s68, 0
	s_cmp_ge_i32 s69, s54
	s_mov_b32 s48, s69
	s_cbranch_scc0 .LBB0_752

; #define PG8_STAGE(bufoff, gbase, voff) do { _Pragma("unroll") for (int _i = 0; _i < 2; ++_i) \
;         __builtin_amdgcn_global_load_lds((const unsigned*)((const char*)(gbase) + (voff)[_i]), (LAS unsigned*)(lds + (bufoff) + ldsw + _i * 8192), 16, 0, 0); } while (0)
; #define PG8_WAIT_V(n) asm volatile("s_waitcnt vmcnt(" #n ")" ::: "memory")
; #define PG8_BAR __builtin_amdgcn_s_barrier()
; template <class Epi, bool ALIGN_EPI = true>
; __device__ __forceinline__ void gemm_phase(LAS unsigned char* lds, const Gemm g, const Sched& S, const Epi& E) {
;     ...
;     for (int i = 0; i < 2; ++i) { int R, C; stage_rc(tid * 16 + i * 8192, R, C); const int Rb = (R & ~31) + perm32(R & 31);
;         voffA[i] = (unsigned)(R * g.lda + C) * 2u; voffB[i] = (unsigned)(Rb * g.ldb + C) * 2u; }
;     const size_t kstep = (size_t)(BK * 2);
;     const size_t hstepA = (size_t)HALF * g.lda * 2, hstepB = (size_t)HALF * g.ldb * 2;
;     const unsigned ldsw = (unsigned)wid * 1024u;
;     const int aoff = lds_byte(wr * 64 + fr, fq * 8), boff = lds_byte(wc * 32 + fr, fq * 8);
;     ...
;     PG8_STAGE(PG8_SB(0, 0), cB, voffB); PG8_STAGE(PG8_SB(0, 1), cB + hstepB, voffB); PG8_STAGE(PG8_SA(0, 0), cA, voffA); PG8_STAGE(PG8_SA(0, 1), cA + hstepA, voffA);
;     if (wr == 1) PG8_BAR;
;     PG8_WAIT_V(2); PG8_BAR;
;     PG8_STAGE(PG8_SB(1, 0), cB + kstep, voffB); PG8_STAGE(PG8_SA(1, 0), cA + kstep, voffA); PG8_STAGE(PG8_SB(1, 1), cB + hstepB + kstep, voffB);
;     PG8_WAIT_V(6); PG8_BAR;
.LBB0_907:
	v_readlane_b32 s52, v246, 10
	v_readlane_b32 s53, v246, 11
	v_readlane_b32 s54, v246, 12
	v_readlane_b32 s55, v246, 13
	v_readlane_b32 s56, v246, 14
	v_readlane_b32 s57, v246, 15
	s_add_u32 s50, s18, s4
	v_readlane_b32 s58, v246, 16
	v_readlane_b32 s59, v246, 17
	v_readlane_b32 s60, v246, 18
	v_readlane_b32 s61, v246, 19
	s_mov_b64 s[52:53], s[56:57]
	s_addc_u32 s51, s19, s5
	s_lshl_b64 s[4:5], s[94:95], 2
	s_mov_b64 s[54:55], s[58:59]
	s_mov_b64 s[56:57], s[60:61]
	s_add_u32 s4, s56, s4
	s_addc_u32 s5, s57, s5
	s_ashr_i32 s16, s6, 31
	s_lshr_b32 s16, s16, 26
	s_lshl_b32 s7, s7, 5
	s_add_i32 s16, s6, s16
	s_and_b32 s54, s7, 0x60
	s_add_i32 m0, s36, 0x18000
	v_lshl_add_u64 v[10:11], v[10:11], 0, s[8:9]
	s_ashr_i32 s52, s16, 6
	s_lshl_b32 s53, s15, 6
	s_lshl_b32 s15, s15, 13
	s_lshl_b32 s7, s54, 7
	s_waitcnt vmcnt(2)
	s_barrier
	global_load_lds_dwordx4 v[10:11], off
	v_lshl_add_u64 v[8:9], v[8:9], 0, s[8:9]
	s_add_i32 m0, s36, 0x1a000
	s_add_i32 s55, s36, 0x8000
	s_add_i32 s56, s36, 0xa000
	global_load_lds_dwordx4 v[8:9], off
	v_lshl_add_u64 v[4:5], v[4:5], 0, s[8:9]
	s_mov_b32 m0, s55
	s_add_u32 s16, s26, 0x10080
	global_load_lds_dwordx4 v[4:5], off
	v_lshl_add_u64 v[4:5], v[6:7], 0, s[8:9]
	s_mov_b32 m0, s56
	s_addc_u32 s17, s27, 0
	global_load_lds_dwordx4 v[4:5], off
	s_add_i32 m0, s36, 0x1c000
	v_lshl_add_u64 v[4:5], s[16:17], 0, v[2:3]
	global_load_lds_dwordx4 v[4:5], off
	v_lshl_add_u64 v[4:5], s[16:17], 0, v[148:149]
	s_add_i32 m0, s36, 0x1e000
	v_and_b32_e32 v162, 63, v18
	global_load_lds_dwordx4 v[4:5], off
	v_lshlrev_b32_e32 v4, 14, v16
	v_and_b32_e32 v4, 0xffff8000, v4
	v_lshl_add_u32 v4, v15, 11, v4
	v_and_b32_e32 v5, 1, v16
	v_lshl_or_b32 v4, v5, 6, v4
	v_and_b32_e32 v19, 48, v18
	v_lshlrev_b32_e32 v20, 6, v18
	s_movk_i32 s10, 0x3c0
	v_lshlrev_b32_e32 v18, 2, v18
	v_lshl_add_u32 v154, v17, 1, v4
	v_lshlrev_b32_e32 v4, 14, v12
	v_and_or_b32 v19, v20, s10, v19
	v_and_b32_e32 v18, 32, v18
	s_cmp_gt_i32 s6, 63
	v_and_b32_e32 v4, 0xffff8000, v4
	v_readlane_b32 s16, v243, 16
	v_bitop3_b32 v163, s7, v19, v18 bitop3:0xf6
	v_add_u32_e32 v163, 0x10000, v163
	s_waitcnt vmcnt(6)
	s_cselect_b64 s[6:7], -1, 0
	s_add_i32 s57, s52, -2
	v_lshl_add_u32 v4, v13, 11, v4
	v_and_b32_e32 v5, 1, v12
	v_readlane_b32 s17, v243, 17
	v_bitop3_b32 v20, v19, s15, v18 bitop3:0xde
	s_cmpk_lt_u32 s14, 0x100
	v_lshl_or_b32 v4, v5, 6, v4
	s_mov_b32 s60, s16
	v_readlane_b32 s16, v243, 12
	s_cselect_b64 s[14:15], -1, 0
	v_mov_b32_e32 v155, v3
	v_lshl_add_u32 v156, v14, 1, v4
	v_mov_b32_e32 v157, v3
	s_mov_b32 s47, 0
	v_add_u32_e32 v164, 0, v20
	s_mov_b32 s59, s16
	v_readlane_b32 s62, v246, 20
	v_readlane_b32 s63, v246, 21
	v_readlane_b32 s64, v246, 22
	v_readlane_b32 s65, v246, 23
	v_readlane_b32 s66, v246, 24
	v_readlane_b32 s67, v246, 25
	s_barrier
	v_readlane_b32 s17, v243, 13
	s_branch .LBB0_910

; #define PG8_STAGE(bufoff, gbase, voff) do { _Pragma("unroll") for (int _i = 0; _i < 2; ++_i) \
;         __builtin_amdgcn_global_load_lds((const unsigned*)((const char*)(gbase) + (voff)[_i]), (LAS unsigned*)(lds + (bufoff) + ldsw + _i * 8192), 16, 0, 0); } while (0)
; #define PG8_LDA(dst, b, h) do { _Pragma("unroll") for (int m = 0; m < 4; ++m) _Pragma("unroll") for (int k = 0; k < 2; ++k) dst[m][k] = *(const LAS bf16x8*)(lds + PG8_SA(b, h) + aoff + m * 2048 + k * 1024); } while (0)
; #define PG8_LDB(dst, b, h) do { _Pragma("unroll") for (int n = 0; n < 2; ++n) _Pragma("unroll") for (int k = 0; k < 2; ++k) dst[n][k] = *(const LAS bf16x8*)(lds + PG8_SB(b, h) + boff + n * 2048 + k * 1024); } while (0)
; #define PG8_MMA(ai, bj, At, Bt) do { __builtin_amdgcn_s_setprio(1); _Pragma("unroll") for (int m = 0; m < 4; ++m) _Pragma("unroll") for (int n = 0; n < 2; ++n) _Pragma("unroll") for (int k = 0; k < 2; ++k) \
;         acc[ai][bj][m][n] = __builtin_amdgcn_mfma_f32_16x16x32_bf16(Bt[n][k], At[m][k], acc[ai][bj][m][n], 0, 0, 0); __builtin_amdgcn_s_setprio(0); } while (0)
; #define PG8_WAIT_V(n) asm volatile("s_waitcnt vmcnt(" #n ")" ::: "memory")
; #define PG8_WAIT_L(n) asm volatile("s_waitcnt lgkmcnt(" #n ")" ::: "memory")
; #define PG8_BAR __builtin_amdgcn_s_barrier()
; template <class Epi, bool ALIGN_EPI = true>
; __device__ __forceinline__ void gemm_phase(LAS unsigned char* lds, const Gemm g, const Sched& S, const Epi& E) {
;     ...
;         for (int t = t_lo; t < t_hi; t += 2) {
;             const bool last = (t == nt - 2);
;             const char* a1 = cA + (size_t)(t + 1) * kstep;
;             const char* a2 = last ? nA : cA + (size_t)(t + 2) * kstep; const char* b2 = last ? nB : cB + (size_t)(t + 2) * kstep;
;             const char* a3 = a2 + kstep; const char* b3 = b2 + kstep;
;             const int rflag = __builtin_amdgcn_readfirstlane(t | (int)(ui == 0));
;             PG8_LDB(B0, 0, 0); PG8_LDB(B1, 0, 1); PG8_SCHED; PG8_LDA(At, 0, 0); PG8_STAGE(PG8_SA(1, 1), a1 + hstepA, voffA);
;             if constexpr (Epi::NSTORES > 0) PG8_WAIT_RELAX(rflag, 8 + Epi::NSTORES); else PG8_WAIT_V(8);
;             PG8_WAIT_L(0); PG8_BAR; PG8_MMA(0, 0, At, B0); PG8_MMA(0, 1, At, B1); PG8_BAR; PG8_SCHED;
;             PG8_LDA(At, 0, 1); PG8_STAGE(PG8_SB(0, 0), b2, voffB); PG8_STAGE(PG8_SB(0, 1), b2 + hstepB, voffB); PG8_STAGE(PG8_SA(0, 0), a2, voffA);
.LBB0_919:
	s_add_i32 s65, s46, 2
	s_add_u32 s26, s40, 0xfffc0080
	s_addc_u32 s27, s41, -1
	s_add_i32 s66, 0, 0x10000
	s_cmp_eq_u32 s57, s46
	v_add_u32_e32 v133, s46, v132
	s_cselect_b32 s47, s17, s27
	s_cselect_b32 s46, s19, s26
	s_cselect_b32 s27, s61, s64
	s_cselect_b32 s26, s62, s63
	s_add_i32 s68, 0, 0x14000
	ds_read_b128 v[134:137], v163
	ds_read_b128 v[138:141], v163 offset:1024
	ds_read_b128 v[142:145], v163 offset:2048
	ds_read_b128 v[158:161], v163 offset:3072
	ds_read_b128 v[166:169], v163 offset:16384
	ds_read_b128 v[170:173], v163 offset:17408
	ds_read_b128 v[174:177], v163 offset:18432
	ds_read_b128 v[178:181], v163 offset:19456
	ds_read_b128 v[182:185], v164
	ds_read_b128 v[186:189], v164 offset:1024
	ds_read_b128 v[190:193], v164 offset:2048
	ds_read_b128 v[194:197], v164 offset:3072
	ds_read_b128 v[206:209], v164 offset:4096
	ds_read_b128 v[224:227], v164 offset:5120
	ds_read_b128 v[228:231], v164 offset:6144
	ds_read_b128 v[232:235], v164 offset:7168
	s_mov_b32 m0, s55
	s_add_u32 s100, s40, 0xfffc0000
	s_addc_u32 s101, s41, -1
	global_load_lds_dwordx4 v154, s[100:101]
	s_mov_b32 m0, s56
	s_nop 0
	global_load_lds_dwordx4 v156, s[100:101]
	s_add_i32 m0, s36, 0xc000
	s_nop 0
	global_load_lds_dwordx4 v154, s[40:41]
	s_add_i32 m0, s36, 0xe000
	v_readfirstlane_b32 s69, v133
	global_load_lds_dwordx4 v156, s[40:41]
	s_cmp_eq_u32 s69, 0
	s_cbranch_scc1 .Lrw10
	s_waitcnt vmcnt(8)
.Lrw10:
	s_waitcnt vmcnt(24) lgkmcnt(0)
	s_barrier
	s_setprio 1
	v_mfma_f32_16x16x32_bf16 v[128:131], v[134:137], v[182:185], v[128:131]
	v_mfma_f32_16x16x32_bf16 v[124:127], v[142:145], v[182:185], v[124:127]
	v_mfma_f32_16x16x32_bf16 v[112:115], v[134:137], v[190:193], v[112:115]
	v_mfma_f32_16x16x32_bf16 v[108:111], v[142:145], v[190:193], v[108:111]
	v_mfma_f32_16x16x32_bf16 v[96:99], v[134:137], v[206:209], v[96:99]
	v_mfma_f32_16x16x32_bf16 v[92:95], v[142:145], v[206:209], v[92:95]
	v_mfma_f32_16x16x32_bf16 v[80:83], v[134:137], v[228:231], v[80:83]
	v_mfma_f32_16x16x32_bf16 v[76:79], v[142:145], v[228:231], v[76:79]
	v_mfma_f32_16x16x32_bf16 v[128:131], v[138:141], v[186:189], v[128:131]
	v_mfma_f32_16x16x32_bf16 v[124:127], v[158:161], v[186:189], v[124:127]
	v_mfma_f32_16x16x32_bf16 v[112:115], v[138:141], v[194:197], v[112:115]
	v_mfma_f32_16x16x32_bf16 v[108:111], v[158:161], v[194:197], v[108:111]
	v_mfma_f32_16x16x32_bf16 v[96:99], v[138:141], v[224:227], v[96:99]
	v_mfma_f32_16x16x32_bf16 v[92:95], v[158:161], v[224:227], v[92:95]
	v_mfma_f32_16x16x32_bf16 v[80:83], v[138:141], v[232:235], v[80:83]
	v_mfma_f32_16x16x32_bf16 v[76:79], v[158:161], v[232:235], v[76:79]
	s_setprio 0
	s_setprio 1
	v_mfma_f32_16x16x32_bf16 v[120:123], v[166:169], v[182:185], v[120:123]
	v_mfma_f32_16x16x32_bf16 v[116:119], v[174:177], v[182:185], v[116:119]
	v_mfma_f32_16x16x32_bf16 v[104:107], v[166:169], v[190:193], v[104:107]
	v_mfma_f32_16x16x32_bf16 v[100:103], v[174:177], v[190:193], v[100:103]
	v_mfma_f32_16x16x32_bf16 v[88:91], v[166:169], v[206:209], v[88:91]
	v_mfma_f32_16x16x32_bf16 v[84:87], v[174:177], v[206:209], v[84:87]
	v_mfma_f32_16x16x32_bf16 v[72:75], v[166:169], v[228:231], v[72:75]
	v_mfma_f32_16x16x32_bf16 v[68:71], v[174:177], v[228:231], v[68:71]
	v_mfma_f32_16x16x32_bf16 v[120:123], v[170:173], v[186:189], v[120:123]
	v_mfma_f32_16x16x32_bf16 v[116:119], v[178:181], v[186:189], v[116:119]
	v_mfma_f32_16x16x32_bf16 v[104:107], v[170:173], v[194:197], v[104:107]
	v_mfma_f32_16x16x32_bf16 v[100:103], v[178:181], v[194:197], v[100:103]
	v_mfma_f32_16x16x32_bf16 v[88:91], v[170:173], v[224:227], v[88:91]
	v_mfma_f32_16x16x32_bf16 v[84:87], v[178:181], v[224:227], v[84:87]
	v_mfma_f32_16x16x32_bf16 v[72:75], v[170:173], v[232:235], v[72:75]
	v_mfma_f32_16x16x32_bf16 v[68:71], v[178:181], v[232:235], v[68:71]
	s_setprio 0
	s_barrier
	s_add_i32 s66, s66, s35
	s_mov_b32 m0, s66
	ds_read_b128 v[182:185], v164 offset:16384
	ds_read_b128 v[186:189], v164 offset:17408
	ds_read_b128 v[190:193], v164 offset:18432
	ds_read_b128 v[194:197], v164 offset:19456
	ds_read_b128 v[206:209], v164 offset:20480
	ds_read_b128 v[224:227], v164 offset:21504
	ds_read_b128 v[228:231], v164 offset:22528
	ds_read_b128 v[232:235], v164 offset:23552
	global_load_lds_dwordx4 v2, s[26:27]
	s_add_i32 m0, s66, 0x2000
	s_add_u32 s66, s26, 0x10000
	s_addc_u32 s67, s27, 0
	s_add_i32 s68, s68, s35
	global_load_lds_dwordx4 v148, s[26:27]
	s_mov_b32 m0, s68
	s_nop 0
	global_load_lds_dwordx4 v2, s[66:67]
	s_add_i32 m0, s68, 0x2000
	s_nop 0
	global_load_lds_dwordx4 v148, s[66:67]
; #define PG8_STAGE(bufoff, gbase, voff) do { _Pragma("unroll") for (int _i = 0; _i < 2; ++_i) \
;         __builtin_amdgcn_global_load_lds((const unsigned*)((const char*)(gbase) + (voff)[_i]), (LAS unsigned*)(lds + (bufoff) + ldsw + _i * 8192), 16, 0, 0); } while (0)
; #define PG8_LDA(dst, b, h) do { _Pragma("unroll") for (int m = 0; m < 4; ++m) _Pragma("unroll") for (int k = 0; k < 2; ++k) dst[m][k] = *(const LAS bf16x8*)(lds + PG8_SA(b, h) + aoff + m * 2048 + k * 1024); } while (0)
; #define PG8_LDB(dst, b, h) do { _Pragma("unroll") for (int n = 0; n < 2; ++n) _Pragma("unroll") for (int k = 0; k < 2; ++k) dst[n][k] = *(const LAS bf16x8*)(lds + PG8_SB(b, h) + boff + n * 2048 + k * 1024); } while (0)
; #define PG8_MMA(ai, bj, At, Bt) do { __builtin_amdgcn_s_setprio(1); _Pragma("unroll") for (int m = 0; m < 4; ++m) _Pragma("unroll") for (int n = 0; n < 2; ++n) _Pragma("unroll") for (int k = 0; k < 2; ++k) \
;         acc[ai][bj][m][n] = __builtin_amdgcn_mfma_f32_16x16x32_bf16(Bt[n][k], At[m][k], acc[ai][bj][m][n], 0, 0, 0); __builtin_amdgcn_s_setprio(0); } while (0)
; #define PG8_WAIT_V(n) asm volatile("s_waitcnt vmcnt(" #n ")" ::: "memory")
; #define PG8_WAIT_L(n) asm volatile("s_waitcnt lgkmcnt(" #n ")" ::: "memory")
; #define PG8_BAR __builtin_amdgcn_s_barrier()
; #define PG8_WAIT_RELAX(flag, n) asm volatile("s_cmp_eq_u32 %0, 0\n\ts_cbranch_scc1 .Lrw%=\n\ts_waitcnt vmcnt(8)\n.Lrw%=:\n\ts_waitcnt vmcnt(%1)" :: "s"(flag), "n"(n) : "scc", "memory")
; #define PG8_SCHED __builtin_amdgcn_sched_barrier(0)
; template <class Epi, bool ALIGN_EPI = true>
; __device__ __forceinline__ void gemm_phase(LAS unsigned char* lds, const Gemm g, const Sched& S, const Epi& E) {
;     ...
;             if constexpr (Epi::NSTORES > 0) PG8_WAIT_RELAX(rflag, 8 + Epi::NSTORES); else PG8_WAIT_V(8);
;             PG8_WAIT_L(0); PG8_BAR; PG8_MMA(1, 0, At, B0); PG8_MMA(1, 1, At, B1); PG8_BAR; PG8_SCHED;
;             PG8_LDB(B0, 1, 0); PG8_LDB(B1, 1, 1); PG8_SCHED; PG8_LDA(At, 1, 0); PG8_STAGE(PG8_SA(0, 1), a2 + hstepA, voffA);
;             PG8_WAIT_V(8); PG8_WAIT_L(0); PG8_BAR; PG8_MMA(0, 0, At, B0); PG8_MMA(0, 1, At, B1); PG8_BAR; PG8_SCHED;
.Lrw11:
	s_waitcnt vmcnt(6) lgkmcnt(0)
	s_barrier
	s_setprio 1
	v_mfma_f32_16x16x32_bf16 v[64:67], v[134:137], v[182:185], v[64:67]
	v_mfma_f32_16x16x32_bf16 v[60:63], v[142:145], v[182:185], v[60:63]
	v_mfma_f32_16x16x32_bf16 v[48:51], v[134:137], v[190:193], v[48:51]
	v_mfma_f32_16x16x32_bf16 v[44:47], v[142:145], v[190:193], v[44:47]
	v_mfma_f32_16x16x32_bf16 v[32:35], v[134:137], v[206:209], v[32:35]
	v_mfma_f32_16x16x32_bf16 v[28:31], v[142:145], v[206:209], v[28:31]
	v_mfma_f32_16x16x32_bf16 v[16:19], v[134:137], v[228:231], v[16:19]
	v_mfma_f32_16x16x32_bf16 v[12:15], v[142:145], v[228:231], v[12:15]
	v_mfma_f32_16x16x32_bf16 v[64:67], v[138:141], v[186:189], v[64:67]
	v_mfma_f32_16x16x32_bf16 v[60:63], v[158:161], v[186:189], v[60:63]
	v_mfma_f32_16x16x32_bf16 v[48:51], v[138:141], v[194:197], v[48:51]
	v_mfma_f32_16x16x32_bf16 v[44:47], v[158:161], v[194:197], v[44:47]
	v_mfma_f32_16x16x32_bf16 v[32:35], v[138:141], v[224:227], v[32:35]
	v_mfma_f32_16x16x32_bf16 v[28:31], v[158:161], v[224:227], v[28:31]
	v_mfma_f32_16x16x32_bf16 v[16:19], v[138:141], v[232:235], v[16:19]
	v_mfma_f32_16x16x32_bf16 v[12:15], v[158:161], v[232:235], v[12:15]
	s_setprio 0
	s_setprio 1
	v_mfma_f32_16x16x32_bf16 v[56:59], v[166:169], v[182:185], v[56:59]
	v_mfma_f32_16x16x32_bf16 v[52:55], v[174:177], v[182:185], v[52:55]
	v_mfma_f32_16x16x32_bf16 v[40:43], v[166:169], v[190:193], v[40:43]
	v_mfma_f32_16x16x32_bf16 v[36:39], v[174:177], v[190:193], v[36:39]
	v_mfma_f32_16x16x32_bf16 v[24:27], v[166:169], v[206:209], v[24:27]
	v_mfma_f32_16x16x32_bf16 v[20:23], v[174:177], v[206:209], v[20:23]
	v_mfma_f32_16x16x32_bf16 v[8:11], v[166:169], v[228:231], v[8:11]
	v_mfma_f32_16x16x32_bf16 v[4:7], v[174:177], v[228:231], v[4:7]
	v_mfma_f32_16x16x32_bf16 v[56:59], v[170:173], v[186:189], v[56:59]
	v_mfma_f32_16x16x32_bf16 v[52:55], v[178:181], v[186:189], v[52:55]
	v_mfma_f32_16x16x32_bf16 v[40:43], v[170:173], v[194:197], v[40:43]
	v_mfma_f32_16x16x32_bf16 v[36:39], v[178:181], v[194:197], v[36:39]
	v_mfma_f32_16x16x32_bf16 v[24:27], v[170:173], v[224:227], v[24:27]
	v_mfma_f32_16x16x32_bf16 v[20:23], v[178:181], v[224:227], v[20:23]
	v_mfma_f32_16x16x32_bf16 v[8:11], v[170:173], v[232:235], v[8:11]
	v_mfma_f32_16x16x32_bf16 v[4:7], v[178:181], v[232:235], v[4:7]
	s_setprio 0
	s_barrier
	s_add_i32 s66, 0, 0x18000
	s_add_i32 s67, 0, 0x1c000
	ds_read_b128 v[134:137], v163 offset:32768
	ds_read_b128 v[138:141], v163 offset:33792
	ds_read_b128 v[142:145], v163 offset:34816
	ds_read_b128 v[158:161], v163 offset:35840
	ds_read_b128 v[166:169], v163 offset:49152
	ds_read_b128 v[170:173], v163 offset:50176
	ds_read_b128 v[174:177], v163 offset:51200
	ds_read_b128 v[178:181], v163 offset:52224
	s_add_u32 s46, s46, 0x40000
	s_addc_u32 s47, s47, 0
	ds_read_b128 v[182:185], v164 offset:32768
	ds_read_b128 v[186:189], v164 offset:33792
	ds_read_b128 v[190:193], v164 offset:34816
	ds_read_b128 v[194:197], v164 offset:35840
	ds_read_b128 v[206:209], v164 offset:36864
	ds_read_b128 v[224:227], v164 offset:37888
	ds_read_b128 v[228:231], v164 offset:38912
	ds_read_b128 v[232:235], v164 offset:39936
	s_mov_b32 m0, s36
	s_add_u32 s100, s46, 0xfffc0000
	s_addc_u32 s101, s47, -1
	global_load_lds_dwordx4 v152, s[100:101]
	s_mov_b32 m0, s37
	s_nop 0
	global_load_lds_dwordx4 v150, s[100:101]
	s_mov_b32 m0, s48
	s_nop 0
	global_load_lds_dwordx4 v152, s[46:47]
	s_mov_b32 m0, s49
	s_nop 0
	global_load_lds_dwordx4 v150, s[46:47]
	s_waitcnt vmcnt(8) lgkmcnt(0)
	s_barrier
; #define PG8_STAGE(bufoff, gbase, voff) do { _Pragma("unroll") for (int _i = 0; _i < 2; ++_i) \
;         __builtin_amdgcn_global_load_lds((const unsigned*)((const char*)(gbase) + (voff)[_i]), (LAS unsigned*)(lds + (bufoff) + ldsw + _i * 8192), 16, 0, 0); } while (0)
; #define PG8_LDA(dst, b, h) do { _Pragma("unroll") for (int m = 0; m < 4; ++m) _Pragma("unroll") for (int k = 0; k < 2; ++k) dst[m][k] = *(const LAS bf16x8*)(lds + PG8_SA(b, h) + aoff + m * 2048 + k * 1024); } while (0)
; #define PG8_MMA(ai, bj, At, Bt) do { __builtin_amdgcn_s_setprio(1); _Pragma("unroll") for (int m = 0; m < 4; ++m) _Pragma("unroll") for (int n = 0; n < 2; ++n) _Pragma("unroll") for (int k = 0; k < 2; ++k) \
;         acc[ai][bj][m][n] = __builtin_amdgcn_mfma_f32_16x16x32_bf16(Bt[n][k], At[m][k], acc[ai][bj][m][n], 0, 0, 0); __builtin_amdgcn_s_setprio(0); } while (0)
; #define PG8_WAIT_V(n) asm volatile("s_waitcnt vmcnt(" #n ")" ::: "memory")
; #define PG8_WAIT_L(n) asm volatile("s_waitcnt lgkmcnt(" #n ")" ::: "memory")
; #define PG8_BAR __builtin_amdgcn_s_barrier()
; #define PG8_SCHED __builtin_amdgcn_sched_barrier(0)
; template <class Epi, bool ALIGN_EPI = true>
; __device__ __forceinline__ void gemm_phase(LAS unsigned char* lds, const Gemm g, const Sched& S, const Epi& E) {
;     ...
;             PG8_WAIT_V(8); PG8_WAIT_L(0); PG8_BAR; PG8_MMA(0, 0, At, B0); PG8_MMA(0, 1, At, B1); PG8_BAR; PG8_SCHED;
;             PG8_LDA(At, 1, 1); PG8_STAGE(PG8_SB(1, 0), b3, voffB); PG8_STAGE(PG8_SB(1, 1), b3 + hstepB, voffB); PG8_STAGE(PG8_SA(1, 0), a3, voffA);
;             PG8_WAIT_V(8); PG8_WAIT_L(0); PG8_BAR; PG8_MMA(1, 0, At, B0); PG8_MMA(1, 1, At, B1); PG8_BAR; PG8_SCHED;
;         }
	s_setprio 1
	v_mfma_f32_16x16x32_bf16 v[128:131], v[134:137], v[182:185], v[128:131]
	v_mfma_f32_16x16x32_bf16 v[124:127], v[142:145], v[182:185], v[124:127]
	v_mfma_f32_16x16x32_bf16 v[112:115], v[134:137], v[190:193], v[112:115]
	v_mfma_f32_16x16x32_bf16 v[108:111], v[142:145], v[190:193], v[108:111]
	v_mfma_f32_16x16x32_bf16 v[96:99], v[134:137], v[206:209], v[96:99]
	v_mfma_f32_16x16x32_bf16 v[92:95], v[142:145], v[206:209], v[92:95]
	v_mfma_f32_16x16x32_bf16 v[80:83], v[134:137], v[228:231], v[80:83]
	v_mfma_f32_16x16x32_bf16 v[76:79], v[142:145], v[228:231], v[76:79]
	v_mfma_f32_16x16x32_bf16 v[128:131], v[138:141], v[186:189], v[128:131]
	v_mfma_f32_16x16x32_bf16 v[124:127], v[158:161], v[186:189], v[124:127]
	v_mfma_f32_16x16x32_bf16 v[112:115], v[138:141], v[194:197], v[112:115]
	v_mfma_f32_16x16x32_bf16 v[108:111], v[158:161], v[194:197], v[108:111]
	v_mfma_f32_16x16x32_bf16 v[96:99], v[138:141], v[224:227], v[96:99]
	v_mfma_f32_16x16x32_bf16 v[92:95], v[158:161], v[224:227], v[92:95]
	v_mfma_f32_16x16x32_bf16 v[80:83], v[138:141], v[232:235], v[80:83]
	v_mfma_f32_16x16x32_bf16 v[76:79], v[158:161], v[232:235], v[76:79]
	s_setprio 0
	s_setprio 1
	v_mfma_f32_16x16x32_bf16 v[120:123], v[166:169], v[182:185], v[120:123]
	v_mfma_f32_16x16x32_bf16 v[116:119], v[174:177], v[182:185], v[116:119]
	v_mfma_f32_16x16x32_bf16 v[104:107], v[166:169], v[190:193], v[104:107]
	v_mfma_f32_16x16x32_bf16 v[100:103], v[174:177], v[190:193], v[100:103]
	v_mfma_f32_16x16x32_bf16 v[88:91], v[166:169], v[206:209], v[88:91]
	v_mfma_f32_16x16x32_bf16 v[84:87], v[174:177], v[206:209], v[84:87]
	v_mfma_f32_16x16x32_bf16 v[72:75], v[166:169], v[228:231], v[72:75]
	v_mfma_f32_16x16x32_bf16 v[68:71], v[174:177], v[228:231], v[68:71]
	v_mfma_f32_16x16x32_bf16 v[120:123], v[170:173], v[186:189], v[120:123]
	v_mfma_f32_16x16x32_bf16 v[116:119], v[178:181], v[186:189], v[116:119]
	v_mfma_f32_16x16x32_bf16 v[104:107], v[170:173], v[194:197], v[104:107]
	v_mfma_f32_16x16x32_bf16 v[100:103], v[178:181], v[194:197], v[100:103]
	v_mfma_f32_16x16x32_bf16 v[88:91], v[170:173], v[224:227], v[88:91]
	v_mfma_f32_16x16x32_bf16 v[84:87], v[178:181], v[224:227], v[84:87]
	v_mfma_f32_16x16x32_bf16 v[72:75], v[170:173], v[232:235], v[72:75]
	v_mfma_f32_16x16x32_bf16 v[68:71], v[178:181], v[232:235], v[68:71]
	s_setprio 0
	s_barrier
	s_add_u32 s100, s26, 0x80
	s_addc_u32 s101, s27, 0
	s_add_i32 s46, s66, s35
	s_mov_b32 m0, s46
	ds_read_b128 v[182:185], v164 offset:49152
	ds_read_b128 v[186:189], v164 offset:50176
	ds_read_b128 v[190:193], v164 offset:51200
	ds_read_b128 v[194:197], v164 offset:52224
	ds_read_b128 v[206:209], v164 offset:53248
	ds_read_b128 v[224:227], v164 offset:54272
	ds_read_b128 v[228:231], v164 offset:55296
	ds_read_b128 v[232:235], v164 offset:56320
	global_load_lds_dwordx4 v2, s[100:101]
	s_add_i32 m0, s46, 0x2000
	s_add_u32 s26, s26, 0x10080
	s_addc_u32 s27, s27, 0
	s_add_i32 s46, s67, s35
	global_load_lds_dwordx4 v148, s[100:101]
	s_mov_b32 m0, s46
	s_nop 0
	global_load_lds_dwordx4 v2, s[26:27]
	s_add_i32 m0, s46, 0x2000
	s_nop 0
	global_load_lds_dwordx4 v148, s[26:27]
	s_waitcnt vmcnt(6) lgkmcnt(0)
	s_barrier
	s_setprio 1
	v_mfma_f32_16x16x32_bf16 v[64:67], v[134:137], v[182:185], v[64:67]
	v_mfma_f32_16x16x32_bf16 v[60:63], v[142:145], v[182:185], v[60:63]
	v_mfma_f32_16x16x32_bf16 v[48:51], v[134:137], v[190:193], v[48:51]
	v_mfma_f32_16x16x32_bf16 v[44:47], v[142:145], v[190:193], v[44:47]
	v_mfma_f32_16x16x32_bf16 v[32:35], v[134:137], v[206:209], v[32:35]
	v_mfma_f32_16x16x32_bf16 v[28:31], v[142:145], v[206:209], v[28:31]
	v_mfma_f32_16x16x32_bf16 v[16:19], v[134:137], v[228:231], v[16:19]
	v_mfma_f32_16x16x32_bf16 v[12:15], v[142:145], v[228:231], v[12:15]
	v_mfma_f32_16x16x32_bf16 v[64:67], v[138:141], v[186:189], v[64:67]
	v_mfma_f32_16x16x32_bf16 v[60:63], v[158:161], v[186:189], v[60:63]
	v_mfma_f32_16x16x32_bf16 v[48:51], v[138:141], v[194:197], v[48:51]
	v_mfma_f32_16x16x32_bf16 v[44:47], v[158:161], v[194:197], v[44:47]
	v_mfma_f32_16x16x32_bf16 v[32:35], v[138:141], v[224:227], v[32:35]
	v_mfma_f32_16x16x32_bf16 v[28:31], v[158:161], v[224:227], v[28:31]
	v_mfma_f32_16x16x32_bf16 v[16:19], v[138:141], v[232:235], v[16:19]
	v_mfma_f32_16x16x32_bf16 v[12:15], v[158:161], v[232:235], v[12:15]
	s_setprio 0
	s_setprio 1
	v_mfma_f32_16x16x32_bf16 v[56:59], v[166:169], v[182:185], v[56:59]
	v_mfma_f32_16x16x32_bf16 v[52:55], v[174:177], v[182:185], v[52:55]
	v_mfma_f32_16x16x32_bf16 v[40:43], v[166:169], v[190:193], v[40:43]
	v_mfma_f32_16x16x32_bf16 v[36:39], v[174:177], v[190:193], v[36:39]
	v_mfma_f32_16x16x32_bf16 v[24:27], v[166:169], v[206:209], v[24:27]
	v_mfma_f32_16x16x32_bf16 v[20:23], v[174:177], v[206:209], v[20:23]
	v_mfma_f32_16x16x32_bf16 v[8:11], v[166:169], v[228:231], v[8:11]
	v_mfma_f32_16x16x32_bf16 v[4:7], v[174:177], v[228:231], v[4:7]
	v_mfma_f32_16x16x32_bf16 v[56:59], v[170:173], v[186:189], v[56:59]
	v_mfma_f32_16x16x32_bf16 v[52:55], v[178:181], v[186:189], v[52:55]
	v_mfma_f32_16x16x32_bf16 v[40:43], v[170:173], v[194:197], v[40:43]
	v_mfma_f32_16x16x32_bf16 v[36:39], v[178:181], v[194:197], v[36:39]
	v_mfma_f32_16x16x32_bf16 v[24:27], v[170:173], v[224:227], v[24:27]
	v_mfma_f32_16x16x32_bf16 v[20:23], v[178:181], v[224:227], v[20:23]
	v_mfma_f32_16x16x32_bf16 v[8:11], v[170:173], v[232:235], v[8:11]
	v_mfma_f32_16x16x32_bf16 v[4:7], v[178:181], v[232:235], v[4:7]
	s_setprio 0
	s_barrier
	s_add_u32 s40, s40, 0x100
	s_addc_u32 s41, s41, 0
	s_add_u32 s63, s63, 0x100
	s_addc_u32 s64, s64, 0
	s_cmp_ge_i32 s65, s52
	s_mov_b32 s46, s65
	s_cbranch_scc0 .LBB0_919

; #define PG8_STAGE(bufoff, gbase, voff) do { _Pragma("unroll") for (int _i = 0; _i < 2; ++_i) \
;         __builtin_amdgcn_global_load_lds((const unsigned*)((const char*)(gbase) + (voff)[_i]), (LAS unsigned*)(lds + (bufoff) + ldsw + _i * 8192), 16, 0, 0); } while (0)
; #define PG8_WAIT_V(n) asm volatile("s_waitcnt vmcnt(" #n ")" ::: "memory")
; #define PG8_BAR __builtin_amdgcn_s_barrier()
; template <class Epi, bool ALIGN_EPI = true>
; __device__ __forceinline__ void gemm_phase(LAS unsigned char* lds, const Gemm g, const Sched& S, const Epi& E) {
;     ...
;     for (int i = 0; i < 2; ++i) { int R, C; stage_rc(tid * 16 + i * 8192, R, C); const int Rb = (R & ~31) + perm32(R & 31);
;         voffA[i] = (unsigned)(R * g.lda + C) * 2u; voffB[i] = (unsigned)(Rb * g.ldb + C) * 2u; }
;     const size_t kstep = (size_t)(BK * 2);
;     const size_t hstepA = (size_t)HALF * g.lda * 2, hstepB = (size_t)HALF * g.ldb * 2;
;     const unsigned ldsw = (unsigned)wid * 1024u;
;     const int aoff = lds_byte(wr * 64 + fr, fq * 8), boff = lds_byte(wc * 32 + fr, fq * 8);
;     ...
;     f32x4 acc[2][2][4][2];
; #pragma unroll
;     for (int a = 0; a < 2; ++a)
; #pragma unroll
;         for (int b = 0; b < 2; ++b)
; #pragma unroll
;             for (int m = 0; m < 4; ++m)
; #pragma unroll
;                 for (int n = 0; n < 2; ++n) acc[a][b][m][n] = (f32x4){0.f, 0.f, 0.f, 0.f};
;     bf16x8 At[4][2], B0[2][2], B1[2][2];
;     const char* cA = (const char*)g.A + cur.aoff; const char* cB = (const char*)g.Bt + cur.boff;
;     PG8_STAGE(PG8_SB(0, 0), cB, voffB); PG8_STAGE(PG8_SB(0, 1), cB + hstepB, voffB); PG8_STAGE(PG8_SA(0, 0), cA, voffA); PG8_STAGE(PG8_SA(0, 1), cA + hstepA, voffA);
;     if (wr == 1) PG8_BAR;
;     PG8_WAIT_V(2); PG8_BAR;
;     PG8_STAGE(PG8_SB(1, 0), cB + kstep, voffB); PG8_STAGE(PG8_SA(1, 0), cA + kstep, voffA); PG8_STAGE(PG8_SB(1, 1), cB + hstepB + kstep, voffB);
;     PG8_WAIT_V(6); PG8_BAR;
.LBB0_946:
	v_readlane_b32 s36, v246, 42
	v_readlane_b32 s38, v246, 44
	v_readlane_b32 s39, v246, 45
	s_add_u32 s52, s38, s44
	s_addc_u32 s53, s39, s45
	s_add_u32 s24, s38, s24
	s_addc_u32 s25, s39, s25
	v_readlane_b32 s37, v246, 43
	s_add_u32 s36, s38, s20
	s_addc_u32 s37, s39, s21
	s_add_u32 s20, s38, s22
	s_addc_u32 s21, s39, s23
	s_add_u32 s18, s38, s18
	s_addc_u32 s19, s39, s19
	s_add_u32 s16, s38, s16
	s_addc_u32 s17, s39, s17
	s_add_u32 s6, s38, s6
	s_addc_u32 s7, s39, s7
	s_add_u32 s54, s38, s4
	s_addc_u32 s44, s39, s5
	s_add_u32 s4, s38, s14
	s_addc_u32 s5, s39, s15
	s_lshl_b64 s[0:1], s[0:1], 2
	s_mov_b64 s[38:39], s[52:53]
	s_add_u32 s52, s4, s0
	s_addc_u32 s53, s5, s1
	s_ashr_i32 s0, s56, 31
	s_lshr_b32 s0, s0, 26
	s_add_i32 s0, s56, s0
	s_ashr_i32 s31, s0, 6
	s_lshl_b32 s0, s30, 5
	s_and_b32 s45, s0, 0x60
	s_add_i32 m0, s48, 0x18000
	v_lshl_add_u64 v[10:11], v[10:11], 0, s[8:9]
	s_lshl_b32 s34, s33, 6
	s_lshl_b32 s4, s33, 13
	s_lshl_b32 s5, s45, 7
	s_waitcnt vmcnt(2)
	s_barrier
	global_load_lds_dwordx4 v[10:11], off
	v_lshl_add_u64 v[8:9], v[8:9], 0, s[8:9]
	s_add_i32 m0, s48, 0x1a000
	s_add_i32 s30, s48, 0x8000
	s_add_i32 s33, s48, 0xa000
	global_load_lds_dwordx4 v[8:9], off
	v_lshl_add_u64 v[4:5], v[4:5], 0, s[8:9]
	s_mov_b32 m0, s30
	s_add_u32 s0, s40, 0x80080
	global_load_lds_dwordx4 v[4:5], off
	v_lshl_add_u64 v[4:5], v[6:7], 0, s[8:9]
	s_mov_b32 m0, s33
	s_addc_u32 s1, s41, 0
	global_load_lds_dwordx4 v[4:5], off
	s_add_i32 m0, s48, 0x1c000
	v_lshl_add_u64 v[4:5], s[0:1], 0, v[152:153]
	global_load_lds_dwordx4 v[4:5], off
	v_lshl_add_u64 v[4:5], s[0:1], 0, v[156:157]
	s_add_i32 m0, s48, 0x1e000
	s_movk_i32 s0, 0x3c0
	global_load_lds_dwordx4 v[4:5], off
	v_and_b32_e32 v4, 48, v12
	v_lshlrev_b32_e32 v5, 6, v12
	v_and_or_b32 v4, v5, s0, v4
	v_lshlrev_b32_e32 v5, 2, v12
	v_and_b32_e32 v5, 32, v5
	v_bitop3_b32 v6, v4, s4, v5 bitop3:0xde
	v_bitop3_b32 v185, s5, v4, v5 bitop3:0xf6
	v_add_u32_e32 v185, 0x10000, v185
	v_lshlrev_b32_e32 v4, 15, v2
	v_writelane_b32 v242, s24, 29
	v_and_b32_e32 v4, 0xffff0000, v4
	v_lshl_add_u32 v4, v13, 12, v4
	v_writelane_b32 v242, s25, 30
	v_and_b32_e32 v2, 1, v2
	v_writelane_b32 v242, s20, 31
	v_lshl_or_b32 v2, v2, 6, v4
	s_cmp_gt_i32 s56, 63
	v_writelane_b32 v242, s21, 32
	v_lshl_add_u32 v158, v14, 1, v2
	v_lshlrev_b32_e32 v2, 15, v15
	v_writelane_b32 v242, s18, 35
	s_cselect_b64 s[84:85], -1, 0
	s_add_i32 s88, s31, -2
	v_and_b32_e32 v2, 0xffff0000, v2
	v_writelane_b32 v242, s19, 36
	s_cmpk_lt_u32 s58, 0x100
	v_lshl_add_u32 v2, v16, 12, v2
	v_and_b32_e32 v4, 1, v15
	v_writelane_b32 v242, s16, 37
	s_waitcnt vmcnt(6)
	s_cselect_b64 s[56:57], -1, 0
	s_and_b32 s0, s58, 0xffffff00
	v_lshl_or_b32 v2, v4, 6, v2
	v_mov_b32_e32 v4, v3
	v_mov_b32_e32 v5, v3
	v_writelane_b32 v242, s17, 38
	v_and_b32_e32 v184, 63, v12
	s_add_i32 s89, s0, 0
	v_lshl_add_u32 v160, v17, 1, v2
	v_mov_b32_e32 v2, v3
	v_add_u32_e32 v186, 0, v6
	v_mov_b64_e32 v[8:9], v[4:5]
	v_mov_b64_e32 v[12:13], v[4:5]
	v_mov_b64_e32 v[16:17], v[4:5]
	v_mov_b64_e32 v[20:21], v[4:5]
	v_mov_b64_e32 v[24:25], v[4:5]
	v_mov_b64_e32 v[28:29], v[4:5]
	v_mov_b64_e32 v[32:33], v[4:5]
	v_mov_b64_e32 v[36:37], v[4:5]
	v_mov_b64_e32 v[40:41], v[4:5]
	v_mov_b64_e32 v[44:45], v[4:5]
	v_mov_b64_e32 v[48:49], v[4:5]
	v_mov_b64_e32 v[52:53], v[4:5]
	v_mov_b64_e32 v[56:57], v[4:5]
	v_mov_b64_e32 v[60:61], v[4:5]
	v_mov_b64_e32 v[64:65], v[4:5]
	v_mov_b64_e32 v[68:69], v[4:5]
	v_mov_b64_e32 v[72:73], v[4:5]
	v_mov_b64_e32 v[76:77], v[4:5]
	v_mov_b64_e32 v[80:81], v[4:5]
	v_mov_b64_e32 v[84:85], v[4:5]
	v_mov_b64_e32 v[88:89], v[4:5]
	v_mov_b64_e32 v[92:93], v[4:5]
	v_mov_b64_e32 v[96:97], v[4:5]
	v_mov_b64_e32 v[100:101], v[4:5]
	v_mov_b64_e32 v[104:105], v[4:5]
	v_mov_b64_e32 v[108:109], v[4:5]
	v_mov_b64_e32 v[112:113], v[4:5]
	v_mov_b64_e32 v[116:117], v[4:5]
	v_mov_b64_e32 v[120:121], v[4:5]
	v_mov_b64_e32 v[124:125], v[4:5]
	v_mov_b64_e32 v[128:129], v[4:5]
	v_mov_b64_e32 v[132:133], v[4:5]
	v_writelane_b32 v242, s6, 33
	s_add_i32 s89, s89, 0x20000
	v_mov_b32_e32 v159, v3
	v_mov_b32_e32 v161, v3
	s_mov_b32 s92, 0
	v_mov_b64_e32 v[6:7], v[2:3]
	v_mov_b64_e32 v[10:11], v[2:3]
	v_mov_b64_e32 v[14:15], v[2:3]
	v_mov_b64_e32 v[18:19], v[2:3]
	v_mov_b64_e32 v[22:23], v[2:3]
	v_mov_b64_e32 v[26:27], v[2:3]
	v_mov_b64_e32 v[30:31], v[2:3]
	v_mov_b64_e32 v[34:35], v[2:3]
	v_mov_b64_e32 v[38:39], v[2:3]
	v_mov_b64_e32 v[42:43], v[2:3]
	v_mov_b64_e32 v[46:47], v[2:3]
	v_mov_b64_e32 v[50:51], v[2:3]
	v_mov_b64_e32 v[54:55], v[2:3]
	v_mov_b64_e32 v[58:59], v[2:3]
	v_mov_b64_e32 v[62:63], v[2:3]
	v_mov_b64_e32 v[66:67], v[2:3]
	v_mov_b64_e32 v[70:71], v[2:3]
	v_mov_b64_e32 v[74:75], v[2:3]
	v_mov_b64_e32 v[78:79], v[2:3]
	v_mov_b64_e32 v[82:83], v[2:3]
	v_mov_b64_e32 v[86:87], v[2:3]
	v_mov_b64_e32 v[90:91], v[2:3]
	v_mov_b64_e32 v[94:95], v[2:3]
	v_mov_b64_e32 v[98:99], v[2:3]
	v_mov_b64_e32 v[102:103], v[2:3]
	v_mov_b64_e32 v[106:107], v[2:3]
	v_mov_b64_e32 v[110:111], v[2:3]
	v_mov_b64_e32 v[114:115], v[2:3]
	v_mov_b64_e32 v[118:119], v[2:3]
	v_mov_b64_e32 v[122:123], v[2:3]
	v_mov_b64_e32 v[126:127], v[2:3]
	v_mov_b64_e32 v[130:131], v[2:3]
	v_writelane_b32 v242, s7, 34
	s_barrier
	s_branch .LBB0_949

; #define PG8_STAGE(bufoff, gbase, voff) do { _Pragma("unroll") for (int _i = 0; _i < 2; ++_i) \
;         __builtin_amdgcn_global_load_lds((const unsigned*)((const char*)(gbase) + (voff)[_i]), (LAS unsigned*)(lds + (bufoff) + ldsw + _i * 8192), 16, 0, 0); } while (0)
; #define PG8_LDA(dst, b, h) do { _Pragma("unroll") for (int m = 0; m < 4; ++m) _Pragma("unroll") for (int k = 0; k < 2; ++k) dst[m][k] = *(const LAS bf16x8*)(lds + PG8_SA(b, h) + aoff + m * 2048 + k * 1024); } while (0)
; #define PG8_LDB(dst, b, h) do { _Pragma("unroll") for (int n = 0; n < 2; ++n) _Pragma("unroll") for (int k = 0; k < 2; ++k) dst[n][k] = *(const LAS bf16x8*)(lds + PG8_SB(b, h) + boff + n * 2048 + k * 1024); } while (0)
; #define PG8_MMA(ai, bj, At, Bt) do { __builtin_amdgcn_s_setprio(1); _Pragma("unroll") for (int m = 0; m < 4; ++m) _Pragma("unroll") for (int n = 0; n < 2; ++n) _Pragma("unroll") for (int k = 0; k < 2; ++k) \
;         acc[ai][bj][m][n] = __builtin_amdgcn_mfma_f32_16x16x32_bf16(Bt[n][k], At[m][k], acc[ai][bj][m][n], 0, 0, 0); __builtin_amdgcn_s_setprio(0); } while (0)
; #define PG8_WAIT_V(n) asm volatile("s_waitcnt vmcnt(" #n ")" ::: "memory")
; #define PG8_WAIT_L(n) asm volatile("s_waitcnt lgkmcnt(" #n ")" ::: "memory")
; #define PG8_BAR __builtin_amdgcn_s_barrier()
; template <class Epi, bool ALIGN_EPI = true>
; __device__ __forceinline__ void gemm_phase(LAS unsigned char* lds, const Gemm g, const Sched& S, const Epi& E) {
;     ...
;         for (int t = t_lo; t < t_hi; t += 2) {
;             const bool last = (t == nt - 2);
;             const char* a1 = cA + (size_t)(t + 1) * kstep;
;             const char* a2 = last ? nA : cA + (size_t)(t + 2) * kstep; const char* b2 = last ? nB : cB + (size_t)(t + 2) * kstep;
;             const char* a3 = a2 + kstep; const char* b3 = b2 + kstep;
;             const int rflag = __builtin_amdgcn_readfirstlane(t | (int)(ui == 0));
;             PG8_LDB(B0, 0, 0); PG8_LDB(B1, 0, 1); PG8_SCHED; PG8_LDA(At, 0, 0); PG8_STAGE(PG8_SA(1, 1), a1 + hstepA, voffA);
;             if constexpr (Epi::NSTORES > 0) PG8_WAIT_RELAX(rflag, 8 + Epi::NSTORES); else PG8_WAIT_V(8);
;             PG8_WAIT_L(0); PG8_BAR; PG8_MMA(0, 0, At, B0); PG8_MMA(0, 1, At, B1); PG8_BAR; PG8_SCHED;
;             PG8_LDA(At, 0, 1); PG8_STAGE(PG8_SB(0, 0), b2, voffB); PG8_STAGE(PG8_SB(0, 1), b2 + hstepB, voffB); PG8_STAGE(PG8_SA(0, 0), a2, voffA);
.LBB0_954:
	s_add_i32 s22, s6, 2
	s_add_u32 s7, s4, 0xfff80080
	s_addc_u32 s14, s5, -1
	s_add_i32 s23, 0, 0x10000
	s_cmp_eq_u32 s88, s6
	v_add_u32_e32 v182, s6, v2
	s_cselect_b32 s15, s16, s14
	s_cselect_b32 s14, s17, s7
	s_waitcnt lgkmcnt(0)
	s_cselect_b32 s7, s18, s21
	s_cselect_b32 s6, s19, s20
	s_add_i32 s58, 0, 0x14000
	ds_read_b128 v[134:137], v185
	ds_read_b128 v[138:141], v185 offset:1024
	ds_read_b128 v[142:145], v185 offset:2048
	ds_read_b128 v[146:149], v185 offset:3072
	ds_read_b128 v[162:165], v185 offset:16384
	ds_read_b128 v[166:169], v185 offset:17408
	ds_read_b128 v[170:173], v185 offset:18432
	ds_read_b128 v[174:177], v185 offset:19456
	ds_read_b128 v[178:181], v186
	ds_read_b128 v[188:191], v186 offset:1024
	ds_read_b128 v[192:195], v186 offset:2048
	ds_read_b128 v[206:209], v186 offset:3072
	ds_read_b128 v[224:227], v186 offset:4096
	ds_read_b128 v[228:231], v186 offset:5120
	ds_read_b128 v[232:235], v186 offset:6144
	ds_read_b128 v[236:239], v186 offset:7168
	s_mov_b32 m0, s30
	s_add_u32 s100, s4, 0xfff80000
	s_addc_u32 s101, s5, -1
	global_load_lds_dwordx4 v158, s[100:101]
	s_mov_b32 m0, s33
	s_nop 0
	global_load_lds_dwordx4 v160, s[100:101]
	s_add_i32 m0, s48, 0xc000
	s_nop 0
	global_load_lds_dwordx4 v158, s[4:5]
	s_add_i32 m0, s48, 0xe000
	v_readfirstlane_b32 s59, v182
	global_load_lds_dwordx4 v160, s[4:5]
	s_cmp_eq_u32 s59, 0
	s_cbranch_scc1 .Lrw12
	s_waitcnt vmcnt(8)
.Lrw12:
	s_waitcnt vmcnt(24) lgkmcnt(0)
	s_barrier
	s_setprio 1
	v_mfma_f32_16x16x32_bf16 v[130:133], v[134:137], v[178:181], v[130:133]
	v_mfma_f32_16x16x32_bf16 v[126:129], v[142:145], v[178:181], v[126:129]
	v_mfma_f32_16x16x32_bf16 v[122:125], v[134:137], v[192:195], v[122:125]
	v_mfma_f32_16x16x32_bf16 v[118:121], v[142:145], v[192:195], v[118:121]
	v_mfma_f32_16x16x32_bf16 v[114:117], v[134:137], v[224:227], v[114:117]
	v_mfma_f32_16x16x32_bf16 v[110:113], v[142:145], v[224:227], v[110:113]
	v_mfma_f32_16x16x32_bf16 v[106:109], v[134:137], v[232:235], v[106:109]
	v_mfma_f32_16x16x32_bf16 v[102:105], v[142:145], v[232:235], v[102:105]
	v_mfma_f32_16x16x32_bf16 v[130:133], v[138:141], v[188:191], v[130:133]
	v_mfma_f32_16x16x32_bf16 v[126:129], v[146:149], v[188:191], v[126:129]
	v_mfma_f32_16x16x32_bf16 v[122:125], v[138:141], v[206:209], v[122:125]
	v_mfma_f32_16x16x32_bf16 v[118:121], v[146:149], v[206:209], v[118:121]
	v_mfma_f32_16x16x32_bf16 v[114:117], v[138:141], v[228:231], v[114:117]
	v_mfma_f32_16x16x32_bf16 v[110:113], v[146:149], v[228:231], v[110:113]
	v_mfma_f32_16x16x32_bf16 v[106:109], v[138:141], v[236:239], v[106:109]
	v_mfma_f32_16x16x32_bf16 v[102:105], v[146:149], v[236:239], v[102:105]
	s_setprio 0
	s_setprio 1
	v_mfma_f32_16x16x32_bf16 v[98:101], v[162:165], v[178:181], v[98:101]
	v_mfma_f32_16x16x32_bf16 v[94:97], v[170:173], v[178:181], v[94:97]
	v_mfma_f32_16x16x32_bf16 v[90:93], v[162:165], v[192:195], v[90:93]
	v_mfma_f32_16x16x32_bf16 v[86:89], v[170:173], v[192:195], v[86:89]
	v_mfma_f32_16x16x32_bf16 v[82:85], v[162:165], v[224:227], v[82:85]
	v_mfma_f32_16x16x32_bf16 v[78:81], v[170:173], v[224:227], v[78:81]
	v_mfma_f32_16x16x32_bf16 v[74:77], v[162:165], v[232:235], v[74:77]
	v_mfma_f32_16x16x32_bf16 v[70:73], v[170:173], v[232:235], v[70:73]
	v_mfma_f32_16x16x32_bf16 v[98:101], v[166:169], v[188:191], v[98:101]
	v_mfma_f32_16x16x32_bf16 v[94:97], v[174:177], v[188:191], v[94:97]
	v_mfma_f32_16x16x32_bf16 v[90:93], v[166:169], v[206:209], v[90:93]
	v_mfma_f32_16x16x32_bf16 v[86:89], v[174:177], v[206:209], v[86:89]
	v_mfma_f32_16x16x32_bf16 v[82:85], v[166:169], v[228:231], v[82:85]
	v_mfma_f32_16x16x32_bf16 v[78:81], v[174:177], v[228:231], v[78:81]
	v_mfma_f32_16x16x32_bf16 v[74:77], v[166:169], v[236:239], v[74:77]
	v_mfma_f32_16x16x32_bf16 v[70:73], v[174:177], v[236:239], v[70:73]
	s_setprio 0
	s_barrier
	s_add_i32 s23, s23, s94
	s_mov_b32 m0, s23
	ds_read_b128 v[178:181], v186 offset:16384
	ds_read_b128 v[188:191], v186 offset:17408
	ds_read_b128 v[192:195], v186 offset:18432
	ds_read_b128 v[206:209], v186 offset:19456
	ds_read_b128 v[224:227], v186 offset:20480
	ds_read_b128 v[228:231], v186 offset:21504
	ds_read_b128 v[232:235], v186 offset:22528
	ds_read_b128 v[236:239], v186 offset:23552
	global_load_lds_dwordx4 v152, s[6:7]
	s_add_i32 m0, s23, 0x2000
	s_add_u32 s24, s6, 0x80000
	s_addc_u32 s25, s7, 0
	s_add_i32 s23, s58, s94
	global_load_lds_dwordx4 v156, s[6:7]
	s_mov_b32 m0, s23
	s_nop 0
	global_load_lds_dwordx4 v152, s[24:25]
	s_add_i32 m0, s23, 0x2000
	s_nop 0
	global_load_lds_dwordx4 v156, s[24:25]
; #define PG8_STAGE(bufoff, gbase, voff) do { _Pragma("unroll") for (int _i = 0; _i < 2; ++_i) \
;         __builtin_amdgcn_global_load_lds((const unsigned*)((const char*)(gbase) + (voff)[_i]), (LAS unsigned*)(lds + (bufoff) + ldsw + _i * 8192), 16, 0, 0); } while (0)
; #define PG8_LDA(dst, b, h) do { _Pragma("unroll") for (int m = 0; m < 4; ++m) _Pragma("unroll") for (int k = 0; k < 2; ++k) dst[m][k] = *(const LAS bf16x8*)(lds + PG8_SA(b, h) + aoff + m * 2048 + k * 1024); } while (0)
; #define PG8_LDB(dst, b, h) do { _Pragma("unroll") for (int n = 0; n < 2; ++n) _Pragma("unroll") for (int k = 0; k < 2; ++k) dst[n][k] = *(const LAS bf16x8*)(lds + PG8_SB(b, h) + boff + n * 2048 + k * 1024); } while (0)
; #define PG8_MMA(ai, bj, At, Bt) do { __builtin_amdgcn_s_setprio(1); _Pragma("unroll") for (int m = 0; m < 4; ++m) _Pragma("unroll") for (int n = 0; n < 2; ++n) _Pragma("unroll") for (int k = 0; k < 2; ++k) \
;         acc[ai][bj][m][n] = __builtin_amdgcn_mfma_f32_16x16x32_bf16(Bt[n][k], At[m][k], acc[ai][bj][m][n], 0, 0, 0); __builtin_amdgcn_s_setprio(0); } while (0)
; #define PG8_WAIT_V(n) asm volatile("s_waitcnt vmcnt(" #n ")" ::: "memory")
; #define PG8_WAIT_L(n) asm volatile("s_waitcnt lgkmcnt(" #n ")" ::: "memory")
; #define PG8_BAR __builtin_amdgcn_s_barrier()
; #define PG8_WAIT_RELAX(flag, n) asm volatile("s_cmp_eq_u32 %0, 0\n\ts_cbranch_scc1 .Lrw%=\n\ts_waitcnt vmcnt(8)\n.Lrw%=:\n\ts_waitcnt vmcnt(%1)" :: "s"(flag), "n"(n) : "scc", "memory")
; #define PG8_SCHED __builtin_amdgcn_sched_barrier(0)
; template <class Epi, bool ALIGN_EPI = true>
; __device__ __forceinline__ void gemm_phase(LAS unsigned char* lds, const Gemm g, const Sched& S, const Epi& E) {
;     ...
;             if constexpr (Epi::NSTORES > 0) PG8_WAIT_RELAX(rflag, 8 + Epi::NSTORES); else PG8_WAIT_V(8);
;             PG8_WAIT_L(0); PG8_BAR; PG8_MMA(1, 0, At, B0); PG8_MMA(1, 1, At, B1); PG8_BAR; PG8_SCHED;
;             PG8_LDB(B0, 1, 0); PG8_LDB(B1, 1, 1); PG8_SCHED; PG8_LDA(At, 1, 0); PG8_STAGE(PG8_SA(0, 1), a2 + hstepA, voffA);
;             PG8_WAIT_V(8); PG8_WAIT_L(0); PG8_BAR; PG8_MMA(0, 0, At, B0); PG8_MMA(0, 1, At, B1); PG8_BAR; PG8_SCHED;
.Lrw13:
	s_waitcnt vmcnt(6) lgkmcnt(0)
	s_barrier
	s_setprio 1
	v_mfma_f32_16x16x32_bf16 v[66:69], v[134:137], v[178:181], v[66:69]
	v_mfma_f32_16x16x32_bf16 v[62:65], v[142:145], v[178:181], v[62:65]
	v_mfma_f32_16x16x32_bf16 v[58:61], v[134:137], v[192:195], v[58:61]
	v_mfma_f32_16x16x32_bf16 v[54:57], v[142:145], v[192:195], v[54:57]
	v_mfma_f32_16x16x32_bf16 v[50:53], v[134:137], v[224:227], v[50:53]
	v_mfma_f32_16x16x32_bf16 v[46:49], v[142:145], v[224:227], v[46:49]
	v_mfma_f32_16x16x32_bf16 v[42:45], v[134:137], v[232:235], v[42:45]
	v_mfma_f32_16x16x32_bf16 v[38:41], v[142:145], v[232:235], v[38:41]
	v_mfma_f32_16x16x32_bf16 v[66:69], v[138:141], v[188:191], v[66:69]
	v_mfma_f32_16x16x32_bf16 v[62:65], v[146:149], v[188:191], v[62:65]
	v_mfma_f32_16x16x32_bf16 v[58:61], v[138:141], v[206:209], v[58:61]
	v_mfma_f32_16x16x32_bf16 v[54:57], v[146:149], v[206:209], v[54:57]
	v_mfma_f32_16x16x32_bf16 v[50:53], v[138:141], v[228:231], v[50:53]
	v_mfma_f32_16x16x32_bf16 v[46:49], v[146:149], v[228:231], v[46:49]
	v_mfma_f32_16x16x32_bf16 v[42:45], v[138:141], v[236:239], v[42:45]
	v_mfma_f32_16x16x32_bf16 v[38:41], v[146:149], v[236:239], v[38:41]
	s_setprio 0
	s_setprio 1
	v_mfma_f32_16x16x32_bf16 v[34:37], v[162:165], v[178:181], v[34:37]
	v_mfma_f32_16x16x32_bf16 v[30:33], v[170:173], v[178:181], v[30:33]
	v_mfma_f32_16x16x32_bf16 v[26:29], v[162:165], v[192:195], v[26:29]
	v_mfma_f32_16x16x32_bf16 v[22:25], v[170:173], v[192:195], v[22:25]
	v_mfma_f32_16x16x32_bf16 v[18:21], v[162:165], v[224:227], v[18:21]
	v_mfma_f32_16x16x32_bf16 v[14:17], v[170:173], v[224:227], v[14:17]
	v_mfma_f32_16x16x32_bf16 v[10:13], v[162:165], v[232:235], v[10:13]
	v_mfma_f32_16x16x32_bf16 v[4:7], v[170:173], v[232:235], v[6:9]
	v_mfma_f32_16x16x32_bf16 v[34:37], v[166:169], v[188:191], v[34:37]
	v_mfma_f32_16x16x32_bf16 v[30:33], v[174:177], v[188:191], v[30:33]
	v_mfma_f32_16x16x32_bf16 v[26:29], v[166:169], v[206:209], v[26:29]
	v_mfma_f32_16x16x32_bf16 v[22:25], v[174:177], v[206:209], v[22:25]
	v_mfma_f32_16x16x32_bf16 v[18:21], v[166:169], v[228:231], v[18:21]
	v_mfma_f32_16x16x32_bf16 v[14:17], v[174:177], v[228:231], v[14:17]
	v_mfma_f32_16x16x32_bf16 v[10:13], v[166:169], v[236:239], v[10:13]
	v_mfma_f32_16x16x32_bf16 v[4:7], v[174:177], v[236:239], v[4:7]
	s_setprio 0
	s_barrier
	s_add_i32 s23, 0, 0x18000
	s_add_i32 s24, 0, 0x1c000
	ds_read_b128 v[134:137], v185 offset:32768
	ds_read_b128 v[138:141], v185 offset:33792
	ds_read_b128 v[142:145], v185 offset:34816
	ds_read_b128 v[146:149], v185 offset:35840
	ds_read_b128 v[162:165], v185 offset:49152
	ds_read_b128 v[166:169], v185 offset:50176
	ds_read_b128 v[170:173], v185 offset:51200
	ds_read_b128 v[174:177], v185 offset:52224
	s_add_u32 s14, s14, 0x80000
	s_addc_u32 s15, s15, 0
	ds_read_b128 v[178:181], v186 offset:32768
	ds_read_b128 v[188:191], v186 offset:33792
	ds_read_b128 v[192:195], v186 offset:34816
	ds_read_b128 v[206:209], v186 offset:35840
	ds_read_b128 v[224:227], v186 offset:36864
	ds_read_b128 v[228:231], v186 offset:37888
	ds_read_b128 v[232:235], v186 offset:38912
	ds_read_b128 v[236:239], v186 offset:39936
	s_mov_b32 m0, s48
	s_add_u32 s100, s14, 0xfff80000
	s_addc_u32 s101, s15, -1
	global_load_lds_dwordx4 v150, s[100:101]
	s_mov_b32 m0, s49
	s_nop 0
	global_load_lds_dwordx4 v154, s[100:101]
	s_mov_b32 m0, s46
	s_nop 0
	global_load_lds_dwordx4 v150, s[14:15]
	s_mov_b32 m0, s47
	s_nop 0
	global_load_lds_dwordx4 v154, s[14:15]
	s_waitcnt vmcnt(8) lgkmcnt(0)
	s_barrier
; #define PG8_STAGE(bufoff, gbase, voff) do { _Pragma("unroll") for (int _i = 0; _i < 2; ++_i) \
;         __builtin_amdgcn_global_load_lds((const unsigned*)((const char*)(gbase) + (voff)[_i]), (LAS unsigned*)(lds + (bufoff) + ldsw + _i * 8192), 16, 0, 0); } while (0)
; #define PG8_LDA(dst, b, h) do { _Pragma("unroll") for (int m = 0; m < 4; ++m) _Pragma("unroll") for (int k = 0; k < 2; ++k) dst[m][k] = *(const LAS bf16x8*)(lds + PG8_SA(b, h) + aoff + m * 2048 + k * 1024); } while (0)
; #define PG8_MMA(ai, bj, At, Bt) do { __builtin_amdgcn_s_setprio(1); _Pragma("unroll") for (int m = 0; m < 4; ++m) _Pragma("unroll") for (int n = 0; n < 2; ++n) _Pragma("unroll") for (int k = 0; k < 2; ++k) \
;         acc[ai][bj][m][n] = __builtin_amdgcn_mfma_f32_16x16x32_bf16(Bt[n][k], At[m][k], acc[ai][bj][m][n], 0, 0, 0); __builtin_amdgcn_s_setprio(0); } while (0)
; #define PG8_WAIT_V(n) asm volatile("s_waitcnt vmcnt(" #n ")" ::: "memory")
; #define PG8_WAIT_L(n) asm volatile("s_waitcnt lgkmcnt(" #n ")" ::: "memory")
; #define PG8_BAR __builtin_amdgcn_s_barrier()
; #define PG8_SCHED __builtin_amdgcn_sched_barrier(0)
; template <class Epi, bool ALIGN_EPI = true>
; __device__ __forceinline__ void gemm_phase(LAS unsigned char* lds, const Gemm g, const Sched& S, const Epi& E) {
;     ...
;             PG8_WAIT_V(8); PG8_WAIT_L(0); PG8_BAR; PG8_MMA(0, 0, At, B0); PG8_MMA(0, 1, At, B1); PG8_BAR; PG8_SCHED;
;             PG8_LDA(At, 1, 1); PG8_STAGE(PG8_SB(1, 0), b3, voffB); PG8_STAGE(PG8_SB(1, 1), b3 + hstepB, voffB); PG8_STAGE(PG8_SA(1, 0), a3, voffA);
;             PG8_WAIT_V(8); PG8_WAIT_L(0); PG8_BAR; PG8_MMA(1, 0, At, B0); PG8_MMA(1, 1, At, B1); PG8_BAR; PG8_SCHED;
;         }
	s_setprio 1
	v_mfma_f32_16x16x32_bf16 v[130:133], v[134:137], v[178:181], v[130:133]
	v_mfma_f32_16x16x32_bf16 v[126:129], v[142:145], v[178:181], v[126:129]
	v_mfma_f32_16x16x32_bf16 v[122:125], v[134:137], v[192:195], v[122:125]
	v_mfma_f32_16x16x32_bf16 v[118:121], v[142:145], v[192:195], v[118:121]
	v_mfma_f32_16x16x32_bf16 v[114:117], v[134:137], v[224:227], v[114:117]
	v_mfma_f32_16x16x32_bf16 v[110:113], v[142:145], v[224:227], v[110:113]
	v_mfma_f32_16x16x32_bf16 v[106:109], v[134:137], v[232:235], v[106:109]
	v_mfma_f32_16x16x32_bf16 v[102:105], v[142:145], v[232:235], v[102:105]
	v_mfma_f32_16x16x32_bf16 v[130:133], v[138:141], v[188:191], v[130:133]
	v_mfma_f32_16x16x32_bf16 v[126:129], v[146:149], v[188:191], v[126:129]
	v_mfma_f32_16x16x32_bf16 v[122:125], v[138:141], v[206:209], v[122:125]
	v_mfma_f32_16x16x32_bf16 v[118:121], v[146:149], v[206:209], v[118:121]
	v_mfma_f32_16x16x32_bf16 v[114:117], v[138:141], v[228:231], v[114:117]
	v_mfma_f32_16x16x32_bf16 v[110:113], v[146:149], v[228:231], v[110:113]
	v_mfma_f32_16x16x32_bf16 v[106:109], v[138:141], v[236:239], v[106:109]
	v_mfma_f32_16x16x32_bf16 v[102:105], v[146:149], v[236:239], v[102:105]
	s_setprio 0
	s_setprio 1
	v_mfma_f32_16x16x32_bf16 v[98:101], v[162:165], v[178:181], v[98:101]
	v_mfma_f32_16x16x32_bf16 v[94:97], v[170:173], v[178:181], v[94:97]
	v_mfma_f32_16x16x32_bf16 v[90:93], v[162:165], v[192:195], v[90:93]
	v_mfma_f32_16x16x32_bf16 v[86:89], v[170:173], v[192:195], v[86:89]
	v_mfma_f32_16x16x32_bf16 v[82:85], v[162:165], v[224:227], v[82:85]
	v_mfma_f32_16x16x32_bf16 v[78:81], v[170:173], v[224:227], v[78:81]
	v_mfma_f32_16x16x32_bf16 v[74:77], v[162:165], v[232:235], v[74:77]
	v_mfma_f32_16x16x32_bf16 v[70:73], v[170:173], v[232:235], v[70:73]
	v_mfma_f32_16x16x32_bf16 v[98:101], v[166:169], v[188:191], v[98:101]
	v_mfma_f32_16x16x32_bf16 v[94:97], v[174:177], v[188:191], v[94:97]
	v_mfma_f32_16x16x32_bf16 v[90:93], v[166:169], v[206:209], v[90:93]
	v_mfma_f32_16x16x32_bf16 v[86:89], v[174:177], v[206:209], v[86:89]
	v_mfma_f32_16x16x32_bf16 v[82:85], v[166:169], v[228:231], v[82:85]
	v_mfma_f32_16x16x32_bf16 v[78:81], v[174:177], v[228:231], v[78:81]
	v_mfma_f32_16x16x32_bf16 v[74:77], v[166:169], v[236:239], v[74:77]
	v_mfma_f32_16x16x32_bf16 v[70:73], v[174:177], v[236:239], v[70:73]
	s_setprio 0
	s_barrier
	s_add_u32 s100, s6, 0x80
	s_addc_u32 s101, s7, 0
	s_add_i32 s14, s23, s94
	s_mov_b32 m0, s14
	ds_read_b128 v[178:181], v186 offset:49152
	ds_read_b128 v[188:191], v186 offset:50176
	ds_read_b128 v[192:195], v186 offset:51200
	ds_read_b128 v[206:209], v186 offset:52224
	ds_read_b128 v[224:227], v186 offset:53248
	ds_read_b128 v[228:231], v186 offset:54272
	ds_read_b128 v[232:235], v186 offset:55296
	ds_read_b128 v[236:239], v186 offset:56320
	global_load_lds_dwordx4 v152, s[100:101]
	s_add_i32 m0, s14, 0x2000
	s_add_u32 s6, s6, 0x80080
	s_addc_u32 s7, s7, 0
	s_add_i32 s14, s24, s94
	global_load_lds_dwordx4 v156, s[100:101]
	s_mov_b32 m0, s14
	s_nop 0
	global_load_lds_dwordx4 v152, s[6:7]
	s_add_i32 m0, s14, 0x2000
	s_nop 0
	global_load_lds_dwordx4 v156, s[6:7]
	s_waitcnt vmcnt(6) lgkmcnt(0)
	s_barrier
	s_setprio 1
	v_mfma_f32_16x16x32_bf16 v[66:69], v[134:137], v[178:181], v[66:69]
	v_mfma_f32_16x16x32_bf16 v[62:65], v[142:145], v[178:181], v[62:65]
	v_mfma_f32_16x16x32_bf16 v[58:61], v[134:137], v[192:195], v[58:61]
	v_mfma_f32_16x16x32_bf16 v[54:57], v[142:145], v[192:195], v[54:57]
	v_mfma_f32_16x16x32_bf16 v[50:53], v[134:137], v[224:227], v[50:53]
	v_mfma_f32_16x16x32_bf16 v[46:49], v[142:145], v[224:227], v[46:49]
	v_mfma_f32_16x16x32_bf16 v[42:45], v[134:137], v[232:235], v[42:45]
	v_mfma_f32_16x16x32_bf16 v[38:41], v[142:145], v[232:235], v[38:41]
	v_mfma_f32_16x16x32_bf16 v[66:69], v[138:141], v[188:191], v[66:69]
	v_mfma_f32_16x16x32_bf16 v[62:65], v[146:149], v[188:191], v[62:65]
	v_mfma_f32_16x16x32_bf16 v[58:61], v[138:141], v[206:209], v[58:61]
	v_mfma_f32_16x16x32_bf16 v[54:57], v[146:149], v[206:209], v[54:57]
	v_mfma_f32_16x16x32_bf16 v[50:53], v[138:141], v[228:231], v[50:53]
	v_mfma_f32_16x16x32_bf16 v[46:49], v[146:149], v[228:231], v[46:49]
	v_mfma_f32_16x16x32_bf16 v[42:45], v[138:141], v[236:239], v[42:45]
	v_mfma_f32_16x16x32_bf16 v[38:41], v[146:149], v[236:239], v[38:41]
	s_setprio 0
	s_setprio 1
	v_mfma_f32_16x16x32_bf16 v[34:37], v[162:165], v[178:181], v[34:37]
	v_mfma_f32_16x16x32_bf16 v[30:33], v[170:173], v[178:181], v[30:33]
	v_mfma_f32_16x16x32_bf16 v[26:29], v[162:165], v[192:195], v[26:29]
	v_mfma_f32_16x16x32_bf16 v[22:25], v[170:173], v[192:195], v[22:25]
	v_mfma_f32_16x16x32_bf16 v[18:21], v[162:165], v[224:227], v[18:21]
	v_mfma_f32_16x16x32_bf16 v[14:17], v[170:173], v[224:227], v[14:17]
	v_mfma_f32_16x16x32_bf16 v[8:11], v[162:165], v[232:235], v[10:13]
	v_mfma_f32_16x16x32_bf16 v[4:7], v[170:173], v[232:235], v[4:7]
	v_mfma_f32_16x16x32_bf16 v[34:37], v[166:169], v[188:191], v[34:37]
	v_mfma_f32_16x16x32_bf16 v[30:33], v[174:177], v[188:191], v[30:33]
	v_mfma_f32_16x16x32_bf16 v[26:29], v[166:169], v[206:209], v[26:29]
	v_mfma_f32_16x16x32_bf16 v[22:25], v[174:177], v[206:209], v[22:25]
	v_mfma_f32_16x16x32_bf16 v[18:21], v[166:169], v[228:231], v[18:21]
	v_mfma_f32_16x16x32_bf16 v[14:17], v[174:177], v[228:231], v[14:17]
	v_mfma_f32_16x16x32_bf16 v[10:13], v[166:169], v[236:239], v[8:11]
	v_mfma_f32_16x16x32_bf16 v[6:9], v[174:177], v[236:239], v[4:7]
	s_setprio 0
	s_barrier
	s_add_u32 s4, s4, 0x100
	s_addc_u32 s5, s5, 0
	s_add_u32 s20, s20, 0x100
	s_addc_u32 s21, s21, 0
	s_cmp_ge_i32 s22, s31
	s_mov_b32 s6, s22
	s_cbranch_scc0 .LBB0_954

; #define PG8_STAGE(bufoff, gbase, voff) do { _Pragma("unroll") for (int _i = 0; _i < 2; ++_i) \
;         __builtin_amdgcn_global_load_lds((const unsigned*)((const char*)(gbase) + (voff)[_i]), (LAS unsigned*)(lds + (bufoff) + ldsw + _i * 8192), 16, 0, 0); } while (0)
; #define PG8_WAIT_V(n) asm volatile("s_waitcnt vmcnt(" #n ")" ::: "memory")
; #define PG8_BAR __builtin_amdgcn_s_barrier()
; template <class Epi, bool ALIGN_EPI = true>
; __device__ __forceinline__ void gemm_phase(LAS unsigned char* lds, const Gemm g, const Sched& S, const Epi& E) {
;     ...
;     for (int i = 0; i < 2; ++i) { int R, C; stage_rc(tid * 16 + i * 8192, R, C); const int Rb = (R & ~31) + perm32(R & 31);
;         voffA[i] = (unsigned)(R * g.lda + C) * 2u; voffB[i] = (unsigned)(Rb * g.ldb + C) * 2u; }
;     const size_t kstep = (size_t)(BK * 2);
;     const size_t hstepA = (size_t)HALF * g.lda * 2, hstepB = (size_t)HALF * g.ldb * 2;
;     const unsigned ldsw = (unsigned)wid * 1024u;
;     const int aoff = lds_byte(wr * 64 + fr, fq * 8), boff = lds_byte(wc * 32 + fr, fq * 8);
;     ...
;     PG8_STAGE(PG8_SB(0, 0), cB, voffB); PG8_STAGE(PG8_SB(0, 1), cB + hstepB, voffB); PG8_STAGE(PG8_SA(0, 0), cA, voffA); PG8_STAGE(PG8_SA(0, 1), cA + hstepA, voffA);
;     if (wr == 1) PG8_BAR;
;     PG8_WAIT_V(2); PG8_BAR;
;     PG8_STAGE(PG8_SB(1, 0), cB + kstep, voffB); PG8_STAGE(PG8_SA(1, 0), cA + kstep, voffA); PG8_STAGE(PG8_SB(1, 1), cB + hstepB + kstep, voffB);
;     PG8_WAIT_V(6); PG8_BAR;
.LBB0_1220:
	v_readlane_b32 s20, v246, 42
	v_readlane_b32 s22, v246, 44
	v_readlane_b32 s23, v246, 45
	s_add_u32 s78, s22, s4
	s_addc_u32 s79, s23, s5
	s_add_u32 s4, s22, s14
	s_addc_u32 s5, s23, s15
	s_add_u32 s6, s22, s6
	s_addc_u32 s7, s23, s7
	s_ashr_i32 s14, s17, 31
	v_and_b32_e32 v223, 63, v2
	s_lshr_b32 s14, s14, 26
	v_and_b32_e32 v12, 48, v2
	v_lshlrev_b32_e32 v13, 6, v2
	s_movk_i32 s10, 0x3c0
	v_lshlrev_b32_e32 v2, 2, v2
	s_and_b32 s19, s19, 3
	s_add_i32 s17, s17, s14
	s_lshl_b32 s14, s18, 13
	v_and_or_b32 v12, v13, s10, v12
	v_and_b32_e32 v2, 32, v2
	s_add_i32 m0, s36, 0x18000
	v_lshl_add_u64 v[10:11], v[10:11], 0, s[8:9]
	s_ashr_i32 s85, s17, 6
	s_lshl_b32 s80, s18, 6
	v_bitop3_b32 v13, v12, s14, v2 bitop3:0xde
	s_lshl_b32 s14, s19, 12
	s_waitcnt vmcnt(2)
	s_barrier
	global_load_lds_dwordx4 v[10:11], off
	v_lshl_add_u64 v[8:9], v[8:9], 0, s[8:9]
	s_add_i32 m0, s36, 0x1a000
	s_add_i32 s81, s36, 0x8000
	s_add_i32 s82, s36, 0xa000
	v_bitop3_b32 v224, v12, s14, v2 bitop3:0xde
	v_add_u32_e32 v224, 0x10000, v224
	global_load_lds_dwordx4 v[8:9], off
	v_lshl_add_u64 v[4:5], v[4:5], 0, s[8:9]
	s_mov_b32 m0, s81
	s_add_u32 s14, s54, 0x80080
	global_load_lds_dwordx4 v[4:5], off
	v_lshl_add_u64 v[4:5], v[6:7], 0, s[8:9]
	s_mov_b32 m0, s82
	s_addc_u32 s15, s55, 0
	global_load_lds_dwordx4 v[4:5], off
	s_add_i32 m0, s36, 0x1c000
	v_lshl_add_u64 v[4:5], s[14:15], 0, v[206:207]
	global_load_lds_dwordx4 v[4:5], off
	v_lshl_add_u64 v[4:5], s[14:15], 0, v[194:195]
	s_add_i32 m0, s36, 0x1e000
	s_lshl_b32 s83, s19, 6
	global_load_lds_dwordx4 v[4:5], off
	s_ashr_i32 s84, s17, 7
	s_add_i32 s85, s85, -2
	v_readlane_b32 s18, v243, 43
	s_waitcnt vmcnt(6)
	s_cmpk_lt_u32 s16, 0x100
	v_readlane_b32 s19, v243, 44
	s_cselect_b64 s[14:15], -1, 0
	s_cmp_gt_i32 s84, 0
	s_mov_b32 s48, s18
	v_readlane_b32 s18, v243, 39
	s_mov_b32 s86, 0
	s_cselect_b64 s[16:17], -1, 0
	v_add_u32_e32 v225, 0, v13
	s_mov_b32 s49, s18
	v_readlane_b32 s21, v246, 43
	s_barrier
	v_readlane_b32 s19, v243, 40
	s_branch .LBB0_1223

; #define PG8_STAGE(bufoff, gbase, voff) do { _Pragma("unroll") for (int _i = 0; _i < 2; ++_i) \
;         __builtin_amdgcn_global_load_lds((const unsigned*)((const char*)(gbase) + (voff)[_i]), (LAS unsigned*)(lds + (bufoff) + ldsw + _i * 8192), 16, 0, 0); } while (0)
; #define PG8_LDA(dst, b, h) do { _Pragma("unroll") for (int m = 0; m < 4; ++m) _Pragma("unroll") for (int k = 0; k < 2; ++k) dst[m][k] = *(const LAS bf16x8*)(lds + PG8_SA(b, h) + aoff + m * 2048 + k * 1024); } while (0)
; #define PG8_LDB(dst, b, h) do { _Pragma("unroll") for (int n = 0; n < 2; ++n) _Pragma("unroll") for (int k = 0; k < 2; ++k) dst[n][k] = *(const LAS bf16x8*)(lds + PG8_SB(b, h) + boff + n * 2048 + k * 1024); } while (0)
; #define PG8_MMA(ai, bj, At, Bt) do { __builtin_amdgcn_s_setprio(1); _Pragma("unroll") for (int m = 0; m < 4; ++m) _Pragma("unroll") for (int n = 0; n < 2; ++n) _Pragma("unroll") for (int k = 0; k < 2; ++k) \
;         acc[ai][bj][m][n] = __builtin_amdgcn_mfma_f32_16x16x32_bf16(Bt[n][k], At[m][k], acc[ai][bj][m][n], 0, 0, 0); __builtin_amdgcn_s_setprio(0); } while (0)
; #define PG8_WAIT_V(n) asm volatile("s_waitcnt vmcnt(" #n ")" ::: "memory")
; #define PG8_WAIT_L(n) asm volatile("s_waitcnt lgkmcnt(" #n ")" ::: "memory")
; #define PG8_BAR __builtin_amdgcn_s_barrier()
; template <class Epi, bool ALIGN_EPI = true>
; __device__ __forceinline__ void gemm_phase(LAS unsigned char* lds, const Gemm g, const Sched& S, const Epi& E) {
;     ...
;         for (int t = t_lo; t < t_hi; t += 2) {
;             const bool last = (t == nt - 2);
;             const char* a1 = cA + (size_t)(t + 1) * kstep;
;             const char* a2 = last ? nA : cA + (size_t)(t + 2) * kstep; const char* b2 = last ? nB : cB + (size_t)(t + 2) * kstep;
;             const char* a3 = a2 + kstep; const char* b3 = b2 + kstep;
;             const int rflag = __builtin_amdgcn_readfirstlane(t | (int)(ui == 0));
;             PG8_LDB(B0, 0, 0); PG8_LDB(B1, 0, 1); PG8_SCHED; PG8_LDA(At, 0, 0); PG8_STAGE(PG8_SA(1, 1), a1 + hstepA, voffA);
;             if constexpr (Epi::NSTORES > 0) PG8_WAIT_RELAX(rflag, 8 + Epi::NSTORES); else PG8_WAIT_V(8);
;             PG8_WAIT_L(0); PG8_BAR; PG8_MMA(0, 0, At, B0); PG8_MMA(0, 1, At, B1); PG8_BAR; PG8_SCHED;
;             PG8_LDA(At, 0, 1); PG8_STAGE(PG8_SB(0, 0), b2, voffB); PG8_STAGE(PG8_SB(0, 1), b2 + hstepB, voffB); PG8_STAGE(PG8_SA(0, 0), a2, voffA);
.LBB0_1237:
	s_add_i32 s94, s24, 1
	s_lshl_b64 s[92:93], s[94:95], 7
	s_add_i32 s94, s24, 2
	s_lshl_b64 s[26:27], s[94:95], 7
	s_add_u32 s25, s56, s26
	s_addc_u32 s91, s57, s27
	s_add_u32 s96, s54, s26
	s_addc_u32 s97, s55, s27
	s_add_i32 vcc_lo, 0, 0x10000
	s_cmp_eq_u32 s85, s24
	s_cselect_b32 s27, s19, s91
	s_cselect_b32 s26, s87, s25
	s_cselect_b32 s25, s88, s97
	s_cselect_b32 s24, s89, s96
	s_add_i32 s91, 0, 0x14000
	ds_read_b128 v[134:137], v224
	ds_read_b128 v[138:141], v224 offset:1024
	ds_read_b128 v[142:145], v224 offset:2048
	ds_read_b128 v[146:149], v224 offset:3072
	ds_read_b128 v[150:153], v224 offset:16384
	ds_read_b128 v[154:157], v224 offset:17408
	ds_read_b128 v[158:161], v224 offset:18432
	ds_read_b128 v[162:165], v224 offset:19456
	s_add_u32 s92, s56, s92
	s_addc_u32 s93, s57, s93
	s_add_u32 s92, s92, 0x80000
	s_addc_u32 s93, s93, 0
	ds_read_b128 v[166:169], v225
	ds_read_b128 v[170:173], v225 offset:1024
	ds_read_b128 v[174:177], v225 offset:2048
	ds_read_b128 v[178:181], v225 offset:3072
	ds_read_b128 v[182:185], v225 offset:4096
	ds_read_b128 v[186:189], v225 offset:5120
	ds_read_b128 v[190:193], v225 offset:6144
	ds_read_b128 v[226:229], v225 offset:7168
	s_mov_b32 m0, s81
	s_add_u32 s100, s92, 0xfff80000
	s_addc_u32 s101, s93, -1
	global_load_lds_dwordx4 v208, s[100:101]
	s_mov_b32 m0, s82
	s_nop 0
	global_load_lds_dwordx4 v196, s[100:101]
	s_add_i32 m0, s36, 0xc000
	s_nop 0
	global_load_lds_dwordx4 v208, s[92:93]
	s_add_i32 m0, s36, 0xe000
	s_nop 0
	global_load_lds_dwordx4 v196, s[92:93]
	s_waitcnt vmcnt(8) lgkmcnt(0)
	s_barrier
	s_setprio 1
	v_mfma_f32_16x16x32_bf16 v[130:133], v[134:137], v[166:169], v[130:133]
	v_mfma_f32_16x16x32_bf16 v[126:129], v[142:145], v[166:169], v[126:129]
	v_mfma_f32_16x16x32_bf16 v[114:117], v[134:137], v[174:177], v[114:117]
	v_mfma_f32_16x16x32_bf16 v[110:113], v[142:145], v[174:177], v[110:113]
	v_mfma_f32_16x16x32_bf16 v[98:101], v[134:137], v[182:185], v[98:101]
	v_mfma_f32_16x16x32_bf16 v[94:97], v[142:145], v[182:185], v[94:97]
	v_mfma_f32_16x16x32_bf16 v[82:85], v[134:137], v[190:193], v[82:85]
	v_mfma_f32_16x16x32_bf16 v[78:81], v[142:145], v[190:193], v[78:81]
	v_mfma_f32_16x16x32_bf16 v[130:133], v[138:141], v[170:173], v[130:133]
	v_mfma_f32_16x16x32_bf16 v[126:129], v[146:149], v[170:173], v[126:129]
	v_mfma_f32_16x16x32_bf16 v[114:117], v[138:141], v[178:181], v[114:117]
	v_mfma_f32_16x16x32_bf16 v[110:113], v[146:149], v[178:181], v[110:113]
	v_mfma_f32_16x16x32_bf16 v[98:101], v[138:141], v[186:189], v[98:101]
	v_mfma_f32_16x16x32_bf16 v[94:97], v[146:149], v[186:189], v[94:97]
	v_mfma_f32_16x16x32_bf16 v[82:85], v[138:141], v[226:229], v[82:85]
	v_mfma_f32_16x16x32_bf16 v[78:81], v[146:149], v[226:229], v[78:81]
	s_setprio 0
	s_setprio 1
	v_mfma_f32_16x16x32_bf16 v[122:125], v[150:153], v[166:169], v[122:125]
	v_mfma_f32_16x16x32_bf16 v[118:121], v[158:161], v[166:169], v[118:121]
	v_mfma_f32_16x16x32_bf16 v[106:109], v[150:153], v[174:177], v[106:109]
	v_mfma_f32_16x16x32_bf16 v[102:105], v[158:161], v[174:177], v[102:105]
	v_mfma_f32_16x16x32_bf16 v[90:93], v[150:153], v[182:185], v[90:93]
	v_mfma_f32_16x16x32_bf16 v[86:89], v[158:161], v[182:185], v[86:89]
	v_mfma_f32_16x16x32_bf16 v[74:77], v[150:153], v[190:193], v[74:77]
	v_mfma_f32_16x16x32_bf16 v[70:73], v[158:161], v[190:193], v[70:73]
	v_mfma_f32_16x16x32_bf16 v[122:125], v[154:157], v[170:173], v[122:125]
	v_mfma_f32_16x16x32_bf16 v[118:121], v[162:165], v[170:173], v[118:121]
	v_mfma_f32_16x16x32_bf16 v[106:109], v[154:157], v[178:181], v[106:109]
	v_mfma_f32_16x16x32_bf16 v[102:105], v[162:165], v[178:181], v[102:105]
	v_mfma_f32_16x16x32_bf16 v[90:93], v[154:157], v[186:189], v[90:93]
	v_mfma_f32_16x16x32_bf16 v[86:89], v[162:165], v[186:189], v[86:89]
	v_mfma_f32_16x16x32_bf16 v[74:77], v[154:157], v[226:229], v[74:77]
	v_mfma_f32_16x16x32_bf16 v[70:73], v[162:165], v[226:229], v[70:73]
	s_setprio 0
	s_barrier
	s_add_i32 s92, vcc_lo, s35
	s_mov_b32 m0, s92
	ds_read_b128 v[166:169], v225 offset:16384
	ds_read_b128 v[170:173], v225 offset:17408
	ds_read_b128 v[174:177], v225 offset:18432
	ds_read_b128 v[178:181], v225 offset:19456
	ds_read_b128 v[182:185], v225 offset:20480
	ds_read_b128 v[186:189], v225 offset:21504
	ds_read_b128 v[190:193], v225 offset:22528
	ds_read_b128 v[226:229], v225 offset:23552
	global_load_lds_dwordx4 v206, s[24:25]
	s_add_i32 m0, s92, 0x2000
	s_add_u32 s92, s24, 0x80000
	s_addc_u32 s93, s25, 0
	s_add_i32 s91, s91, s35
	global_load_lds_dwordx4 v194, s[24:25]
	s_mov_b32 m0, s91
	s_nop 0
	global_load_lds_dwordx4 v206, s[92:93]
	s_add_i32 m0, s91, 0x2000
	s_nop 0
	global_load_lds_dwordx4 v194, s[92:93]
	s_waitcnt vmcnt(6) lgkmcnt(0)
	s_barrier
; #define PG8_STAGE(bufoff, gbase, voff) do { _Pragma("unroll") for (int _i = 0; _i < 2; ++_i) \
;         __builtin_amdgcn_global_load_lds((const unsigned*)((const char*)(gbase) + (voff)[_i]), (LAS unsigned*)(lds + (bufoff) + ldsw + _i * 8192), 16, 0, 0); } while (0)
; #define PG8_LDA(dst, b, h) do { _Pragma("unroll") for (int m = 0; m < 4; ++m) _Pragma("unroll") for (int k = 0; k < 2; ++k) dst[m][k] = *(const LAS bf16x8*)(lds + PG8_SA(b, h) + aoff + m * 2048 + k * 1024); } while (0)
; #define PG8_LDB(dst, b, h) do { _Pragma("unroll") for (int n = 0; n < 2; ++n) _Pragma("unroll") for (int k = 0; k < 2; ++k) dst[n][k] = *(const LAS bf16x8*)(lds + PG8_SB(b, h) + boff + n * 2048 + k * 1024); } while (0)
; #define PG8_MMA(ai, bj, At, Bt) do { __builtin_amdgcn_s_setprio(1); _Pragma("unroll") for (int m = 0; m < 4; ++m) _Pragma("unroll") for (int n = 0; n < 2; ++n) _Pragma("unroll") for (int k = 0; k < 2; ++k) \
;         acc[ai][bj][m][n] = __builtin_amdgcn_mfma_f32_16x16x32_bf16(Bt[n][k], At[m][k], acc[ai][bj][m][n], 0, 0, 0); __builtin_amdgcn_s_setprio(0); } while (0)
; #define PG8_WAIT_V(n) asm volatile("s_waitcnt vmcnt(" #n ")" ::: "memory")
; #define PG8_WAIT_L(n) asm volatile("s_waitcnt lgkmcnt(" #n ")" ::: "memory")
; #define PG8_BAR __builtin_amdgcn_s_barrier()
; #define PG8_WAIT_RELAX(flag, n) asm volatile("s_cmp_eq_u32 %0, 0\n\ts_cbranch_scc1 .Lrw%=\n\ts_waitcnt vmcnt(8)\n.Lrw%=:\n\ts_waitcnt vmcnt(%1)" :: "s"(flag), "n"(n) : "scc", "memory")
; #define PG8_SCHED __builtin_amdgcn_sched_barrier(0)
; template <class Epi, bool ALIGN_EPI = true>
; __device__ __forceinline__ void gemm_phase(LAS unsigned char* lds, const Gemm g, const Sched& S, const Epi& E) {
;     ...
;             if constexpr (Epi::NSTORES > 0) PG8_WAIT_RELAX(rflag, 8 + Epi::NSTORES); else PG8_WAIT_V(8);
;             PG8_WAIT_L(0); PG8_BAR; PG8_MMA(1, 0, At, B0); PG8_MMA(1, 1, At, B1); PG8_BAR; PG8_SCHED;
;             PG8_LDB(B0, 1, 0); PG8_LDB(B1, 1, 1); PG8_SCHED; PG8_LDA(At, 1, 0); PG8_STAGE(PG8_SA(0, 1), a2 + hstepA, voffA);
;             PG8_WAIT_V(8); PG8_WAIT_L(0); PG8_BAR; PG8_MMA(0, 0, At, B0); PG8_MMA(0, 1, At, B1); PG8_BAR; PG8_SCHED;
	s_setprio 1
	v_mfma_f32_16x16x32_bf16 v[66:69], v[134:137], v[166:169], v[66:69]
	v_mfma_f32_16x16x32_bf16 v[62:65], v[142:145], v[166:169], v[62:65]
	v_mfma_f32_16x16x32_bf16 v[50:53], v[134:137], v[174:177], v[50:53]
	v_mfma_f32_16x16x32_bf16 v[46:49], v[142:145], v[174:177], v[46:49]
	v_mfma_f32_16x16x32_bf16 v[34:37], v[134:137], v[182:185], v[34:37]
	v_mfma_f32_16x16x32_bf16 v[30:33], v[142:145], v[182:185], v[30:33]
	v_mfma_f32_16x16x32_bf16 v[18:21], v[134:137], v[190:193], v[18:21]
	v_mfma_f32_16x16x32_bf16 v[14:17], v[142:145], v[190:193], v[14:17]
	v_mfma_f32_16x16x32_bf16 v[66:69], v[138:141], v[170:173], v[66:69]
	v_mfma_f32_16x16x32_bf16 v[62:65], v[146:149], v[170:173], v[62:65]
	v_mfma_f32_16x16x32_bf16 v[50:53], v[138:141], v[178:181], v[50:53]
	v_mfma_f32_16x16x32_bf16 v[46:49], v[146:149], v[178:181], v[46:49]
	v_mfma_f32_16x16x32_bf16 v[34:37], v[138:141], v[186:189], v[34:37]
	v_mfma_f32_16x16x32_bf16 v[30:33], v[146:149], v[186:189], v[30:33]
	v_mfma_f32_16x16x32_bf16 v[18:21], v[138:141], v[226:229], v[18:21]
	v_mfma_f32_16x16x32_bf16 v[14:17], v[146:149], v[226:229], v[14:17]
	s_setprio 0
	s_setprio 1
	v_mfma_f32_16x16x32_bf16 v[58:61], v[150:153], v[166:169], v[58:61]
	v_mfma_f32_16x16x32_bf16 v[54:57], v[158:161], v[166:169], v[54:57]
	v_mfma_f32_16x16x32_bf16 v[42:45], v[150:153], v[174:177], v[42:45]
	v_mfma_f32_16x16x32_bf16 v[38:41], v[158:161], v[174:177], v[38:41]
	v_mfma_f32_16x16x32_bf16 v[26:29], v[150:153], v[182:185], v[26:29]
	v_mfma_f32_16x16x32_bf16 v[22:25], v[158:161], v[182:185], v[22:25]
	v_mfma_f32_16x16x32_bf16 v[10:13], v[150:153], v[190:193], v[10:13]
	v_mfma_f32_16x16x32_bf16 v[4:7], v[158:161], v[190:193], v[6:9]
	v_mfma_f32_16x16x32_bf16 v[58:61], v[154:157], v[170:173], v[58:61]
	v_mfma_f32_16x16x32_bf16 v[54:57], v[162:165], v[170:173], v[54:57]
	v_mfma_f32_16x16x32_bf16 v[42:45], v[154:157], v[178:181], v[42:45]
	v_mfma_f32_16x16x32_bf16 v[38:41], v[162:165], v[178:181], v[38:41]
	v_mfma_f32_16x16x32_bf16 v[26:29], v[154:157], v[186:189], v[26:29]
	v_mfma_f32_16x16x32_bf16 v[22:25], v[162:165], v[186:189], v[22:25]
	v_mfma_f32_16x16x32_bf16 v[10:13], v[154:157], v[226:229], v[10:13]
	v_mfma_f32_16x16x32_bf16 v[4:7], v[162:165], v[226:229], v[4:7]
	s_setprio 0
	s_barrier
	s_add_i32 s91, 0, 0x18000
	s_add_i32 s92, 0, 0x1c000
	ds_read_b128 v[134:137], v224 offset:32768
	ds_read_b128 v[138:141], v224 offset:33792
	ds_read_b128 v[142:145], v224 offset:34816
	ds_read_b128 v[146:149], v224 offset:35840
	ds_read_b128 v[150:153], v224 offset:49152
	ds_read_b128 v[154:157], v224 offset:50176
	ds_read_b128 v[158:161], v224 offset:51200
	ds_read_b128 v[162:165], v224 offset:52224
	s_add_u32 s26, s26, 0x80000
	s_addc_u32 s27, s27, 0
	ds_read_b128 v[166:169], v225 offset:32768
	ds_read_b128 v[170:173], v225 offset:33792
	ds_read_b128 v[174:177], v225 offset:34816
	ds_read_b128 v[178:181], v225 offset:35840
	ds_read_b128 v[182:185], v225 offset:36864
	ds_read_b128 v[186:189], v225 offset:37888
	ds_read_b128 v[190:193], v225 offset:38912
	ds_read_b128 v[226:229], v225 offset:39936
	s_mov_b32 m0, s36
	s_add_u32 s100, s26, 0xfff80000
	s_addc_u32 s101, s27, -1
	global_load_lds_dwordx4 v208, s[100:101]
	s_mov_b32 m0, s37
	s_nop 0
	global_load_lds_dwordx4 v196, s[100:101]
	s_mov_b32 m0, s76
	s_nop 0
	global_load_lds_dwordx4 v208, s[26:27]
	s_mov_b32 m0, s77
	s_nop 0
	global_load_lds_dwordx4 v196, s[26:27]
	s_waitcnt vmcnt(8) lgkmcnt(0)
	s_barrier
; #define PG8_STAGE(bufoff, gbase, voff) do { _Pragma("unroll") for (int _i = 0; _i < 2; ++_i) \
;         __builtin_amdgcn_global_load_lds((const unsigned*)((const char*)(gbase) + (voff)[_i]), (LAS unsigned*)(lds + (bufoff) + ldsw + _i * 8192), 16, 0, 0); } while (0)
; #define PG8_LDA(dst, b, h) do { _Pragma("unroll") for (int m = 0; m < 4; ++m) _Pragma("unroll") for (int k = 0; k < 2; ++k) dst[m][k] = *(const LAS bf16x8*)(lds + PG8_SA(b, h) + aoff + m * 2048 + k * 1024); } while (0)
; #define PG8_MMA(ai, bj, At, Bt) do { __builtin_amdgcn_s_setprio(1); _Pragma("unroll") for (int m = 0; m < 4; ++m) _Pragma("unroll") for (int n = 0; n < 2; ++n) _Pragma("unroll") for (int k = 0; k < 2; ++k) \
;         acc[ai][bj][m][n] = __builtin_amdgcn_mfma_f32_16x16x32_bf16(Bt[n][k], At[m][k], acc[ai][bj][m][n], 0, 0, 0); __builtin_amdgcn_s_setprio(0); } while (0)
; #define PG8_WAIT_V(n) asm volatile("s_waitcnt vmcnt(" #n ")" ::: "memory")
; #define PG8_WAIT_L(n) asm volatile("s_waitcnt lgkmcnt(" #n ")" ::: "memory")
; #define PG8_BAR __builtin_amdgcn_s_barrier()
; #define PG8_SCHED __builtin_amdgcn_sched_barrier(0)
; template <class Epi, bool ALIGN_EPI = true>
; __device__ __forceinline__ void gemm_phase(LAS unsigned char* lds, const Gemm g, const Sched& S, const Epi& E) {
;     ...
;             PG8_WAIT_V(8); PG8_WAIT_L(0); PG8_BAR; PG8_MMA(0, 0, At, B0); PG8_MMA(0, 1, At, B1); PG8_BAR; PG8_SCHED;
;             PG8_LDA(At, 1, 1); PG8_STAGE(PG8_SB(1, 0), b3, voffB); PG8_STAGE(PG8_SB(1, 1), b3 + hstepB, voffB); PG8_STAGE(PG8_SA(1, 0), a3, voffA);
;             PG8_WAIT_V(8); PG8_WAIT_L(0); PG8_BAR; PG8_MMA(1, 0, At, B0); PG8_MMA(1, 1, At, B1); PG8_BAR; PG8_SCHED;
;         }
	s_setprio 1
	v_mfma_f32_16x16x32_bf16 v[130:133], v[134:137], v[166:169], v[130:133]
	v_mfma_f32_16x16x32_bf16 v[126:129], v[142:145], v[166:169], v[126:129]
	v_mfma_f32_16x16x32_bf16 v[114:117], v[134:137], v[174:177], v[114:117]
	v_mfma_f32_16x16x32_bf16 v[110:113], v[142:145], v[174:177], v[110:113]
	v_mfma_f32_16x16x32_bf16 v[98:101], v[134:137], v[182:185], v[98:101]
	v_mfma_f32_16x16x32_bf16 v[94:97], v[142:145], v[182:185], v[94:97]
	v_mfma_f32_16x16x32_bf16 v[82:85], v[134:137], v[190:193], v[82:85]
	v_mfma_f32_16x16x32_bf16 v[78:81], v[142:145], v[190:193], v[78:81]
	v_mfma_f32_16x16x32_bf16 v[130:133], v[138:141], v[170:173], v[130:133]
	v_mfma_f32_16x16x32_bf16 v[126:129], v[146:149], v[170:173], v[126:129]
	v_mfma_f32_16x16x32_bf16 v[114:117], v[138:141], v[178:181], v[114:117]
	v_mfma_f32_16x16x32_bf16 v[110:113], v[146:149], v[178:181], v[110:113]
	v_mfma_f32_16x16x32_bf16 v[98:101], v[138:141], v[186:189], v[98:101]
	v_mfma_f32_16x16x32_bf16 v[94:97], v[146:149], v[186:189], v[94:97]
	v_mfma_f32_16x16x32_bf16 v[82:85], v[138:141], v[226:229], v[82:85]
	v_mfma_f32_16x16x32_bf16 v[78:81], v[146:149], v[226:229], v[78:81]
	s_setprio 0
	s_setprio 1
	v_mfma_f32_16x16x32_bf16 v[122:125], v[150:153], v[166:169], v[122:125]
	v_mfma_f32_16x16x32_bf16 v[118:121], v[158:161], v[166:169], v[118:121]
	v_mfma_f32_16x16x32_bf16 v[106:109], v[150:153], v[174:177], v[106:109]
	v_mfma_f32_16x16x32_bf16 v[102:105], v[158:161], v[174:177], v[102:105]
	v_mfma_f32_16x16x32_bf16 v[90:93], v[150:153], v[182:185], v[90:93]
	v_mfma_f32_16x16x32_bf16 v[86:89], v[158:161], v[182:185], v[86:89]
	v_mfma_f32_16x16x32_bf16 v[74:77], v[150:153], v[190:193], v[74:77]
	v_mfma_f32_16x16x32_bf16 v[70:73], v[158:161], v[190:193], v[70:73]
	v_mfma_f32_16x16x32_bf16 v[122:125], v[154:157], v[170:173], v[122:125]
	v_mfma_f32_16x16x32_bf16 v[118:121], v[162:165], v[170:173], v[118:121]
	v_mfma_f32_16x16x32_bf16 v[106:109], v[154:157], v[178:181], v[106:109]
	v_mfma_f32_16x16x32_bf16 v[102:105], v[162:165], v[178:181], v[102:105]
	v_mfma_f32_16x16x32_bf16 v[90:93], v[154:157], v[186:189], v[90:93]
	v_mfma_f32_16x16x32_bf16 v[86:89], v[162:165], v[186:189], v[86:89]
	v_mfma_f32_16x16x32_bf16 v[74:77], v[154:157], v[226:229], v[74:77]
	v_mfma_f32_16x16x32_bf16 v[70:73], v[162:165], v[226:229], v[70:73]
	s_setprio 0
	s_barrier
	s_add_u32 s100, s24, 0x80
	s_addc_u32 s101, s25, 0
	s_add_i32 s26, s91, s35
	s_mov_b32 m0, s26
	ds_read_b128 v[166:169], v225 offset:49152
	ds_read_b128 v[170:173], v225 offset:50176
	ds_read_b128 v[174:177], v225 offset:51200
	ds_read_b128 v[178:181], v225 offset:52224
	ds_read_b128 v[182:185], v225 offset:53248
	ds_read_b128 v[186:189], v225 offset:54272
	ds_read_b128 v[190:193], v225 offset:55296
	ds_read_b128 v[226:229], v225 offset:56320
	global_load_lds_dwordx4 v206, s[100:101]
	s_add_i32 m0, s26, 0x2000
	s_add_u32 s24, s24, 0x80080
	s_addc_u32 s25, s25, 0
	s_add_i32 s26, s92, s35
	global_load_lds_dwordx4 v194, s[100:101]
	s_mov_b32 m0, s26
	s_nop 0
	global_load_lds_dwordx4 v206, s[24:25]
	s_add_i32 m0, s26, 0x2000
	s_nop 0
	global_load_lds_dwordx4 v194, s[24:25]
	s_waitcnt vmcnt(6) lgkmcnt(0)
	s_barrier
	s_setprio 1
	v_mfma_f32_16x16x32_bf16 v[66:69], v[134:137], v[166:169], v[66:69]
	v_mfma_f32_16x16x32_bf16 v[62:65], v[142:145], v[166:169], v[62:65]
	v_mfma_f32_16x16x32_bf16 v[50:53], v[134:137], v[174:177], v[50:53]
	v_mfma_f32_16x16x32_bf16 v[46:49], v[142:145], v[174:177], v[46:49]
	v_mfma_f32_16x16x32_bf16 v[34:37], v[134:137], v[182:185], v[34:37]
	v_mfma_f32_16x16x32_bf16 v[30:33], v[142:145], v[182:185], v[30:33]
	v_mfma_f32_16x16x32_bf16 v[18:21], v[134:137], v[190:193], v[18:21]
	v_mfma_f32_16x16x32_bf16 v[14:17], v[142:145], v[190:193], v[14:17]
	v_mfma_f32_16x16x32_bf16 v[66:69], v[138:141], v[170:173], v[66:69]
	v_mfma_f32_16x16x32_bf16 v[62:65], v[146:149], v[170:173], v[62:65]
	v_mfma_f32_16x16x32_bf16 v[50:53], v[138:141], v[178:181], v[50:53]
	v_mfma_f32_16x16x32_bf16 v[46:49], v[146:149], v[178:181], v[46:49]
	v_mfma_f32_16x16x32_bf16 v[34:37], v[138:141], v[186:189], v[34:37]
	v_mfma_f32_16x16x32_bf16 v[30:33], v[146:149], v[186:189], v[30:33]
	v_mfma_f32_16x16x32_bf16 v[18:21], v[138:141], v[226:229], v[18:21]
	v_mfma_f32_16x16x32_bf16 v[14:17], v[146:149], v[226:229], v[14:17]
	s_setprio 0
	s_setprio 1
	v_mfma_f32_16x16x32_bf16 v[58:61], v[150:153], v[166:169], v[58:61]
	v_mfma_f32_16x16x32_bf16 v[54:57], v[158:161], v[166:169], v[54:57]
	v_mfma_f32_16x16x32_bf16 v[42:45], v[150:153], v[174:177], v[42:45]
	v_mfma_f32_16x16x32_bf16 v[38:41], v[158:161], v[174:177], v[38:41]
	v_mfma_f32_16x16x32_bf16 v[26:29], v[150:153], v[182:185], v[26:29]
	v_mfma_f32_16x16x32_bf16 v[22:25], v[158:161], v[182:185], v[22:25]
	v_mfma_f32_16x16x32_bf16 v[8:11], v[150:153], v[190:193], v[10:13]
	v_mfma_f32_16x16x32_bf16 v[4:7], v[158:161], v[190:193], v[4:7]
	v_mfma_f32_16x16x32_bf16 v[58:61], v[154:157], v[170:173], v[58:61]
	v_mfma_f32_16x16x32_bf16 v[54:57], v[162:165], v[170:173], v[54:57]
	v_mfma_f32_16x16x32_bf16 v[42:45], v[154:157], v[178:181], v[42:45]
	v_mfma_f32_16x16x32_bf16 v[38:41], v[162:165], v[178:181], v[38:41]
	v_mfma_f32_16x16x32_bf16 v[26:29], v[154:157], v[186:189], v[26:29]
	v_mfma_f32_16x16x32_bf16 v[22:25], v[162:165], v[186:189], v[22:25]
	v_mfma_f32_16x16x32_bf16 v[10:13], v[154:157], v[226:229], v[8:11]
	v_mfma_f32_16x16x32_bf16 v[6:9], v[162:165], v[226:229], v[4:7]
	s_setprio 0
	s_barrier
	s_cmp_ge_i32 s94, s90
	s_mov_b32 s24, s94
	s_cbranch_scc0 .LBB0_1237
	s_branch .LBB0_1232

; #define PG8_STAGE(bufoff, gbase, voff) do { _Pragma("unroll") for (int _i = 0; _i < 2; ++_i) \
;         __builtin_amdgcn_global_load_lds((const unsigned*)((const char*)(gbase) + (voff)[_i]), (LAS unsigned*)(lds + (bufoff) + ldsw + _i * 8192), 16, 0, 0); } while (0)
; #define PG8_WAIT_V(n) asm volatile("s_waitcnt vmcnt(" #n ")" ::: "memory")
; #define PG8_BAR __builtin_amdgcn_s_barrier()
; template <class Epi, bool ALIGN_EPI = true>
; __device__ __forceinline__ void gemm_phase(LAS unsigned char* lds, const Gemm g, const Sched& S, const Epi& E) {
;     ...
;     for (int i = 0; i < 2; ++i) { int R, C; stage_rc(tid * 16 + i * 8192, R, C); const int Rb = (R & ~31) + perm32(R & 31);
;         voffA[i] = (unsigned)(R * g.lda + C) * 2u; voffB[i] = (unsigned)(Rb * g.ldb + C) * 2u; }
;     const size_t kstep = (size_t)(BK * 2);
;     const size_t hstepA = (size_t)HALF * g.lda * 2, hstepB = (size_t)HALF * g.ldb * 2;
;     const unsigned ldsw = (unsigned)wid * 1024u;
;     const int aoff = lds_byte(wr * 64 + fr, fq * 8), boff = lds_byte(wc * 32 + fr, fq * 8);
;     ...
;     f32x4 acc[2][2][4][2];
; #pragma unroll
;     for (int a = 0; a < 2; ++a)
; #pragma unroll
;         for (int b = 0; b < 2; ++b)
; #pragma unroll
;             for (int m = 0; m < 4; ++m)
; #pragma unroll
;                 for (int n = 0; n < 2; ++n) acc[a][b][m][n] = (f32x4){0.f, 0.f, 0.f, 0.f};
;     bf16x8 At[4][2], B0[2][2], B1[2][2];
;     const char* cA = (const char*)g.A + cur.aoff; const char* cB = (const char*)g.Bt + cur.boff;
;     PG8_STAGE(PG8_SB(0, 0), cB, voffB); PG8_STAGE(PG8_SB(0, 1), cB + hstepB, voffB); PG8_STAGE(PG8_SA(0, 0), cA, voffA); PG8_STAGE(PG8_SA(0, 1), cA + hstepA, voffA);
;     if (wr == 1) PG8_BAR;
;     PG8_WAIT_V(2); PG8_BAR;
;     PG8_STAGE(PG8_SB(1, 0), cB + kstep, voffB); PG8_STAGE(PG8_SA(1, 0), cA + kstep, voffA); PG8_STAGE(PG8_SB(1, 1), cB + hstepB + kstep, voffB);
;     PG8_WAIT_V(6); PG8_BAR;
.LBB0_1300:
	s_ashr_i32 s19, s18, 31
	s_lshr_b32 s19, s19, 26
	s_and_b32 s5, s5, 3
	s_add_i32 s19, s18, s19
	s_add_i32 m0, s52, 0x18000
	v_lshl_add_u64 v[10:11], v[10:11], 0, s[8:9]
	s_ashr_i32 s56, s19, 6
	s_lshl_b32 s31, s4, 6
	s_lshl_b32 s4, s4, 13
	s_lshl_b32 s19, s5, 12
	s_waitcnt vmcnt(2)
	s_barrier
	global_load_lds_dwordx4 v[10:11], off
	v_lshl_add_u64 v[8:9], v[8:9], 0, s[8:9]
	s_add_i32 m0, s52, 0x1a000
	s_add_i32 s57, s52, 0x8000
	s_add_i32 s58, s52, 0xa000
	global_load_lds_dwordx4 v[8:9], off
	v_lshl_add_u64 v[6:7], v[6:7], 0, s[8:9]
	s_mov_b32 m0, s57
	s_add_u32 s20, s14, 0x80080
	global_load_lds_dwordx4 v[6:7], off
	v_lshl_add_u64 v[4:5], v[4:5], 0, s[8:9]
	s_mov_b32 m0, s58
	s_addc_u32 s21, s15, 0
	global_load_lds_dwordx4 v[4:5], off
	s_add_i32 m0, s52, 0x1c000
	v_lshl_add_u64 v[4:5], s[20:21], 0, v[138:139]
	global_load_lds_dwordx4 v[4:5], off
	v_lshl_add_u64 v[4:5], s[20:21], 0, v[134:135]
	s_add_i32 m0, s52, 0x1e000
	s_movk_i32 s10, 0x3c0
	global_load_lds_dwordx4 v[4:5], off
	v_and_b32_e32 v4, 48, v146
	v_lshlrev_b32_e32 v5, 6, v146
	v_and_or_b32 v4, v5, s10, v4
	v_lshlrev_b32_e32 v5, 2, v146
	v_and_b32_e32 v5, 32, v5
	v_bitop3_b32 v6, v4, s4, v5 bitop3:0xde
	v_bitop3_b32 v147, v4, s19, v5 bitop3:0xde
	v_add_u32_e32 v147, 0x10000, v147
	v_lshlrev_b32_e32 v4, 15, v15
	v_and_b32_e32 v4, 0xffff0000, v4
	v_lshl_add_u32 v4, v14, 12, v4
	v_and_b32_e32 v5, 1, v15
	v_lshl_or_b32 v4, v5, 6, v4
	v_lshl_add_u32 v142, v16, 1, v4
	v_lshlrev_b32_e32 v4, 15, v2
	v_and_b32_e32 v4, 0xffff0000, v4
	v_lshl_add_u32 v4, v12, 12, v4
	v_and_b32_e32 v2, 1, v2
	v_readlane_b32 s20, v243, 43
	s_waitcnt vmcnt(6)
	v_lshl_or_b32 v2, v2, 6, v4
	v_mov_b32_e32 v4, v3
	v_mov_b32_e32 v5, v3
	v_readlane_b32 s21, v243, 44
	s_cmp_gt_i32 s18, 63
	v_lshl_add_u32 v144, v13, 1, v2
	v_mov_b32_e32 v2, v3
	v_add_u32_e32 v148, 0, v6
	v_mov_b64_e32 v[8:9], v[4:5]
	v_mov_b64_e32 v[12:13], v[4:5]
	v_mov_b64_e32 v[24:25], v[4:5]
	v_mov_b64_e32 v[28:29], v[4:5]
	v_mov_b64_e32 v[40:41], v[4:5]
	v_mov_b64_e32 v[44:45], v[4:5]
	v_mov_b64_e32 v[56:57], v[4:5]
	v_mov_b64_e32 v[60:61], v[4:5]
	v_mov_b64_e32 v[16:17], v[4:5]
	v_mov_b64_e32 v[20:21], v[4:5]
	v_mov_b64_e32 v[32:33], v[4:5]
	v_mov_b64_e32 v[36:37], v[4:5]
	v_mov_b64_e32 v[48:49], v[4:5]
	v_mov_b64_e32 v[52:53], v[4:5]
	v_mov_b64_e32 v[64:65], v[4:5]
	v_mov_b64_e32 v[68:69], v[4:5]
	v_mov_b64_e32 v[72:73], v[4:5]
	v_mov_b64_e32 v[76:77], v[4:5]
	v_mov_b64_e32 v[88:89], v[4:5]
	v_mov_b64_e32 v[92:93], v[4:5]
	v_mov_b64_e32 v[104:105], v[4:5]
	v_mov_b64_e32 v[108:109], v[4:5]
	v_mov_b64_e32 v[120:121], v[4:5]
	v_mov_b64_e32 v[124:125], v[4:5]
	v_mov_b64_e32 v[80:81], v[4:5]
	v_mov_b64_e32 v[84:85], v[4:5]
	v_mov_b64_e32 v[96:97], v[4:5]
	v_mov_b64_e32 v[100:101], v[4:5]
	v_mov_b64_e32 v[112:113], v[4:5]
	v_mov_b64_e32 v[116:117], v[4:5]
	v_mov_b64_e32 v[128:129], v[4:5]
	v_mov_b64_e32 v[132:133], v[4:5]
	s_mov_b32 s4, s20
	v_readlane_b32 s20, v243, 39
	s_cselect_b64 s[18:19], -1, 0
	s_add_i32 s59, s56, -2
	v_mov_b32_e32 v143, v3
	v_mov_b32_e32 v145, v3
	s_mov_b32 s60, 0
	v_mov_b64_e32 v[6:7], v[2:3]
	v_mov_b64_e32 v[10:11], v[2:3]
	v_mov_b64_e32 v[22:23], v[2:3]
	v_mov_b64_e32 v[26:27], v[2:3]
	v_mov_b64_e32 v[38:39], v[2:3]
	v_mov_b64_e32 v[42:43], v[2:3]
	v_mov_b64_e32 v[54:55], v[2:3]
	v_mov_b64_e32 v[58:59], v[2:3]
	v_mov_b64_e32 v[14:15], v[2:3]
	v_mov_b64_e32 v[18:19], v[2:3]
	v_mov_b64_e32 v[30:31], v[2:3]
	v_mov_b64_e32 v[34:35], v[2:3]
	v_mov_b64_e32 v[46:47], v[2:3]
	v_mov_b64_e32 v[50:51], v[2:3]
	v_mov_b64_e32 v[62:63], v[2:3]
	v_mov_b64_e32 v[66:67], v[2:3]
	v_mov_b64_e32 v[70:71], v[2:3]
	v_mov_b64_e32 v[74:75], v[2:3]
	v_mov_b64_e32 v[86:87], v[2:3]
	v_mov_b64_e32 v[90:91], v[2:3]
	v_mov_b64_e32 v[102:103], v[2:3]
	v_mov_b64_e32 v[106:107], v[2:3]
	v_mov_b64_e32 v[118:119], v[2:3]
	v_mov_b64_e32 v[122:123], v[2:3]
	v_mov_b64_e32 v[78:79], v[2:3]
	v_mov_b64_e32 v[82:83], v[2:3]
	v_mov_b64_e32 v[94:95], v[2:3]
	v_mov_b64_e32 v[98:99], v[2:3]
	v_mov_b64_e32 v[110:111], v[2:3]
	v_mov_b64_e32 v[114:115], v[2:3]
	v_mov_b64_e32 v[126:127], v[2:3]
	v_mov_b64_e32 v[130:131], v[2:3]
	s_mov_b32 s61, s20
	s_barrier
	v_readlane_b32 s21, v243, 40
	s_branch .LBB0_1302

; #define PG8_STAGE(bufoff, gbase, voff) do { _Pragma("unroll") for (int _i = 0; _i < 2; ++_i) \
;         __builtin_amdgcn_global_load_lds((const unsigned*)((const char*)(gbase) + (voff)[_i]), (LAS unsigned*)(lds + (bufoff) + ldsw + _i * 8192), 16, 0, 0); } while (0)
; #define PG8_LDA(dst, b, h) do { _Pragma("unroll") for (int m = 0; m < 4; ++m) _Pragma("unroll") for (int k = 0; k < 2; ++k) dst[m][k] = *(const LAS bf16x8*)(lds + PG8_SA(b, h) + aoff + m * 2048 + k * 1024); } while (0)
; #define PG8_LDB(dst, b, h) do { _Pragma("unroll") for (int n = 0; n < 2; ++n) _Pragma("unroll") for (int k = 0; k < 2; ++k) dst[n][k] = *(const LAS bf16x8*)(lds + PG8_SB(b, h) + boff + n * 2048 + k * 1024); } while (0)
; #define PG8_MMA(ai, bj, At, Bt) do { __builtin_amdgcn_s_setprio(1); _Pragma("unroll") for (int m = 0; m < 4; ++m) _Pragma("unroll") for (int n = 0; n < 2; ++n) _Pragma("unroll") for (int k = 0; k < 2; ++k) \
;         acc[ai][bj][m][n] = __builtin_amdgcn_mfma_f32_16x16x32_bf16(Bt[n][k], At[m][k], acc[ai][bj][m][n], 0, 0, 0); __builtin_amdgcn_s_setprio(0); } while (0)
; template <class Epi, bool ALIGN_EPI = true>
; __device__ __forceinline__ void gemm_phase(LAS unsigned char* lds, const Gemm g, const Sched& S, const Epi& E) {
;     ...
;         for (int t = t_lo; t < t_hi; t += 2) {
;             const bool last = (t == nt - 2);
;             const char* a1 = cA + (size_t)(t + 1) * kstep;
;             const char* a2 = last ? nA : cA + (size_t)(t + 2) * kstep; const char* b2 = last ? nB : cB + (size_t)(t + 2) * kstep;
;             const char* a3 = a2 + kstep; const char* b3 = b2 + kstep;
;             const int rflag = __builtin_amdgcn_readfirstlane(t | (int)(ui == 0));
;             PG8_LDB(B0, 0, 0); PG8_LDB(B1, 0, 1); PG8_SCHED; PG8_LDA(At, 0, 0); PG8_STAGE(PG8_SA(1, 1), a1 + hstepA, voffA);
;             if constexpr (Epi::NSTORES > 0) PG8_WAIT_RELAX(rflag, 8 + Epi::NSTORES); else PG8_WAIT_V(8);
;             PG8_WAIT_L(0); PG8_BAR; PG8_MMA(0, 0, At, B0); PG8_MMA(0, 1, At, B1); PG8_BAR; PG8_SCHED;
;             PG8_LDA(At, 0, 1); PG8_STAGE(PG8_SB(0, 0), b2, voffB); PG8_STAGE(PG8_SB(0, 1), b2 + hstepB, voffB); PG8_STAGE(PG8_SA(0, 0), a2, voffA);
;             if constexpr (Epi::NSTORES > 0) PG8_WAIT_RELAX(rflag, 8 + Epi::NSTORES); else PG8_WAIT_V(8);
;             PG8_WAIT_L(0); PG8_BAR; PG8_MMA(1, 0, At, B0); PG8_MMA(1, 1, At, B1); PG8_BAR; PG8_SCHED;
.LBB0_1311:
	s_add_i32 s67, s48, 2
	s_add_u32 s49, s46, 0xfff80080
	s_addc_u32 s50, s47, -1
	s_add_i32 s68, 0, 0x10000
	s_cmp_eq_u32 s59, s48
	s_cselect_b32 s51, s21, s50
	s_cselect_b32 s50, s23, s49
	s_cselect_b32 s49, s63, s66
	s_cselect_b32 s48, s64, s65
	s_add_i32 s70, 0, 0x14000
	ds_read_b128 v[150:153], v147
	ds_read_b128 v[154:157], v147 offset:1024
	ds_read_b128 v[158:161], v147 offset:2048
	ds_read_b128 v[162:165], v147 offset:3072
	ds_read_b128 v[166:169], v147 offset:16384
	ds_read_b128 v[170:173], v147 offset:17408
	ds_read_b128 v[174:177], v147 offset:18432
	ds_read_b128 v[178:181], v147 offset:19456
	ds_read_b128 v[182:185], v148
	ds_read_b128 v[186:189], v148 offset:1024
	ds_read_b128 v[190:193], v148 offset:2048
	ds_read_b128 v[194:197], v148 offset:3072
	ds_read_b128 v[206:209], v148 offset:4096
	ds_read_b128 v[224:227], v148 offset:5120
	ds_read_b128 v[228:231], v148 offset:6144
	ds_read_b128 v[232:235], v148 offset:7168
	s_mov_b32 m0, s57
	s_add_u32 s100, s46, 0xfff80000
	s_addc_u32 s101, s47, -1
	global_load_lds_dwordx4 v142, s[100:101]
	s_mov_b32 m0, s58
	s_nop 0
	global_load_lds_dwordx4 v144, s[100:101]
	s_add_i32 m0, s52, 0xc000
	s_nop 0
	global_load_lds_dwordx4 v142, s[46:47]
	s_add_i32 m0, s52, 0xe000
	s_nop 0
	global_load_lds_dwordx4 v144, s[46:47]
	s_waitcnt vmcnt(8) lgkmcnt(0)
	s_barrier
	s_setprio 1
	v_mfma_f32_16x16x32_bf16 v[130:133], v[150:153], v[182:185], v[130:133]
	v_mfma_f32_16x16x32_bf16 v[126:129], v[158:161], v[182:185], v[126:129]
	v_mfma_f32_16x16x32_bf16 v[114:117], v[150:153], v[190:193], v[114:117]
	v_mfma_f32_16x16x32_bf16 v[110:113], v[158:161], v[190:193], v[110:113]
	v_mfma_f32_16x16x32_bf16 v[98:101], v[150:153], v[206:209], v[98:101]
	v_mfma_f32_16x16x32_bf16 v[94:97], v[158:161], v[206:209], v[94:97]
	v_mfma_f32_16x16x32_bf16 v[82:85], v[150:153], v[228:231], v[82:85]
	v_mfma_f32_16x16x32_bf16 v[78:81], v[158:161], v[228:231], v[78:81]
	v_mfma_f32_16x16x32_bf16 v[130:133], v[154:157], v[186:189], v[130:133]
	v_mfma_f32_16x16x32_bf16 v[126:129], v[162:165], v[186:189], v[126:129]
	v_mfma_f32_16x16x32_bf16 v[114:117], v[154:157], v[194:197], v[114:117]
	v_mfma_f32_16x16x32_bf16 v[110:113], v[162:165], v[194:197], v[110:113]
	v_mfma_f32_16x16x32_bf16 v[98:101], v[154:157], v[224:227], v[98:101]
	v_mfma_f32_16x16x32_bf16 v[94:97], v[162:165], v[224:227], v[94:97]
	v_mfma_f32_16x16x32_bf16 v[82:85], v[154:157], v[232:235], v[82:85]
	v_mfma_f32_16x16x32_bf16 v[78:81], v[162:165], v[232:235], v[78:81]
	s_setprio 0
	s_setprio 1
	v_mfma_f32_16x16x32_bf16 v[122:125], v[166:169], v[182:185], v[122:125]
	v_mfma_f32_16x16x32_bf16 v[118:121], v[174:177], v[182:185], v[118:121]
	v_mfma_f32_16x16x32_bf16 v[106:109], v[166:169], v[190:193], v[106:109]
	v_mfma_f32_16x16x32_bf16 v[102:105], v[174:177], v[190:193], v[102:105]
	v_mfma_f32_16x16x32_bf16 v[90:93], v[166:169], v[206:209], v[90:93]
	v_mfma_f32_16x16x32_bf16 v[86:89], v[174:177], v[206:209], v[86:89]
	v_mfma_f32_16x16x32_bf16 v[74:77], v[166:169], v[228:231], v[74:77]
	v_mfma_f32_16x16x32_bf16 v[70:73], v[174:177], v[228:231], v[70:73]
	v_mfma_f32_16x16x32_bf16 v[122:125], v[170:173], v[186:189], v[122:125]
	v_mfma_f32_16x16x32_bf16 v[118:121], v[178:181], v[186:189], v[118:121]
	v_mfma_f32_16x16x32_bf16 v[106:109], v[170:173], v[194:197], v[106:109]
	v_mfma_f32_16x16x32_bf16 v[102:105], v[178:181], v[194:197], v[102:105]
	v_mfma_f32_16x16x32_bf16 v[90:93], v[170:173], v[224:227], v[90:93]
	v_mfma_f32_16x16x32_bf16 v[86:89], v[178:181], v[224:227], v[86:89]
	v_mfma_f32_16x16x32_bf16 v[74:77], v[170:173], v[232:235], v[74:77]
	v_mfma_f32_16x16x32_bf16 v[70:73], v[178:181], v[232:235], v[70:73]
	s_setprio 0
	s_barrier
	s_add_i32 s68, s68, s37
	s_mov_b32 m0, s68
	ds_read_b128 v[182:185], v148 offset:16384
	ds_read_b128 v[186:189], v148 offset:17408
	ds_read_b128 v[190:193], v148 offset:18432
	ds_read_b128 v[194:197], v148 offset:19456
	ds_read_b128 v[206:209], v148 offset:20480
	ds_read_b128 v[224:227], v148 offset:21504
	ds_read_b128 v[228:231], v148 offset:22528
	ds_read_b128 v[232:235], v148 offset:23552
	global_load_lds_dwordx4 v138, s[48:49]
	s_add_i32 m0, s68, 0x2000
	s_add_u32 s68, s48, 0x80000
	s_addc_u32 s69, s49, 0
	s_add_i32 s70, s70, s37
	global_load_lds_dwordx4 v134, s[48:49]
	s_mov_b32 m0, s70
	s_nop 0
	global_load_lds_dwordx4 v138, s[68:69]
	s_add_i32 m0, s70, 0x2000
	s_nop 0
	global_load_lds_dwordx4 v134, s[68:69]
	s_waitcnt vmcnt(6) lgkmcnt(0)
	s_barrier
	s_setprio 1
	v_mfma_f32_16x16x32_bf16 v[66:69], v[150:153], v[182:185], v[66:69]
	v_mfma_f32_16x16x32_bf16 v[62:65], v[158:161], v[182:185], v[62:65]
	v_mfma_f32_16x16x32_bf16 v[50:53], v[150:153], v[190:193], v[50:53]
	v_mfma_f32_16x16x32_bf16 v[46:49], v[158:161], v[190:193], v[46:49]
	v_mfma_f32_16x16x32_bf16 v[34:37], v[150:153], v[206:209], v[34:37]
	v_mfma_f32_16x16x32_bf16 v[30:33], v[158:161], v[206:209], v[30:33]
	v_mfma_f32_16x16x32_bf16 v[18:21], v[150:153], v[228:231], v[18:21]
	v_mfma_f32_16x16x32_bf16 v[14:17], v[158:161], v[228:231], v[14:17]
	v_mfma_f32_16x16x32_bf16 v[66:69], v[154:157], v[186:189], v[66:69]
	v_mfma_f32_16x16x32_bf16 v[62:65], v[162:165], v[186:189], v[62:65]
	v_mfma_f32_16x16x32_bf16 v[50:53], v[154:157], v[194:197], v[50:53]
	v_mfma_f32_16x16x32_bf16 v[46:49], v[162:165], v[194:197], v[46:49]
	v_mfma_f32_16x16x32_bf16 v[34:37], v[154:157], v[224:227], v[34:37]
	v_mfma_f32_16x16x32_bf16 v[30:33], v[162:165], v[224:227], v[30:33]
	v_mfma_f32_16x16x32_bf16 v[18:21], v[154:157], v[232:235], v[18:21]
	v_mfma_f32_16x16x32_bf16 v[14:17], v[162:165], v[232:235], v[14:17]
	s_setprio 0
	s_setprio 1
	v_mfma_f32_16x16x32_bf16 v[58:61], v[166:169], v[182:185], v[58:61]
	v_mfma_f32_16x16x32_bf16 v[54:57], v[174:177], v[182:185], v[54:57]
	v_mfma_f32_16x16x32_bf16 v[42:45], v[166:169], v[190:193], v[42:45]
	v_mfma_f32_16x16x32_bf16 v[38:41], v[174:177], v[190:193], v[38:41]
	v_mfma_f32_16x16x32_bf16 v[26:29], v[166:169], v[206:209], v[26:29]
	v_mfma_f32_16x16x32_bf16 v[22:25], v[174:177], v[206:209], v[22:25]
	v_mfma_f32_16x16x32_bf16 v[10:13], v[166:169], v[228:231], v[10:13]
	v_mfma_f32_16x16x32_bf16 v[4:7], v[174:177], v[228:231], v[6:9]
	v_mfma_f32_16x16x32_bf16 v[58:61], v[170:173], v[186:189], v[58:61]
	v_mfma_f32_16x16x32_bf16 v[54:57], v[178:181], v[186:189], v[54:57]
	v_mfma_f32_16x16x32_bf16 v[42:45], v[170:173], v[194:197], v[42:45]
	v_mfma_f32_16x16x32_bf16 v[38:41], v[178:181], v[194:197], v[38:41]
	v_mfma_f32_16x16x32_bf16 v[26:29], v[170:173], v[224:227], v[26:29]
	v_mfma_f32_16x16x32_bf16 v[22:25], v[178:181], v[224:227], v[22:25]
	v_mfma_f32_16x16x32_bf16 v[10:13], v[170:173], v[232:235], v[10:13]
	v_mfma_f32_16x16x32_bf16 v[4:7], v[178:181], v[232:235], v[4:7]
	s_setprio 0
	s_barrier
; #define PG8_STAGE(bufoff, gbase, voff) do { _Pragma("unroll") for (int _i = 0; _i < 2; ++_i) \
;         __builtin_amdgcn_global_load_lds((const unsigned*)((const char*)(gbase) + (voff)[_i]), (LAS unsigned*)(lds + (bufoff) + ldsw + _i * 8192), 16, 0, 0); } while (0)
; #define PG8_LDA(dst, b, h) do { _Pragma("unroll") for (int m = 0; m < 4; ++m) _Pragma("unroll") for (int k = 0; k < 2; ++k) dst[m][k] = *(const LAS bf16x8*)(lds + PG8_SA(b, h) + aoff + m * 2048 + k * 1024); } while (0)
; #define PG8_LDB(dst, b, h) do { _Pragma("unroll") for (int n = 0; n < 2; ++n) _Pragma("unroll") for (int k = 0; k < 2; ++k) dst[n][k] = *(const LAS bf16x8*)(lds + PG8_SB(b, h) + boff + n * 2048 + k * 1024); } while (0)
; #define PG8_MMA(ai, bj, At, Bt) do { __builtin_amdgcn_s_setprio(1); _Pragma("unroll") for (int m = 0; m < 4; ++m) _Pragma("unroll") for (int n = 0; n < 2; ++n) _Pragma("unroll") for (int k = 0; k < 2; ++k) \
;         acc[ai][bj][m][n] = __builtin_amdgcn_mfma_f32_16x16x32_bf16(Bt[n][k], At[m][k], acc[ai][bj][m][n], 0, 0, 0); __builtin_amdgcn_s_setprio(0); } while (0)
; #define PG8_WAIT_V(n) asm volatile("s_waitcnt vmcnt(" #n ")" ::: "memory")
; #define PG8_WAIT_L(n) asm volatile("s_waitcnt lgkmcnt(" #n ")" ::: "memory")
; #define PG8_BAR __builtin_amdgcn_s_barrier()
; #define PG8_SCHED __builtin_amdgcn_sched_barrier(0)
; template <class Epi, bool ALIGN_EPI = true>
; __device__ __forceinline__ void gemm_phase(LAS unsigned char* lds, const Gemm g, const Sched& S, const Epi& E) {
;     ...
;             PG8_LDB(B0, 1, 0); PG8_LDB(B1, 1, 1); PG8_SCHED; PG8_LDA(At, 1, 0); PG8_STAGE(PG8_SA(0, 1), a2 + hstepA, voffA);
;             PG8_WAIT_V(8); PG8_WAIT_L(0); PG8_BAR; PG8_MMA(0, 0, At, B0); PG8_MMA(0, 1, At, B1); PG8_BAR; PG8_SCHED;
;             PG8_LDA(At, 1, 1); PG8_STAGE(PG8_SB(1, 0), b3, voffB); PG8_STAGE(PG8_SB(1, 1), b3 + hstepB, voffB); PG8_STAGE(PG8_SA(1, 0), a3, voffA);
;             PG8_WAIT_V(8); PG8_WAIT_L(0); PG8_BAR; PG8_MMA(1, 0, At, B0); PG8_MMA(1, 1, At, B1); PG8_BAR; PG8_SCHED;
;         }
	s_add_i32 s68, 0, 0x18000
	s_add_i32 s69, 0, 0x1c000
	ds_read_b128 v[150:153], v147 offset:32768
	ds_read_b128 v[154:157], v147 offset:33792
	ds_read_b128 v[158:161], v147 offset:34816
	ds_read_b128 v[162:165], v147 offset:35840
	ds_read_b128 v[166:169], v147 offset:49152
	ds_read_b128 v[170:173], v147 offset:50176
	ds_read_b128 v[174:177], v147 offset:51200
	ds_read_b128 v[178:181], v147 offset:52224
	s_add_u32 s50, s50, 0x80000
	s_addc_u32 s51, s51, 0
	ds_read_b128 v[182:185], v148 offset:32768
	ds_read_b128 v[186:189], v148 offset:33792
	ds_read_b128 v[190:193], v148 offset:34816
	ds_read_b128 v[194:197], v148 offset:35840
	ds_read_b128 v[206:209], v148 offset:36864
	ds_read_b128 v[224:227], v148 offset:37888
	ds_read_b128 v[228:231], v148 offset:38912
	ds_read_b128 v[232:235], v148 offset:39936
	s_mov_b32 m0, s52
	s_add_u32 s100, s50, 0xfff80000
	s_addc_u32 s101, s51, -1
	global_load_lds_dwordx4 v140, s[100:101]
	s_mov_b32 m0, s53
	s_nop 0
	global_load_lds_dwordx4 v136, s[100:101]
	s_mov_b32 m0, s54
	s_nop 0
	global_load_lds_dwordx4 v140, s[50:51]
	s_mov_b32 m0, s55
	s_nop 0
	global_load_lds_dwordx4 v136, s[50:51]
	s_waitcnt vmcnt(8) lgkmcnt(0)
	s_barrier
	s_setprio 1
	v_mfma_f32_16x16x32_bf16 v[130:133], v[150:153], v[182:185], v[130:133]
	v_mfma_f32_16x16x32_bf16 v[126:129], v[158:161], v[182:185], v[126:129]
	v_mfma_f32_16x16x32_bf16 v[114:117], v[150:153], v[190:193], v[114:117]
	v_mfma_f32_16x16x32_bf16 v[110:113], v[158:161], v[190:193], v[110:113]
	v_mfma_f32_16x16x32_bf16 v[98:101], v[150:153], v[206:209], v[98:101]
	v_mfma_f32_16x16x32_bf16 v[94:97], v[158:161], v[206:209], v[94:97]
	v_mfma_f32_16x16x32_bf16 v[82:85], v[150:153], v[228:231], v[82:85]
	v_mfma_f32_16x16x32_bf16 v[78:81], v[158:161], v[228:231], v[78:81]
	v_mfma_f32_16x16x32_bf16 v[130:133], v[154:157], v[186:189], v[130:133]
	v_mfma_f32_16x16x32_bf16 v[126:129], v[162:165], v[186:189], v[126:129]
	v_mfma_f32_16x16x32_bf16 v[114:117], v[154:157], v[194:197], v[114:117]
	v_mfma_f32_16x16x32_bf16 v[110:113], v[162:165], v[194:197], v[110:113]
	v_mfma_f32_16x16x32_bf16 v[98:101], v[154:157], v[224:227], v[98:101]
	v_mfma_f32_16x16x32_bf16 v[94:97], v[162:165], v[224:227], v[94:97]
	v_mfma_f32_16x16x32_bf16 v[82:85], v[154:157], v[232:235], v[82:85]
	v_mfma_f32_16x16x32_bf16 v[78:81], v[162:165], v[232:235], v[78:81]
	s_setprio 0
	s_setprio 1
	v_mfma_f32_16x16x32_bf16 v[122:125], v[166:169], v[182:185], v[122:125]
	v_mfma_f32_16x16x32_bf16 v[118:121], v[174:177], v[182:185], v[118:121]
	v_mfma_f32_16x16x32_bf16 v[106:109], v[166:169], v[190:193], v[106:109]
	v_mfma_f32_16x16x32_bf16 v[102:105], v[174:177], v[190:193], v[102:105]
	v_mfma_f32_16x16x32_bf16 v[90:93], v[166:169], v[206:209], v[90:93]
	v_mfma_f32_16x16x32_bf16 v[86:89], v[174:177], v[206:209], v[86:89]
	v_mfma_f32_16x16x32_bf16 v[74:77], v[166:169], v[228:231], v[74:77]
	v_mfma_f32_16x16x32_bf16 v[70:73], v[174:177], v[228:231], v[70:73]
	v_mfma_f32_16x16x32_bf16 v[122:125], v[170:173], v[186:189], v[122:125]
	v_mfma_f32_16x16x32_bf16 v[118:121], v[178:181], v[186:189], v[118:121]
	v_mfma_f32_16x16x32_bf16 v[106:109], v[170:173], v[194:197], v[106:109]
	v_mfma_f32_16x16x32_bf16 v[102:105], v[178:181], v[194:197], v[102:105]
	v_mfma_f32_16x16x32_bf16 v[90:93], v[170:173], v[224:227], v[90:93]
	v_mfma_f32_16x16x32_bf16 v[86:89], v[178:181], v[224:227], v[86:89]
	v_mfma_f32_16x16x32_bf16 v[74:77], v[170:173], v[232:235], v[74:77]
	v_mfma_f32_16x16x32_bf16 v[70:73], v[178:181], v[232:235], v[70:73]
	s_setprio 0
	s_barrier
	s_add_u32 s100, s48, 0x80
	s_addc_u32 s101, s49, 0
	s_add_i32 s50, s68, s37
	s_mov_b32 m0, s50
	ds_read_b128 v[182:185], v148 offset:49152
	ds_read_b128 v[186:189], v148 offset:50176
	ds_read_b128 v[190:193], v148 offset:51200
	ds_read_b128 v[194:197], v148 offset:52224
	ds_read_b128 v[206:209], v148 offset:53248
	ds_read_b128 v[224:227], v148 offset:54272
	ds_read_b128 v[228:231], v148 offset:55296
	ds_read_b128 v[232:235], v148 offset:56320
	global_load_lds_dwordx4 v138, s[100:101]
	s_add_i32 m0, s50, 0x2000
	s_add_u32 s48, s48, 0x80080
	s_addc_u32 s49, s49, 0
	s_add_i32 s50, s69, s37
	global_load_lds_dwordx4 v134, s[100:101]
	s_mov_b32 m0, s50
	s_nop 0
	global_load_lds_dwordx4 v138, s[48:49]
	s_add_i32 m0, s50, 0x2000
	s_nop 0
	global_load_lds_dwordx4 v134, s[48:49]
	s_waitcnt vmcnt(6) lgkmcnt(0)
	s_barrier
	s_setprio 1
	v_mfma_f32_16x16x32_bf16 v[66:69], v[150:153], v[182:185], v[66:69]
	v_mfma_f32_16x16x32_bf16 v[62:65], v[158:161], v[182:185], v[62:65]
	v_mfma_f32_16x16x32_bf16 v[50:53], v[150:153], v[190:193], v[50:53]
	v_mfma_f32_16x16x32_bf16 v[46:49], v[158:161], v[190:193], v[46:49]
	v_mfma_f32_16x16x32_bf16 v[34:37], v[150:153], v[206:209], v[34:37]
	v_mfma_f32_16x16x32_bf16 v[30:33], v[158:161], v[206:209], v[30:33]
	v_mfma_f32_16x16x32_bf16 v[18:21], v[150:153], v[228:231], v[18:21]
	v_mfma_f32_16x16x32_bf16 v[14:17], v[158:161], v[228:231], v[14:17]
	v_mfma_f32_16x16x32_bf16 v[66:69], v[154:157], v[186:189], v[66:69]
	v_mfma_f32_16x16x32_bf16 v[62:65], v[162:165], v[186:189], v[62:65]
	v_mfma_f32_16x16x32_bf16 v[50:53], v[154:157], v[194:197], v[50:53]
	v_mfma_f32_16x16x32_bf16 v[46:49], v[162:165], v[194:197], v[46:49]
	v_mfma_f32_16x16x32_bf16 v[34:37], v[154:157], v[224:227], v[34:37]
	v_mfma_f32_16x16x32_bf16 v[30:33], v[162:165], v[224:227], v[30:33]
	v_mfma_f32_16x16x32_bf16 v[18:21], v[154:157], v[232:235], v[18:21]
	v_mfma_f32_16x16x32_bf16 v[14:17], v[162:165], v[232:235], v[14:17]
	s_setprio 0
	s_setprio 1
	v_mfma_f32_16x16x32_bf16 v[58:61], v[166:169], v[182:185], v[58:61]
	v_mfma_f32_16x16x32_bf16 v[54:57], v[174:177], v[182:185], v[54:57]
	v_mfma_f32_16x16x32_bf16 v[42:45], v[166:169], v[190:193], v[42:45]
	v_mfma_f32_16x16x32_bf16 v[38:41], v[174:177], v[190:193], v[38:41]
	v_mfma_f32_16x16x32_bf16 v[26:29], v[166:169], v[206:209], v[26:29]
	v_mfma_f32_16x16x32_bf16 v[22:25], v[174:177], v[206:209], v[22:25]
	v_mfma_f32_16x16x32_bf16 v[8:11], v[166:169], v[228:231], v[10:13]
	v_mfma_f32_16x16x32_bf16 v[4:7], v[174:177], v[228:231], v[4:7]
	v_mfma_f32_16x16x32_bf16 v[58:61], v[170:173], v[186:189], v[58:61]
	v_mfma_f32_16x16x32_bf16 v[54:57], v[178:181], v[186:189], v[54:57]
	v_mfma_f32_16x16x32_bf16 v[42:45], v[170:173], v[194:197], v[42:45]
	v_mfma_f32_16x16x32_bf16 v[38:41], v[178:181], v[194:197], v[38:41]
	v_mfma_f32_16x16x32_bf16 v[26:29], v[170:173], v[224:227], v[26:29]
	v_mfma_f32_16x16x32_bf16 v[22:25], v[178:181], v[224:227], v[22:25]
	v_mfma_f32_16x16x32_bf16 v[10:13], v[170:173], v[232:235], v[8:11]
	v_mfma_f32_16x16x32_bf16 v[6:9], v[178:181], v[232:235], v[4:7]
	s_setprio 0
	s_barrier
	s_add_u32 s46, s46, 0x100
	s_addc_u32 s47, s47, 0
	s_add_u32 s65, s65, 0x100
	s_addc_u32 s66, s66, 0
	s_cmp_ge_i32 s67, s56
	s_mov_b32 s48, s67
	s_cbranch_scc0 .LBB0_1311

; #define PG8_STAGE(bufoff, gbase, voff) do { _Pragma("unroll") for (int _i = 0; _i < 2; ++_i) \
;         __builtin_amdgcn_global_load_lds((const unsigned*)((const char*)(gbase) + (voff)[_i]), (LAS unsigned*)(lds + (bufoff) + ldsw + _i * 8192), 16, 0, 0); } while (0)
; #define PG8_WAIT_V(n) asm volatile("s_waitcnt vmcnt(" #n ")" ::: "memory")
; #define PG8_BAR __builtin_amdgcn_s_barrier()
; template <class Epi, bool ALIGN_EPI = true>
; __device__ __forceinline__ void gemm_phase(LAS unsigned char* lds, const Gemm g, const Sched& S, const Epi& E) {
;     ...
;     for (int i = 0; i < 2; ++i) { int R, C; stage_rc(tid * 16 + i * 8192, R, C); const int Rb = (R & ~31) + perm32(R & 31);
;         voffA[i] = (unsigned)(R * g.lda + C) * 2u; voffB[i] = (unsigned)(Rb * g.ldb + C) * 2u; }
;     const size_t kstep = (size_t)(BK * 2);
;     const size_t hstepA = (size_t)HALF * g.lda * 2, hstepB = (size_t)HALF * g.ldb * 2;
;     const unsigned ldsw = (unsigned)wid * 1024u;
;     const int aoff = lds_byte(wr * 64 + fr, fq * 8), boff = lds_byte(wc * 32 + fr, fq * 8);
;     ...
;     f32x4 acc[2][2][4][2];
; #pragma unroll
;     for (int a = 0; a < 2; ++a)
; #pragma unroll
;         for (int b = 0; b < 2; ++b)
; #pragma unroll
;             for (int m = 0; m < 4; ++m)
; #pragma unroll
;                 for (int n = 0; n < 2; ++n) acc[a][b][m][n] = (f32x4){0.f, 0.f, 0.f, 0.f};
;     bf16x8 At[4][2], B0[2][2], B1[2][2];
;     const char* cA = (const char*)g.A + cur.aoff; const char* cB = (const char*)g.Bt + cur.boff;
;     PG8_STAGE(PG8_SB(0, 0), cB, voffB); PG8_STAGE(PG8_SB(0, 1), cB + hstepB, voffB); PG8_STAGE(PG8_SA(0, 0), cA, voffA); PG8_STAGE(PG8_SA(0, 1), cA + hstepA, voffA);
;     if (wr == 1) PG8_BAR;
;     PG8_WAIT_V(2); PG8_BAR;
;     PG8_STAGE(PG8_SB(1, 0), cB + kstep, voffB); PG8_STAGE(PG8_SA(1, 0), cA + kstep, voffA); PG8_STAGE(PG8_SB(1, 1), cB + hstepB + kstep, voffB);
;     PG8_WAIT_V(6); PG8_BAR;
.LBB0_1391:
	s_and_b32 s30, s18, 3
	s_ashr_i32 s18, s16, 31
	s_lshr_b32 s18, s18, 26
	s_add_i32 s18, s16, s18
	s_add_i32 m0, s52, 0x18000
	v_lshl_add_u64 v[10:11], v[10:11], 0, s[8:9]
	s_ashr_i32 s56, s18, 6
	s_lshl_b32 s33, s17, 6
	s_lshl_b32 s17, s17, 13
	s_lshl_b32 s20, s30, 12
	s_waitcnt vmcnt(2)
	s_barrier
	global_load_lds_dwordx4 v[10:11], off
	v_lshl_add_u64 v[8:9], v[8:9], 0, s[8:9]
	s_add_i32 m0, s52, 0x1a000
	s_add_i32 s57, s52, 0x8000
	s_add_i32 s58, s52, 0xa000
	global_load_lds_dwordx4 v[8:9], off
	v_lshl_add_u64 v[6:7], v[6:7], 0, s[8:9]
	s_mov_b32 m0, s57
	s_add_u32 s18, s6, 0x80080
	global_load_lds_dwordx4 v[6:7], off
	v_lshl_add_u64 v[4:5], v[4:5], 0, s[8:9]
	s_mov_b32 m0, s58
	s_addc_u32 s19, s7, 0
	global_load_lds_dwordx4 v[4:5], off
	s_add_i32 m0, s52, 0x1c000
	v_lshl_add_u64 v[4:5], s[18:19], 0, v[138:139]
	global_load_lds_dwordx4 v[4:5], off
	v_lshl_add_u64 v[4:5], s[18:19], 0, v[134:135]
	s_add_i32 m0, s52, 0x1e000
	s_movk_i32 s10, 0x3c0
	global_load_lds_dwordx4 v[4:5], off
	v_and_b32_e32 v4, 48, v146
	v_lshlrev_b32_e32 v5, 6, v146
	v_and_or_b32 v4, v5, s10, v4
	v_lshlrev_b32_e32 v5, 2, v146
	v_and_b32_e32 v5, 32, v5
	v_bitop3_b32 v6, v4, s17, v5 bitop3:0xde
	v_bitop3_b32 v147, v4, s20, v5 bitop3:0xde
	v_add_u32_e32 v147, 0x10000, v147
	v_lshlrev_b32_e32 v4, 15, v15
	v_and_b32_e32 v4, 0xffff0000, v4
	v_lshl_add_u32 v4, v14, 12, v4
	v_and_b32_e32 v5, 1, v15
	v_lshl_or_b32 v4, v5, 6, v4
	v_lshl_add_u32 v142, v16, 1, v4
	v_lshlrev_b32_e32 v4, 15, v2
	v_and_b32_e32 v4, 0xffff0000, v4
	v_lshl_add_u32 v4, v12, 12, v4
	v_and_b32_e32 v2, 1, v2
	v_readlane_b32 s18, v243, 16
	s_waitcnt vmcnt(6)
	v_lshl_or_b32 v2, v2, 6, v4
	v_mov_b32_e32 v4, v3
	v_mov_b32_e32 v5, v3
	v_readlane_b32 s19, v243, 17
	s_cmp_gt_i32 s16, 63
	v_lshl_add_u32 v144, v13, 1, v2
	v_mov_b32_e32 v2, v3
	v_add_u32_e32 v148, 0, v6
	v_mov_b64_e32 v[8:9], v[4:5]
	v_mov_b64_e32 v[12:13], v[4:5]
	v_mov_b64_e32 v[24:25], v[4:5]
	v_mov_b64_e32 v[28:29], v[4:5]
	v_mov_b64_e32 v[40:41], v[4:5]
	v_mov_b64_e32 v[44:45], v[4:5]
	v_mov_b64_e32 v[56:57], v[4:5]
	v_mov_b64_e32 v[60:61], v[4:5]
	v_mov_b64_e32 v[16:17], v[4:5]
	v_mov_b64_e32 v[20:21], v[4:5]
	v_mov_b64_e32 v[32:33], v[4:5]
	v_mov_b64_e32 v[36:37], v[4:5]
	v_mov_b64_e32 v[48:49], v[4:5]
	v_mov_b64_e32 v[52:53], v[4:5]
	v_mov_b64_e32 v[64:65], v[4:5]
	v_mov_b64_e32 v[68:69], v[4:5]
	v_mov_b64_e32 v[72:73], v[4:5]
	v_mov_b64_e32 v[76:77], v[4:5]
	v_mov_b64_e32 v[88:89], v[4:5]
	v_mov_b64_e32 v[92:93], v[4:5]
	v_mov_b64_e32 v[104:105], v[4:5]
	v_mov_b64_e32 v[108:109], v[4:5]
	v_mov_b64_e32 v[120:121], v[4:5]
	v_mov_b64_e32 v[124:125], v[4:5]
	v_mov_b64_e32 v[80:81], v[4:5]
	v_mov_b64_e32 v[84:85], v[4:5]
	v_mov_b64_e32 v[96:97], v[4:5]
	v_mov_b64_e32 v[100:101], v[4:5]
	v_mov_b64_e32 v[112:113], v[4:5]
	v_mov_b64_e32 v[116:117], v[4:5]
	v_mov_b64_e32 v[128:129], v[4:5]
	v_mov_b64_e32 v[132:133], v[4:5]
	s_mov_b32 s31, s18
	v_readlane_b32 s18, v243, 12
	s_cselect_b64 s[16:17], -1, 0
	s_add_i32 s59, s56, -2
	v_mov_b32_e32 v143, v3
	v_mov_b32_e32 v145, v3
	s_mov_b32 s60, 0
	v_mov_b64_e32 v[6:7], v[2:3]
	v_mov_b64_e32 v[10:11], v[2:3]
	v_mov_b64_e32 v[22:23], v[2:3]
	v_mov_b64_e32 v[26:27], v[2:3]
	v_mov_b64_e32 v[38:39], v[2:3]
	v_mov_b64_e32 v[42:43], v[2:3]
	v_mov_b64_e32 v[54:55], v[2:3]
	v_mov_b64_e32 v[58:59], v[2:3]
	v_mov_b64_e32 v[14:15], v[2:3]
	v_mov_b64_e32 v[18:19], v[2:3]
	v_mov_b64_e32 v[30:31], v[2:3]
	v_mov_b64_e32 v[34:35], v[2:3]
	v_mov_b64_e32 v[46:47], v[2:3]
	v_mov_b64_e32 v[50:51], v[2:3]
	v_mov_b64_e32 v[62:63], v[2:3]
	v_mov_b64_e32 v[66:67], v[2:3]
	v_mov_b64_e32 v[70:71], v[2:3]
	v_mov_b64_e32 v[74:75], v[2:3]
	v_mov_b64_e32 v[86:87], v[2:3]
	v_mov_b64_e32 v[90:91], v[2:3]
	v_mov_b64_e32 v[102:103], v[2:3]
	v_mov_b64_e32 v[106:107], v[2:3]
	v_mov_b64_e32 v[118:119], v[2:3]
	v_mov_b64_e32 v[122:123], v[2:3]
	v_mov_b64_e32 v[78:79], v[2:3]
	v_mov_b64_e32 v[82:83], v[2:3]
	v_mov_b64_e32 v[94:95], v[2:3]
	v_mov_b64_e32 v[98:99], v[2:3]
	v_mov_b64_e32 v[110:111], v[2:3]
	v_mov_b64_e32 v[114:115], v[2:3]
	v_mov_b64_e32 v[126:127], v[2:3]
	v_mov_b64_e32 v[130:131], v[2:3]
	s_mov_b32 s61, s18
	s_barrier
	v_readlane_b32 s19, v243, 13
	s_branch .LBB0_1393

; #define PG8_STAGE(bufoff, gbase, voff) do { _Pragma("unroll") for (int _i = 0; _i < 2; ++_i) \
;         __builtin_amdgcn_global_load_lds((const unsigned*)((const char*)(gbase) + (voff)[_i]), (LAS unsigned*)(lds + (bufoff) + ldsw + _i * 8192), 16, 0, 0); } while (0)
; #define PG8_LDA(dst, b, h) do { _Pragma("unroll") for (int m = 0; m < 4; ++m) _Pragma("unroll") for (int k = 0; k < 2; ++k) dst[m][k] = *(const LAS bf16x8*)(lds + PG8_SA(b, h) + aoff + m * 2048 + k * 1024); } while (0)
; #define PG8_LDB(dst, b, h) do { _Pragma("unroll") for (int n = 0; n < 2; ++n) _Pragma("unroll") for (int k = 0; k < 2; ++k) dst[n][k] = *(const LAS bf16x8*)(lds + PG8_SB(b, h) + boff + n * 2048 + k * 1024); } while (0)
; #define PG8_MMA(ai, bj, At, Bt) do { __builtin_amdgcn_s_setprio(1); _Pragma("unroll") for (int m = 0; m < 4; ++m) _Pragma("unroll") for (int n = 0; n < 2; ++n) _Pragma("unroll") for (int k = 0; k < 2; ++k) \
;         acc[ai][bj][m][n] = __builtin_amdgcn_mfma_f32_16x16x32_bf16(Bt[n][k], At[m][k], acc[ai][bj][m][n], 0, 0, 0); __builtin_amdgcn_s_setprio(0); } while (0)
; template <class Epi, bool ALIGN_EPI = true>
; __device__ __forceinline__ void gemm_phase(LAS unsigned char* lds, const Gemm g, const Sched& S, const Epi& E) {
;     ...
;         for (int t = t_lo; t < t_hi; t += 2) {
;             const bool last = (t == nt - 2);
;             const char* a1 = cA + (size_t)(t + 1) * kstep;
;             const char* a2 = last ? nA : cA + (size_t)(t + 2) * kstep; const char* b2 = last ? nB : cB + (size_t)(t + 2) * kstep;
;             const char* a3 = a2 + kstep; const char* b3 = b2 + kstep;
;             const int rflag = __builtin_amdgcn_readfirstlane(t | (int)(ui == 0));
;             PG8_LDB(B0, 0, 0); PG8_LDB(B1, 0, 1); PG8_SCHED; PG8_LDA(At, 0, 0); PG8_STAGE(PG8_SA(1, 1), a1 + hstepA, voffA);
;             if constexpr (Epi::NSTORES > 0) PG8_WAIT_RELAX(rflag, 8 + Epi::NSTORES); else PG8_WAIT_V(8);
;             PG8_WAIT_L(0); PG8_BAR; PG8_MMA(0, 0, At, B0); PG8_MMA(0, 1, At, B1); PG8_BAR; PG8_SCHED;
;             PG8_LDA(At, 0, 1); PG8_STAGE(PG8_SB(0, 0), b2, voffB); PG8_STAGE(PG8_SB(0, 1), b2 + hstepB, voffB); PG8_STAGE(PG8_SA(0, 0), a2, voffA);
;             if constexpr (Epi::NSTORES > 0) PG8_WAIT_RELAX(rflag, 8 + Epi::NSTORES); else PG8_WAIT_V(8);
;             PG8_WAIT_L(0); PG8_BAR; PG8_MMA(1, 0, At, B0); PG8_MMA(1, 1, At, B1); PG8_BAR; PG8_SCHED;
.LBB0_1402:
	s_add_i32 s67, s46, 2
	s_add_u32 s47, s44, 0xfff80080
	s_addc_u32 s48, s45, -1
	s_add_i32 s68, 0, 0x10000
	s_cmp_eq_u32 s59, s46
	s_cselect_b32 s49, s19, s48
	s_cselect_b32 s48, s21, s47
	s_cselect_b32 s47, s63, s66
	s_cselect_b32 s46, s64, s65
	s_add_i32 s70, 0, 0x14000
	ds_read_b128 v[150:153], v147
	ds_read_b128 v[154:157], v147 offset:1024
	ds_read_b128 v[158:161], v147 offset:2048
	ds_read_b128 v[162:165], v147 offset:3072
	ds_read_b128 v[166:169], v147 offset:16384
	ds_read_b128 v[170:173], v147 offset:17408
	ds_read_b128 v[174:177], v147 offset:18432
	ds_read_b128 v[178:181], v147 offset:19456
	ds_read_b128 v[182:185], v148
	ds_read_b128 v[186:189], v148 offset:1024
	ds_read_b128 v[190:193], v148 offset:2048
	ds_read_b128 v[194:197], v148 offset:3072
	ds_read_b128 v[206:209], v148 offset:4096
	ds_read_b128 v[224:227], v148 offset:5120
	ds_read_b128 v[228:231], v148 offset:6144
	ds_read_b128 v[232:235], v148 offset:7168
	s_mov_b32 m0, s57
	s_add_u32 s100, s44, 0xfff80000
	s_addc_u32 s101, s45, -1
	global_load_lds_dwordx4 v142, s[100:101]
	s_mov_b32 m0, s58
	s_nop 0
	global_load_lds_dwordx4 v144, s[100:101]
	s_add_i32 m0, s52, 0xc000
	s_nop 0
	global_load_lds_dwordx4 v142, s[44:45]
	s_add_i32 m0, s52, 0xe000
	s_nop 0
	global_load_lds_dwordx4 v144, s[44:45]
	s_waitcnt vmcnt(8) lgkmcnt(0)
	s_barrier
	s_setprio 1
	v_mfma_f32_16x16x32_bf16 v[130:133], v[150:153], v[182:185], v[130:133]
	v_mfma_f32_16x16x32_bf16 v[126:129], v[158:161], v[182:185], v[126:129]
	v_mfma_f32_16x16x32_bf16 v[114:117], v[150:153], v[190:193], v[114:117]
	v_mfma_f32_16x16x32_bf16 v[110:113], v[158:161], v[190:193], v[110:113]
	v_mfma_f32_16x16x32_bf16 v[98:101], v[150:153], v[206:209], v[98:101]
	v_mfma_f32_16x16x32_bf16 v[94:97], v[158:161], v[206:209], v[94:97]
	v_mfma_f32_16x16x32_bf16 v[82:85], v[150:153], v[228:231], v[82:85]
	v_mfma_f32_16x16x32_bf16 v[78:81], v[158:161], v[228:231], v[78:81]
	v_mfma_f32_16x16x32_bf16 v[130:133], v[154:157], v[186:189], v[130:133]
	v_mfma_f32_16x16x32_bf16 v[126:129], v[162:165], v[186:189], v[126:129]
	v_mfma_f32_16x16x32_bf16 v[114:117], v[154:157], v[194:197], v[114:117]
	v_mfma_f32_16x16x32_bf16 v[110:113], v[162:165], v[194:197], v[110:113]
	v_mfma_f32_16x16x32_bf16 v[98:101], v[154:157], v[224:227], v[98:101]
	v_mfma_f32_16x16x32_bf16 v[94:97], v[162:165], v[224:227], v[94:97]
	v_mfma_f32_16x16x32_bf16 v[82:85], v[154:157], v[232:235], v[82:85]
	v_mfma_f32_16x16x32_bf16 v[78:81], v[162:165], v[232:235], v[78:81]
	s_setprio 0
	s_setprio 1
	v_mfma_f32_16x16x32_bf16 v[122:125], v[166:169], v[182:185], v[122:125]
	v_mfma_f32_16x16x32_bf16 v[118:121], v[174:177], v[182:185], v[118:121]
	v_mfma_f32_16x16x32_bf16 v[106:109], v[166:169], v[190:193], v[106:109]
	v_mfma_f32_16x16x32_bf16 v[102:105], v[174:177], v[190:193], v[102:105]
	v_mfma_f32_16x16x32_bf16 v[90:93], v[166:169], v[206:209], v[90:93]
	v_mfma_f32_16x16x32_bf16 v[86:89], v[174:177], v[206:209], v[86:89]
	v_mfma_f32_16x16x32_bf16 v[74:77], v[166:169], v[228:231], v[74:77]
	v_mfma_f32_16x16x32_bf16 v[70:73], v[174:177], v[228:231], v[70:73]
	v_mfma_f32_16x16x32_bf16 v[122:125], v[170:173], v[186:189], v[122:125]
	v_mfma_f32_16x16x32_bf16 v[118:121], v[178:181], v[186:189], v[118:121]
	v_mfma_f32_16x16x32_bf16 v[106:109], v[170:173], v[194:197], v[106:109]
	v_mfma_f32_16x16x32_bf16 v[102:105], v[178:181], v[194:197], v[102:105]
	v_mfma_f32_16x16x32_bf16 v[90:93], v[170:173], v[224:227], v[90:93]
	v_mfma_f32_16x16x32_bf16 v[86:89], v[178:181], v[224:227], v[86:89]
	v_mfma_f32_16x16x32_bf16 v[74:77], v[170:173], v[232:235], v[74:77]
	v_mfma_f32_16x16x32_bf16 v[70:73], v[178:181], v[232:235], v[70:73]
	s_setprio 0
	s_barrier
	s_add_i32 s68, s68, s51
	s_mov_b32 m0, s68
	ds_read_b128 v[182:185], v148 offset:16384
	ds_read_b128 v[186:189], v148 offset:17408
	ds_read_b128 v[190:193], v148 offset:18432
	ds_read_b128 v[194:197], v148 offset:19456
	ds_read_b128 v[206:209], v148 offset:20480
	ds_read_b128 v[224:227], v148 offset:21504
	ds_read_b128 v[228:231], v148 offset:22528
	ds_read_b128 v[232:235], v148 offset:23552
	global_load_lds_dwordx4 v138, s[46:47]
	s_add_i32 m0, s68, 0x2000
	s_add_u32 s68, s46, 0x80000
	s_addc_u32 s69, s47, 0
	s_add_i32 s70, s70, s51
	global_load_lds_dwordx4 v134, s[46:47]
	s_mov_b32 m0, s70
	s_nop 0
	global_load_lds_dwordx4 v138, s[68:69]
	s_add_i32 m0, s70, 0x2000
	s_nop 0
	global_load_lds_dwordx4 v134, s[68:69]
	s_waitcnt vmcnt(6) lgkmcnt(0)
	s_barrier
	s_setprio 1
	v_mfma_f32_16x16x32_bf16 v[66:69], v[150:153], v[182:185], v[66:69]
	v_mfma_f32_16x16x32_bf16 v[62:65], v[158:161], v[182:185], v[62:65]
	v_mfma_f32_16x16x32_bf16 v[50:53], v[150:153], v[190:193], v[50:53]
	v_mfma_f32_16x16x32_bf16 v[46:49], v[158:161], v[190:193], v[46:49]
	v_mfma_f32_16x16x32_bf16 v[34:37], v[150:153], v[206:209], v[34:37]
	v_mfma_f32_16x16x32_bf16 v[30:33], v[158:161], v[206:209], v[30:33]
	v_mfma_f32_16x16x32_bf16 v[18:21], v[150:153], v[228:231], v[18:21]
	v_mfma_f32_16x16x32_bf16 v[14:17], v[158:161], v[228:231], v[14:17]
	v_mfma_f32_16x16x32_bf16 v[66:69], v[154:157], v[186:189], v[66:69]
	v_mfma_f32_16x16x32_bf16 v[62:65], v[162:165], v[186:189], v[62:65]
	v_mfma_f32_16x16x32_bf16 v[50:53], v[154:157], v[194:197], v[50:53]
	v_mfma_f32_16x16x32_bf16 v[46:49], v[162:165], v[194:197], v[46:49]
	v_mfma_f32_16x16x32_bf16 v[34:37], v[154:157], v[224:227], v[34:37]
	v_mfma_f32_16x16x32_bf16 v[30:33], v[162:165], v[224:227], v[30:33]
	v_mfma_f32_16x16x32_bf16 v[18:21], v[154:157], v[232:235], v[18:21]
	v_mfma_f32_16x16x32_bf16 v[14:17], v[162:165], v[232:235], v[14:17]
	s_setprio 0
	s_setprio 1
	v_mfma_f32_16x16x32_bf16 v[58:61], v[166:169], v[182:185], v[58:61]
	v_mfma_f32_16x16x32_bf16 v[54:57], v[174:177], v[182:185], v[54:57]
	v_mfma_f32_16x16x32_bf16 v[42:45], v[166:169], v[190:193], v[42:45]
	v_mfma_f32_16x16x32_bf16 v[38:41], v[174:177], v[190:193], v[38:41]
	v_mfma_f32_16x16x32_bf16 v[26:29], v[166:169], v[206:209], v[26:29]
	v_mfma_f32_16x16x32_bf16 v[22:25], v[174:177], v[206:209], v[22:25]
	v_mfma_f32_16x16x32_bf16 v[10:13], v[166:169], v[228:231], v[10:13]
	v_mfma_f32_16x16x32_bf16 v[4:7], v[174:177], v[228:231], v[6:9]
	v_mfma_f32_16x16x32_bf16 v[58:61], v[170:173], v[186:189], v[58:61]
	v_mfma_f32_16x16x32_bf16 v[54:57], v[178:181], v[186:189], v[54:57]
	v_mfma_f32_16x16x32_bf16 v[42:45], v[170:173], v[194:197], v[42:45]
	v_mfma_f32_16x16x32_bf16 v[38:41], v[178:181], v[194:197], v[38:41]
	v_mfma_f32_16x16x32_bf16 v[26:29], v[170:173], v[224:227], v[26:29]
	v_mfma_f32_16x16x32_bf16 v[22:25], v[178:181], v[224:227], v[22:25]
	v_mfma_f32_16x16x32_bf16 v[10:13], v[170:173], v[232:235], v[10:13]
	v_mfma_f32_16x16x32_bf16 v[4:7], v[178:181], v[232:235], v[4:7]
	s_setprio 0
	s_barrier
; #define PG8_STAGE(bufoff, gbase, voff) do { _Pragma("unroll") for (int _i = 0; _i < 2; ++_i) \
;         __builtin_amdgcn_global_load_lds((const unsigned*)((const char*)(gbase) + (voff)[_i]), (LAS unsigned*)(lds + (bufoff) + ldsw + _i * 8192), 16, 0, 0); } while (0)
; #define PG8_LDA(dst, b, h) do { _Pragma("unroll") for (int m = 0; m < 4; ++m) _Pragma("unroll") for (int k = 0; k < 2; ++k) dst[m][k] = *(const LAS bf16x8*)(lds + PG8_SA(b, h) + aoff + m * 2048 + k * 1024); } while (0)
; #define PG8_LDB(dst, b, h) do { _Pragma("unroll") for (int n = 0; n < 2; ++n) _Pragma("unroll") for (int k = 0; k < 2; ++k) dst[n][k] = *(const LAS bf16x8*)(lds + PG8_SB(b, h) + boff + n * 2048 + k * 1024); } while (0)
; #define PG8_MMA(ai, bj, At, Bt) do { __builtin_amdgcn_s_setprio(1); _Pragma("unroll") for (int m = 0; m < 4; ++m) _Pragma("unroll") for (int n = 0; n < 2; ++n) _Pragma("unroll") for (int k = 0; k < 2; ++k) \
;         acc[ai][bj][m][n] = __builtin_amdgcn_mfma_f32_16x16x32_bf16(Bt[n][k], At[m][k], acc[ai][bj][m][n], 0, 0, 0); __builtin_amdgcn_s_setprio(0); } while (0)
; #define PG8_WAIT_V(n) asm volatile("s_waitcnt vmcnt(" #n ")" ::: "memory")
; #define PG8_WAIT_L(n) asm volatile("s_waitcnt lgkmcnt(" #n ")" ::: "memory")
; #define PG8_BAR __builtin_amdgcn_s_barrier()
; #define PG8_SCHED __builtin_amdgcn_sched_barrier(0)
; template <class Epi, bool ALIGN_EPI = true>
; __device__ __forceinline__ void gemm_phase(LAS unsigned char* lds, const Gemm g, const Sched& S, const Epi& E) {
;     ...
;             PG8_LDB(B0, 1, 0); PG8_LDB(B1, 1, 1); PG8_SCHED; PG8_LDA(At, 1, 0); PG8_STAGE(PG8_SA(0, 1), a2 + hstepA, voffA);
;             PG8_WAIT_V(8); PG8_WAIT_L(0); PG8_BAR; PG8_MMA(0, 0, At, B0); PG8_MMA(0, 1, At, B1); PG8_BAR; PG8_SCHED;
;             PG8_LDA(At, 1, 1); PG8_STAGE(PG8_SB(1, 0), b3, voffB); PG8_STAGE(PG8_SB(1, 1), b3 + hstepB, voffB); PG8_STAGE(PG8_SA(1, 0), a3, voffA);
;             PG8_WAIT_V(8); PG8_WAIT_L(0); PG8_BAR; PG8_MMA(1, 0, At, B0); PG8_MMA(1, 1, At, B1); PG8_BAR; PG8_SCHED;
;         }
	s_add_i32 s68, 0, 0x18000
	s_add_i32 s69, 0, 0x1c000
	ds_read_b128 v[150:153], v147 offset:32768
	ds_read_b128 v[154:157], v147 offset:33792
	ds_read_b128 v[158:161], v147 offset:34816
	ds_read_b128 v[162:165], v147 offset:35840
	ds_read_b128 v[166:169], v147 offset:49152
	ds_read_b128 v[170:173], v147 offset:50176
	ds_read_b128 v[174:177], v147 offset:51200
	ds_read_b128 v[178:181], v147 offset:52224
	s_add_u32 s48, s48, 0x80000
	s_addc_u32 s49, s49, 0
	ds_read_b128 v[182:185], v148 offset:32768
	ds_read_b128 v[186:189], v148 offset:33792
	ds_read_b128 v[190:193], v148 offset:34816
	ds_read_b128 v[194:197], v148 offset:35840
	ds_read_b128 v[206:209], v148 offset:36864
	ds_read_b128 v[224:227], v148 offset:37888
	ds_read_b128 v[228:231], v148 offset:38912
	ds_read_b128 v[232:235], v148 offset:39936
	s_mov_b32 m0, s52
	s_add_u32 s100, s48, 0xfff80000
	s_addc_u32 s101, s49, -1
	global_load_lds_dwordx4 v140, s[100:101]
	s_mov_b32 m0, s53
	s_nop 0
	global_load_lds_dwordx4 v136, s[100:101]
	s_mov_b32 m0, s54
	s_nop 0
	global_load_lds_dwordx4 v140, s[48:49]
	s_mov_b32 m0, s55
	s_nop 0
	global_load_lds_dwordx4 v136, s[48:49]
	s_waitcnt vmcnt(8) lgkmcnt(0)
	s_barrier
	s_setprio 1
	v_mfma_f32_16x16x32_bf16 v[130:133], v[150:153], v[182:185], v[130:133]
	v_mfma_f32_16x16x32_bf16 v[126:129], v[158:161], v[182:185], v[126:129]
	v_mfma_f32_16x16x32_bf16 v[114:117], v[150:153], v[190:193], v[114:117]
	v_mfma_f32_16x16x32_bf16 v[110:113], v[158:161], v[190:193], v[110:113]
	v_mfma_f32_16x16x32_bf16 v[98:101], v[150:153], v[206:209], v[98:101]
	v_mfma_f32_16x16x32_bf16 v[94:97], v[158:161], v[206:209], v[94:97]
	v_mfma_f32_16x16x32_bf16 v[82:85], v[150:153], v[228:231], v[82:85]
	v_mfma_f32_16x16x32_bf16 v[78:81], v[158:161], v[228:231], v[78:81]
	v_mfma_f32_16x16x32_bf16 v[130:133], v[154:157], v[186:189], v[130:133]
	v_mfma_f32_16x16x32_bf16 v[126:129], v[162:165], v[186:189], v[126:129]
	v_mfma_f32_16x16x32_bf16 v[114:117], v[154:157], v[194:197], v[114:117]
	v_mfma_f32_16x16x32_bf16 v[110:113], v[162:165], v[194:197], v[110:113]
	v_mfma_f32_16x16x32_bf16 v[98:101], v[154:157], v[224:227], v[98:101]
	v_mfma_f32_16x16x32_bf16 v[94:97], v[162:165], v[224:227], v[94:97]
	v_mfma_f32_16x16x32_bf16 v[82:85], v[154:157], v[232:235], v[82:85]
	v_mfma_f32_16x16x32_bf16 v[78:81], v[162:165], v[232:235], v[78:81]
	s_setprio 0
	s_setprio 1
	v_mfma_f32_16x16x32_bf16 v[122:125], v[166:169], v[182:185], v[122:125]
	v_mfma_f32_16x16x32_bf16 v[118:121], v[174:177], v[182:185], v[118:121]
	v_mfma_f32_16x16x32_bf16 v[106:109], v[166:169], v[190:193], v[106:109]
	v_mfma_f32_16x16x32_bf16 v[102:105], v[174:177], v[190:193], v[102:105]
	v_mfma_f32_16x16x32_bf16 v[90:93], v[166:169], v[206:209], v[90:93]
	v_mfma_f32_16x16x32_bf16 v[86:89], v[174:177], v[206:209], v[86:89]
	v_mfma_f32_16x16x32_bf16 v[74:77], v[166:169], v[228:231], v[74:77]
	v_mfma_f32_16x16x32_bf16 v[70:73], v[174:177], v[228:231], v[70:73]
	v_mfma_f32_16x16x32_bf16 v[122:125], v[170:173], v[186:189], v[122:125]
	v_mfma_f32_16x16x32_bf16 v[118:121], v[178:181], v[186:189], v[118:121]
	v_mfma_f32_16x16x32_bf16 v[106:109], v[170:173], v[194:197], v[106:109]
	v_mfma_f32_16x16x32_bf16 v[102:105], v[178:181], v[194:197], v[102:105]
	v_mfma_f32_16x16x32_bf16 v[90:93], v[170:173], v[224:227], v[90:93]
	v_mfma_f32_16x16x32_bf16 v[86:89], v[178:181], v[224:227], v[86:89]
	v_mfma_f32_16x16x32_bf16 v[74:77], v[170:173], v[232:235], v[74:77]
	v_mfma_f32_16x16x32_bf16 v[70:73], v[178:181], v[232:235], v[70:73]
	s_setprio 0
	s_barrier
	s_add_u32 s100, s46, 0x80
	s_addc_u32 s101, s47, 0
	s_add_i32 s48, s68, s51
	s_mov_b32 m0, s48
	ds_read_b128 v[182:185], v148 offset:49152
	ds_read_b128 v[186:189], v148 offset:50176
	ds_read_b128 v[190:193], v148 offset:51200
	ds_read_b128 v[194:197], v148 offset:52224
	ds_read_b128 v[206:209], v148 offset:53248
	ds_read_b128 v[224:227], v148 offset:54272
	ds_read_b128 v[228:231], v148 offset:55296
	ds_read_b128 v[232:235], v148 offset:56320
	global_load_lds_dwordx4 v138, s[100:101]
	s_add_i32 m0, s48, 0x2000
	s_add_u32 s46, s46, 0x80080
	s_addc_u32 s47, s47, 0
	s_add_i32 s48, s69, s51
	global_load_lds_dwordx4 v134, s[100:101]
	s_mov_b32 m0, s48
	s_nop 0
	global_load_lds_dwordx4 v138, s[46:47]
	s_add_i32 m0, s48, 0x2000
	s_nop 0
	global_load_lds_dwordx4 v134, s[46:47]
	s_waitcnt vmcnt(6) lgkmcnt(0)
	s_barrier
	s_setprio 1
	v_mfma_f32_16x16x32_bf16 v[66:69], v[150:153], v[182:185], v[66:69]
	v_mfma_f32_16x16x32_bf16 v[62:65], v[158:161], v[182:185], v[62:65]
	v_mfma_f32_16x16x32_bf16 v[50:53], v[150:153], v[190:193], v[50:53]
	v_mfma_f32_16x16x32_bf16 v[46:49], v[158:161], v[190:193], v[46:49]
	v_mfma_f32_16x16x32_bf16 v[34:37], v[150:153], v[206:209], v[34:37]
	v_mfma_f32_16x16x32_bf16 v[30:33], v[158:161], v[206:209], v[30:33]
	v_mfma_f32_16x16x32_bf16 v[18:21], v[150:153], v[228:231], v[18:21]
	v_mfma_f32_16x16x32_bf16 v[14:17], v[158:161], v[228:231], v[14:17]
	v_mfma_f32_16x16x32_bf16 v[66:69], v[154:157], v[186:189], v[66:69]
	v_mfma_f32_16x16x32_bf16 v[62:65], v[162:165], v[186:189], v[62:65]
	v_mfma_f32_16x16x32_bf16 v[50:53], v[154:157], v[194:197], v[50:53]
	v_mfma_f32_16x16x32_bf16 v[46:49], v[162:165], v[194:197], v[46:49]
	v_mfma_f32_16x16x32_bf16 v[34:37], v[154:157], v[224:227], v[34:37]
	v_mfma_f32_16x16x32_bf16 v[30:33], v[162:165], v[224:227], v[30:33]
	v_mfma_f32_16x16x32_bf16 v[18:21], v[154:157], v[232:235], v[18:21]
	v_mfma_f32_16x16x32_bf16 v[14:17], v[162:165], v[232:235], v[14:17]
	s_setprio 0
	s_setprio 1
	v_mfma_f32_16x16x32_bf16 v[58:61], v[166:169], v[182:185], v[58:61]
	v_mfma_f32_16x16x32_bf16 v[54:57], v[174:177], v[182:185], v[54:57]
	v_mfma_f32_16x16x32_bf16 v[42:45], v[166:169], v[190:193], v[42:45]
	v_mfma_f32_16x16x32_bf16 v[38:41], v[174:177], v[190:193], v[38:41]
	v_mfma_f32_16x16x32_bf16 v[26:29], v[166:169], v[206:209], v[26:29]
	v_mfma_f32_16x16x32_bf16 v[22:25], v[174:177], v[206:209], v[22:25]
	v_mfma_f32_16x16x32_bf16 v[8:11], v[166:169], v[228:231], v[10:13]
	v_mfma_f32_16x16x32_bf16 v[4:7], v[174:177], v[228:231], v[4:7]
	v_mfma_f32_16x16x32_bf16 v[58:61], v[170:173], v[186:189], v[58:61]
	v_mfma_f32_16x16x32_bf16 v[54:57], v[178:181], v[186:189], v[54:57]
	v_mfma_f32_16x16x32_bf16 v[42:45], v[170:173], v[194:197], v[42:45]
	v_mfma_f32_16x16x32_bf16 v[38:41], v[178:181], v[194:197], v[38:41]
	v_mfma_f32_16x16x32_bf16 v[26:29], v[170:173], v[224:227], v[26:29]
	v_mfma_f32_16x16x32_bf16 v[22:25], v[178:181], v[224:227], v[22:25]
	v_mfma_f32_16x16x32_bf16 v[10:13], v[170:173], v[232:235], v[8:11]
	v_mfma_f32_16x16x32_bf16 v[6:9], v[178:181], v[232:235], v[4:7]
	s_setprio 0
	s_barrier
	s_add_u32 s44, s44, 0x100
	s_addc_u32 s45, s45, 0
	s_add_u32 s65, s65, 0x100
	s_addc_u32 s66, s66, 0
	s_cmp_ge_i32 s67, s56
	s_mov_b32 s46, s67
	s_cbranch_scc0 .LBB0_1402

; #define PG8_STAGE(bufoff, gbase, voff) do { _Pragma("unroll") for (int _i = 0; _i < 2; ++_i) \
;         __builtin_amdgcn_global_load_lds((const unsigned*)((const char*)(gbase) + (voff)[_i]), (LAS unsigned*)(lds + (bufoff) + ldsw + _i * 8192), 16, 0, 0); } while (0)
; #define PG8_LDA(dst, b, h) do { _Pragma("unroll") for (int m = 0; m < 4; ++m) _Pragma("unroll") for (int k = 0; k < 2; ++k) dst[m][k] = *(const LAS bf16x8*)(lds + PG8_SA(b, h) + aoff + m * 2048 + k * 1024); } while (0)
; #define PG8_LDB(dst, b, h) do { _Pragma("unroll") for (int n = 0; n < 2; ++n) _Pragma("unroll") for (int k = 0; k < 2; ++k) dst[n][k] = *(const LAS bf16x8*)(lds + PG8_SB(b, h) + boff + n * 2048 + k * 1024); } while (0)
; #define PG8_MMA(ai, bj, At, Bt) do { __builtin_amdgcn_s_setprio(1); _Pragma("unroll") for (int m = 0; m < 4; ++m) _Pragma("unroll") for (int n = 0; n < 2; ++n) _Pragma("unroll") for (int k = 0; k < 2; ++k) \
;         acc[ai][bj][m][n] = __builtin_amdgcn_mfma_f32_16x16x32_bf16(Bt[n][k], At[m][k], acc[ai][bj][m][n], 0, 0, 0); __builtin_amdgcn_s_setprio(0); } while (0)
; #define PG8_WAIT_V(n) asm volatile("s_waitcnt vmcnt(" #n ")" ::: "memory")
; #define PG8_WAIT_L(n) asm volatile("s_waitcnt lgkmcnt(" #n ")" ::: "memory")
; #define PG8_BAR __builtin_amdgcn_s_barrier()
; template <class Epi, bool ALIGN_EPI = true>
; __device__ __forceinline__ void gemm_phase(LAS unsigned char* lds, const Gemm g, const Sched& S, const Epi& E) {
;     ...
;         for (int t = t_lo; t < t_hi; t += 2) {
;             const bool last = (t == nt - 2);
;             const char* a1 = cA + (size_t)(t + 1) * kstep;
;             const char* a2 = last ? nA : cA + (size_t)(t + 2) * kstep; const char* b2 = last ? nB : cB + (size_t)(t + 2) * kstep;
;             const char* a3 = a2 + kstep; const char* b3 = b2 + kstep;
;             const int rflag = __builtin_amdgcn_readfirstlane(t | (int)(ui == 0));
;             PG8_LDB(B0, 0, 0); PG8_LDB(B1, 0, 1); PG8_SCHED; PG8_LDA(At, 0, 0); PG8_STAGE(PG8_SA(1, 1), a1 + hstepA, voffA);
;             if constexpr (Epi::NSTORES > 0) PG8_WAIT_RELAX(rflag, 8 + Epi::NSTORES); else PG8_WAIT_V(8);
;             PG8_WAIT_L(0); PG8_BAR; PG8_MMA(0, 0, At, B0); PG8_MMA(0, 1, At, B1); PG8_BAR; PG8_SCHED;
;             PG8_LDA(At, 0, 1); PG8_STAGE(PG8_SB(0, 0), b2, voffB); PG8_STAGE(PG8_SB(0, 1), b2 + hstepB, voffB); PG8_STAGE(PG8_SA(0, 0), a2, voffA);
.LBB0_1457:
	s_add_i32 s69, s46, 2
	s_add_u32 s26, s44, 0xffc00080
	s_addc_u32 s27, s45, -1
	s_add_i32 s70, 0, 0x10000
	s_cmp_eq_u32 s59, s46
	v_add_u32_e32 v223, s46, v145
	s_cselect_b32 s47, s19, s27
	s_cselect_b32 s46, s64, s26
	s_cselect_b32 s27, s65, s68
	s_cselect_b32 s26, s66, s67
	s_add_i32 s72, 0, 0x14000
	v_add_u32_e32 v158, s70, v143
	v_add_u32_e32 v174, s72, v143
	ds_read_b128 v[146:149], v158
	ds_read_b128 v[150:153], v158 offset:1024
	ds_read_b128 v[154:157], v158 offset:2048
	ds_read_b128 v[158:161], v158 offset:3072
	ds_read_b128 v[162:165], v174
	ds_read_b128 v[166:169], v174 offset:1024
	ds_read_b128 v[170:173], v174 offset:2048
	ds_read_b128 v[174:177], v174 offset:3072
	ds_read_b128 v[178:181], v144
	ds_read_b128 v[182:185], v144 offset:1024
	ds_read_b128 v[186:189], v144 offset:2048
	ds_read_b128 v[190:193], v144 offset:3072
	ds_read_b128 v[194:197], v144 offset:4096
	ds_read_b128 v[206:209], v144 offset:5120
	ds_read_b128 v[224:227], v144 offset:6144
	ds_read_b128 v[228:231], v144 offset:7168
	s_mov_b32 m0, s57
	s_add_u32 s100, s44, 0xffc00000
	s_addc_u32 s101, s45, -1
	global_load_lds_dwordx4 v138, s[100:101]
	s_mov_b32 m0, s58
	s_nop 0
	global_load_lds_dwordx4 v140, s[100:101]
	s_add_i32 m0, s48, 0xc000
	s_nop 0
	global_load_lds_dwordx4 v138, s[44:45]
	s_add_i32 m0, s48, 0xe000
	v_readfirstlane_b32 s73, v223
	global_load_lds_dwordx4 v140, s[44:45]
	s_cmp_eq_u32 s73, 0
	s_cbranch_scc1 .Lrw14
	s_waitcnt vmcnt(8)
.Lrw14:
	s_waitcnt vmcnt(24) lgkmcnt(0)
	s_barrier
	s_setprio 1
	v_mfma_f32_16x16x32_bf16 v[124:127], v[146:149], v[178:181], v[124:127]
	v_mfma_f32_16x16x32_bf16 v[128:131], v[154:157], v[178:181], v[128:131]
	v_mfma_f32_16x16x32_bf16 v[112:115], v[146:149], v[186:189], v[112:115]
	v_mfma_f32_16x16x32_bf16 v[108:111], v[154:157], v[186:189], v[108:111]
	v_mfma_f32_16x16x32_bf16 v[96:99], v[146:149], v[194:197], v[96:99]
	v_mfma_f32_16x16x32_bf16 v[92:95], v[154:157], v[194:197], v[92:95]
	v_mfma_f32_16x16x32_bf16 v[80:83], v[146:149], v[224:227], v[80:83]
	v_mfma_f32_16x16x32_bf16 v[76:79], v[154:157], v[224:227], v[76:79]
	v_mfma_f32_16x16x32_bf16 v[124:127], v[150:153], v[182:185], v[124:127]
	v_mfma_f32_16x16x32_bf16 v[128:131], v[158:161], v[182:185], v[128:131]
	v_mfma_f32_16x16x32_bf16 v[112:115], v[150:153], v[190:193], v[112:115]
	v_mfma_f32_16x16x32_bf16 v[108:111], v[158:161], v[190:193], v[108:111]
	v_mfma_f32_16x16x32_bf16 v[96:99], v[150:153], v[206:209], v[96:99]
	v_mfma_f32_16x16x32_bf16 v[92:95], v[158:161], v[206:209], v[92:95]
	v_mfma_f32_16x16x32_bf16 v[80:83], v[150:153], v[228:231], v[80:83]
	v_mfma_f32_16x16x32_bf16 v[76:79], v[158:161], v[228:231], v[76:79]
	s_setprio 0
	s_setprio 1
	v_mfma_f32_16x16x32_bf16 v[120:123], v[162:165], v[178:181], v[120:123]
	v_mfma_f32_16x16x32_bf16 v[116:119], v[170:173], v[178:181], v[116:119]
	v_mfma_f32_16x16x32_bf16 v[104:107], v[162:165], v[186:189], v[104:107]
	v_mfma_f32_16x16x32_bf16 v[100:103], v[170:173], v[186:189], v[100:103]
	v_mfma_f32_16x16x32_bf16 v[88:91], v[162:165], v[194:197], v[88:91]
	v_mfma_f32_16x16x32_bf16 v[84:87], v[170:173], v[194:197], v[84:87]
	v_mfma_f32_16x16x32_bf16 v[72:75], v[162:165], v[224:227], v[72:75]
	v_mfma_f32_16x16x32_bf16 v[68:71], v[170:173], v[224:227], v[68:71]
	v_mfma_f32_16x16x32_bf16 v[120:123], v[166:169], v[182:185], v[120:123]
	v_mfma_f32_16x16x32_bf16 v[116:119], v[174:177], v[182:185], v[116:119]
	v_mfma_f32_16x16x32_bf16 v[104:107], v[166:169], v[190:193], v[104:107]
	v_mfma_f32_16x16x32_bf16 v[100:103], v[174:177], v[190:193], v[100:103]
	v_mfma_f32_16x16x32_bf16 v[88:91], v[166:169], v[206:209], v[88:91]
	v_mfma_f32_16x16x32_bf16 v[84:87], v[174:177], v[206:209], v[84:87]
	v_mfma_f32_16x16x32_bf16 v[72:75], v[166:169], v[228:231], v[72:75]
	v_mfma_f32_16x16x32_bf16 v[68:71], v[174:177], v[228:231], v[68:71]
	s_setprio 0
	s_barrier
	s_add_i32 s70, s70, s37
	s_mov_b32 m0, s70
	ds_read_b128 v[178:181], v144 offset:16384
	ds_read_b128 v[182:185], v144 offset:17408
	ds_read_b128 v[186:189], v144 offset:18432
	ds_read_b128 v[190:193], v144 offset:19456
	ds_read_b128 v[194:197], v144 offset:20480
	ds_read_b128 v[206:209], v144 offset:21504
	ds_read_b128 v[224:227], v144 offset:22528
	ds_read_b128 v[228:231], v144 offset:23552
	global_load_lds_dwordx4 v2, s[26:27]
	s_add_i32 m0, s70, 0x2000
	s_add_u32 s70, s26, 0x80000
	s_addc_u32 s71, s27, 0
	s_add_i32 s72, s72, s37
	global_load_lds_dwordx4 v132, s[26:27]
	s_mov_b32 m0, s72
	s_nop 0
	global_load_lds_dwordx4 v2, s[70:71]
	s_add_i32 m0, s72, 0x2000
	s_nop 0
	global_load_lds_dwordx4 v132, s[70:71]
; #define PG8_STAGE(bufoff, gbase, voff) do { _Pragma("unroll") for (int _i = 0; _i < 2; ++_i) \
;         __builtin_amdgcn_global_load_lds((const unsigned*)((const char*)(gbase) + (voff)[_i]), (LAS unsigned*)(lds + (bufoff) + ldsw + _i * 8192), 16, 0, 0); } while (0)
; #define PG8_LDA(dst, b, h) do { _Pragma("unroll") for (int m = 0; m < 4; ++m) _Pragma("unroll") for (int k = 0; k < 2; ++k) dst[m][k] = *(const LAS bf16x8*)(lds + PG8_SA(b, h) + aoff + m * 2048 + k * 1024); } while (0)
; #define PG8_LDB(dst, b, h) do { _Pragma("unroll") for (int n = 0; n < 2; ++n) _Pragma("unroll") for (int k = 0; k < 2; ++k) dst[n][k] = *(const LAS bf16x8*)(lds + PG8_SB(b, h) + boff + n * 2048 + k * 1024); } while (0)
; #define PG8_MMA(ai, bj, At, Bt) do { __builtin_amdgcn_s_setprio(1); _Pragma("unroll") for (int m = 0; m < 4; ++m) _Pragma("unroll") for (int n = 0; n < 2; ++n) _Pragma("unroll") for (int k = 0; k < 2; ++k) \
;         acc[ai][bj][m][n] = __builtin_amdgcn_mfma_f32_16x16x32_bf16(Bt[n][k], At[m][k], acc[ai][bj][m][n], 0, 0, 0); __builtin_amdgcn_s_setprio(0); } while (0)
; #define PG8_WAIT_V(n) asm volatile("s_waitcnt vmcnt(" #n ")" ::: "memory")
; #define PG8_WAIT_L(n) asm volatile("s_waitcnt lgkmcnt(" #n ")" ::: "memory")
; #define PG8_BAR __builtin_amdgcn_s_barrier()
; #define PG8_WAIT_RELAX(flag, n) asm volatile("s_cmp_eq_u32 %0, 0\n\ts_cbranch_scc1 .Lrw%=\n\ts_waitcnt vmcnt(8)\n.Lrw%=:\n\ts_waitcnt vmcnt(%1)" :: "s"(flag), "n"(n) : "scc", "memory")
; #define PG8_SCHED __builtin_amdgcn_sched_barrier(0)
; template <class Epi, bool ALIGN_EPI = true>
; __device__ __forceinline__ void gemm_phase(LAS unsigned char* lds, const Gemm g, const Sched& S, const Epi& E) {
;     ...
;             if constexpr (Epi::NSTORES > 0) PG8_WAIT_RELAX(rflag, 8 + Epi::NSTORES); else PG8_WAIT_V(8);
;             PG8_WAIT_L(0); PG8_BAR; PG8_MMA(1, 0, At, B0); PG8_MMA(1, 1, At, B1); PG8_BAR; PG8_SCHED;
;             PG8_LDB(B0, 1, 0); PG8_LDB(B1, 1, 1); PG8_SCHED; PG8_LDA(At, 1, 0); PG8_STAGE(PG8_SA(0, 1), a2 + hstepA, voffA);
;             PG8_WAIT_V(8); PG8_WAIT_L(0); PG8_BAR; PG8_MMA(0, 0, At, B0); PG8_MMA(0, 1, At, B1); PG8_BAR; PG8_SCHED;
.Lrw15:
	s_waitcnt vmcnt(6) lgkmcnt(0)
	s_barrier
	s_setprio 1
	v_mfma_f32_16x16x32_bf16 v[64:67], v[146:149], v[178:181], v[64:67]
	v_mfma_f32_16x16x32_bf16 v[60:63], v[154:157], v[178:181], v[60:63]
	v_mfma_f32_16x16x32_bf16 v[48:51], v[146:149], v[186:189], v[48:51]
	v_mfma_f32_16x16x32_bf16 v[44:47], v[154:157], v[186:189], v[44:47]
	v_mfma_f32_16x16x32_bf16 v[32:35], v[146:149], v[194:197], v[32:35]
	v_mfma_f32_16x16x32_bf16 v[28:31], v[154:157], v[194:197], v[28:31]
	v_mfma_f32_16x16x32_bf16 v[16:19], v[146:149], v[224:227], v[16:19]
	v_mfma_f32_16x16x32_bf16 v[12:15], v[154:157], v[224:227], v[12:15]
	v_mfma_f32_16x16x32_bf16 v[64:67], v[150:153], v[182:185], v[64:67]
	v_mfma_f32_16x16x32_bf16 v[60:63], v[158:161], v[182:185], v[60:63]
	v_mfma_f32_16x16x32_bf16 v[48:51], v[150:153], v[190:193], v[48:51]
	v_mfma_f32_16x16x32_bf16 v[44:47], v[158:161], v[190:193], v[44:47]
	v_mfma_f32_16x16x32_bf16 v[32:35], v[150:153], v[206:209], v[32:35]
	v_mfma_f32_16x16x32_bf16 v[28:31], v[158:161], v[206:209], v[28:31]
	v_mfma_f32_16x16x32_bf16 v[16:19], v[150:153], v[228:231], v[16:19]
	v_mfma_f32_16x16x32_bf16 v[12:15], v[158:161], v[228:231], v[12:15]
	s_setprio 0
	s_setprio 1
	v_mfma_f32_16x16x32_bf16 v[56:59], v[162:165], v[178:181], v[56:59]
	v_mfma_f32_16x16x32_bf16 v[52:55], v[170:173], v[178:181], v[52:55]
	v_mfma_f32_16x16x32_bf16 v[40:43], v[162:165], v[186:189], v[40:43]
	v_mfma_f32_16x16x32_bf16 v[36:39], v[170:173], v[186:189], v[36:39]
	v_mfma_f32_16x16x32_bf16 v[24:27], v[162:165], v[194:197], v[24:27]
	v_mfma_f32_16x16x32_bf16 v[20:23], v[170:173], v[194:197], v[20:23]
	v_mfma_f32_16x16x32_bf16 v[8:11], v[162:165], v[224:227], v[8:11]
	v_mfma_f32_16x16x32_bf16 v[4:7], v[170:173], v[224:227], v[4:7]
	v_mfma_f32_16x16x32_bf16 v[56:59], v[166:169], v[182:185], v[56:59]
	v_mfma_f32_16x16x32_bf16 v[52:55], v[174:177], v[182:185], v[52:55]
	v_mfma_f32_16x16x32_bf16 v[40:43], v[166:169], v[190:193], v[40:43]
	v_mfma_f32_16x16x32_bf16 v[36:39], v[174:177], v[190:193], v[36:39]
	v_mfma_f32_16x16x32_bf16 v[24:27], v[166:169], v[206:209], v[24:27]
	v_mfma_f32_16x16x32_bf16 v[20:23], v[174:177], v[206:209], v[20:23]
	v_mfma_f32_16x16x32_bf16 v[8:11], v[166:169], v[228:231], v[8:11]
	v_mfma_f32_16x16x32_bf16 v[4:7], v[174:177], v[228:231], v[4:7]
	s_setprio 0
	s_barrier
	s_add_i32 s70, 0, 0x18000
	s_add_i32 s71, 0, 0x1c000
	v_add_u32_e32 v158, s70, v143
	v_add_u32_e32 v174, s71, v143
	ds_read_b128 v[146:149], v158
	ds_read_b128 v[150:153], v158 offset:1024
	ds_read_b128 v[154:157], v158 offset:2048
	ds_read_b128 v[158:161], v158 offset:3072
	ds_read_b128 v[162:165], v174
	ds_read_b128 v[166:169], v174 offset:1024
	ds_read_b128 v[170:173], v174 offset:2048
	ds_read_b128 v[174:177], v174 offset:3072
	s_add_u32 s46, s46, 0x400000
	s_addc_u32 s47, s47, 0
	ds_read_b128 v[178:181], v144 offset:32768
	ds_read_b128 v[182:185], v144 offset:33792
	ds_read_b128 v[186:189], v144 offset:34816
	ds_read_b128 v[190:193], v144 offset:35840
	ds_read_b128 v[194:197], v144 offset:36864
	ds_read_b128 v[206:209], v144 offset:37888
	ds_read_b128 v[224:227], v144 offset:38912
	ds_read_b128 v[228:231], v144 offset:39936
	s_mov_b32 m0, s48
	s_add_u32 s100, s46, 0xffc00000
	s_addc_u32 s101, s47, -1
	global_load_lds_dwordx4 v136, s[100:101]
	s_mov_b32 m0, s49
	s_nop 0
	global_load_lds_dwordx4 v134, s[100:101]
	s_mov_b32 m0, s50
	s_nop 0
	global_load_lds_dwordx4 v136, s[46:47]
	s_mov_b32 m0, s51
	s_nop 0
	global_load_lds_dwordx4 v134, s[46:47]
	s_waitcnt vmcnt(8) lgkmcnt(0)
	s_barrier
; #define PG8_STAGE(bufoff, gbase, voff) do { _Pragma("unroll") for (int _i = 0; _i < 2; ++_i) \
;         __builtin_amdgcn_global_load_lds((const unsigned*)((const char*)(gbase) + (voff)[_i]), (LAS unsigned*)(lds + (bufoff) + ldsw + _i * 8192), 16, 0, 0); } while (0)
; #define PG8_LDA(dst, b, h) do { _Pragma("unroll") for (int m = 0; m < 4; ++m) _Pragma("unroll") for (int k = 0; k < 2; ++k) dst[m][k] = *(const LAS bf16x8*)(lds + PG8_SA(b, h) + aoff + m * 2048 + k * 1024); } while (0)
; #define PG8_MMA(ai, bj, At, Bt) do { __builtin_amdgcn_s_setprio(1); _Pragma("unroll") for (int m = 0; m < 4; ++m) _Pragma("unroll") for (int n = 0; n < 2; ++n) _Pragma("unroll") for (int k = 0; k < 2; ++k) \
;         acc[ai][bj][m][n] = __builtin_amdgcn_mfma_f32_16x16x32_bf16(Bt[n][k], At[m][k], acc[ai][bj][m][n], 0, 0, 0); __builtin_amdgcn_s_setprio(0); } while (0)
; #define PG8_WAIT_V(n) asm volatile("s_waitcnt vmcnt(" #n ")" ::: "memory")
; #define PG8_WAIT_L(n) asm volatile("s_waitcnt lgkmcnt(" #n ")" ::: "memory")
; #define PG8_BAR __builtin_amdgcn_s_barrier()
; #define PG8_SCHED __builtin_amdgcn_sched_barrier(0)
; template <class Epi, bool ALIGN_EPI = true>
; __device__ __forceinline__ void gemm_phase(LAS unsigned char* lds, const Gemm g, const Sched& S, const Epi& E) {
;     ...
;             PG8_WAIT_V(8); PG8_WAIT_L(0); PG8_BAR; PG8_MMA(0, 0, At, B0); PG8_MMA(0, 1, At, B1); PG8_BAR; PG8_SCHED;
;             PG8_LDA(At, 1, 1); PG8_STAGE(PG8_SB(1, 0), b3, voffB); PG8_STAGE(PG8_SB(1, 1), b3 + hstepB, voffB); PG8_STAGE(PG8_SA(1, 0), a3, voffA);
;             PG8_WAIT_V(8); PG8_WAIT_L(0); PG8_BAR; PG8_MMA(1, 0, At, B0); PG8_MMA(1, 1, At, B1); PG8_BAR; PG8_SCHED;
;         }
	s_setprio 1
	v_mfma_f32_16x16x32_bf16 v[124:127], v[146:149], v[178:181], v[124:127]
	v_mfma_f32_16x16x32_bf16 v[128:131], v[154:157], v[178:181], v[128:131]
	v_mfma_f32_16x16x32_bf16 v[112:115], v[146:149], v[186:189], v[112:115]
	v_mfma_f32_16x16x32_bf16 v[108:111], v[154:157], v[186:189], v[108:111]
	v_mfma_f32_16x16x32_bf16 v[96:99], v[146:149], v[194:197], v[96:99]
	v_mfma_f32_16x16x32_bf16 v[92:95], v[154:157], v[194:197], v[92:95]
	v_mfma_f32_16x16x32_bf16 v[80:83], v[146:149], v[224:227], v[80:83]
	v_mfma_f32_16x16x32_bf16 v[76:79], v[154:157], v[224:227], v[76:79]
	v_mfma_f32_16x16x32_bf16 v[124:127], v[150:153], v[182:185], v[124:127]
	v_mfma_f32_16x16x32_bf16 v[128:131], v[158:161], v[182:185], v[128:131]
	v_mfma_f32_16x16x32_bf16 v[112:115], v[150:153], v[190:193], v[112:115]
	v_mfma_f32_16x16x32_bf16 v[108:111], v[158:161], v[190:193], v[108:111]
	v_mfma_f32_16x16x32_bf16 v[96:99], v[150:153], v[206:209], v[96:99]
	v_mfma_f32_16x16x32_bf16 v[92:95], v[158:161], v[206:209], v[92:95]
	v_mfma_f32_16x16x32_bf16 v[80:83], v[150:153], v[228:231], v[80:83]
	v_mfma_f32_16x16x32_bf16 v[76:79], v[158:161], v[228:231], v[76:79]
	s_setprio 0
	s_setprio 1
	v_mfma_f32_16x16x32_bf16 v[120:123], v[162:165], v[178:181], v[120:123]
	v_mfma_f32_16x16x32_bf16 v[116:119], v[170:173], v[178:181], v[116:119]
	v_mfma_f32_16x16x32_bf16 v[104:107], v[162:165], v[186:189], v[104:107]
	v_mfma_f32_16x16x32_bf16 v[100:103], v[170:173], v[186:189], v[100:103]
	v_mfma_f32_16x16x32_bf16 v[88:91], v[162:165], v[194:197], v[88:91]
	v_mfma_f32_16x16x32_bf16 v[84:87], v[170:173], v[194:197], v[84:87]
	v_mfma_f32_16x16x32_bf16 v[72:75], v[162:165], v[224:227], v[72:75]
	v_mfma_f32_16x16x32_bf16 v[68:71], v[170:173], v[224:227], v[68:71]
	v_mfma_f32_16x16x32_bf16 v[120:123], v[166:169], v[182:185], v[120:123]
	v_mfma_f32_16x16x32_bf16 v[116:119], v[174:177], v[182:185], v[116:119]
	v_mfma_f32_16x16x32_bf16 v[104:107], v[166:169], v[190:193], v[104:107]
	v_mfma_f32_16x16x32_bf16 v[100:103], v[174:177], v[190:193], v[100:103]
	v_mfma_f32_16x16x32_bf16 v[88:91], v[166:169], v[206:209], v[88:91]
	v_mfma_f32_16x16x32_bf16 v[84:87], v[174:177], v[206:209], v[84:87]
	v_mfma_f32_16x16x32_bf16 v[72:75], v[166:169], v[228:231], v[72:75]
	v_mfma_f32_16x16x32_bf16 v[68:71], v[174:177], v[228:231], v[68:71]
	s_setprio 0
	s_barrier
	s_add_u32 s100, s26, 0x80
	s_addc_u32 s101, s27, 0
	s_add_i32 s46, s70, s37
	s_mov_b32 m0, s46
	ds_read_b128 v[178:181], v144 offset:49152
	ds_read_b128 v[182:185], v144 offset:50176
	ds_read_b128 v[186:189], v144 offset:51200
	ds_read_b128 v[190:193], v144 offset:52224
	ds_read_b128 v[194:197], v144 offset:53248
	ds_read_b128 v[206:209], v144 offset:54272
	ds_read_b128 v[224:227], v144 offset:55296
	ds_read_b128 v[228:231], v144 offset:56320
	global_load_lds_dwordx4 v2, s[100:101]
	s_add_i32 m0, s46, 0x2000
	s_add_u32 s26, s26, 0x80080
	s_addc_u32 s27, s27, 0
	s_add_i32 s46, s71, s37
	global_load_lds_dwordx4 v132, s[100:101]
	s_mov_b32 m0, s46
	s_nop 0
	global_load_lds_dwordx4 v2, s[26:27]
	s_add_i32 m0, s46, 0x2000
	s_nop 0
	global_load_lds_dwordx4 v132, s[26:27]
	s_waitcnt vmcnt(6) lgkmcnt(0)
	s_barrier
	s_setprio 1
	v_mfma_f32_16x16x32_bf16 v[64:67], v[146:149], v[178:181], v[64:67]
	v_mfma_f32_16x16x32_bf16 v[60:63], v[154:157], v[178:181], v[60:63]
	v_mfma_f32_16x16x32_bf16 v[48:51], v[146:149], v[186:189], v[48:51]
	v_mfma_f32_16x16x32_bf16 v[44:47], v[154:157], v[186:189], v[44:47]
	v_mfma_f32_16x16x32_bf16 v[32:35], v[146:149], v[194:197], v[32:35]
	v_mfma_f32_16x16x32_bf16 v[28:31], v[154:157], v[194:197], v[28:31]
	v_mfma_f32_16x16x32_bf16 v[16:19], v[146:149], v[224:227], v[16:19]
	v_mfma_f32_16x16x32_bf16 v[12:15], v[154:157], v[224:227], v[12:15]
	v_mfma_f32_16x16x32_bf16 v[64:67], v[150:153], v[182:185], v[64:67]
	v_mfma_f32_16x16x32_bf16 v[60:63], v[158:161], v[182:185], v[60:63]
	v_mfma_f32_16x16x32_bf16 v[48:51], v[150:153], v[190:193], v[48:51]
	v_mfma_f32_16x16x32_bf16 v[44:47], v[158:161], v[190:193], v[44:47]
	v_mfma_f32_16x16x32_bf16 v[32:35], v[150:153], v[206:209], v[32:35]
	v_mfma_f32_16x16x32_bf16 v[28:31], v[158:161], v[206:209], v[28:31]
	v_mfma_f32_16x16x32_bf16 v[16:19], v[150:153], v[228:231], v[16:19]
	v_mfma_f32_16x16x32_bf16 v[12:15], v[158:161], v[228:231], v[12:15]
	s_setprio 0
	s_setprio 1
	v_mfma_f32_16x16x32_bf16 v[56:59], v[162:165], v[178:181], v[56:59]
	v_mfma_f32_16x16x32_bf16 v[52:55], v[170:173], v[178:181], v[52:55]
	v_mfma_f32_16x16x32_bf16 v[40:43], v[162:165], v[186:189], v[40:43]
	v_mfma_f32_16x16x32_bf16 v[36:39], v[170:173], v[186:189], v[36:39]
	v_mfma_f32_16x16x32_bf16 v[24:27], v[162:165], v[194:197], v[24:27]
	v_mfma_f32_16x16x32_bf16 v[20:23], v[170:173], v[194:197], v[20:23]
	v_mfma_f32_16x16x32_bf16 v[8:11], v[162:165], v[224:227], v[8:11]
	v_mfma_f32_16x16x32_bf16 v[4:7], v[170:173], v[224:227], v[4:7]
	v_mfma_f32_16x16x32_bf16 v[56:59], v[166:169], v[182:185], v[56:59]
	v_mfma_f32_16x16x32_bf16 v[52:55], v[174:177], v[182:185], v[52:55]
	v_mfma_f32_16x16x32_bf16 v[40:43], v[166:169], v[190:193], v[40:43]
	v_mfma_f32_16x16x32_bf16 v[36:39], v[174:177], v[190:193], v[36:39]
	v_mfma_f32_16x16x32_bf16 v[24:27], v[166:169], v[206:209], v[24:27]
	v_mfma_f32_16x16x32_bf16 v[20:23], v[174:177], v[206:209], v[20:23]
	v_mfma_f32_16x16x32_bf16 v[8:11], v[166:169], v[228:231], v[8:11]
	v_mfma_f32_16x16x32_bf16 v[4:7], v[174:177], v[228:231], v[4:7]
	s_setprio 0
	s_barrier
	s_add_u32 s44, s44, 0x100
	s_addc_u32 s45, s45, 0
	s_add_u32 s67, s67, 0x100
	s_addc_u32 s68, s68, 0
	s_cmp_ge_i32 s69, s54
	s_mov_b32 s46, s69
	s_cbranch_scc0 .LBB0_1457

; #define PG8_STAGE(bufoff, gbase, voff) do { _Pragma("unroll") for (int _i = 0; _i < 2; ++_i) \
;         __builtin_amdgcn_global_load_lds((const unsigned*)((const char*)(gbase) + (voff)[_i]), (LAS unsigned*)(lds + (bufoff) + ldsw + _i * 8192), 16, 0, 0); } while (0)
; #define PG8_LDA(dst, b, h) do { _Pragma("unroll") for (int m = 0; m < 4; ++m) _Pragma("unroll") for (int k = 0; k < 2; ++k) dst[m][k] = *(const LAS bf16x8*)(lds + PG8_SA(b, h) + aoff + m * 2048 + k * 1024); } while (0)
; #define PG8_LDB(dst, b, h) do { _Pragma("unroll") for (int n = 0; n < 2; ++n) _Pragma("unroll") for (int k = 0; k < 2; ++k) dst[n][k] = *(const LAS bf16x8*)(lds + PG8_SB(b, h) + boff + n * 2048 + k * 1024); } while (0)
; #define PG8_MMA(ai, bj, At, Bt) do { __builtin_amdgcn_s_setprio(1); _Pragma("unroll") for (int m = 0; m < 4; ++m) _Pragma("unroll") for (int n = 0; n < 2; ++n) _Pragma("unroll") for (int k = 0; k < 2; ++k) \
;         acc[ai][bj][m][n] = __builtin_amdgcn_mfma_f32_16x16x32_bf16(Bt[n][k], At[m][k], acc[ai][bj][m][n], 0, 0, 0); __builtin_amdgcn_s_setprio(0); } while (0)
; #define PG8_WAIT_V(n) asm volatile("s_waitcnt vmcnt(" #n ")" ::: "memory")
; #define PG8_WAIT_L(n) asm volatile("s_waitcnt lgkmcnt(" #n ")" ::: "memory")
; #define PG8_BAR __builtin_amdgcn_s_barrier()
; #define PG8_SCHED __builtin_amdgcn_sched_barrier(0)
; template <class Epi, bool ALIGN_EPI = true>
; __device__ __forceinline__ void gemm_phase(LAS unsigned char* lds, const Gemm g, const Sched& S, const Epi& E) {
;     ...
;             const int rflag = __builtin_amdgcn_readfirstlane(t | (int)(ui == 0));
;             PG8_LDB(B0, 0, 0); PG8_LDB(B1, 0, 1); PG8_SCHED; PG8_LDA(At, 0, 0); PG8_STAGE(PG8_SA(1, 1), a1 + hstepA, voffA);
;             if constexpr (Epi::NSTORES > 0) PG8_WAIT_RELAX(rflag, 8 + Epi::NSTORES); else PG8_WAIT_V(8);
;             PG8_WAIT_L(0); PG8_BAR; PG8_MMA(0, 0, At, B0); PG8_MMA(0, 1, At, B1); PG8_BAR; PG8_SCHED;
;             PG8_LDA(At, 0, 1); PG8_STAGE(PG8_SB(0, 0), b2, voffB); PG8_STAGE(PG8_SB(0, 1), b2 + hstepB, voffB); PG8_STAGE(PG8_SA(0, 0), a2, voffA);
;             if constexpr (Epi::NSTORES > 0) PG8_WAIT_RELAX(rflag, 8 + Epi::NSTORES); else PG8_WAIT_V(8);
;             PG8_WAIT_L(0); PG8_BAR; PG8_MMA(1, 0, At, B0); PG8_MMA(1, 1, At, B1); PG8_BAR; PG8_SCHED;
.LBB0_1479:
	s_add_i32 s67, s44, 2
	s_add_u32 s26, s42, 0xfff80080
	s_addc_u32 s27, s43, -1
	s_add_i32 s68, 0, 0x10000
	s_cmp_eq_u32 s57, s44
	v_add_u32_e32 v223, s44, v145
	s_cselect_b32 s45, s17, s27
	s_cselect_b32 s44, s62, s26
	s_cselect_b32 s27, s63, s66
	s_cselect_b32 s26, s64, s65
	s_add_i32 s70, 0, 0x14000
	v_add_u32_e32 v158, s68, v143
	v_add_u32_e32 v174, s70, v143
	ds_read_b128 v[146:149], v158
	ds_read_b128 v[150:153], v158 offset:1024
	ds_read_b128 v[154:157], v158 offset:2048
	ds_read_b128 v[158:161], v158 offset:3072
	ds_read_b128 v[162:165], v174
	ds_read_b128 v[166:169], v174 offset:1024
	ds_read_b128 v[170:173], v174 offset:2048
	ds_read_b128 v[174:177], v174 offset:3072
	ds_read_b128 v[178:181], v144
	ds_read_b128 v[182:185], v144 offset:1024
	ds_read_b128 v[186:189], v144 offset:2048
	ds_read_b128 v[190:193], v144 offset:3072
	ds_read_b128 v[194:197], v144 offset:4096
	ds_read_b128 v[206:209], v144 offset:5120
	ds_read_b128 v[224:227], v144 offset:6144
	ds_read_b128 v[228:231], v144 offset:7168
	s_mov_b32 m0, s55
	s_add_u32 s100, s42, 0xfff80000
	s_addc_u32 s101, s43, -1
	global_load_lds_dwordx4 v138, s[100:101]
	s_mov_b32 m0, s56
	s_nop 0
	global_load_lds_dwordx4 v140, s[100:101]
	s_add_i32 m0, s46, 0xc000
	s_nop 0
	global_load_lds_dwordx4 v138, s[42:43]
	s_add_i32 m0, s46, 0xe000
	v_readfirstlane_b32 s71, v223
	global_load_lds_dwordx4 v140, s[42:43]
	s_cmp_eq_u32 s71, 0
	s_cbranch_scc1 .Lrw16
	s_waitcnt vmcnt(8)
.Lrw16:
	s_waitcnt vmcnt(24) lgkmcnt(0)
	s_barrier
	s_setprio 1
	v_mfma_f32_16x16x32_bf16 v[124:127], v[146:149], v[178:181], v[124:127]
	v_mfma_f32_16x16x32_bf16 v[128:131], v[154:157], v[178:181], v[128:131]
	v_mfma_f32_16x16x32_bf16 v[112:115], v[146:149], v[186:189], v[112:115]
	v_mfma_f32_16x16x32_bf16 v[108:111], v[154:157], v[186:189], v[108:111]
	v_mfma_f32_16x16x32_bf16 v[96:99], v[146:149], v[194:197], v[96:99]
	v_mfma_f32_16x16x32_bf16 v[92:95], v[154:157], v[194:197], v[92:95]
	v_mfma_f32_16x16x32_bf16 v[80:83], v[146:149], v[224:227], v[80:83]
	v_mfma_f32_16x16x32_bf16 v[76:79], v[154:157], v[224:227], v[76:79]
	v_mfma_f32_16x16x32_bf16 v[124:127], v[150:153], v[182:185], v[124:127]
	v_mfma_f32_16x16x32_bf16 v[128:131], v[158:161], v[182:185], v[128:131]
	v_mfma_f32_16x16x32_bf16 v[112:115], v[150:153], v[190:193], v[112:115]
	v_mfma_f32_16x16x32_bf16 v[108:111], v[158:161], v[190:193], v[108:111]
	v_mfma_f32_16x16x32_bf16 v[96:99], v[150:153], v[206:209], v[96:99]
	v_mfma_f32_16x16x32_bf16 v[92:95], v[158:161], v[206:209], v[92:95]
	v_mfma_f32_16x16x32_bf16 v[80:83], v[150:153], v[228:231], v[80:83]
	v_mfma_f32_16x16x32_bf16 v[76:79], v[158:161], v[228:231], v[76:79]
	s_setprio 0
	s_setprio 1
	v_mfma_f32_16x16x32_bf16 v[120:123], v[162:165], v[178:181], v[120:123]
	v_mfma_f32_16x16x32_bf16 v[116:119], v[170:173], v[178:181], v[116:119]
	v_mfma_f32_16x16x32_bf16 v[104:107], v[162:165], v[186:189], v[104:107]
	v_mfma_f32_16x16x32_bf16 v[100:103], v[170:173], v[186:189], v[100:103]
	v_mfma_f32_16x16x32_bf16 v[88:91], v[162:165], v[194:197], v[88:91]
	v_mfma_f32_16x16x32_bf16 v[84:87], v[170:173], v[194:197], v[84:87]
	v_mfma_f32_16x16x32_bf16 v[72:75], v[162:165], v[224:227], v[72:75]
	v_mfma_f32_16x16x32_bf16 v[68:71], v[170:173], v[224:227], v[68:71]
	v_mfma_f32_16x16x32_bf16 v[120:123], v[166:169], v[182:185], v[120:123]
	v_mfma_f32_16x16x32_bf16 v[116:119], v[174:177], v[182:185], v[116:119]
	v_mfma_f32_16x16x32_bf16 v[104:107], v[166:169], v[190:193], v[104:107]
	v_mfma_f32_16x16x32_bf16 v[100:103], v[174:177], v[190:193], v[100:103]
	v_mfma_f32_16x16x32_bf16 v[88:91], v[166:169], v[206:209], v[88:91]
	v_mfma_f32_16x16x32_bf16 v[84:87], v[174:177], v[206:209], v[84:87]
	v_mfma_f32_16x16x32_bf16 v[72:75], v[166:169], v[228:231], v[72:75]
	v_mfma_f32_16x16x32_bf16 v[68:71], v[174:177], v[228:231], v[68:71]
	s_setprio 0
	s_barrier
	s_add_i32 s68, s68, s37
	s_mov_b32 m0, s68
	ds_read_b128 v[178:181], v144 offset:16384
	ds_read_b128 v[182:185], v144 offset:17408
	ds_read_b128 v[186:189], v144 offset:18432
	ds_read_b128 v[190:193], v144 offset:19456
	ds_read_b128 v[194:197], v144 offset:20480
	ds_read_b128 v[206:209], v144 offset:21504
	ds_read_b128 v[224:227], v144 offset:22528
	ds_read_b128 v[228:231], v144 offset:23552
	global_load_lds_dwordx4 v2, s[26:27]
	s_add_i32 m0, s68, 0x2000
	s_add_u32 s68, s26, 0x400000
	s_addc_u32 s69, s27, 0
	s_add_i32 s70, s70, s37
	global_load_lds_dwordx4 v132, s[26:27]
	s_mov_b32 m0, s70
	s_nop 0
	global_load_lds_dwordx4 v2, s[68:69]
	s_add_i32 m0, s70, 0x2000
	s_nop 0
	global_load_lds_dwordx4 v132, s[68:69]
; #define PG8_STAGE(bufoff, gbase, voff) do { _Pragma("unroll") for (int _i = 0; _i < 2; ++_i) \
;         __builtin_amdgcn_global_load_lds((const unsigned*)((const char*)(gbase) + (voff)[_i]), (LAS unsigned*)(lds + (bufoff) + ldsw + _i * 8192), 16, 0, 0); } while (0)
; #define PG8_LDA(dst, b, h) do { _Pragma("unroll") for (int m = 0; m < 4; ++m) _Pragma("unroll") for (int k = 0; k < 2; ++k) dst[m][k] = *(const LAS bf16x8*)(lds + PG8_SA(b, h) + aoff + m * 2048 + k * 1024); } while (0)
; #define PG8_LDB(dst, b, h) do { _Pragma("unroll") for (int n = 0; n < 2; ++n) _Pragma("unroll") for (int k = 0; k < 2; ++k) dst[n][k] = *(const LAS bf16x8*)(lds + PG8_SB(b, h) + boff + n * 2048 + k * 1024); } while (0)
; #define PG8_MMA(ai, bj, At, Bt) do { __builtin_amdgcn_s_setprio(1); _Pragma("unroll") for (int m = 0; m < 4; ++m) _Pragma("unroll") for (int n = 0; n < 2; ++n) _Pragma("unroll") for (int k = 0; k < 2; ++k) \
;         acc[ai][bj][m][n] = __builtin_amdgcn_mfma_f32_16x16x32_bf16(Bt[n][k], At[m][k], acc[ai][bj][m][n], 0, 0, 0); __builtin_amdgcn_s_setprio(0); } while (0)
; #define PG8_WAIT_V(n) asm volatile("s_waitcnt vmcnt(" #n ")" ::: "memory")
; #define PG8_WAIT_L(n) asm volatile("s_waitcnt lgkmcnt(" #n ")" ::: "memory")
; #define PG8_BAR __builtin_amdgcn_s_barrier()
; #define PG8_WAIT_RELAX(flag, n) asm volatile("s_cmp_eq_u32 %0, 0\n\ts_cbranch_scc1 .Lrw%=\n\ts_waitcnt vmcnt(8)\n.Lrw%=:\n\ts_waitcnt vmcnt(%1)" :: "s"(flag), "n"(n) : "scc", "memory")
; #define PG8_SCHED __builtin_amdgcn_sched_barrier(0)
; template <class Epi, bool ALIGN_EPI = true>
; __device__ __forceinline__ void gemm_phase(LAS unsigned char* lds, const Gemm g, const Sched& S, const Epi& E) {
;     ...
;             if constexpr (Epi::NSTORES > 0) PG8_WAIT_RELAX(rflag, 8 + Epi::NSTORES); else PG8_WAIT_V(8);
;             PG8_WAIT_L(0); PG8_BAR; PG8_MMA(1, 0, At, B0); PG8_MMA(1, 1, At, B1); PG8_BAR; PG8_SCHED;
;             PG8_LDB(B0, 1, 0); PG8_LDB(B1, 1, 1); PG8_SCHED; PG8_LDA(At, 1, 0); PG8_STAGE(PG8_SA(0, 1), a2 + hstepA, voffA);
;             PG8_WAIT_V(8); PG8_WAIT_L(0); PG8_BAR; PG8_MMA(0, 0, At, B0); PG8_MMA(0, 1, At, B1); PG8_BAR; PG8_SCHED;
.Lrw17:
	s_waitcnt vmcnt(6) lgkmcnt(0)
	s_barrier
	s_setprio 1
	v_mfma_f32_16x16x32_bf16 v[64:67], v[146:149], v[178:181], v[64:67]
	v_mfma_f32_16x16x32_bf16 v[60:63], v[154:157], v[178:181], v[60:63]
	v_mfma_f32_16x16x32_bf16 v[48:51], v[146:149], v[186:189], v[48:51]
	v_mfma_f32_16x16x32_bf16 v[44:47], v[154:157], v[186:189], v[44:47]
	v_mfma_f32_16x16x32_bf16 v[32:35], v[146:149], v[194:197], v[32:35]
	v_mfma_f32_16x16x32_bf16 v[28:31], v[154:157], v[194:197], v[28:31]
	v_mfma_f32_16x16x32_bf16 v[16:19], v[146:149], v[224:227], v[16:19]
	v_mfma_f32_16x16x32_bf16 v[12:15], v[154:157], v[224:227], v[12:15]
	v_mfma_f32_16x16x32_bf16 v[64:67], v[150:153], v[182:185], v[64:67]
	v_mfma_f32_16x16x32_bf16 v[60:63], v[158:161], v[182:185], v[60:63]
	v_mfma_f32_16x16x32_bf16 v[48:51], v[150:153], v[190:193], v[48:51]
	v_mfma_f32_16x16x32_bf16 v[44:47], v[158:161], v[190:193], v[44:47]
	v_mfma_f32_16x16x32_bf16 v[32:35], v[150:153], v[206:209], v[32:35]
	v_mfma_f32_16x16x32_bf16 v[28:31], v[158:161], v[206:209], v[28:31]
	v_mfma_f32_16x16x32_bf16 v[16:19], v[150:153], v[228:231], v[16:19]
	v_mfma_f32_16x16x32_bf16 v[12:15], v[158:161], v[228:231], v[12:15]
	s_setprio 0
	s_setprio 1
	v_mfma_f32_16x16x32_bf16 v[56:59], v[162:165], v[178:181], v[56:59]
	v_mfma_f32_16x16x32_bf16 v[52:55], v[170:173], v[178:181], v[52:55]
	v_mfma_f32_16x16x32_bf16 v[40:43], v[162:165], v[186:189], v[40:43]
	v_mfma_f32_16x16x32_bf16 v[36:39], v[170:173], v[186:189], v[36:39]
	v_mfma_f32_16x16x32_bf16 v[24:27], v[162:165], v[194:197], v[24:27]
	v_mfma_f32_16x16x32_bf16 v[20:23], v[170:173], v[194:197], v[20:23]
	v_mfma_f32_16x16x32_bf16 v[8:11], v[162:165], v[224:227], v[8:11]
	v_mfma_f32_16x16x32_bf16 v[4:7], v[170:173], v[224:227], v[4:7]
	v_mfma_f32_16x16x32_bf16 v[56:59], v[166:169], v[182:185], v[56:59]
	v_mfma_f32_16x16x32_bf16 v[52:55], v[174:177], v[182:185], v[52:55]
	v_mfma_f32_16x16x32_bf16 v[40:43], v[166:169], v[190:193], v[40:43]
	v_mfma_f32_16x16x32_bf16 v[36:39], v[174:177], v[190:193], v[36:39]
	v_mfma_f32_16x16x32_bf16 v[24:27], v[166:169], v[206:209], v[24:27]
	v_mfma_f32_16x16x32_bf16 v[20:23], v[174:177], v[206:209], v[20:23]
	v_mfma_f32_16x16x32_bf16 v[8:11], v[166:169], v[228:231], v[8:11]
	v_mfma_f32_16x16x32_bf16 v[4:7], v[174:177], v[228:231], v[4:7]
	s_setprio 0
	s_barrier
	s_add_i32 s68, 0, 0x18000
	s_add_i32 s69, 0, 0x1c000
	v_add_u32_e32 v158, s68, v143
	v_add_u32_e32 v174, s69, v143
	ds_read_b128 v[146:149], v158
	ds_read_b128 v[150:153], v158 offset:1024
	ds_read_b128 v[154:157], v158 offset:2048
	ds_read_b128 v[158:161], v158 offset:3072
	ds_read_b128 v[162:165], v174
	ds_read_b128 v[166:169], v174 offset:1024
	ds_read_b128 v[170:173], v174 offset:2048
	ds_read_b128 v[174:177], v174 offset:3072
	s_add_u32 s44, s44, 0x80000
	s_addc_u32 s45, s45, 0
	ds_read_b128 v[178:181], v144 offset:32768
	ds_read_b128 v[182:185], v144 offset:33792
	ds_read_b128 v[186:189], v144 offset:34816
	ds_read_b128 v[190:193], v144 offset:35840
	ds_read_b128 v[194:197], v144 offset:36864
	ds_read_b128 v[206:209], v144 offset:37888
	ds_read_b128 v[224:227], v144 offset:38912
	ds_read_b128 v[228:231], v144 offset:39936
	s_mov_b32 m0, s46
	s_add_u32 s100, s44, 0xfff80000
	s_addc_u32 s101, s45, -1
	global_load_lds_dwordx4 v136, s[100:101]
	s_mov_b32 m0, s47
	s_nop 0
	global_load_lds_dwordx4 v134, s[100:101]
	s_mov_b32 m0, s48
	s_nop 0
	global_load_lds_dwordx4 v136, s[44:45]
	s_mov_b32 m0, s49
	s_nop 0
	global_load_lds_dwordx4 v134, s[44:45]
	s_waitcnt vmcnt(8) lgkmcnt(0)
	s_barrier
; #define PG8_STAGE(bufoff, gbase, voff) do { _Pragma("unroll") for (int _i = 0; _i < 2; ++_i) \
;         __builtin_amdgcn_global_load_lds((const unsigned*)((const char*)(gbase) + (voff)[_i]), (LAS unsigned*)(lds + (bufoff) + ldsw + _i * 8192), 16, 0, 0); } while (0)
; #define PG8_LDA(dst, b, h) do { _Pragma("unroll") for (int m = 0; m < 4; ++m) _Pragma("unroll") for (int k = 0; k < 2; ++k) dst[m][k] = *(const LAS bf16x8*)(lds + PG8_SA(b, h) + aoff + m * 2048 + k * 1024); } while (0)
; #define PG8_MMA(ai, bj, At, Bt) do { __builtin_amdgcn_s_setprio(1); _Pragma("unroll") for (int m = 0; m < 4; ++m) _Pragma("unroll") for (int n = 0; n < 2; ++n) _Pragma("unroll") for (int k = 0; k < 2; ++k) \
;         acc[ai][bj][m][n] = __builtin_amdgcn_mfma_f32_16x16x32_bf16(Bt[n][k], At[m][k], acc[ai][bj][m][n], 0, 0, 0); __builtin_amdgcn_s_setprio(0); } while (0)
; #define PG8_WAIT_V(n) asm volatile("s_waitcnt vmcnt(" #n ")" ::: "memory")
; #define PG8_WAIT_L(n) asm volatile("s_waitcnt lgkmcnt(" #n ")" ::: "memory")
; #define PG8_BAR __builtin_amdgcn_s_barrier()
; #define PG8_SCHED __builtin_amdgcn_sched_barrier(0)
; template <class Epi, bool ALIGN_EPI = true>
; __device__ __forceinline__ void gemm_phase(LAS unsigned char* lds, const Gemm g, const Sched& S, const Epi& E) {
;     ...
;             PG8_WAIT_V(8); PG8_WAIT_L(0); PG8_BAR; PG8_MMA(0, 0, At, B0); PG8_MMA(0, 1, At, B1); PG8_BAR; PG8_SCHED;
;             PG8_LDA(At, 1, 1); PG8_STAGE(PG8_SB(1, 0), b3, voffB); PG8_STAGE(PG8_SB(1, 1), b3 + hstepB, voffB); PG8_STAGE(PG8_SA(1, 0), a3, voffA);
;             PG8_WAIT_V(8); PG8_WAIT_L(0); PG8_BAR; PG8_MMA(1, 0, At, B0); PG8_MMA(1, 1, At, B1); PG8_BAR; PG8_SCHED;
;         }
	s_setprio 1
	v_mfma_f32_16x16x32_bf16 v[124:127], v[146:149], v[178:181], v[124:127]
	v_mfma_f32_16x16x32_bf16 v[128:131], v[154:157], v[178:181], v[128:131]
	v_mfma_f32_16x16x32_bf16 v[112:115], v[146:149], v[186:189], v[112:115]
	v_mfma_f32_16x16x32_bf16 v[108:111], v[154:157], v[186:189], v[108:111]
	v_mfma_f32_16x16x32_bf16 v[96:99], v[146:149], v[194:197], v[96:99]
	v_mfma_f32_16x16x32_bf16 v[92:95], v[154:157], v[194:197], v[92:95]
	v_mfma_f32_16x16x32_bf16 v[80:83], v[146:149], v[224:227], v[80:83]
	v_mfma_f32_16x16x32_bf16 v[76:79], v[154:157], v[224:227], v[76:79]
	v_mfma_f32_16x16x32_bf16 v[124:127], v[150:153], v[182:185], v[124:127]
	v_mfma_f32_16x16x32_bf16 v[128:131], v[158:161], v[182:185], v[128:131]
	v_mfma_f32_16x16x32_bf16 v[112:115], v[150:153], v[190:193], v[112:115]
	v_mfma_f32_16x16x32_bf16 v[108:111], v[158:161], v[190:193], v[108:111]
	v_mfma_f32_16x16x32_bf16 v[96:99], v[150:153], v[206:209], v[96:99]
	v_mfma_f32_16x16x32_bf16 v[92:95], v[158:161], v[206:209], v[92:95]
	v_mfma_f32_16x16x32_bf16 v[80:83], v[150:153], v[228:231], v[80:83]
	v_mfma_f32_16x16x32_bf16 v[76:79], v[158:161], v[228:231], v[76:79]
	s_setprio 0
	s_setprio 1
	v_mfma_f32_16x16x32_bf16 v[120:123], v[162:165], v[178:181], v[120:123]
	v_mfma_f32_16x16x32_bf16 v[116:119], v[170:173], v[178:181], v[116:119]
	v_mfma_f32_16x16x32_bf16 v[104:107], v[162:165], v[186:189], v[104:107]
	v_mfma_f32_16x16x32_bf16 v[100:103], v[170:173], v[186:189], v[100:103]
	v_mfma_f32_16x16x32_bf16 v[88:91], v[162:165], v[194:197], v[88:91]
	v_mfma_f32_16x16x32_bf16 v[84:87], v[170:173], v[194:197], v[84:87]
	v_mfma_f32_16x16x32_bf16 v[72:75], v[162:165], v[224:227], v[72:75]
	v_mfma_f32_16x16x32_bf16 v[68:71], v[170:173], v[224:227], v[68:71]
	v_mfma_f32_16x16x32_bf16 v[120:123], v[166:169], v[182:185], v[120:123]
	v_mfma_f32_16x16x32_bf16 v[116:119], v[174:177], v[182:185], v[116:119]
	v_mfma_f32_16x16x32_bf16 v[104:107], v[166:169], v[190:193], v[104:107]
	v_mfma_f32_16x16x32_bf16 v[100:103], v[174:177], v[190:193], v[100:103]
	v_mfma_f32_16x16x32_bf16 v[88:91], v[166:169], v[206:209], v[88:91]
	v_mfma_f32_16x16x32_bf16 v[84:87], v[174:177], v[206:209], v[84:87]
	v_mfma_f32_16x16x32_bf16 v[72:75], v[166:169], v[228:231], v[72:75]
	v_mfma_f32_16x16x32_bf16 v[68:71], v[174:177], v[228:231], v[68:71]
	s_setprio 0
	s_barrier
	s_add_u32 s100, s26, 0x80
	s_addc_u32 s101, s27, 0
	s_add_i32 s44, s68, s37
	s_mov_b32 m0, s44
	ds_read_b128 v[178:181], v144 offset:49152
	ds_read_b128 v[182:185], v144 offset:50176
	ds_read_b128 v[186:189], v144 offset:51200
	ds_read_b128 v[190:193], v144 offset:52224
	ds_read_b128 v[194:197], v144 offset:53248
	ds_read_b128 v[206:209], v144 offset:54272
	ds_read_b128 v[224:227], v144 offset:55296
	ds_read_b128 v[228:231], v144 offset:56320
	global_load_lds_dwordx4 v2, s[100:101]
	s_add_i32 m0, s44, 0x2000
	s_add_u32 s26, s26, 0x400080
	s_addc_u32 s27, s27, 0
	s_add_i32 s44, s69, s37
	global_load_lds_dwordx4 v132, s[100:101]
	s_mov_b32 m0, s44
	s_nop 0
	global_load_lds_dwordx4 v2, s[26:27]
	s_add_i32 m0, s44, 0x2000
	s_nop 0
	global_load_lds_dwordx4 v132, s[26:27]
	s_waitcnt vmcnt(6) lgkmcnt(0)
	s_barrier
	s_setprio 1
	v_mfma_f32_16x16x32_bf16 v[64:67], v[146:149], v[178:181], v[64:67]
	v_mfma_f32_16x16x32_bf16 v[60:63], v[154:157], v[178:181], v[60:63]
	v_mfma_f32_16x16x32_bf16 v[48:51], v[146:149], v[186:189], v[48:51]
	v_mfma_f32_16x16x32_bf16 v[44:47], v[154:157], v[186:189], v[44:47]
	v_mfma_f32_16x16x32_bf16 v[32:35], v[146:149], v[194:197], v[32:35]
	v_mfma_f32_16x16x32_bf16 v[28:31], v[154:157], v[194:197], v[28:31]
	v_mfma_f32_16x16x32_bf16 v[16:19], v[146:149], v[224:227], v[16:19]
	v_mfma_f32_16x16x32_bf16 v[12:15], v[154:157], v[224:227], v[12:15]
	v_mfma_f32_16x16x32_bf16 v[64:67], v[150:153], v[182:185], v[64:67]
	v_mfma_f32_16x16x32_bf16 v[60:63], v[158:161], v[182:185], v[60:63]
	v_mfma_f32_16x16x32_bf16 v[48:51], v[150:153], v[190:193], v[48:51]
	v_mfma_f32_16x16x32_bf16 v[44:47], v[158:161], v[190:193], v[44:47]
	v_mfma_f32_16x16x32_bf16 v[32:35], v[150:153], v[206:209], v[32:35]
	v_mfma_f32_16x16x32_bf16 v[28:31], v[158:161], v[206:209], v[28:31]
	v_mfma_f32_16x16x32_bf16 v[16:19], v[150:153], v[228:231], v[16:19]
	v_mfma_f32_16x16x32_bf16 v[12:15], v[158:161], v[228:231], v[12:15]
	s_setprio 0
	s_setprio 1
	v_mfma_f32_16x16x32_bf16 v[56:59], v[162:165], v[178:181], v[56:59]
	v_mfma_f32_16x16x32_bf16 v[52:55], v[170:173], v[178:181], v[52:55]
	v_mfma_f32_16x16x32_bf16 v[40:43], v[162:165], v[186:189], v[40:43]
	v_mfma_f32_16x16x32_bf16 v[36:39], v[170:173], v[186:189], v[36:39]
	v_mfma_f32_16x16x32_bf16 v[24:27], v[162:165], v[194:197], v[24:27]
	v_mfma_f32_16x16x32_bf16 v[20:23], v[170:173], v[194:197], v[20:23]
	v_mfma_f32_16x16x32_bf16 v[8:11], v[162:165], v[224:227], v[8:11]
	v_mfma_f32_16x16x32_bf16 v[4:7], v[170:173], v[224:227], v[4:7]
	v_mfma_f32_16x16x32_bf16 v[56:59], v[166:169], v[182:185], v[56:59]
	v_mfma_f32_16x16x32_bf16 v[52:55], v[174:177], v[182:185], v[52:55]
	v_mfma_f32_16x16x32_bf16 v[40:43], v[166:169], v[190:193], v[40:43]
	v_mfma_f32_16x16x32_bf16 v[36:39], v[174:177], v[190:193], v[36:39]
	v_mfma_f32_16x16x32_bf16 v[24:27], v[166:169], v[206:209], v[24:27]
	v_mfma_f32_16x16x32_bf16 v[20:23], v[174:177], v[206:209], v[20:23]
	v_mfma_f32_16x16x32_bf16 v[8:11], v[166:169], v[228:231], v[8:11]
	v_mfma_f32_16x16x32_bf16 v[4:7], v[174:177], v[228:231], v[4:7]
	s_setprio 0
	s_barrier
	s_add_u32 s42, s42, 0x100
	s_addc_u32 s43, s43, 0
	s_add_u32 s65, s65, 0x100
	s_addc_u32 s66, s66, 0
	s_cmp_ge_i32 s67, s52
	s_mov_b32 s44, s67
	s_cbranch_scc0 .LBB0_1479

; #define PG8_STAGE(bufoff, gbase, voff) do { _Pragma("unroll") for (int _i = 0; _i < 2; ++_i) \
;         __builtin_amdgcn_global_load_lds((const unsigned*)((const char*)(gbase) + (voff)[_i]), (LAS unsigned*)(lds + (bufoff) + ldsw + _i * 8192), 16, 0, 0); } while (0)
; #define PG8_WAIT_V(n) asm volatile("s_waitcnt vmcnt(" #n ")" ::: "memory")
; #define PG8_BAR __builtin_amdgcn_s_barrier()
; template <class Epi, bool ALIGN_EPI = true>
; __device__ __forceinline__ void gemm_phase(LAS unsigned char* lds, const Gemm g, const Sched& S, const Epi& E) {
;     ...
;     for (int i = 0; i < 2; ++i) { int R, C; stage_rc(tid * 16 + i * 8192, R, C); const int Rb = (R & ~31) + perm32(R & 31);
;         voffA[i] = (unsigned)(R * g.lda + C) * 2u; voffB[i] = (unsigned)(Rb * g.ldb + C) * 2u; }
;     const size_t kstep = (size_t)(BK * 2);
;     const size_t hstepA = (size_t)HALF * g.lda * 2, hstepB = (size_t)HALF * g.ldb * 2;
;     const unsigned ldsw = (unsigned)wid * 1024u;
;     const int aoff = lds_byte(wr * 64 + fr, fq * 8), boff = lds_byte(wc * 32 + fr, fq * 8);
;     ...
;     f32x4 acc[2][2][4][2];
; #pragma unroll
;     for (int a = 0; a < 2; ++a)
; #pragma unroll
;         for (int b = 0; b < 2; ++b)
; #pragma unroll
;             for (int m = 0; m < 4; ++m)
; #pragma unroll
;                 for (int n = 0; n < 2; ++n) acc[a][b][m][n] = (f32x4){0.f, 0.f, 0.f, 0.f};
;     bf16x8 At[4][2], B0[2][2], B1[2][2];
;     const char* cA = (const char*)g.A + cur.aoff; const char* cB = (const char*)g.Bt + cur.boff;
;     PG8_STAGE(PG8_SB(0, 0), cB, voffB); PG8_STAGE(PG8_SB(0, 1), cB + hstepB, voffB); PG8_STAGE(PG8_SA(0, 0), cA, voffA); PG8_STAGE(PG8_SA(0, 1), cA + hstepA, voffA);
;     if (wr == 1) PG8_BAR;
;     PG8_WAIT_V(2); PG8_BAR;
;     PG8_STAGE(PG8_SB(1, 0), cB + kstep, voffB); PG8_STAGE(PG8_SA(1, 0), cA + kstep, voffA); PG8_STAGE(PG8_SB(1, 1), cB + hstepB + kstep, voffB);
;     PG8_WAIT_V(6); PG8_BAR;
.LBB0_1918:
	s_ashr_i32 s19, s18, 31
	s_lshr_b32 s19, s19, 26
	s_and_b32 s5, s5, 3
	s_add_i32 s19, s18, s19
	s_add_i32 m0, s52, 0x18000
	v_lshl_add_u64 v[10:11], v[10:11], 0, s[8:9]
	s_ashr_i32 s56, s19, 6
	s_lshl_b32 s31, s4, 6
	s_lshl_b32 s4, s4, 13
	s_lshl_b32 s19, s5, 12
	s_waitcnt vmcnt(2)
	s_barrier
	global_load_lds_dwordx4 v[10:11], off
	v_lshl_add_u64 v[8:9], v[8:9], 0, s[8:9]
	s_add_i32 m0, s52, 0x1a000
	s_add_i32 s57, s52, 0x8000
	s_add_i32 s58, s52, 0xa000
	global_load_lds_dwordx4 v[8:9], off
	v_lshl_add_u64 v[6:7], v[6:7], 0, s[8:9]
	s_mov_b32 m0, s57
	s_add_u32 s20, s14, 0x40080
	global_load_lds_dwordx4 v[6:7], off
	v_lshl_add_u64 v[4:5], v[4:5], 0, s[8:9]
	s_mov_b32 m0, s58
	s_addc_u32 s21, s15, 0
	global_load_lds_dwordx4 v[4:5], off
	s_add_i32 m0, s52, 0x1c000
	v_lshl_add_u64 v[4:5], s[20:21], 0, v[138:139]
	global_load_lds_dwordx4 v[4:5], off
	v_lshl_add_u64 v[4:5], s[20:21], 0, v[134:135]
	s_add_i32 m0, s52, 0x1e000
	s_movk_i32 s10, 0x3c0
	global_load_lds_dwordx4 v[4:5], off
	v_and_b32_e32 v4, 48, v146
	v_lshlrev_b32_e32 v5, 6, v146
	v_and_or_b32 v4, v5, s10, v4
	v_lshlrev_b32_e32 v5, 2, v146
	v_and_b32_e32 v5, 32, v5
	v_bitop3_b32 v6, v4, s4, v5 bitop3:0xde
	v_bitop3_b32 v147, v4, s19, v5 bitop3:0xde
	v_add_u32_e32 v147, 0x10000, v147
	v_lshlrev_b32_e32 v4, 14, v15
	v_and_b32_e32 v4, 0xffff8000, v4
	v_lshl_add_u32 v4, v14, 11, v4
	v_and_b32_e32 v5, 1, v15
	v_lshl_or_b32 v4, v5, 6, v4
	v_lshl_add_u32 v142, v16, 1, v4
	v_lshlrev_b32_e32 v4, 14, v2
	v_and_b32_e32 v4, 0xffff8000, v4
	v_lshl_add_u32 v4, v12, 11, v4
	v_and_b32_e32 v2, 1, v2
	v_readlane_b32 s20, v243, 43
	s_waitcnt vmcnt(6)
	v_lshl_or_b32 v2, v2, 6, v4
	v_mov_b32_e32 v4, v3
	v_mov_b32_e32 v5, v3
	v_readlane_b32 s21, v243, 44
	s_cmp_gt_i32 s18, 63
	v_lshl_add_u32 v144, v13, 1, v2
	v_mov_b32_e32 v2, v3
	v_add_u32_e32 v148, 0, v6
	v_mov_b64_e32 v[8:9], v[4:5]
	v_mov_b64_e32 v[12:13], v[4:5]
	v_mov_b64_e32 v[24:25], v[4:5]
	v_mov_b64_e32 v[28:29], v[4:5]
	v_mov_b64_e32 v[40:41], v[4:5]
	v_mov_b64_e32 v[44:45], v[4:5]
	v_mov_b64_e32 v[56:57], v[4:5]
	v_mov_b64_e32 v[60:61], v[4:5]
	v_mov_b64_e32 v[16:17], v[4:5]
	v_mov_b64_e32 v[20:21], v[4:5]
	v_mov_b64_e32 v[32:33], v[4:5]
	v_mov_b64_e32 v[36:37], v[4:5]
	v_mov_b64_e32 v[48:49], v[4:5]
	v_mov_b64_e32 v[52:53], v[4:5]
	v_mov_b64_e32 v[64:65], v[4:5]
	v_mov_b64_e32 v[68:69], v[4:5]
	v_mov_b64_e32 v[72:73], v[4:5]
	v_mov_b64_e32 v[76:77], v[4:5]
	v_mov_b64_e32 v[88:89], v[4:5]
	v_mov_b64_e32 v[92:93], v[4:5]
	v_mov_b64_e32 v[104:105], v[4:5]
	v_mov_b64_e32 v[108:109], v[4:5]
	v_mov_b64_e32 v[120:121], v[4:5]
	v_mov_b64_e32 v[124:125], v[4:5]
	v_mov_b64_e32 v[80:81], v[4:5]
	v_mov_b64_e32 v[84:85], v[4:5]
	v_mov_b64_e32 v[96:97], v[4:5]
	v_mov_b64_e32 v[100:101], v[4:5]
	v_mov_b64_e32 v[112:113], v[4:5]
	v_mov_b64_e32 v[116:117], v[4:5]
	v_mov_b64_e32 v[128:129], v[4:5]
	v_mov_b64_e32 v[132:133], v[4:5]
	s_mov_b32 s4, s20
	v_readlane_b32 s20, v243, 39
	s_cselect_b64 s[18:19], -1, 0
	s_add_i32 s59, s56, -2
	v_mov_b32_e32 v143, v3
	v_mov_b32_e32 v145, v3
	s_mov_b32 s60, 0
	v_mov_b64_e32 v[6:7], v[2:3]
	v_mov_b64_e32 v[10:11], v[2:3]
	v_mov_b64_e32 v[22:23], v[2:3]
	v_mov_b64_e32 v[26:27], v[2:3]
	v_mov_b64_e32 v[38:39], v[2:3]
	v_mov_b64_e32 v[42:43], v[2:3]
	v_mov_b64_e32 v[54:55], v[2:3]
	v_mov_b64_e32 v[58:59], v[2:3]
	v_mov_b64_e32 v[14:15], v[2:3]
	v_mov_b64_e32 v[18:19], v[2:3]
	v_mov_b64_e32 v[30:31], v[2:3]
	v_mov_b64_e32 v[34:35], v[2:3]
	v_mov_b64_e32 v[46:47], v[2:3]
	v_mov_b64_e32 v[50:51], v[2:3]
	v_mov_b64_e32 v[62:63], v[2:3]
	v_mov_b64_e32 v[66:67], v[2:3]
	v_mov_b64_e32 v[70:71], v[2:3]
	v_mov_b64_e32 v[74:75], v[2:3]
	v_mov_b64_e32 v[86:87], v[2:3]
	v_mov_b64_e32 v[90:91], v[2:3]
	v_mov_b64_e32 v[102:103], v[2:3]
	v_mov_b64_e32 v[106:107], v[2:3]
	v_mov_b64_e32 v[118:119], v[2:3]
	v_mov_b64_e32 v[122:123], v[2:3]
	v_mov_b64_e32 v[78:79], v[2:3]
	v_mov_b64_e32 v[82:83], v[2:3]
	v_mov_b64_e32 v[94:95], v[2:3]
	v_mov_b64_e32 v[98:99], v[2:3]
	v_mov_b64_e32 v[110:111], v[2:3]
	v_mov_b64_e32 v[114:115], v[2:3]
	v_mov_b64_e32 v[126:127], v[2:3]
	v_mov_b64_e32 v[130:131], v[2:3]
	s_mov_b32 s61, s20
	s_barrier
	v_readlane_b32 s21, v243, 40
	s_branch .LBB0_1920

; #define PG8_STAGE(bufoff, gbase, voff) do { _Pragma("unroll") for (int _i = 0; _i < 2; ++_i) \
;         __builtin_amdgcn_global_load_lds((const unsigned*)((const char*)(gbase) + (voff)[_i]), (LAS unsigned*)(lds + (bufoff) + ldsw + _i * 8192), 16, 0, 0); } while (0)
; #define PG8_LDA(dst, b, h) do { _Pragma("unroll") for (int m = 0; m < 4; ++m) _Pragma("unroll") for (int k = 0; k < 2; ++k) dst[m][k] = *(const LAS bf16x8*)(lds + PG8_SA(b, h) + aoff + m * 2048 + k * 1024); } while (0)
; #define PG8_LDB(dst, b, h) do { _Pragma("unroll") for (int n = 0; n < 2; ++n) _Pragma("unroll") for (int k = 0; k < 2; ++k) dst[n][k] = *(const LAS bf16x8*)(lds + PG8_SB(b, h) + boff + n * 2048 + k * 1024); } while (0)
; #define PG8_MMA(ai, bj, At, Bt) do { __builtin_amdgcn_s_setprio(1); _Pragma("unroll") for (int m = 0; m < 4; ++m) _Pragma("unroll") for (int n = 0; n < 2; ++n) _Pragma("unroll") for (int k = 0; k < 2; ++k) \
;         acc[ai][bj][m][n] = __builtin_amdgcn_mfma_f32_16x16x32_bf16(Bt[n][k], At[m][k], acc[ai][bj][m][n], 0, 0, 0); __builtin_amdgcn_s_setprio(0); } while (0)
; #define PG8_WAIT_V(n) asm volatile("s_waitcnt vmcnt(" #n ")" ::: "memory")
; #define PG8_WAIT_L(n) asm volatile("s_waitcnt lgkmcnt(" #n ")" ::: "memory")
; #define PG8_BAR __builtin_amdgcn_s_barrier()
; #define PG8_WAIT_RELAX(flag, n) asm volatile("s_cmp_eq_u32 %0, 0\n\ts_cbranch_scc1 .Lrw%=\n\ts_waitcnt vmcnt(8)\n.Lrw%=:\n\ts_waitcnt vmcnt(%1)" :: "s"(flag), "n"(n) : "scc", "memory")
; #define PG8_SCHED __builtin_amdgcn_sched_barrier(0)
; template <class Epi, bool ALIGN_EPI = true>
; __device__ __forceinline__ void gemm_phase(LAS unsigned char* lds, const Gemm g, const Sched& S, const Epi& E) {
;     ...
;             PG8_LDB(B0, 0, 0); PG8_LDB(B1, 0, 1); PG8_SCHED; PG8_LDA(At, 0, 0); PG8_STAGE(PG8_SA(1, 1), a1 + hstepA, voffA);
;             if constexpr (Epi::NSTORES > 0) PG8_WAIT_RELAX(rflag, 8 + Epi::NSTORES); else PG8_WAIT_V(8);
;             PG8_WAIT_L(0); PG8_BAR; PG8_MMA(0, 0, At, B0); PG8_MMA(0, 1, At, B1); PG8_BAR; PG8_SCHED;
;             PG8_LDA(At, 0, 1); PG8_STAGE(PG8_SB(0, 0), b2, voffB); PG8_STAGE(PG8_SB(0, 1), b2 + hstepB, voffB); PG8_STAGE(PG8_SA(0, 0), a2, voffA);
;             if constexpr (Epi::NSTORES > 0) PG8_WAIT_RELAX(rflag, 8 + Epi::NSTORES); else PG8_WAIT_V(8);
;             PG8_WAIT_L(0); PG8_BAR; PG8_MMA(1, 0, At, B0); PG8_MMA(1, 1, At, B1); PG8_BAR; PG8_SCHED;
.LBB0_1929:
	s_add_i32 s67, s48, 2
	s_add_u32 s49, s46, 0xfffc0080
	s_addc_u32 s50, s47, -1
	s_add_i32 s68, 0, 0x10000
	s_cmp_eq_u32 s59, s48
	s_cselect_b32 s51, s21, s50
	s_cselect_b32 s50, s23, s49
	s_cselect_b32 s49, s63, s66
	s_cselect_b32 s48, s64, s65
	s_add_i32 s70, 0, 0x14000
	ds_read_b128 v[150:153], v147
	ds_read_b128 v[154:157], v147 offset:1024
	ds_read_b128 v[158:161], v147 offset:2048
	ds_read_b128 v[162:165], v147 offset:3072
	ds_read_b128 v[166:169], v147 offset:16384
	ds_read_b128 v[170:173], v147 offset:17408
	ds_read_b128 v[174:177], v147 offset:18432
	ds_read_b128 v[178:181], v147 offset:19456
	ds_read_b128 v[182:185], v148
	ds_read_b128 v[186:189], v148 offset:1024
	ds_read_b128 v[190:193], v148 offset:2048
	ds_read_b128 v[194:197], v148 offset:3072
	ds_read_b128 v[206:209], v148 offset:4096
	ds_read_b128 v[224:227], v148 offset:5120
	ds_read_b128 v[228:231], v148 offset:6144
	ds_read_b128 v[232:235], v148 offset:7168
	s_mov_b32 m0, s57
	s_add_u32 s100, s46, 0xfffc0000
	s_addc_u32 s101, s47, -1
	global_load_lds_dwordx4 v142, s[100:101]
	s_mov_b32 m0, s58
	s_nop 0
	global_load_lds_dwordx4 v144, s[100:101]
	s_add_i32 m0, s52, 0xc000
	s_nop 0
	global_load_lds_dwordx4 v142, s[46:47]
	s_add_i32 m0, s52, 0xe000
	s_nop 0
	global_load_lds_dwordx4 v144, s[46:47]
	s_waitcnt vmcnt(8) lgkmcnt(0)
	s_barrier
	s_setprio 1
	v_mfma_f32_16x16x32_bf16 v[130:133], v[150:153], v[182:185], v[130:133]
	v_mfma_f32_16x16x32_bf16 v[126:129], v[158:161], v[182:185], v[126:129]
	v_mfma_f32_16x16x32_bf16 v[114:117], v[150:153], v[190:193], v[114:117]
	v_mfma_f32_16x16x32_bf16 v[110:113], v[158:161], v[190:193], v[110:113]
	v_mfma_f32_16x16x32_bf16 v[98:101], v[150:153], v[206:209], v[98:101]
	v_mfma_f32_16x16x32_bf16 v[94:97], v[158:161], v[206:209], v[94:97]
	v_mfma_f32_16x16x32_bf16 v[82:85], v[150:153], v[228:231], v[82:85]
	v_mfma_f32_16x16x32_bf16 v[78:81], v[158:161], v[228:231], v[78:81]
	v_mfma_f32_16x16x32_bf16 v[130:133], v[154:157], v[186:189], v[130:133]
	v_mfma_f32_16x16x32_bf16 v[126:129], v[162:165], v[186:189], v[126:129]
	v_mfma_f32_16x16x32_bf16 v[114:117], v[154:157], v[194:197], v[114:117]
	v_mfma_f32_16x16x32_bf16 v[110:113], v[162:165], v[194:197], v[110:113]
	v_mfma_f32_16x16x32_bf16 v[98:101], v[154:157], v[224:227], v[98:101]
	v_mfma_f32_16x16x32_bf16 v[94:97], v[162:165], v[224:227], v[94:97]
	v_mfma_f32_16x16x32_bf16 v[82:85], v[154:157], v[232:235], v[82:85]
	v_mfma_f32_16x16x32_bf16 v[78:81], v[162:165], v[232:235], v[78:81]
	s_setprio 0
	s_setprio 1
	v_mfma_f32_16x16x32_bf16 v[122:125], v[166:169], v[182:185], v[122:125]
	v_mfma_f32_16x16x32_bf16 v[118:121], v[174:177], v[182:185], v[118:121]
	v_mfma_f32_16x16x32_bf16 v[106:109], v[166:169], v[190:193], v[106:109]
	v_mfma_f32_16x16x32_bf16 v[102:105], v[174:177], v[190:193], v[102:105]
	v_mfma_f32_16x16x32_bf16 v[90:93], v[166:169], v[206:209], v[90:93]
	v_mfma_f32_16x16x32_bf16 v[86:89], v[174:177], v[206:209], v[86:89]
	v_mfma_f32_16x16x32_bf16 v[74:77], v[166:169], v[228:231], v[74:77]
	v_mfma_f32_16x16x32_bf16 v[70:73], v[174:177], v[228:231], v[70:73]
	v_mfma_f32_16x16x32_bf16 v[122:125], v[170:173], v[186:189], v[122:125]
	v_mfma_f32_16x16x32_bf16 v[118:121], v[178:181], v[186:189], v[118:121]
	v_mfma_f32_16x16x32_bf16 v[106:109], v[170:173], v[194:197], v[106:109]
	v_mfma_f32_16x16x32_bf16 v[102:105], v[178:181], v[194:197], v[102:105]
	v_mfma_f32_16x16x32_bf16 v[90:93], v[170:173], v[224:227], v[90:93]
	v_mfma_f32_16x16x32_bf16 v[86:89], v[178:181], v[224:227], v[86:89]
	v_mfma_f32_16x16x32_bf16 v[74:77], v[170:173], v[232:235], v[74:77]
	v_mfma_f32_16x16x32_bf16 v[70:73], v[178:181], v[232:235], v[70:73]
	s_setprio 0
	s_barrier
	s_add_i32 s68, s68, s37
	s_mov_b32 m0, s68
	ds_read_b128 v[182:185], v148 offset:16384
	ds_read_b128 v[186:189], v148 offset:17408
	ds_read_b128 v[190:193], v148 offset:18432
	ds_read_b128 v[194:197], v148 offset:19456
	ds_read_b128 v[206:209], v148 offset:20480
	ds_read_b128 v[224:227], v148 offset:21504
	ds_read_b128 v[228:231], v148 offset:22528
	ds_read_b128 v[232:235], v148 offset:23552
	global_load_lds_dwordx4 v138, s[48:49]
	s_add_i32 m0, s68, 0x2000
	s_add_u32 s68, s48, 0x40000
	s_addc_u32 s69, s49, 0
	s_add_i32 s70, s70, s37
	global_load_lds_dwordx4 v134, s[48:49]
	s_mov_b32 m0, s70
	s_nop 0
	global_load_lds_dwordx4 v138, s[68:69]
	s_add_i32 m0, s70, 0x2000
	s_nop 0
	global_load_lds_dwordx4 v134, s[68:69]
	s_waitcnt vmcnt(6) lgkmcnt(0)
	s_barrier
	s_setprio 1
	v_mfma_f32_16x16x32_bf16 v[66:69], v[150:153], v[182:185], v[66:69]
	v_mfma_f32_16x16x32_bf16 v[62:65], v[158:161], v[182:185], v[62:65]
	v_mfma_f32_16x16x32_bf16 v[50:53], v[150:153], v[190:193], v[50:53]
	v_mfma_f32_16x16x32_bf16 v[46:49], v[158:161], v[190:193], v[46:49]
	v_mfma_f32_16x16x32_bf16 v[34:37], v[150:153], v[206:209], v[34:37]
	v_mfma_f32_16x16x32_bf16 v[30:33], v[158:161], v[206:209], v[30:33]
	v_mfma_f32_16x16x32_bf16 v[18:21], v[150:153], v[228:231], v[18:21]
	v_mfma_f32_16x16x32_bf16 v[14:17], v[158:161], v[228:231], v[14:17]
	v_mfma_f32_16x16x32_bf16 v[66:69], v[154:157], v[186:189], v[66:69]
	v_mfma_f32_16x16x32_bf16 v[62:65], v[162:165], v[186:189], v[62:65]
	v_mfma_f32_16x16x32_bf16 v[50:53], v[154:157], v[194:197], v[50:53]
	v_mfma_f32_16x16x32_bf16 v[46:49], v[162:165], v[194:197], v[46:49]
	v_mfma_f32_16x16x32_bf16 v[34:37], v[154:157], v[224:227], v[34:37]
	v_mfma_f32_16x16x32_bf16 v[30:33], v[162:165], v[224:227], v[30:33]
	v_mfma_f32_16x16x32_bf16 v[18:21], v[154:157], v[232:235], v[18:21]
	v_mfma_f32_16x16x32_bf16 v[14:17], v[162:165], v[232:235], v[14:17]
	s_setprio 0
	s_setprio 1
	v_mfma_f32_16x16x32_bf16 v[58:61], v[166:169], v[182:185], v[58:61]
	v_mfma_f32_16x16x32_bf16 v[54:57], v[174:177], v[182:185], v[54:57]
	v_mfma_f32_16x16x32_bf16 v[42:45], v[166:169], v[190:193], v[42:45]
	v_mfma_f32_16x16x32_bf16 v[38:41], v[174:177], v[190:193], v[38:41]
	v_mfma_f32_16x16x32_bf16 v[26:29], v[166:169], v[206:209], v[26:29]
	v_mfma_f32_16x16x32_bf16 v[22:25], v[174:177], v[206:209], v[22:25]
	v_mfma_f32_16x16x32_bf16 v[10:13], v[166:169], v[228:231], v[10:13]
	v_mfma_f32_16x16x32_bf16 v[4:7], v[174:177], v[228:231], v[6:9]
	v_mfma_f32_16x16x32_bf16 v[58:61], v[170:173], v[186:189], v[58:61]
	v_mfma_f32_16x16x32_bf16 v[54:57], v[178:181], v[186:189], v[54:57]
	v_mfma_f32_16x16x32_bf16 v[42:45], v[170:173], v[194:197], v[42:45]
	v_mfma_f32_16x16x32_bf16 v[38:41], v[178:181], v[194:197], v[38:41]
	v_mfma_f32_16x16x32_bf16 v[26:29], v[170:173], v[224:227], v[26:29]
	v_mfma_f32_16x16x32_bf16 v[22:25], v[178:181], v[224:227], v[22:25]
	v_mfma_f32_16x16x32_bf16 v[10:13], v[170:173], v[232:235], v[10:13]
	v_mfma_f32_16x16x32_bf16 v[4:7], v[178:181], v[232:235], v[4:7]
	s_setprio 0
	s_barrier
; #define PG8_STAGE(bufoff, gbase, voff) do { _Pragma("unroll") for (int _i = 0; _i < 2; ++_i) \
;         __builtin_amdgcn_global_load_lds((const unsigned*)((const char*)(gbase) + (voff)[_i]), (LAS unsigned*)(lds + (bufoff) + ldsw + _i * 8192), 16, 0, 0); } while (0)
; #define PG8_LDA(dst, b, h) do { _Pragma("unroll") for (int m = 0; m < 4; ++m) _Pragma("unroll") for (int k = 0; k < 2; ++k) dst[m][k] = *(const LAS bf16x8*)(lds + PG8_SA(b, h) + aoff + m * 2048 + k * 1024); } while (0)
; #define PG8_LDB(dst, b, h) do { _Pragma("unroll") for (int n = 0; n < 2; ++n) _Pragma("unroll") for (int k = 0; k < 2; ++k) dst[n][k] = *(const LAS bf16x8*)(lds + PG8_SB(b, h) + boff + n * 2048 + k * 1024); } while (0)
; #define PG8_MMA(ai, bj, At, Bt) do { __builtin_amdgcn_s_setprio(1); _Pragma("unroll") for (int m = 0; m < 4; ++m) _Pragma("unroll") for (int n = 0; n < 2; ++n) _Pragma("unroll") for (int k = 0; k < 2; ++k) \
;         acc[ai][bj][m][n] = __builtin_amdgcn_mfma_f32_16x16x32_bf16(Bt[n][k], At[m][k], acc[ai][bj][m][n], 0, 0, 0); __builtin_amdgcn_s_setprio(0); } while (0)
; #define PG8_WAIT_V(n) asm volatile("s_waitcnt vmcnt(" #n ")" ::: "memory")
; #define PG8_WAIT_L(n) asm volatile("s_waitcnt lgkmcnt(" #n ")" ::: "memory")
; #define PG8_BAR __builtin_amdgcn_s_barrier()
; #define PG8_SCHED __builtin_amdgcn_sched_barrier(0)
; template <class Epi, bool ALIGN_EPI = true>
; __device__ __forceinline__ void gemm_phase(LAS unsigned char* lds, const Gemm g, const Sched& S, const Epi& E) {
;     ...
;             PG8_LDB(B0, 1, 0); PG8_LDB(B1, 1, 1); PG8_SCHED; PG8_LDA(At, 1, 0); PG8_STAGE(PG8_SA(0, 1), a2 + hstepA, voffA);
;             PG8_WAIT_V(8); PG8_WAIT_L(0); PG8_BAR; PG8_MMA(0, 0, At, B0); PG8_MMA(0, 1, At, B1); PG8_BAR; PG8_SCHED;
;             PG8_LDA(At, 1, 1); PG8_STAGE(PG8_SB(1, 0), b3, voffB); PG8_STAGE(PG8_SB(1, 1), b3 + hstepB, voffB); PG8_STAGE(PG8_SA(1, 0), a3, voffA);
;             PG8_WAIT_V(8); PG8_WAIT_L(0); PG8_BAR; PG8_MMA(1, 0, At, B0); PG8_MMA(1, 1, At, B1); PG8_BAR; PG8_SCHED;
	s_add_i32 s68, 0, 0x18000
	s_add_i32 s69, 0, 0x1c000
	ds_read_b128 v[150:153], v147 offset:32768
	ds_read_b128 v[154:157], v147 offset:33792
	ds_read_b128 v[158:161], v147 offset:34816
	ds_read_b128 v[162:165], v147 offset:35840
	ds_read_b128 v[166:169], v147 offset:49152
	ds_read_b128 v[170:173], v147 offset:50176
	ds_read_b128 v[174:177], v147 offset:51200
	ds_read_b128 v[178:181], v147 offset:52224
	s_add_u32 s50, s50, 0x40000
	s_addc_u32 s51, s51, 0
	ds_read_b128 v[182:185], v148 offset:32768
	ds_read_b128 v[186:189], v148 offset:33792
	ds_read_b128 v[190:193], v148 offset:34816
	ds_read_b128 v[194:197], v148 offset:35840
	ds_read_b128 v[206:209], v148 offset:36864
	ds_read_b128 v[224:227], v148 offset:37888
	ds_read_b128 v[228:231], v148 offset:38912
	ds_read_b128 v[232:235], v148 offset:39936
	s_mov_b32 m0, s52
	s_add_u32 s100, s50, 0xfffc0000
	s_addc_u32 s101, s51, -1
	global_load_lds_dwordx4 v140, s[100:101]
	s_mov_b32 m0, s53
	s_nop 0
	global_load_lds_dwordx4 v136, s[100:101]
	s_mov_b32 m0, s54
	s_nop 0
	global_load_lds_dwordx4 v140, s[50:51]
	s_mov_b32 m0, s55
	s_nop 0
	global_load_lds_dwordx4 v136, s[50:51]
	s_waitcnt vmcnt(8) lgkmcnt(0)
	s_barrier
	s_setprio 1
	v_mfma_f32_16x16x32_bf16 v[130:133], v[150:153], v[182:185], v[130:133]
	v_mfma_f32_16x16x32_bf16 v[126:129], v[158:161], v[182:185], v[126:129]
	v_mfma_f32_16x16x32_bf16 v[114:117], v[150:153], v[190:193], v[114:117]
	v_mfma_f32_16x16x32_bf16 v[110:113], v[158:161], v[190:193], v[110:113]
	v_mfma_f32_16x16x32_bf16 v[98:101], v[150:153], v[206:209], v[98:101]
	v_mfma_f32_16x16x32_bf16 v[94:97], v[158:161], v[206:209], v[94:97]
	v_mfma_f32_16x16x32_bf16 v[82:85], v[150:153], v[228:231], v[82:85]
	v_mfma_f32_16x16x32_bf16 v[78:81], v[158:161], v[228:231], v[78:81]
	v_mfma_f32_16x16x32_bf16 v[130:133], v[154:157], v[186:189], v[130:133]
	v_mfma_f32_16x16x32_bf16 v[126:129], v[162:165], v[186:189], v[126:129]
	v_mfma_f32_16x16x32_bf16 v[114:117], v[154:157], v[194:197], v[114:117]
	v_mfma_f32_16x16x32_bf16 v[110:113], v[162:165], v[194:197], v[110:113]
	v_mfma_f32_16x16x32_bf16 v[98:101], v[154:157], v[224:227], v[98:101]
	v_mfma_f32_16x16x32_bf16 v[94:97], v[162:165], v[224:227], v[94:97]
	v_mfma_f32_16x16x32_bf16 v[82:85], v[154:157], v[232:235], v[82:85]
	v_mfma_f32_16x16x32_bf16 v[78:81], v[162:165], v[232:235], v[78:81]
	s_setprio 0
	s_setprio 1
	v_mfma_f32_16x16x32_bf16 v[122:125], v[166:169], v[182:185], v[122:125]
	v_mfma_f32_16x16x32_bf16 v[118:121], v[174:177], v[182:185], v[118:121]
	v_mfma_f32_16x16x32_bf16 v[106:109], v[166:169], v[190:193], v[106:109]
	v_mfma_f32_16x16x32_bf16 v[102:105], v[174:177], v[190:193], v[102:105]
	v_mfma_f32_16x16x32_bf16 v[90:93], v[166:169], v[206:209], v[90:93]
	v_mfma_f32_16x16x32_bf16 v[86:89], v[174:177], v[206:209], v[86:89]
	v_mfma_f32_16x16x32_bf16 v[74:77], v[166:169], v[228:231], v[74:77]
	v_mfma_f32_16x16x32_bf16 v[70:73], v[174:177], v[228:231], v[70:73]
	v_mfma_f32_16x16x32_bf16 v[122:125], v[170:173], v[186:189], v[122:125]
	v_mfma_f32_16x16x32_bf16 v[118:121], v[178:181], v[186:189], v[118:121]
	v_mfma_f32_16x16x32_bf16 v[106:109], v[170:173], v[194:197], v[106:109]
	v_mfma_f32_16x16x32_bf16 v[102:105], v[178:181], v[194:197], v[102:105]
	v_mfma_f32_16x16x32_bf16 v[90:93], v[170:173], v[224:227], v[90:93]
	v_mfma_f32_16x16x32_bf16 v[86:89], v[178:181], v[224:227], v[86:89]
	v_mfma_f32_16x16x32_bf16 v[74:77], v[170:173], v[232:235], v[74:77]
	v_mfma_f32_16x16x32_bf16 v[70:73], v[178:181], v[232:235], v[70:73]
	s_setprio 0
	s_barrier
	s_add_u32 s100, s48, 0x80
	s_addc_u32 s101, s49, 0
	s_add_i32 s50, s68, s37
	s_mov_b32 m0, s50
	ds_read_b128 v[182:185], v148 offset:49152
	ds_read_b128 v[186:189], v148 offset:50176
	ds_read_b128 v[190:193], v148 offset:51200
	ds_read_b128 v[194:197], v148 offset:52224
	ds_read_b128 v[206:209], v148 offset:53248
	ds_read_b128 v[224:227], v148 offset:54272
	ds_read_b128 v[228:231], v148 offset:55296
	ds_read_b128 v[232:235], v148 offset:56320
	global_load_lds_dwordx4 v138, s[100:101]
	s_add_i32 m0, s50, 0x2000
	s_add_u32 s48, s48, 0x40080
	s_addc_u32 s49, s49, 0
	s_add_i32 s50, s69, s37
	global_load_lds_dwordx4 v134, s[100:101]
	s_mov_b32 m0, s50
	s_nop 0
	global_load_lds_dwordx4 v138, s[48:49]
	s_add_i32 m0, s50, 0x2000
	s_nop 0
	global_load_lds_dwordx4 v134, s[48:49]
	s_waitcnt vmcnt(6) lgkmcnt(0)
	s_barrier
	s_setprio 1
	v_mfma_f32_16x16x32_bf16 v[66:69], v[150:153], v[182:185], v[66:69]
	v_mfma_f32_16x16x32_bf16 v[62:65], v[158:161], v[182:185], v[62:65]
	v_mfma_f32_16x16x32_bf16 v[50:53], v[150:153], v[190:193], v[50:53]
	v_mfma_f32_16x16x32_bf16 v[46:49], v[158:161], v[190:193], v[46:49]
	v_mfma_f32_16x16x32_bf16 v[34:37], v[150:153], v[206:209], v[34:37]
	v_mfma_f32_16x16x32_bf16 v[30:33], v[158:161], v[206:209], v[30:33]
	v_mfma_f32_16x16x32_bf16 v[18:21], v[150:153], v[228:231], v[18:21]
	v_mfma_f32_16x16x32_bf16 v[14:17], v[158:161], v[228:231], v[14:17]
	v_mfma_f32_16x16x32_bf16 v[66:69], v[154:157], v[186:189], v[66:69]
	v_mfma_f32_16x16x32_bf16 v[62:65], v[162:165], v[186:189], v[62:65]
	v_mfma_f32_16x16x32_bf16 v[50:53], v[154:157], v[194:197], v[50:53]
	v_mfma_f32_16x16x32_bf16 v[46:49], v[162:165], v[194:197], v[46:49]
	v_mfma_f32_16x16x32_bf16 v[34:37], v[154:157], v[224:227], v[34:37]
	v_mfma_f32_16x16x32_bf16 v[30:33], v[162:165], v[224:227], v[30:33]
	v_mfma_f32_16x16x32_bf16 v[18:21], v[154:157], v[232:235], v[18:21]
	v_mfma_f32_16x16x32_bf16 v[14:17], v[162:165], v[232:235], v[14:17]
	s_setprio 0
	s_setprio 1
	v_mfma_f32_16x16x32_bf16 v[58:61], v[166:169], v[182:185], v[58:61]
	v_mfma_f32_16x16x32_bf16 v[54:57], v[174:177], v[182:185], v[54:57]
	v_mfma_f32_16x16x32_bf16 v[42:45], v[166:169], v[190:193], v[42:45]
	v_mfma_f32_16x16x32_bf16 v[38:41], v[174:177], v[190:193], v[38:41]
	v_mfma_f32_16x16x32_bf16 v[26:29], v[166:169], v[206:209], v[26:29]
	v_mfma_f32_16x16x32_bf16 v[22:25], v[174:177], v[206:209], v[22:25]
	v_mfma_f32_16x16x32_bf16 v[8:11], v[166:169], v[228:231], v[10:13]
	v_mfma_f32_16x16x32_bf16 v[4:7], v[174:177], v[228:231], v[4:7]
	v_mfma_f32_16x16x32_bf16 v[58:61], v[170:173], v[186:189], v[58:61]
	v_mfma_f32_16x16x32_bf16 v[54:57], v[178:181], v[186:189], v[54:57]
	v_mfma_f32_16x16x32_bf16 v[42:45], v[170:173], v[194:197], v[42:45]
	v_mfma_f32_16x16x32_bf16 v[38:41], v[178:181], v[194:197], v[38:41]
	v_mfma_f32_16x16x32_bf16 v[26:29], v[170:173], v[224:227], v[26:29]
	v_mfma_f32_16x16x32_bf16 v[22:25], v[178:181], v[224:227], v[22:25]
	v_mfma_f32_16x16x32_bf16 v[10:13], v[170:173], v[232:235], v[8:11]
	v_mfma_f32_16x16x32_bf16 v[6:9], v[178:181], v[232:235], v[4:7]
	s_setprio 0
	s_barrier
	s_add_u32 s46, s46, 0x100
	s_addc_u32 s47, s47, 0
	s_add_u32 s65, s65, 0x100
	s_addc_u32 s66, s66, 0
	s_cmp_ge_i32 s67, s56
	s_mov_b32 s48, s67
	s_cbranch_scc0 .LBB0_1929

; #define PG8_STAGE(bufoff, gbase, voff) do { _Pragma("unroll") for (int _i = 0; _i < 2; ++_i) \
;         __builtin_amdgcn_global_load_lds((const unsigned*)((const char*)(gbase) + (voff)[_i]), (LAS unsigned*)(lds + (bufoff) + ldsw + _i * 8192), 16, 0, 0); } while (0)
; #define PG8_WAIT_V(n) asm volatile("s_waitcnt vmcnt(" #n ")" ::: "memory")
; #define PG8_BAR __builtin_amdgcn_s_barrier()
; template <class Epi, bool ALIGN_EPI = true>
; __device__ __forceinline__ void gemm_phase(LAS unsigned char* lds, const Gemm g, const Sched& S, const Epi& E) {
;     ...
;     for (int i = 0; i < 2; ++i) { int R, C; stage_rc(tid * 16 + i * 8192, R, C); const int Rb = (R & ~31) + perm32(R & 31);
;         voffA[i] = (unsigned)(R * g.lda + C) * 2u; voffB[i] = (unsigned)(Rb * g.ldb + C) * 2u; }
;     const size_t kstep = (size_t)(BK * 2);
;     const size_t hstepA = (size_t)HALF * g.lda * 2, hstepB = (size_t)HALF * g.ldb * 2;
;     const unsigned ldsw = (unsigned)wid * 1024u;
;     const int aoff = lds_byte(wr * 64 + fr, fq * 8), boff = lds_byte(wc * 32 + fr, fq * 8);
;     ...
;     f32x4 acc[2][2][4][2];
; #pragma unroll
;     for (int a = 0; a < 2; ++a)
; #pragma unroll
;         for (int b = 0; b < 2; ++b)
; #pragma unroll
;             for (int m = 0; m < 4; ++m)
; #pragma unroll
;                 for (int n = 0; n < 2; ++n) acc[a][b][m][n] = (f32x4){0.f, 0.f, 0.f, 0.f};
;     bf16x8 At[4][2], B0[2][2], B1[2][2];
;     const char* cA = (const char*)g.A + cur.aoff; const char* cB = (const char*)g.Bt + cur.boff;
;     PG8_STAGE(PG8_SB(0, 0), cB, voffB); PG8_STAGE(PG8_SB(0, 1), cB + hstepB, voffB); PG8_STAGE(PG8_SA(0, 0), cA, voffA); PG8_STAGE(PG8_SA(0, 1), cA + hstepA, voffA);
;     if (wr == 1) PG8_BAR;
;     PG8_WAIT_V(2); PG8_BAR;
;     PG8_STAGE(PG8_SB(1, 0), cB + kstep, voffB); PG8_STAGE(PG8_SA(1, 0), cA + kstep, voffA); PG8_STAGE(PG8_SB(1, 1), cB + hstepB + kstep, voffB);
;     PG8_WAIT_V(6); PG8_BAR;
.LBB0_2015:
	s_add_u32 s52, s54, s14
	s_addc_u32 s53, s55, s15
	s_ashr_i32 s14, s16, 31
	s_lshr_b32 s14, s14, 26
	s_and_b32 s20, s17, 3
	s_add_i32 s14, s16, s14
	s_add_i32 m0, s36, 0x18000
	v_lshl_add_u64 v[10:11], v[10:11], 0, s[8:9]
	s_ashr_i32 s54, s14, 6
	s_lshl_b32 s55, s19, 6
	s_lshl_b32 s17, s19, 13
	s_lshl_b32 s19, s20, 12
	s_waitcnt vmcnt(2)
	s_barrier
	global_load_lds_dwordx4 v[10:11], off
	v_lshl_add_u64 v[8:9], v[8:9], 0, s[8:9]
	s_add_i32 m0, s36, 0x1a000
	s_add_i32 s56, s36, 0x8000
	s_add_i32 s57, s36, 0xa000
	global_load_lds_dwordx4 v[8:9], off
	v_lshl_add_u64 v[4:5], v[4:5], 0, s[8:9]
	s_mov_b32 m0, s56
	s_add_u32 s14, s0, 0x80080
	global_load_lds_dwordx4 v[4:5], off
	v_lshl_add_u64 v[4:5], v[6:7], 0, s[8:9]
	s_mov_b32 m0, s57
	s_addc_u32 s15, s1, 0
	global_load_lds_dwordx4 v[4:5], off
	s_add_i32 m0, s36, 0x1c000
	v_lshl_add_u64 v[4:5], s[14:15], 0, v[136:137]
	global_load_lds_dwordx4 v[4:5], off
	v_lshl_add_u64 v[4:5], s[14:15], 0, v[140:141]
	s_add_i32 m0, s36, 0x1e000
	s_movk_i32 s10, 0x3c0
	global_load_lds_dwordx4 v[4:5], off
	v_and_b32_e32 v4, 48, v12
	v_lshlrev_b32_e32 v5, 6, v12
	v_and_or_b32 v4, v5, s10, v4
	v_lshlrev_b32_e32 v5, 2, v12
	v_and_b32_e32 v5, 32, v5
	v_bitop3_b32 v6, v4, s17, v5 bitop3:0xde
	v_bitop3_b32 v151, v4, s19, v5 bitop3:0xde
	v_add_u32_e32 v151, 0x10000, v151
	v_lshlrev_b32_e32 v4, 15, v2
	v_and_b32_e32 v4, 0xffff0000, v4
	s_cmp_gt_i32 s16, 63
	v_lshl_add_u32 v4, v13, 12, v4
	v_and_b32_e32 v2, 1, v2
	s_cselect_b64 s[14:15], -1, 0
	s_add_i32 s58, s54, -2
	v_lshl_or_b32 v2, v2, 6, v4
	s_cmpk_lt_u32 s18, 0x100
	v_lshl_add_u32 v142, v14, 1, v2
	v_lshlrev_b32_e32 v2, 15, v15
	s_cselect_b64 s[16:17], -1, 0
	s_and_b32 s18, s18, 0xffffff00
	v_and_b32_e32 v2, 0xffff0000, v2
	s_add_i32 s60, s18, 0
	v_lshl_add_u32 v2, v16, 12, v2
	v_and_b32_e32 v4, 1, v15
	v_readlane_b32 s18, v243, 55
	s_waitcnt vmcnt(6)
	v_lshl_or_b32 v2, v4, 6, v2
	v_mov_b32_e32 v4, v3
	v_mov_b32_e32 v5, v3
	v_readlane_b32 s19, v243, 56
	v_and_b32_e32 v150, 63, v12
	v_lshl_add_u32 v144, v17, 1, v2
	v_mov_b32_e32 v2, v3
	v_add_u32_e32 v152, 0, v6
	v_mov_b64_e32 v[8:9], v[4:5]
	v_mov_b64_e32 v[12:13], v[4:5]
	v_mov_b64_e32 v[16:17], v[4:5]
	v_mov_b64_e32 v[20:21], v[4:5]
	v_mov_b64_e32 v[24:25], v[4:5]
	v_mov_b64_e32 v[28:29], v[4:5]
	v_mov_b64_e32 v[32:33], v[4:5]
	v_mov_b64_e32 v[36:37], v[4:5]
	v_mov_b64_e32 v[40:41], v[4:5]
	v_mov_b64_e32 v[44:45], v[4:5]
	v_mov_b64_e32 v[48:49], v[4:5]
	v_mov_b64_e32 v[52:53], v[4:5]
	v_mov_b64_e32 v[56:57], v[4:5]
	v_mov_b64_e32 v[60:61], v[4:5]
	v_mov_b64_e32 v[64:65], v[4:5]
	v_mov_b64_e32 v[68:69], v[4:5]
	v_mov_b64_e32 v[72:73], v[4:5]
	v_mov_b64_e32 v[76:77], v[4:5]
	v_mov_b64_e32 v[80:81], v[4:5]
	v_mov_b64_e32 v[84:85], v[4:5]
	v_mov_b64_e32 v[88:89], v[4:5]
	v_mov_b64_e32 v[92:93], v[4:5]
	v_mov_b64_e32 v[96:97], v[4:5]
	v_mov_b64_e32 v[100:101], v[4:5]
	v_mov_b64_e32 v[104:105], v[4:5]
	v_mov_b64_e32 v[108:109], v[4:5]
	v_mov_b64_e32 v[112:113], v[4:5]
	v_mov_b64_e32 v[116:117], v[4:5]
	v_mov_b64_e32 v[120:121], v[4:5]
	v_mov_b64_e32 v[124:125], v[4:5]
	v_mov_b64_e32 v[128:129], v[4:5]
	v_mov_b64_e32 v[132:133], v[4:5]
	s_mov_b32 s62, s18
	v_readlane_b32 s18, v243, 51
	s_lshl_b32 s59, s20, 6
	s_add_i32 s60, s60, 0x20000
	v_mov_b32_e32 v143, v3
	v_mov_b32_e32 v145, v3
	s_mov_b32 s61, 0
	v_mov_b64_e32 v[6:7], v[2:3]
	v_mov_b64_e32 v[10:11], v[2:3]
	v_mov_b64_e32 v[14:15], v[2:3]
	v_mov_b64_e32 v[18:19], v[2:3]
	v_mov_b64_e32 v[22:23], v[2:3]
	v_mov_b64_e32 v[26:27], v[2:3]
	v_mov_b64_e32 v[30:31], v[2:3]
	v_mov_b64_e32 v[34:35], v[2:3]
	v_mov_b64_e32 v[38:39], v[2:3]
	v_mov_b64_e32 v[42:43], v[2:3]
	v_mov_b64_e32 v[46:47], v[2:3]
	v_mov_b64_e32 v[50:51], v[2:3]
	v_mov_b64_e32 v[54:55], v[2:3]
	v_mov_b64_e32 v[58:59], v[2:3]
	v_mov_b64_e32 v[62:63], v[2:3]
	v_mov_b64_e32 v[66:67], v[2:3]
	v_mov_b64_e32 v[70:71], v[2:3]
	v_mov_b64_e32 v[74:75], v[2:3]
	v_mov_b64_e32 v[78:79], v[2:3]
	v_mov_b64_e32 v[82:83], v[2:3]
	v_mov_b64_e32 v[86:87], v[2:3]
	v_mov_b64_e32 v[90:91], v[2:3]
	v_mov_b64_e32 v[94:95], v[2:3]
	v_mov_b64_e32 v[98:99], v[2:3]
	v_mov_b64_e32 v[102:103], v[2:3]
	v_mov_b64_e32 v[106:107], v[2:3]
	v_mov_b64_e32 v[110:111], v[2:3]
	v_mov_b64_e32 v[114:115], v[2:3]
	v_mov_b64_e32 v[118:119], v[2:3]
	v_mov_b64_e32 v[122:123], v[2:3]
	v_mov_b64_e32 v[126:127], v[2:3]
	v_mov_b64_e32 v[130:131], v[2:3]
	s_mov_b32 s63, s18
	s_barrier
	v_readlane_b32 s19, v243, 52
	s_branch .LBB0_2018

; #define PG8_STAGE(bufoff, gbase, voff) do { _Pragma("unroll") for (int _i = 0; _i < 2; ++_i) \
;         __builtin_amdgcn_global_load_lds((const unsigned*)((const char*)(gbase) + (voff)[_i]), (LAS unsigned*)(lds + (bufoff) + ldsw + _i * 8192), 16, 0, 0); } while (0)
; #define PG8_LDA(dst, b, h) do { _Pragma("unroll") for (int m = 0; m < 4; ++m) _Pragma("unroll") for (int k = 0; k < 2; ++k) dst[m][k] = *(const LAS bf16x8*)(lds + PG8_SA(b, h) + aoff + m * 2048 + k * 1024); } while (0)
; #define PG8_LDB(dst, b, h) do { _Pragma("unroll") for (int n = 0; n < 2; ++n) _Pragma("unroll") for (int k = 0; k < 2; ++k) dst[n][k] = *(const LAS bf16x8*)(lds + PG8_SB(b, h) + boff + n * 2048 + k * 1024); } while (0)
; #define PG8_MMA(ai, bj, At, Bt) do { __builtin_amdgcn_s_setprio(1); _Pragma("unroll") for (int m = 0; m < 4; ++m) _Pragma("unroll") for (int n = 0; n < 2; ++n) _Pragma("unroll") for (int k = 0; k < 2; ++k) \
;         acc[ai][bj][m][n] = __builtin_amdgcn_mfma_f32_16x16x32_bf16(Bt[n][k], At[m][k], acc[ai][bj][m][n], 0, 0, 0); __builtin_amdgcn_s_setprio(0); } while (0)
; #define PG8_WAIT_V(n) asm volatile("s_waitcnt vmcnt(" #n ")" ::: "memory")
; #define PG8_WAIT_L(n) asm volatile("s_waitcnt lgkmcnt(" #n ")" ::: "memory")
; #define PG8_BAR __builtin_amdgcn_s_barrier()
; #define PG8_SCHED __builtin_amdgcn_sched_barrier(0)
; template <class Epi, bool ALIGN_EPI = true>
; __device__ __forceinline__ void gemm_phase(LAS unsigned char* lds, const Gemm g, const Sched& S, const Epi& E) {
;     ...
;             const int rflag = __builtin_amdgcn_readfirstlane(t | (int)(ui == 0));
;             PG8_LDB(B0, 0, 0); PG8_LDB(B1, 0, 1); PG8_SCHED; PG8_LDA(At, 0, 0); PG8_STAGE(PG8_SA(1, 1), a1 + hstepA, voffA);
;             if constexpr (Epi::NSTORES > 0) PG8_WAIT_RELAX(rflag, 8 + Epi::NSTORES); else PG8_WAIT_V(8);
;             PG8_WAIT_L(0); PG8_BAR; PG8_MMA(0, 0, At, B0); PG8_MMA(0, 1, At, B1); PG8_BAR; PG8_SCHED;
;             PG8_LDA(At, 0, 1); PG8_STAGE(PG8_SB(0, 0), b2, voffB); PG8_STAGE(PG8_SB(0, 1), b2 + hstepB, voffB); PG8_STAGE(PG8_SA(0, 0), a2, voffA);
;             if constexpr (Epi::NSTORES > 0) PG8_WAIT_RELAX(rflag, 8 + Epi::NSTORES); else PG8_WAIT_V(8);
;             PG8_WAIT_L(0); PG8_BAR; PG8_MMA(1, 0, At, B0); PG8_MMA(1, 1, At, B1); PG8_BAR; PG8_SCHED;
.LBB0_2023:
	s_add_i32 s69, s46, 2
	s_add_u32 s47, s26, 0xfff80080
	s_addc_u32 s48, s27, -1
	s_add_i32 s70, 0, 0x10000
	s_cmp_eq_u32 s58, s46
	v_add_u32_e32 v153, s46, v2
	s_cselect_b32 s49, s19, s48
	s_cselect_b32 s48, s21, s47
	s_cselect_b32 s47, s65, s68
	s_cselect_b32 s46, s66, s67
	s_add_i32 s72, 0, 0x14000
	ds_read_b128 v[146:149], v151
	ds_read_b128 v[154:157], v151 offset:1024
	ds_read_b128 v[158:161], v151 offset:2048
	ds_read_b128 v[162:165], v151 offset:3072
	ds_read_b128 v[166:169], v151 offset:16384
	ds_read_b128 v[170:173], v151 offset:17408
	ds_read_b128 v[174:177], v151 offset:18432
	ds_read_b128 v[178:181], v151 offset:19456
	ds_read_b128 v[182:185], v152
	ds_read_b128 v[186:189], v152 offset:1024
	ds_read_b128 v[190:193], v152 offset:2048
	ds_read_b128 v[194:197], v152 offset:3072
	ds_read_b128 v[206:209], v152 offset:4096
	ds_read_b128 v[224:227], v152 offset:5120
	ds_read_b128 v[228:231], v152 offset:6144
	ds_read_b128 v[232:235], v152 offset:7168
	s_mov_b32 m0, s56
	s_add_u32 s100, s26, 0xfff80000
	s_addc_u32 s101, s27, -1
	global_load_lds_dwordx4 v142, s[100:101]
	s_mov_b32 m0, s57
	s_nop 0
	global_load_lds_dwordx4 v144, s[100:101]
	s_add_i32 m0, s36, 0xc000
	s_nop 0
	global_load_lds_dwordx4 v142, s[26:27]
	s_add_i32 m0, s36, 0xe000
	v_readfirstlane_b32 s73, v153
	global_load_lds_dwordx4 v144, s[26:27]
	s_cmp_eq_u32 s73, 0
	s_cbranch_scc1 .Lrw18
	s_waitcnt vmcnt(8)
.Lrw18:
	s_waitcnt vmcnt(16) lgkmcnt(0)
	s_barrier
	s_setprio 1
	v_mfma_f32_16x16x32_bf16 v[130:133], v[146:149], v[182:185], v[130:133]
	v_mfma_f32_16x16x32_bf16 v[126:129], v[158:161], v[182:185], v[126:129]
	v_mfma_f32_16x16x32_bf16 v[122:125], v[146:149], v[190:193], v[122:125]
	v_mfma_f32_16x16x32_bf16 v[118:121], v[158:161], v[190:193], v[118:121]
	v_mfma_f32_16x16x32_bf16 v[114:117], v[146:149], v[206:209], v[114:117]
	v_mfma_f32_16x16x32_bf16 v[110:113], v[158:161], v[206:209], v[110:113]
	v_mfma_f32_16x16x32_bf16 v[106:109], v[146:149], v[228:231], v[106:109]
	v_mfma_f32_16x16x32_bf16 v[102:105], v[158:161], v[228:231], v[102:105]
	v_mfma_f32_16x16x32_bf16 v[130:133], v[154:157], v[186:189], v[130:133]
	v_mfma_f32_16x16x32_bf16 v[126:129], v[162:165], v[186:189], v[126:129]
	v_mfma_f32_16x16x32_bf16 v[122:125], v[154:157], v[194:197], v[122:125]
	v_mfma_f32_16x16x32_bf16 v[118:121], v[162:165], v[194:197], v[118:121]
	v_mfma_f32_16x16x32_bf16 v[114:117], v[154:157], v[224:227], v[114:117]
	v_mfma_f32_16x16x32_bf16 v[110:113], v[162:165], v[224:227], v[110:113]
	v_mfma_f32_16x16x32_bf16 v[106:109], v[154:157], v[232:235], v[106:109]
	v_mfma_f32_16x16x32_bf16 v[102:105], v[162:165], v[232:235], v[102:105]
	s_setprio 0
	s_setprio 1
	v_mfma_f32_16x16x32_bf16 v[98:101], v[166:169], v[182:185], v[98:101]
	v_mfma_f32_16x16x32_bf16 v[94:97], v[174:177], v[182:185], v[94:97]
	v_mfma_f32_16x16x32_bf16 v[90:93], v[166:169], v[190:193], v[90:93]
	v_mfma_f32_16x16x32_bf16 v[86:89], v[174:177], v[190:193], v[86:89]
	v_mfma_f32_16x16x32_bf16 v[82:85], v[166:169], v[206:209], v[82:85]
	v_mfma_f32_16x16x32_bf16 v[78:81], v[174:177], v[206:209], v[78:81]
	v_mfma_f32_16x16x32_bf16 v[74:77], v[166:169], v[228:231], v[74:77]
	v_mfma_f32_16x16x32_bf16 v[70:73], v[174:177], v[228:231], v[70:73]
	v_mfma_f32_16x16x32_bf16 v[98:101], v[170:173], v[186:189], v[98:101]
	v_mfma_f32_16x16x32_bf16 v[94:97], v[178:181], v[186:189], v[94:97]
	v_mfma_f32_16x16x32_bf16 v[90:93], v[170:173], v[194:197], v[90:93]
	v_mfma_f32_16x16x32_bf16 v[86:89], v[178:181], v[194:197], v[86:89]
	v_mfma_f32_16x16x32_bf16 v[82:85], v[170:173], v[224:227], v[82:85]
	v_mfma_f32_16x16x32_bf16 v[78:81], v[178:181], v[224:227], v[78:81]
	v_mfma_f32_16x16x32_bf16 v[74:77], v[170:173], v[232:235], v[74:77]
	v_mfma_f32_16x16x32_bf16 v[70:73], v[178:181], v[232:235], v[70:73]
	s_setprio 0
	s_barrier
	s_add_i32 s70, s70, s35
	s_mov_b32 m0, s70
	ds_read_b128 v[182:185], v152 offset:16384
	ds_read_b128 v[186:189], v152 offset:17408
	ds_read_b128 v[190:193], v152 offset:18432
	ds_read_b128 v[194:197], v152 offset:19456
	ds_read_b128 v[206:209], v152 offset:20480
	ds_read_b128 v[224:227], v152 offset:21504
	ds_read_b128 v[228:231], v152 offset:22528
	ds_read_b128 v[232:235], v152 offset:23552
	global_load_lds_dwordx4 v136, s[46:47]
	s_add_i32 m0, s70, 0x2000
	s_add_u32 s70, s46, 0x80000
	s_addc_u32 s71, s47, 0
	s_add_i32 s72, s72, s35
	global_load_lds_dwordx4 v140, s[46:47]
	s_mov_b32 m0, s72
	s_nop 0
	global_load_lds_dwordx4 v136, s[70:71]
	s_add_i32 m0, s72, 0x2000
	s_nop 0
	global_load_lds_dwordx4 v140, s[70:71]
; #define PG8_STAGE(bufoff, gbase, voff) do { _Pragma("unroll") for (int _i = 0; _i < 2; ++_i) \
;         __builtin_amdgcn_global_load_lds((const unsigned*)((const char*)(gbase) + (voff)[_i]), (LAS unsigned*)(lds + (bufoff) + ldsw + _i * 8192), 16, 0, 0); } while (0)
; #define PG8_LDA(dst, b, h) do { _Pragma("unroll") for (int m = 0; m < 4; ++m) _Pragma("unroll") for (int k = 0; k < 2; ++k) dst[m][k] = *(const LAS bf16x8*)(lds + PG8_SA(b, h) + aoff + m * 2048 + k * 1024); } while (0)
; #define PG8_LDB(dst, b, h) do { _Pragma("unroll") for (int n = 0; n < 2; ++n) _Pragma("unroll") for (int k = 0; k < 2; ++k) dst[n][k] = *(const LAS bf16x8*)(lds + PG8_SB(b, h) + boff + n * 2048 + k * 1024); } while (0)
; #define PG8_MMA(ai, bj, At, Bt) do { __builtin_amdgcn_s_setprio(1); _Pragma("unroll") for (int m = 0; m < 4; ++m) _Pragma("unroll") for (int n = 0; n < 2; ++n) _Pragma("unroll") for (int k = 0; k < 2; ++k) \
;         acc[ai][bj][m][n] = __builtin_amdgcn_mfma_f32_16x16x32_bf16(Bt[n][k], At[m][k], acc[ai][bj][m][n], 0, 0, 0); __builtin_amdgcn_s_setprio(0); } while (0)
; #define PG8_WAIT_V(n) asm volatile("s_waitcnt vmcnt(" #n ")" ::: "memory")
; #define PG8_WAIT_L(n) asm volatile("s_waitcnt lgkmcnt(" #n ")" ::: "memory")
; #define PG8_BAR __builtin_amdgcn_s_barrier()
; #define PG8_WAIT_RELAX(flag, n) asm volatile("s_cmp_eq_u32 %0, 0\n\ts_cbranch_scc1 .Lrw%=\n\ts_waitcnt vmcnt(8)\n.Lrw%=:\n\ts_waitcnt vmcnt(%1)" :: "s"(flag), "n"(n) : "scc", "memory")
; #define PG8_SCHED __builtin_amdgcn_sched_barrier(0)
; template <class Epi, bool ALIGN_EPI = true>
; __device__ __forceinline__ void gemm_phase(LAS unsigned char* lds, const Gemm g, const Sched& S, const Epi& E) {
;     ...
;             if constexpr (Epi::NSTORES > 0) PG8_WAIT_RELAX(rflag, 8 + Epi::NSTORES); else PG8_WAIT_V(8);
;             PG8_WAIT_L(0); PG8_BAR; PG8_MMA(1, 0, At, B0); PG8_MMA(1, 1, At, B1); PG8_BAR; PG8_SCHED;
;             PG8_LDB(B0, 1, 0); PG8_LDB(B1, 1, 1); PG8_SCHED; PG8_LDA(At, 1, 0); PG8_STAGE(PG8_SA(0, 1), a2 + hstepA, voffA);
;             PG8_WAIT_V(8); PG8_WAIT_L(0); PG8_BAR; PG8_MMA(0, 0, At, B0); PG8_MMA(0, 1, At, B1); PG8_BAR; PG8_SCHED;
;             PG8_LDA(At, 1, 1); PG8_STAGE(PG8_SB(1, 0), b3, voffB); PG8_STAGE(PG8_SB(1, 1), b3 + hstepB, voffB); PG8_STAGE(PG8_SA(1, 0), a3, voffA);
.Lrw19:
	s_waitcnt vmcnt(6) lgkmcnt(0)
	s_barrier
	s_setprio 1
	v_mfma_f32_16x16x32_bf16 v[66:69], v[146:149], v[182:185], v[66:69]
	v_mfma_f32_16x16x32_bf16 v[62:65], v[158:161], v[182:185], v[62:65]
	v_mfma_f32_16x16x32_bf16 v[58:61], v[146:149], v[190:193], v[58:61]
	v_mfma_f32_16x16x32_bf16 v[54:57], v[158:161], v[190:193], v[54:57]
	v_mfma_f32_16x16x32_bf16 v[50:53], v[146:149], v[206:209], v[50:53]
	v_mfma_f32_16x16x32_bf16 v[46:49], v[158:161], v[206:209], v[46:49]
	v_mfma_f32_16x16x32_bf16 v[42:45], v[146:149], v[228:231], v[42:45]
	v_mfma_f32_16x16x32_bf16 v[38:41], v[158:161], v[228:231], v[38:41]
	v_mfma_f32_16x16x32_bf16 v[66:69], v[154:157], v[186:189], v[66:69]
	v_mfma_f32_16x16x32_bf16 v[62:65], v[162:165], v[186:189], v[62:65]
	v_mfma_f32_16x16x32_bf16 v[58:61], v[154:157], v[194:197], v[58:61]
	v_mfma_f32_16x16x32_bf16 v[54:57], v[162:165], v[194:197], v[54:57]
	v_mfma_f32_16x16x32_bf16 v[50:53], v[154:157], v[224:227], v[50:53]
	v_mfma_f32_16x16x32_bf16 v[46:49], v[162:165], v[224:227], v[46:49]
	v_mfma_f32_16x16x32_bf16 v[42:45], v[154:157], v[232:235], v[42:45]
	v_mfma_f32_16x16x32_bf16 v[38:41], v[162:165], v[232:235], v[38:41]
	s_setprio 0
	s_setprio 1
	v_mfma_f32_16x16x32_bf16 v[34:37], v[166:169], v[182:185], v[34:37]
	v_mfma_f32_16x16x32_bf16 v[30:33], v[174:177], v[182:185], v[30:33]
	v_mfma_f32_16x16x32_bf16 v[26:29], v[166:169], v[190:193], v[26:29]
	v_mfma_f32_16x16x32_bf16 v[22:25], v[174:177], v[190:193], v[22:25]
	v_mfma_f32_16x16x32_bf16 v[18:21], v[166:169], v[206:209], v[18:21]
	v_mfma_f32_16x16x32_bf16 v[14:17], v[174:177], v[206:209], v[14:17]
	v_mfma_f32_16x16x32_bf16 v[10:13], v[166:169], v[228:231], v[10:13]
	v_mfma_f32_16x16x32_bf16 v[4:7], v[174:177], v[228:231], v[6:9]
	v_mfma_f32_16x16x32_bf16 v[34:37], v[170:173], v[186:189], v[34:37]
	v_mfma_f32_16x16x32_bf16 v[30:33], v[178:181], v[186:189], v[30:33]
	v_mfma_f32_16x16x32_bf16 v[26:29], v[170:173], v[194:197], v[26:29]
	v_mfma_f32_16x16x32_bf16 v[22:25], v[178:181], v[194:197], v[22:25]
	v_mfma_f32_16x16x32_bf16 v[18:21], v[170:173], v[224:227], v[18:21]
	v_mfma_f32_16x16x32_bf16 v[14:17], v[178:181], v[224:227], v[14:17]
	v_mfma_f32_16x16x32_bf16 v[10:13], v[170:173], v[232:235], v[10:13]
	v_mfma_f32_16x16x32_bf16 v[4:7], v[178:181], v[232:235], v[4:7]
	s_setprio 0
	s_barrier
	s_add_i32 s70, 0, 0x18000
	s_add_i32 s71, 0, 0x1c000
	ds_read_b128 v[146:149], v151 offset:32768
	ds_read_b128 v[154:157], v151 offset:33792
	ds_read_b128 v[158:161], v151 offset:34816
	ds_read_b128 v[162:165], v151 offset:35840
	ds_read_b128 v[166:169], v151 offset:49152
	ds_read_b128 v[170:173], v151 offset:50176
	ds_read_b128 v[174:177], v151 offset:51200
	ds_read_b128 v[178:181], v151 offset:52224
	s_add_u32 s48, s48, 0x80000
	s_addc_u32 s49, s49, 0
	ds_read_b128 v[182:185], v152 offset:32768
	ds_read_b128 v[186:189], v152 offset:33792
	ds_read_b128 v[190:193], v152 offset:34816
	ds_read_b128 v[194:197], v152 offset:35840
	ds_read_b128 v[206:209], v152 offset:36864
	ds_read_b128 v[224:227], v152 offset:37888
	ds_read_b128 v[228:231], v152 offset:38912
	ds_read_b128 v[232:235], v152 offset:39936
	s_mov_b32 m0, s36
	s_add_u32 s100, s48, 0xfff80000
	s_addc_u32 s101, s49, -1
	global_load_lds_dwordx4 v134, s[100:101]
	s_mov_b32 m0, s37
	s_nop 0
	global_load_lds_dwordx4 v138, s[100:101]
	s_mov_b32 m0, s50
	s_nop 0
	global_load_lds_dwordx4 v134, s[48:49]
	s_mov_b32 m0, s51
	s_nop 0
	global_load_lds_dwordx4 v138, s[48:49]
	s_waitcnt vmcnt(8) lgkmcnt(0)
	s_barrier
; #define PG8_STAGE(bufoff, gbase, voff) do { _Pragma("unroll") for (int _i = 0; _i < 2; ++_i) \
;         __builtin_amdgcn_global_load_lds((const unsigned*)((const char*)(gbase) + (voff)[_i]), (LAS unsigned*)(lds + (bufoff) + ldsw + _i * 8192), 16, 0, 0); } while (0)
; #define PG8_LDA(dst, b, h) do { _Pragma("unroll") for (int m = 0; m < 4; ++m) _Pragma("unroll") for (int k = 0; k < 2; ++k) dst[m][k] = *(const LAS bf16x8*)(lds + PG8_SA(b, h) + aoff + m * 2048 + k * 1024); } while (0)
; #define PG8_MMA(ai, bj, At, Bt) do { __builtin_amdgcn_s_setprio(1); _Pragma("unroll") for (int m = 0; m < 4; ++m) _Pragma("unroll") for (int n = 0; n < 2; ++n) _Pragma("unroll") for (int k = 0; k < 2; ++k) \
;         acc[ai][bj][m][n] = __builtin_amdgcn_mfma_f32_16x16x32_bf16(Bt[n][k], At[m][k], acc[ai][bj][m][n], 0, 0, 0); __builtin_amdgcn_s_setprio(0); } while (0)
; #define PG8_WAIT_V(n) asm volatile("s_waitcnt vmcnt(" #n ")" ::: "memory")
; #define PG8_WAIT_L(n) asm volatile("s_waitcnt lgkmcnt(" #n ")" ::: "memory")
; #define PG8_BAR __builtin_amdgcn_s_barrier()
; #define PG8_SCHED __builtin_amdgcn_sched_barrier(0)
; template <class Epi, bool ALIGN_EPI = true>
; __device__ __forceinline__ void gemm_phase(LAS unsigned char* lds, const Gemm g, const Sched& S, const Epi& E) {
;     ...
;             PG8_WAIT_V(8); PG8_WAIT_L(0); PG8_BAR; PG8_MMA(0, 0, At, B0); PG8_MMA(0, 1, At, B1); PG8_BAR; PG8_SCHED;
;             PG8_LDA(At, 1, 1); PG8_STAGE(PG8_SB(1, 0), b3, voffB); PG8_STAGE(PG8_SB(1, 1), b3 + hstepB, voffB); PG8_STAGE(PG8_SA(1, 0), a3, voffA);
;             PG8_WAIT_V(8); PG8_WAIT_L(0); PG8_BAR; PG8_MMA(1, 0, At, B0); PG8_MMA(1, 1, At, B1); PG8_BAR; PG8_SCHED;
;         }
	s_setprio 1
	v_mfma_f32_16x16x32_bf16 v[130:133], v[146:149], v[182:185], v[130:133]
	v_mfma_f32_16x16x32_bf16 v[126:129], v[158:161], v[182:185], v[126:129]
	v_mfma_f32_16x16x32_bf16 v[122:125], v[146:149], v[190:193], v[122:125]
	v_mfma_f32_16x16x32_bf16 v[118:121], v[158:161], v[190:193], v[118:121]
	v_mfma_f32_16x16x32_bf16 v[114:117], v[146:149], v[206:209], v[114:117]
	v_mfma_f32_16x16x32_bf16 v[110:113], v[158:161], v[206:209], v[110:113]
	v_mfma_f32_16x16x32_bf16 v[106:109], v[146:149], v[228:231], v[106:109]
	v_mfma_f32_16x16x32_bf16 v[102:105], v[158:161], v[228:231], v[102:105]
	v_mfma_f32_16x16x32_bf16 v[130:133], v[154:157], v[186:189], v[130:133]
	v_mfma_f32_16x16x32_bf16 v[126:129], v[162:165], v[186:189], v[126:129]
	v_mfma_f32_16x16x32_bf16 v[122:125], v[154:157], v[194:197], v[122:125]
	v_mfma_f32_16x16x32_bf16 v[118:121], v[162:165], v[194:197], v[118:121]
	v_mfma_f32_16x16x32_bf16 v[114:117], v[154:157], v[224:227], v[114:117]
	v_mfma_f32_16x16x32_bf16 v[110:113], v[162:165], v[224:227], v[110:113]
	v_mfma_f32_16x16x32_bf16 v[106:109], v[154:157], v[232:235], v[106:109]
	v_mfma_f32_16x16x32_bf16 v[102:105], v[162:165], v[232:235], v[102:105]
	s_setprio 0
	s_setprio 1
	v_mfma_f32_16x16x32_bf16 v[98:101], v[166:169], v[182:185], v[98:101]
	v_mfma_f32_16x16x32_bf16 v[94:97], v[174:177], v[182:185], v[94:97]
	v_mfma_f32_16x16x32_bf16 v[90:93], v[166:169], v[190:193], v[90:93]
	v_mfma_f32_16x16x32_bf16 v[86:89], v[174:177], v[190:193], v[86:89]
	v_mfma_f32_16x16x32_bf16 v[82:85], v[166:169], v[206:209], v[82:85]
	v_mfma_f32_16x16x32_bf16 v[78:81], v[174:177], v[206:209], v[78:81]
	v_mfma_f32_16x16x32_bf16 v[74:77], v[166:169], v[228:231], v[74:77]
	v_mfma_f32_16x16x32_bf16 v[70:73], v[174:177], v[228:231], v[70:73]
	v_mfma_f32_16x16x32_bf16 v[98:101], v[170:173], v[186:189], v[98:101]
	v_mfma_f32_16x16x32_bf16 v[94:97], v[178:181], v[186:189], v[94:97]
	v_mfma_f32_16x16x32_bf16 v[90:93], v[170:173], v[194:197], v[90:93]
	v_mfma_f32_16x16x32_bf16 v[86:89], v[178:181], v[194:197], v[86:89]
	v_mfma_f32_16x16x32_bf16 v[82:85], v[170:173], v[224:227], v[82:85]
	v_mfma_f32_16x16x32_bf16 v[78:81], v[178:181], v[224:227], v[78:81]
	v_mfma_f32_16x16x32_bf16 v[74:77], v[170:173], v[232:235], v[74:77]
	v_mfma_f32_16x16x32_bf16 v[70:73], v[178:181], v[232:235], v[70:73]
	s_setprio 0
	s_barrier
	s_add_u32 s100, s46, 0x80
	s_addc_u32 s101, s47, 0
	s_add_i32 s48, s70, s35
	s_mov_b32 m0, s48
	ds_read_b128 v[182:185], v152 offset:49152
	ds_read_b128 v[186:189], v152 offset:50176
	ds_read_b128 v[190:193], v152 offset:51200
	ds_read_b128 v[194:197], v152 offset:52224
	ds_read_b128 v[206:209], v152 offset:53248
	ds_read_b128 v[224:227], v152 offset:54272
	ds_read_b128 v[228:231], v152 offset:55296
	ds_read_b128 v[232:235], v152 offset:56320
	global_load_lds_dwordx4 v136, s[100:101]
	s_add_i32 m0, s48, 0x2000
	s_add_u32 s46, s46, 0x80080
	s_addc_u32 s47, s47, 0
	s_add_i32 s48, s71, s35
	global_load_lds_dwordx4 v140, s[100:101]
	s_mov_b32 m0, s48
	s_nop 0
	global_load_lds_dwordx4 v136, s[46:47]
	s_add_i32 m0, s48, 0x2000
	s_nop 0
	global_load_lds_dwordx4 v140, s[46:47]
	s_waitcnt vmcnt(6) lgkmcnt(0)
	s_barrier
	s_setprio 1
	v_mfma_f32_16x16x32_bf16 v[66:69], v[146:149], v[182:185], v[66:69]
	v_mfma_f32_16x16x32_bf16 v[62:65], v[158:161], v[182:185], v[62:65]
	v_mfma_f32_16x16x32_bf16 v[58:61], v[146:149], v[190:193], v[58:61]
	v_mfma_f32_16x16x32_bf16 v[54:57], v[158:161], v[190:193], v[54:57]
	v_mfma_f32_16x16x32_bf16 v[50:53], v[146:149], v[206:209], v[50:53]
	v_mfma_f32_16x16x32_bf16 v[46:49], v[158:161], v[206:209], v[46:49]
	v_mfma_f32_16x16x32_bf16 v[42:45], v[146:149], v[228:231], v[42:45]
	v_mfma_f32_16x16x32_bf16 v[38:41], v[158:161], v[228:231], v[38:41]
	v_mfma_f32_16x16x32_bf16 v[66:69], v[154:157], v[186:189], v[66:69]
	v_mfma_f32_16x16x32_bf16 v[62:65], v[162:165], v[186:189], v[62:65]
	v_mfma_f32_16x16x32_bf16 v[58:61], v[154:157], v[194:197], v[58:61]
	v_mfma_f32_16x16x32_bf16 v[54:57], v[162:165], v[194:197], v[54:57]
	v_mfma_f32_16x16x32_bf16 v[50:53], v[154:157], v[224:227], v[50:53]
	v_mfma_f32_16x16x32_bf16 v[46:49], v[162:165], v[224:227], v[46:49]
	v_mfma_f32_16x16x32_bf16 v[42:45], v[154:157], v[232:235], v[42:45]
	v_mfma_f32_16x16x32_bf16 v[38:41], v[162:165], v[232:235], v[38:41]
	s_setprio 0
	s_setprio 1
	v_mfma_f32_16x16x32_bf16 v[34:37], v[166:169], v[182:185], v[34:37]
	v_mfma_f32_16x16x32_bf16 v[30:33], v[174:177], v[182:185], v[30:33]
	v_mfma_f32_16x16x32_bf16 v[26:29], v[166:169], v[190:193], v[26:29]
	v_mfma_f32_16x16x32_bf16 v[22:25], v[174:177], v[190:193], v[22:25]
	v_mfma_f32_16x16x32_bf16 v[18:21], v[166:169], v[206:209], v[18:21]
	v_mfma_f32_16x16x32_bf16 v[14:17], v[174:177], v[206:209], v[14:17]
	v_mfma_f32_16x16x32_bf16 v[8:11], v[166:169], v[228:231], v[10:13]
	v_mfma_f32_16x16x32_bf16 v[4:7], v[174:177], v[228:231], v[4:7]
	v_mfma_f32_16x16x32_bf16 v[34:37], v[170:173], v[186:189], v[34:37]
	v_mfma_f32_16x16x32_bf16 v[30:33], v[178:181], v[186:189], v[30:33]
	v_mfma_f32_16x16x32_bf16 v[26:29], v[170:173], v[194:197], v[26:29]
	v_mfma_f32_16x16x32_bf16 v[22:25], v[178:181], v[194:197], v[22:25]
	v_mfma_f32_16x16x32_bf16 v[18:21], v[170:173], v[224:227], v[18:21]
	v_mfma_f32_16x16x32_bf16 v[14:17], v[178:181], v[224:227], v[14:17]
	v_mfma_f32_16x16x32_bf16 v[10:13], v[170:173], v[232:235], v[8:11]
	v_mfma_f32_16x16x32_bf16 v[6:9], v[178:181], v[232:235], v[4:7]
	s_setprio 0
	s_barrier
	s_add_u32 s26, s26, 0x100
	s_addc_u32 s27, s27, 0
	s_add_u32 s67, s67, 0x100
	s_addc_u32 s68, s68, 0
	s_cmp_ge_i32 s69, s54
	s_mov_b32 s46, s69
	s_cbranch_scc0 .LBB0_2023
	s_mov_b32 s72, 0x8000

; #define PG8_STAGE(bufoff, gbase, voff) do { _Pragma("unroll") for (int _i = 0; _i < 2; ++_i) \
;         __builtin_amdgcn_global_load_lds((const unsigned*)((const char*)(gbase) + (voff)[_i]), (LAS unsigned*)(lds + (bufoff) + ldsw + _i * 8192), 16, 0, 0); } while (0)
; #define PG8_WAIT_V(n) asm volatile("s_waitcnt vmcnt(" #n ")" ::: "memory")
; #define PG8_BAR __builtin_amdgcn_s_barrier()
; template <class Epi, bool ALIGN_EPI = true>
; __device__ __forceinline__ void gemm_phase(LAS unsigned char* lds, const Gemm g, const Sched& S, const Epi& E) {
;     ...
;     for (int i = 0; i < 2; ++i) { int R, C; stage_rc(tid * 16 + i * 8192, R, C); const int Rb = (R & ~31) + perm32(R & 31);
;         voffA[i] = (unsigned)(R * g.lda + C) * 2u; voffB[i] = (unsigned)(Rb * g.ldb + C) * 2u; }
;     const size_t kstep = (size_t)(BK * 2);
;     const size_t hstepA = (size_t)HALF * g.lda * 2, hstepB = (size_t)HALF * g.ldb * 2;
;     const unsigned ldsw = (unsigned)wid * 1024u;
;     const int aoff = lds_byte(wr * 64 + fr, fq * 8), boff = lds_byte(wc * 32 + fr, fq * 8);
;     ...
;     f32x4 acc[2][2][4][2];
; #pragma unroll
;     for (int a = 0; a < 2; ++a)
; #pragma unroll
;         for (int b = 0; b < 2; ++b)
; #pragma unroll
;             for (int m = 0; m < 4; ++m)
; #pragma unroll
;                 for (int n = 0; n < 2; ++n) acc[a][b][m][n] = (f32x4){0.f, 0.f, 0.f, 0.f};
;     bf16x8 At[4][2], B0[2][2], B1[2][2];
;     const char* cA = (const char*)g.A + cur.aoff; const char* cB = (const char*)g.Bt + cur.boff;
;     PG8_STAGE(PG8_SB(0, 0), cB, voffB); PG8_STAGE(PG8_SB(0, 1), cB + hstepB, voffB); PG8_STAGE(PG8_SA(0, 0), cA, voffA); PG8_STAGE(PG8_SA(0, 1), cA + hstepA, voffA);
;     if (wr == 1) PG8_BAR;
;     PG8_WAIT_V(2); PG8_BAR;
;     PG8_STAGE(PG8_SB(1, 0), cB + kstep, voffB); PG8_STAGE(PG8_SA(1, 0), cA + kstep, voffA); PG8_STAGE(PG8_SB(1, 1), cB + hstepB + kstep, voffB);
;     PG8_WAIT_V(6); PG8_BAR;
.LBB0_2276:
	s_ashr_i32 s19, s18, 31
	s_lshr_b32 s19, s19, 26
	s_and_b32 s5, s5, 3
	s_add_i32 s19, s18, s19
	s_add_i32 m0, s50, 0x18000
	v_lshl_add_u64 v[10:11], v[10:11], 0, s[8:9]
	s_ashr_i32 s54, s19, 6
	s_lshl_b32 s31, s4, 6
	s_lshl_b32 s4, s4, 13
	s_lshl_b32 s19, s5, 12
	s_waitcnt vmcnt(2)
	s_barrier
	global_load_lds_dwordx4 v[10:11], off
	v_lshl_add_u64 v[8:9], v[8:9], 0, s[8:9]
	s_add_i32 m0, s50, 0x1a000
	s_add_i32 s55, s50, 0x8000
	s_add_i32 s56, s50, 0xa000
	global_load_lds_dwordx4 v[8:9], off
	v_lshl_add_u64 v[6:7], v[6:7], 0, s[8:9]
	s_mov_b32 m0, s55
	s_add_u32 s20, s14, 0x160080
	global_load_lds_dwordx4 v[6:7], off
	v_lshl_add_u64 v[4:5], v[4:5], 0, s[8:9]
	s_mov_b32 m0, s56
	s_addc_u32 s21, s15, 0
	global_load_lds_dwordx4 v[4:5], off
	s_add_i32 m0, s50, 0x1c000
	v_lshl_add_u64 v[4:5], s[20:21], 0, v[138:139]
	global_load_lds_dwordx4 v[4:5], off
	v_lshl_add_u64 v[4:5], s[20:21], 0, v[134:135]
	s_add_i32 m0, s50, 0x1e000
	s_movk_i32 s10, 0x3c0
	global_load_lds_dwordx4 v[4:5], off
	v_and_b32_e32 v4, 48, v146
	v_lshlrev_b32_e32 v5, 6, v146
	v_and_or_b32 v4, v5, s10, v4
	v_lshlrev_b32_e32 v5, 2, v146
	v_and_b32_e32 v5, 32, v5
	s_movk_i32 s10, 0x1600
	v_bitop3_b32 v6, v4, s4, v5 bitop3:0xde
	v_bitop3_b32 v147, v4, s19, v5 bitop3:0xde
	v_add_u32_e32 v147, 0x10000, v147
	v_lshrrev_b32_e32 v4, 1, v16
	v_mul_lo_u32 v2, v2, s10
	s_mov_b32 s4, 0x16000
	v_mad_u64_u32 v[4:5], s[20:21], v4, s4, v[2:3]
	v_or_b32_e32 v2, v4, v17
	v_add_lshl_u32 v2, v2, v18, 1
	s_mov_b64 s[22:23], 0x160080
	v_lshl_add_u64 v[142:143], v[2:3], 0, s[22:23]
	v_lshrrev_b32_e32 v4, 1, v12
	v_mul_lo_u32 v2, v13, s10
	v_mad_u64_u32 v[4:5], s[20:21], v4, s4, v[2:3]
	v_or_b32_e32 v2, v4, v14
	v_readlane_b32 s20, v243, 43
	s_waitcnt vmcnt(6)
	v_add_lshl_u32 v2, v2, v15, 1
	v_mov_b32_e32 v4, v3
	v_mov_b32_e32 v5, v3
	v_readlane_b32 s21, v243, 44
	s_cmp_gt_i32 s18, 63
	v_lshl_add_u64 v[144:145], v[2:3], 0, s[22:23]
	v_mov_b32_e32 v2, v3
	v_add_u32_e32 v148, 0, v6
	v_mov_b64_e32 v[8:9], v[4:5]
	v_mov_b64_e32 v[12:13], v[4:5]
	v_mov_b64_e32 v[24:25], v[4:5]
	v_mov_b64_e32 v[28:29], v[4:5]
	v_mov_b64_e32 v[40:41], v[4:5]
	v_mov_b64_e32 v[44:45], v[4:5]
	v_mov_b64_e32 v[56:57], v[4:5]
	v_mov_b64_e32 v[60:61], v[4:5]
	v_mov_b64_e32 v[16:17], v[4:5]
	v_mov_b64_e32 v[20:21], v[4:5]
	v_mov_b64_e32 v[32:33], v[4:5]
	v_mov_b64_e32 v[36:37], v[4:5]
	v_mov_b64_e32 v[48:49], v[4:5]
	v_mov_b64_e32 v[52:53], v[4:5]
	v_mov_b64_e32 v[64:65], v[4:5]
	v_mov_b64_e32 v[68:69], v[4:5]
	v_mov_b64_e32 v[72:73], v[4:5]
	v_mov_b64_e32 v[76:77], v[4:5]
	v_mov_b64_e32 v[88:89], v[4:5]
	v_mov_b64_e32 v[92:93], v[4:5]
	v_mov_b64_e32 v[104:105], v[4:5]
	v_mov_b64_e32 v[108:109], v[4:5]
	v_mov_b64_e32 v[120:121], v[4:5]
	v_mov_b64_e32 v[124:125], v[4:5]
	v_mov_b64_e32 v[80:81], v[4:5]
	v_mov_b64_e32 v[84:85], v[4:5]
	v_mov_b64_e32 v[96:97], v[4:5]
	v_mov_b64_e32 v[100:101], v[4:5]
	v_mov_b64_e32 v[112:113], v[4:5]
	v_mov_b64_e32 v[116:117], v[4:5]
	v_mov_b64_e32 v[128:129], v[4:5]
	v_mov_b64_e32 v[132:133], v[4:5]
	s_mov_b32 s4, s20
	v_readlane_b32 s20, v243, 39
	s_cselect_b64 s[18:19], -1, 0
	s_add_i32 s57, s54, -2
	s_mov_b32 s58, 0
	v_mov_b64_e32 v[6:7], v[2:3]
	v_mov_b64_e32 v[10:11], v[2:3]
	v_mov_b64_e32 v[22:23], v[2:3]
	v_mov_b64_e32 v[26:27], v[2:3]
	v_mov_b64_e32 v[38:39], v[2:3]
	v_mov_b64_e32 v[42:43], v[2:3]
	v_mov_b64_e32 v[54:55], v[2:3]
	v_mov_b64_e32 v[58:59], v[2:3]
	v_mov_b64_e32 v[14:15], v[2:3]
	v_mov_b64_e32 v[18:19], v[2:3]
	v_mov_b64_e32 v[30:31], v[2:3]
	v_mov_b64_e32 v[34:35], v[2:3]
	v_mov_b64_e32 v[46:47], v[2:3]
	v_mov_b64_e32 v[50:51], v[2:3]
	v_mov_b64_e32 v[62:63], v[2:3]
	v_mov_b64_e32 v[66:67], v[2:3]
	v_mov_b64_e32 v[70:71], v[2:3]
	v_mov_b64_e32 v[74:75], v[2:3]
	v_mov_b64_e32 v[86:87], v[2:3]
	v_mov_b64_e32 v[90:91], v[2:3]
	v_mov_b64_e32 v[102:103], v[2:3]
	v_mov_b64_e32 v[106:107], v[2:3]
	v_mov_b64_e32 v[118:119], v[2:3]
	v_mov_b64_e32 v[122:123], v[2:3]
	v_mov_b64_e32 v[78:79], v[2:3]
	v_mov_b64_e32 v[82:83], v[2:3]
	v_mov_b64_e32 v[94:95], v[2:3]
	v_mov_b64_e32 v[98:99], v[2:3]
	v_mov_b64_e32 v[110:111], v[2:3]
	v_mov_b64_e32 v[114:115], v[2:3]
	v_mov_b64_e32 v[126:127], v[2:3]
	v_mov_b64_e32 v[130:131], v[2:3]
	v_readlane_b32 s21, v243, 40
	s_mov_b32 s59, s20
	s_barrier
	s_branch .LBB0_2278

; #define PG8_STAGE(bufoff, gbase, voff) do { _Pragma("unroll") for (int _i = 0; _i < 2; ++_i) \
;         __builtin_amdgcn_global_load_lds((const unsigned*)((const char*)(gbase) + (voff)[_i]), (LAS unsigned*)(lds + (bufoff) + ldsw + _i * 8192), 16, 0, 0); } while (0)
; #define PG8_LDA(dst, b, h) do { _Pragma("unroll") for (int m = 0; m < 4; ++m) _Pragma("unroll") for (int k = 0; k < 2; ++k) dst[m][k] = *(const LAS bf16x8*)(lds + PG8_SA(b, h) + aoff + m * 2048 + k * 1024); } while (0)
; #define PG8_LDB(dst, b, h) do { _Pragma("unroll") for (int n = 0; n < 2; ++n) _Pragma("unroll") for (int k = 0; k < 2; ++k) dst[n][k] = *(const LAS bf16x8*)(lds + PG8_SB(b, h) + boff + n * 2048 + k * 1024); } while (0)
; #define PG8_MMA(ai, bj, At, Bt) do { __builtin_amdgcn_s_setprio(1); _Pragma("unroll") for (int m = 0; m < 4; ++m) _Pragma("unroll") for (int n = 0; n < 2; ++n) _Pragma("unroll") for (int k = 0; k < 2; ++k) \
;         acc[ai][bj][m][n] = __builtin_amdgcn_mfma_f32_16x16x32_bf16(Bt[n][k], At[m][k], acc[ai][bj][m][n], 0, 0, 0); __builtin_amdgcn_s_setprio(0); } while (0)
; #define PG8_WAIT_V(n) asm volatile("s_waitcnt vmcnt(" #n ")" ::: "memory")
; #define PG8_WAIT_L(n) asm volatile("s_waitcnt lgkmcnt(" #n ")" ::: "memory")
; #define PG8_BAR __builtin_amdgcn_s_barrier()
; #define PG8_WAIT_RELAX(flag, n) asm volatile("s_cmp_eq_u32 %0, 0\n\ts_cbranch_scc1 .Lrw%=\n\ts_waitcnt vmcnt(8)\n.Lrw%=:\n\ts_waitcnt vmcnt(%1)" :: "s"(flag), "n"(n) : "scc", "memory")
; #define PG8_SCHED __builtin_amdgcn_sched_barrier(0)
; template <class Epi, bool ALIGN_EPI = true>
; __device__ __forceinline__ void gemm_phase(LAS unsigned char* lds, const Gemm g, const Sched& S, const Epi& E) {
;     ...
;             PG8_LDB(B0, 0, 0); PG8_LDB(B1, 0, 1); PG8_SCHED; PG8_LDA(At, 0, 0); PG8_STAGE(PG8_SA(1, 1), a1 + hstepA, voffA);
;             if constexpr (Epi::NSTORES > 0) PG8_WAIT_RELAX(rflag, 8 + Epi::NSTORES); else PG8_WAIT_V(8);
;             PG8_WAIT_L(0); PG8_BAR; PG8_MMA(0, 0, At, B0); PG8_MMA(0, 1, At, B1); PG8_BAR; PG8_SCHED;
;             PG8_LDA(At, 0, 1); PG8_STAGE(PG8_SB(0, 0), b2, voffB); PG8_STAGE(PG8_SB(0, 1), b2 + hstepB, voffB); PG8_STAGE(PG8_SA(0, 0), a2, voffA);
;             if constexpr (Epi::NSTORES > 0) PG8_WAIT_RELAX(rflag, 8 + Epi::NSTORES); else PG8_WAIT_V(8);
;             PG8_WAIT_L(0); PG8_BAR; PG8_MMA(1, 0, At, B0); PG8_MMA(1, 1, At, B1); PG8_BAR; PG8_SCHED;
.LBB0_2287:
	s_add_i32 s69, s44, 2
	s_add_u32 s42, s48, 0x100
	s_addc_u32 s43, s49, 0
	s_add_i32 s70, 0, 0x10000
	s_cmp_eq_u32 s57, s44
	s_cselect_b32 s47, s63, s43
	s_cselect_b32 s46, s64, s42
	s_cselect_b32 s45, s65, s68
	s_cselect_b32 s44, s66, s67
	s_add_i32 s71, 0, 0x14000
	ds_read_b128 v[150:153], v147
	ds_read_b128 v[154:157], v147 offset:1024
	ds_read_b128 v[158:161], v147 offset:2048
	ds_read_b128 v[162:165], v147 offset:3072
	ds_read_b128 v[166:169], v147 offset:16384
	ds_read_b128 v[170:173], v147 offset:17408
	ds_read_b128 v[174:177], v147 offset:18432
	ds_read_b128 v[178:181], v147 offset:19456
	ds_read_b128 v[182:185], v148
	ds_read_b128 v[186:189], v148 offset:1024
	ds_read_b128 v[190:193], v148 offset:2048
	ds_read_b128 v[194:197], v148 offset:3072
	ds_read_b128 v[206:209], v148 offset:4096
	ds_read_b128 v[224:227], v148 offset:5120
	ds_read_b128 v[228:231], v148 offset:6144
	ds_read_b128 v[232:235], v148 offset:7168
	s_mov_b32 m0, s55
	s_add_u32 s100, s48, 0xffea0000
	s_addc_u32 s101, s49, -1
	global_load_lds_dwordx4 v142, s[100:101]
	s_mov_b32 m0, s56
	s_nop 0
	global_load_lds_dwordx4 v144, s[100:101]
	s_add_i32 m0, s50, 0xc000
	s_nop 0
	global_load_lds_dwordx4 v142, s[48:49]
	s_add_i32 m0, s50, 0xe000
	s_nop 0
	global_load_lds_dwordx4 v144, s[48:49]
	s_waitcnt vmcnt(8) lgkmcnt(0)
	s_barrier
	s_setprio 1
	v_mfma_f32_16x16x32_bf16 v[130:133], v[150:153], v[182:185], v[130:133]
	v_mfma_f32_16x16x32_bf16 v[126:129], v[158:161], v[182:185], v[126:129]
	v_mfma_f32_16x16x32_bf16 v[114:117], v[150:153], v[190:193], v[114:117]
	v_mfma_f32_16x16x32_bf16 v[110:113], v[158:161], v[190:193], v[110:113]
	v_mfma_f32_16x16x32_bf16 v[98:101], v[150:153], v[206:209], v[98:101]
	v_mfma_f32_16x16x32_bf16 v[94:97], v[158:161], v[206:209], v[94:97]
	v_mfma_f32_16x16x32_bf16 v[82:85], v[150:153], v[228:231], v[82:85]
	v_mfma_f32_16x16x32_bf16 v[78:81], v[158:161], v[228:231], v[78:81]
	v_mfma_f32_16x16x32_bf16 v[130:133], v[154:157], v[186:189], v[130:133]
	v_mfma_f32_16x16x32_bf16 v[126:129], v[162:165], v[186:189], v[126:129]
	v_mfma_f32_16x16x32_bf16 v[114:117], v[154:157], v[194:197], v[114:117]
	v_mfma_f32_16x16x32_bf16 v[110:113], v[162:165], v[194:197], v[110:113]
	v_mfma_f32_16x16x32_bf16 v[98:101], v[154:157], v[224:227], v[98:101]
	v_mfma_f32_16x16x32_bf16 v[94:97], v[162:165], v[224:227], v[94:97]
	v_mfma_f32_16x16x32_bf16 v[82:85], v[154:157], v[232:235], v[82:85]
	v_mfma_f32_16x16x32_bf16 v[78:81], v[162:165], v[232:235], v[78:81]
	s_setprio 0
	s_setprio 1
	v_mfma_f32_16x16x32_bf16 v[122:125], v[166:169], v[182:185], v[122:125]
	v_mfma_f32_16x16x32_bf16 v[118:121], v[174:177], v[182:185], v[118:121]
	v_mfma_f32_16x16x32_bf16 v[106:109], v[166:169], v[190:193], v[106:109]
	v_mfma_f32_16x16x32_bf16 v[102:105], v[174:177], v[190:193], v[102:105]
	v_mfma_f32_16x16x32_bf16 v[90:93], v[166:169], v[206:209], v[90:93]
	v_mfma_f32_16x16x32_bf16 v[86:89], v[174:177], v[206:209], v[86:89]
	v_mfma_f32_16x16x32_bf16 v[74:77], v[166:169], v[228:231], v[74:77]
	v_mfma_f32_16x16x32_bf16 v[70:73], v[174:177], v[228:231], v[70:73]
	v_mfma_f32_16x16x32_bf16 v[122:125], v[170:173], v[186:189], v[122:125]
	v_mfma_f32_16x16x32_bf16 v[118:121], v[178:181], v[186:189], v[118:121]
	v_mfma_f32_16x16x32_bf16 v[106:109], v[170:173], v[194:197], v[106:109]
	v_mfma_f32_16x16x32_bf16 v[102:105], v[178:181], v[194:197], v[102:105]
	v_mfma_f32_16x16x32_bf16 v[90:93], v[170:173], v[224:227], v[90:93]
	v_mfma_f32_16x16x32_bf16 v[86:89], v[178:181], v[224:227], v[86:89]
	v_mfma_f32_16x16x32_bf16 v[74:77], v[170:173], v[232:235], v[74:77]
	v_mfma_f32_16x16x32_bf16 v[70:73], v[178:181], v[232:235], v[70:73]
	s_setprio 0
	s_barrier
	s_add_i32 s48, s70, s37
	s_mov_b32 m0, s48
	ds_read_b128 v[182:185], v148 offset:16384
	ds_read_b128 v[186:189], v148 offset:17408
	ds_read_b128 v[190:193], v148 offset:18432
	ds_read_b128 v[194:197], v148 offset:19456
	ds_read_b128 v[206:209], v148 offset:20480
	ds_read_b128 v[224:227], v148 offset:21504
	ds_read_b128 v[228:231], v148 offset:22528
	ds_read_b128 v[232:235], v148 offset:23552
	global_load_lds_dwordx4 v138, s[44:45]
	s_add_i32 m0, s48, 0x2000
	s_add_u32 s48, s44, 0x160000
	s_addc_u32 s49, s45, 0
	s_add_i32 s70, s71, s37
	global_load_lds_dwordx4 v134, s[44:45]
	s_mov_b32 m0, s70
	s_nop 0
	global_load_lds_dwordx4 v138, s[48:49]
	s_add_i32 m0, s70, 0x2000
	s_nop 0
	global_load_lds_dwordx4 v134, s[48:49]
	s_waitcnt vmcnt(6) lgkmcnt(0)
	s_barrier
	s_setprio 1
	v_mfma_f32_16x16x32_bf16 v[66:69], v[150:153], v[182:185], v[66:69]
	v_mfma_f32_16x16x32_bf16 v[62:65], v[158:161], v[182:185], v[62:65]
	v_mfma_f32_16x16x32_bf16 v[50:53], v[150:153], v[190:193], v[50:53]
	v_mfma_f32_16x16x32_bf16 v[46:49], v[158:161], v[190:193], v[46:49]
	v_mfma_f32_16x16x32_bf16 v[34:37], v[150:153], v[206:209], v[34:37]
	v_mfma_f32_16x16x32_bf16 v[30:33], v[158:161], v[206:209], v[30:33]
	v_mfma_f32_16x16x32_bf16 v[18:21], v[150:153], v[228:231], v[18:21]
	v_mfma_f32_16x16x32_bf16 v[14:17], v[158:161], v[228:231], v[14:17]
	v_mfma_f32_16x16x32_bf16 v[66:69], v[154:157], v[186:189], v[66:69]
	v_mfma_f32_16x16x32_bf16 v[62:65], v[162:165], v[186:189], v[62:65]
	v_mfma_f32_16x16x32_bf16 v[50:53], v[154:157], v[194:197], v[50:53]
	v_mfma_f32_16x16x32_bf16 v[46:49], v[162:165], v[194:197], v[46:49]
	v_mfma_f32_16x16x32_bf16 v[34:37], v[154:157], v[224:227], v[34:37]
	v_mfma_f32_16x16x32_bf16 v[30:33], v[162:165], v[224:227], v[30:33]
	v_mfma_f32_16x16x32_bf16 v[18:21], v[154:157], v[232:235], v[18:21]
	v_mfma_f32_16x16x32_bf16 v[14:17], v[162:165], v[232:235], v[14:17]
	s_setprio 0
	s_setprio 1
	v_mfma_f32_16x16x32_bf16 v[58:61], v[166:169], v[182:185], v[58:61]
	v_mfma_f32_16x16x32_bf16 v[54:57], v[174:177], v[182:185], v[54:57]
	v_mfma_f32_16x16x32_bf16 v[42:45], v[166:169], v[190:193], v[42:45]
	v_mfma_f32_16x16x32_bf16 v[38:41], v[174:177], v[190:193], v[38:41]
	v_mfma_f32_16x16x32_bf16 v[26:29], v[166:169], v[206:209], v[26:29]
	v_mfma_f32_16x16x32_bf16 v[22:25], v[174:177], v[206:209], v[22:25]
	v_mfma_f32_16x16x32_bf16 v[10:13], v[166:169], v[228:231], v[10:13]
	v_mfma_f32_16x16x32_bf16 v[4:7], v[174:177], v[228:231], v[6:9]
	v_mfma_f32_16x16x32_bf16 v[58:61], v[170:173], v[186:189], v[58:61]
	v_mfma_f32_16x16x32_bf16 v[54:57], v[178:181], v[186:189], v[54:57]
	v_mfma_f32_16x16x32_bf16 v[42:45], v[170:173], v[194:197], v[42:45]
	v_mfma_f32_16x16x32_bf16 v[38:41], v[178:181], v[194:197], v[38:41]
	v_mfma_f32_16x16x32_bf16 v[26:29], v[170:173], v[224:227], v[26:29]
	v_mfma_f32_16x16x32_bf16 v[22:25], v[178:181], v[224:227], v[22:25]
	v_mfma_f32_16x16x32_bf16 v[10:13], v[170:173], v[232:235], v[10:13]
	v_mfma_f32_16x16x32_bf16 v[4:7], v[178:181], v[232:235], v[4:7]
	s_setprio 0
	s_barrier
; #define PG8_STAGE(bufoff, gbase, voff) do { _Pragma("unroll") for (int _i = 0; _i < 2; ++_i) \
;         __builtin_amdgcn_global_load_lds((const unsigned*)((const char*)(gbase) + (voff)[_i]), (LAS unsigned*)(lds + (bufoff) + ldsw + _i * 8192), 16, 0, 0); } while (0)
; #define PG8_LDA(dst, b, h) do { _Pragma("unroll") for (int m = 0; m < 4; ++m) _Pragma("unroll") for (int k = 0; k < 2; ++k) dst[m][k] = *(const LAS bf16x8*)(lds + PG8_SA(b, h) + aoff + m * 2048 + k * 1024); } while (0)
; #define PG8_LDB(dst, b, h) do { _Pragma("unroll") for (int n = 0; n < 2; ++n) _Pragma("unroll") for (int k = 0; k < 2; ++k) dst[n][k] = *(const LAS bf16x8*)(lds + PG8_SB(b, h) + boff + n * 2048 + k * 1024); } while (0)
; #define PG8_MMA(ai, bj, At, Bt) do { __builtin_amdgcn_s_setprio(1); _Pragma("unroll") for (int m = 0; m < 4; ++m) _Pragma("unroll") for (int n = 0; n < 2; ++n) _Pragma("unroll") for (int k = 0; k < 2; ++k) \
;         acc[ai][bj][m][n] = __builtin_amdgcn_mfma_f32_16x16x32_bf16(Bt[n][k], At[m][k], acc[ai][bj][m][n], 0, 0, 0); __builtin_amdgcn_s_setprio(0); } while (0)
; #define PG8_WAIT_V(n) asm volatile("s_waitcnt vmcnt(" #n ")" ::: "memory")
; #define PG8_WAIT_L(n) asm volatile("s_waitcnt lgkmcnt(" #n ")" ::: "memory")
; #define PG8_BAR __builtin_amdgcn_s_barrier()
; #define PG8_SCHED __builtin_amdgcn_sched_barrier(0)
; template <class Epi, bool ALIGN_EPI = true>
; __device__ __forceinline__ void gemm_phase(LAS unsigned char* lds, const Gemm g, const Sched& S, const Epi& E) {
;     ...
;             PG8_LDB(B0, 1, 0); PG8_LDB(B1, 1, 1); PG8_SCHED; PG8_LDA(At, 1, 0); PG8_STAGE(PG8_SA(0, 1), a2 + hstepA, voffA);
;             PG8_WAIT_V(8); PG8_WAIT_L(0); PG8_BAR; PG8_MMA(0, 0, At, B0); PG8_MMA(0, 1, At, B1); PG8_BAR; PG8_SCHED;
;             PG8_LDA(At, 1, 1); PG8_STAGE(PG8_SB(1, 0), b3, voffB); PG8_STAGE(PG8_SB(1, 1), b3 + hstepB, voffB); PG8_STAGE(PG8_SA(1, 0), a3, voffA);
;             PG8_WAIT_V(8); PG8_WAIT_L(0); PG8_BAR; PG8_MMA(1, 0, At, B0); PG8_MMA(1, 1, At, B1); PG8_BAR; PG8_SCHED;
;         }
	s_add_i32 s48, 0, 0x18000
	s_add_i32 s49, 0, 0x1c000
	ds_read_b128 v[150:153], v147 offset:32768
	ds_read_b128 v[154:157], v147 offset:33792
	ds_read_b128 v[158:161], v147 offset:34816
	ds_read_b128 v[162:165], v147 offset:35840
	ds_read_b128 v[166:169], v147 offset:49152
	ds_read_b128 v[170:173], v147 offset:50176
	ds_read_b128 v[174:177], v147 offset:51200
	ds_read_b128 v[178:181], v147 offset:52224
	s_add_u32 s46, s46, 0x160000
	s_addc_u32 s47, s47, 0
	ds_read_b128 v[182:185], v148 offset:32768
	ds_read_b128 v[186:189], v148 offset:33792
	ds_read_b128 v[190:193], v148 offset:34816
	ds_read_b128 v[194:197], v148 offset:35840
	ds_read_b128 v[206:209], v148 offset:36864
	ds_read_b128 v[224:227], v148 offset:37888
	ds_read_b128 v[228:231], v148 offset:38912
	ds_read_b128 v[232:235], v148 offset:39936
	s_mov_b32 m0, s50
	s_add_u32 s100, s46, 0xffea0000
	s_addc_u32 s101, s47, -1
	global_load_lds_dwordx4 v140, s[100:101]
	s_mov_b32 m0, s51
	s_nop 0
	global_load_lds_dwordx4 v136, s[100:101]
	s_mov_b32 m0, s52
	s_nop 0
	global_load_lds_dwordx4 v140, s[46:47]
	s_mov_b32 m0, s53
	s_nop 0
	global_load_lds_dwordx4 v136, s[46:47]
	s_waitcnt vmcnt(8) lgkmcnt(0)
	s_barrier
	s_setprio 1
	v_mfma_f32_16x16x32_bf16 v[130:133], v[150:153], v[182:185], v[130:133]
	v_mfma_f32_16x16x32_bf16 v[126:129], v[158:161], v[182:185], v[126:129]
	v_mfma_f32_16x16x32_bf16 v[114:117], v[150:153], v[190:193], v[114:117]
	v_mfma_f32_16x16x32_bf16 v[110:113], v[158:161], v[190:193], v[110:113]
	v_mfma_f32_16x16x32_bf16 v[98:101], v[150:153], v[206:209], v[98:101]
	v_mfma_f32_16x16x32_bf16 v[94:97], v[158:161], v[206:209], v[94:97]
	v_mfma_f32_16x16x32_bf16 v[82:85], v[150:153], v[228:231], v[82:85]
	v_mfma_f32_16x16x32_bf16 v[78:81], v[158:161], v[228:231], v[78:81]
	v_mfma_f32_16x16x32_bf16 v[130:133], v[154:157], v[186:189], v[130:133]
	v_mfma_f32_16x16x32_bf16 v[126:129], v[162:165], v[186:189], v[126:129]
	v_mfma_f32_16x16x32_bf16 v[114:117], v[154:157], v[194:197], v[114:117]
	v_mfma_f32_16x16x32_bf16 v[110:113], v[162:165], v[194:197], v[110:113]
	v_mfma_f32_16x16x32_bf16 v[98:101], v[154:157], v[224:227], v[98:101]
	v_mfma_f32_16x16x32_bf16 v[94:97], v[162:165], v[224:227], v[94:97]
	v_mfma_f32_16x16x32_bf16 v[82:85], v[154:157], v[232:235], v[82:85]
	v_mfma_f32_16x16x32_bf16 v[78:81], v[162:165], v[232:235], v[78:81]
	s_setprio 0
	s_setprio 1
	v_mfma_f32_16x16x32_bf16 v[122:125], v[166:169], v[182:185], v[122:125]
	v_mfma_f32_16x16x32_bf16 v[118:121], v[174:177], v[182:185], v[118:121]
	v_mfma_f32_16x16x32_bf16 v[106:109], v[166:169], v[190:193], v[106:109]
	v_mfma_f32_16x16x32_bf16 v[102:105], v[174:177], v[190:193], v[102:105]
	v_mfma_f32_16x16x32_bf16 v[90:93], v[166:169], v[206:209], v[90:93]
	v_mfma_f32_16x16x32_bf16 v[86:89], v[174:177], v[206:209], v[86:89]
	v_mfma_f32_16x16x32_bf16 v[74:77], v[166:169], v[228:231], v[74:77]
	v_mfma_f32_16x16x32_bf16 v[70:73], v[174:177], v[228:231], v[70:73]
	v_mfma_f32_16x16x32_bf16 v[122:125], v[170:173], v[186:189], v[122:125]
	v_mfma_f32_16x16x32_bf16 v[118:121], v[178:181], v[186:189], v[118:121]
	v_mfma_f32_16x16x32_bf16 v[106:109], v[170:173], v[194:197], v[106:109]
	v_mfma_f32_16x16x32_bf16 v[102:105], v[178:181], v[194:197], v[102:105]
	v_mfma_f32_16x16x32_bf16 v[90:93], v[170:173], v[224:227], v[90:93]
	v_mfma_f32_16x16x32_bf16 v[86:89], v[178:181], v[224:227], v[86:89]
	v_mfma_f32_16x16x32_bf16 v[74:77], v[170:173], v[232:235], v[74:77]
	v_mfma_f32_16x16x32_bf16 v[70:73], v[178:181], v[232:235], v[70:73]
	s_setprio 0
	s_barrier
	s_add_u32 s100, s44, 0x80
	s_addc_u32 s101, s45, 0
	s_add_i32 s46, s48, s37
	s_mov_b32 m0, s46
	ds_read_b128 v[182:185], v148 offset:49152
	ds_read_b128 v[186:189], v148 offset:50176
	ds_read_b128 v[190:193], v148 offset:51200
	ds_read_b128 v[194:197], v148 offset:52224
	ds_read_b128 v[206:209], v148 offset:53248
	ds_read_b128 v[224:227], v148 offset:54272
	ds_read_b128 v[228:231], v148 offset:55296
	ds_read_b128 v[232:235], v148 offset:56320
	global_load_lds_dwordx4 v138, s[100:101]
	s_add_i32 m0, s46, 0x2000
	s_add_u32 s44, s44, 0x160080
	s_addc_u32 s45, s45, 0
	s_add_i32 s46, s49, s37
	global_load_lds_dwordx4 v134, s[100:101]
	s_mov_b32 m0, s46
	s_nop 0
	global_load_lds_dwordx4 v138, s[44:45]
	s_add_i32 m0, s46, 0x2000
	s_nop 0
	global_load_lds_dwordx4 v134, s[44:45]
	s_waitcnt vmcnt(6) lgkmcnt(0)
	s_barrier
	s_setprio 1
	v_mfma_f32_16x16x32_bf16 v[66:69], v[150:153], v[182:185], v[66:69]
	v_mfma_f32_16x16x32_bf16 v[62:65], v[158:161], v[182:185], v[62:65]
	v_mfma_f32_16x16x32_bf16 v[50:53], v[150:153], v[190:193], v[50:53]
	v_mfma_f32_16x16x32_bf16 v[46:49], v[158:161], v[190:193], v[46:49]
	v_mfma_f32_16x16x32_bf16 v[34:37], v[150:153], v[206:209], v[34:37]
	v_mfma_f32_16x16x32_bf16 v[30:33], v[158:161], v[206:209], v[30:33]
	v_mfma_f32_16x16x32_bf16 v[18:21], v[150:153], v[228:231], v[18:21]
	v_mfma_f32_16x16x32_bf16 v[14:17], v[158:161], v[228:231], v[14:17]
	v_mfma_f32_16x16x32_bf16 v[66:69], v[154:157], v[186:189], v[66:69]
	v_mfma_f32_16x16x32_bf16 v[62:65], v[162:165], v[186:189], v[62:65]
	v_mfma_f32_16x16x32_bf16 v[50:53], v[154:157], v[194:197], v[50:53]
	v_mfma_f32_16x16x32_bf16 v[46:49], v[162:165], v[194:197], v[46:49]
	v_mfma_f32_16x16x32_bf16 v[34:37], v[154:157], v[224:227], v[34:37]
	v_mfma_f32_16x16x32_bf16 v[30:33], v[162:165], v[224:227], v[30:33]
	v_mfma_f32_16x16x32_bf16 v[18:21], v[154:157], v[232:235], v[18:21]
	v_mfma_f32_16x16x32_bf16 v[14:17], v[162:165], v[232:235], v[14:17]
	s_setprio 0
	s_setprio 1
	v_mfma_f32_16x16x32_bf16 v[58:61], v[166:169], v[182:185], v[58:61]
	v_mfma_f32_16x16x32_bf16 v[54:57], v[174:177], v[182:185], v[54:57]
	v_mfma_f32_16x16x32_bf16 v[42:45], v[166:169], v[190:193], v[42:45]
	v_mfma_f32_16x16x32_bf16 v[38:41], v[174:177], v[190:193], v[38:41]
	v_mfma_f32_16x16x32_bf16 v[26:29], v[166:169], v[206:209], v[26:29]
	v_mfma_f32_16x16x32_bf16 v[22:25], v[174:177], v[206:209], v[22:25]
	v_mfma_f32_16x16x32_bf16 v[8:11], v[166:169], v[228:231], v[10:13]
	v_mfma_f32_16x16x32_bf16 v[4:7], v[174:177], v[228:231], v[4:7]
	v_mfma_f32_16x16x32_bf16 v[58:61], v[170:173], v[186:189], v[58:61]
	v_mfma_f32_16x16x32_bf16 v[54:57], v[178:181], v[186:189], v[54:57]
	v_mfma_f32_16x16x32_bf16 v[42:45], v[170:173], v[194:197], v[42:45]
	v_mfma_f32_16x16x32_bf16 v[38:41], v[178:181], v[194:197], v[38:41]
	v_mfma_f32_16x16x32_bf16 v[26:29], v[170:173], v[224:227], v[26:29]
	v_mfma_f32_16x16x32_bf16 v[22:25], v[178:181], v[224:227], v[22:25]
	v_mfma_f32_16x16x32_bf16 v[10:13], v[170:173], v[232:235], v[8:11]
	v_mfma_f32_16x16x32_bf16 v[6:9], v[178:181], v[232:235], v[4:7]
	s_setprio 0
	s_barrier
	s_add_u32 s67, s67, 0x100
	s_addc_u32 s68, s68, 0
	s_cmp_ge_i32 s69, s54
	s_mov_b64 s[48:49], s[42:43]
	s_mov_b32 s44, s69
	s_cbranch_scc0 .LBB0_2287
